# removed redundant mid-block s_setprio 0/1 flips and post-barrier lgkmcnt(0) in all K-loops
# speedup vs baseline: 1.0151x; 1.0038x over previous
; #define PG8_STAGE(bufoff, gbase, voff) do { _Pragma("unroll") for (int _i = 0; _i < 2; ++_i) \
;         __builtin_amdgcn_global_load_lds((const unsigned*)((const char*)(gbase) + (voff)[_i]), (LAS unsigned*)(lds + (bufoff) + ldsw + _i * 8192), 16, 0, 0); } while (0)
; #define PG8_LDA(dst, b, h) do { _Pragma("unroll") for (int m = 0; m < 4; ++m) _Pragma("unroll") for (int k = 0; k < 2; ++k) dst[m][k] = *(const LAS bf16x8*)(lds + PG8_SA(b, h) + aoff + m * 2048 + k * 1024); } while (0)
; #define PG8_LDB(dst, b, h) do { _Pragma("unroll") for (int n = 0; n < 2; ++n) _Pragma("unroll") for (int k = 0; k < 2; ++k) dst[n][k] = *(const LAS bf16x8*)(lds + PG8_SB(b, h) + boff + n * 2048 + k * 1024); } while (0)
; #define PG8_MMA(ai, bj, At, Bt) do { __builtin_amdgcn_s_setprio(1); _Pragma("unroll") for (int m = 0; m < 4; ++m) _Pragma("unroll") for (int n = 0; n < 2; ++n) _Pragma("unroll") for (int k = 0; k < 2; ++k) \
;         acc[ai][bj][m][n] = __builtin_amdgcn_mfma_f32_16x16x32_bf16(Bt[n][k], At[m][k], acc[ai][bj][m][n], 0, 0, 0); __builtin_amdgcn_s_setprio(0); } while (0)
; #define PG8_WAIT_V(n) asm volatile("s_waitcnt vmcnt(" #n ")" ::: "memory")
; #define PG8_WAIT_L(n) asm volatile("s_waitcnt lgkmcnt(" #n ")" ::: "memory")
; #define PG8_BAR __builtin_amdgcn_s_barrier()
; #define PG8_SCHED __builtin_amdgcn_sched_barrier(0)
; template <class Epi, class Sched>
; __device__ __forceinline__ void gemm_phase(const int tid, LAS unsigned char* lds, const int lda, const int ldb, const int K, const Sched& S, const Epi& E) {
;     ...
;             const bool last = (t == nt - 2);
;             const char* a1 = cA + (size_t)(t + 1) * kstep;
;             const char* a2 = last ? nA : cA + (size_t)(t + 2) * kstep; const char* b2 = last ? nB : cB + (size_t)(t + 2) * kstep;
;             const char* a3 = a2 + kstep; const char* b3 = b2 + kstep;
;             PG8_LDB(B0, 0, 0); PG8_LDB(B1, 0, 1); PG8_SCHED; PG8_LDA(At, 0, 0); PG8_STAGE(PG8_SA(1, 1), a1 + hstepA, voffA);
;             PG8_WAIT_V(8); PG8_WAIT_L(0); PG8_BAR; PG8_MMA(0, 0, At, B0); PG8_MMA(0, 1, At, B1); PG8_BAR; PG8_SCHED;
;             PG8_LDA(At, 0, 1); PG8_STAGE(PG8_SB(0, 0), b2, voffB); PG8_STAGE(PG8_SB(0, 1), b2 + hstepB, voffB); PG8_STAGE(PG8_SA(0, 0), a2, voffA);
;             PG8_WAIT_V(8); PG8_WAIT_L(0); PG8_BAR; if (!cur.half) { PG8_MMA(1, 0, At, B0); PG8_MMA(1, 1, At, B1); } PG8_BAR; PG8_SCHED;
.LBB0_53:
	s_add_i32 s24, s58, 2
	s_add_u32 s52, s50, 0x100
	s_addc_u32 s53, s51, 0
	s_add_i32 s14, 0, 0x10000
	s_cmp_eq_u32 s68, s58
	s_cselect_b32 s61, s55, s53
	s_cselect_b32 s60, s54, s52
	v_add_u32_e32 v153, s14, v137
	s_cselect_b32 s59, s57, vcc_hi
	s_cselect_b32 s58, s56, vcc_lo
	s_add_i32 s15, 0, 0x14000
	ds_read_b128 v[142:145], v153
	ds_read_b128 v[154:157], v153 offset:1024
	ds_read_b128 v[158:161], v153 offset:2048
	ds_read_b128 v[162:165], v153 offset:3072
	v_add_u32_e32 v153, s15, v137
	ds_read_b128 v[180:183], v153
	ds_read_b128 v[184:187], v153 offset:1024
	ds_read_b128 v[190:193], v153 offset:2048
	ds_read_b128 v[194:197], v153 offset:3072
	v_lshl_add_u64 v[166:167], s[50:51], 0, v[138:139]
	s_add_i32 m0, s26, 0xc000
	ds_read_b128 v[206:209], v152
	ds_read_b128 v[210:213], v152 offset:1024
	ds_read_b128 v[214:217], v152 offset:2048
	ds_read_b128 v[218:221], v152 offset:3072
	ds_read_b128 v[222:225], v152 offset:4096
	ds_read_b128 v[226:229], v152 offset:5120
	ds_read_b128 v[230:233], v152 offset:6144
	ds_read_b128 v[234:237], v152 offset:7168
	global_load_lds_dwordx4 v[166:167], off
	v_lshl_add_u64 v[166:167], s[50:51], 0, v[140:141]
	s_add_i32 m0, s26, 0xe000
	s_nop 0
	global_load_lds_dwordx4 v[166:167], off
	s_waitcnt vmcnt(8)
	s_waitcnt lgkmcnt(0)
	s_barrier
	s_setprio 1
	v_mfma_f32_16x16x32_bf16 v[124:127], v[142:145], v[206:209], v[124:127]
	v_mfma_f32_16x16x32_bf16 v[120:123], v[158:161], v[206:209], v[120:123]
	v_mfma_f32_16x16x32_bf16 v[108:111], v[142:145], v[214:217], v[108:111]
	v_mfma_f32_16x16x32_bf16 v[104:107], v[158:161], v[214:217], v[104:107]
	v_mfma_f32_16x16x32_bf16 v[92:95], v[142:145], v[222:225], v[92:95]
	v_mfma_f32_16x16x32_bf16 v[88:91], v[158:161], v[222:225], v[88:91]
	v_mfma_f32_16x16x32_bf16 v[76:79], v[142:145], v[230:233], v[76:79]
	v_mfma_f32_16x16x32_bf16 v[72:75], v[158:161], v[230:233], v[72:75]
	v_mfma_f32_16x16x32_bf16 v[124:127], v[154:157], v[210:213], v[124:127]
	v_mfma_f32_16x16x32_bf16 v[120:123], v[162:165], v[210:213], v[120:123]
	v_mfma_f32_16x16x32_bf16 v[108:111], v[154:157], v[218:221], v[108:111]
	v_mfma_f32_16x16x32_bf16 v[104:107], v[162:165], v[218:221], v[104:107]
	v_mfma_f32_16x16x32_bf16 v[92:95], v[154:157], v[226:229], v[92:95]
	v_mfma_f32_16x16x32_bf16 v[88:91], v[162:165], v[226:229], v[88:91]
	v_mfma_f32_16x16x32_bf16 v[76:79], v[154:157], v[234:237], v[76:79]
	v_mfma_f32_16x16x32_bf16 v[72:75], v[162:165], v[234:237], v[72:75]
	v_mfma_f32_16x16x32_bf16 v[116:119], v[180:183], v[206:209], v[116:119]
	v_mfma_f32_16x16x32_bf16 v[112:115], v[190:193], v[206:209], v[112:115]
	v_mfma_f32_16x16x32_bf16 v[100:103], v[180:183], v[214:217], v[100:103]
	v_mfma_f32_16x16x32_bf16 v[96:99], v[190:193], v[214:217], v[96:99]
	v_mfma_f32_16x16x32_bf16 v[84:87], v[180:183], v[222:225], v[84:87]
	v_mfma_f32_16x16x32_bf16 v[80:83], v[190:193], v[222:225], v[80:83]
	v_mfma_f32_16x16x32_bf16 v[68:71], v[180:183], v[230:233], v[68:71]
	v_mfma_f32_16x16x32_bf16 v[64:67], v[190:193], v[230:233], v[64:67]
	v_mfma_f32_16x16x32_bf16 v[116:119], v[184:187], v[210:213], v[116:119]
	v_mfma_f32_16x16x32_bf16 v[112:115], v[194:197], v[210:213], v[112:115]
	v_mfma_f32_16x16x32_bf16 v[100:103], v[184:187], v[218:221], v[100:103]
	v_mfma_f32_16x16x32_bf16 v[96:99], v[194:197], v[218:221], v[96:99]
	v_mfma_f32_16x16x32_bf16 v[84:87], v[184:187], v[226:229], v[84:87]
	v_mfma_f32_16x16x32_bf16 v[80:83], v[194:197], v[226:229], v[80:83]
	v_mfma_f32_16x16x32_bf16 v[68:71], v[184:187], v[234:237], v[68:71]
	v_mfma_f32_16x16x32_bf16 v[64:67], v[194:197], v[234:237], v[64:67]
	s_setprio 0
	s_barrier
	s_add_i32 s14, s14, s31
	v_lshl_add_u64 v[166:167], s[58:59], 0, v[130:131]
	s_mov_b32 m0, s14
	ds_read_b128 v[206:209], v152 offset:16384
	ds_read_b128 v[210:213], v152 offset:17408
	ds_read_b128 v[214:217], v152 offset:18432
	ds_read_b128 v[218:221], v152 offset:19456
	ds_read_b128 v[222:225], v152 offset:20480
	ds_read_b128 v[226:229], v152 offset:21504
	ds_read_b128 v[230:233], v152 offset:22528
	ds_read_b128 v[234:237], v152 offset:23552
	global_load_lds_dwordx4 v[166:167], off
	s_add_i32 m0, s14, 0x2000
	s_add_u32 s50, s58, 0xb0000
	v_lshl_add_u64 v[238:239], s[58:59], 0, v[134:135]
	s_addc_u32 s51, s59, 0
	s_add_i32 s14, s15, s31
	global_load_lds_dwordx4 v[238:239], off
	v_lshl_add_u64 v[240:241], s[50:51], 0, v[130:131]
	s_mov_b32 m0, s14
	v_lshl_add_u64 v[242:243], s[60:61], 0, v[132:133]
	global_load_lds_dwordx4 v[240:241], off
	v_lshl_add_u64 v[240:241], s[50:51], 0, v[134:135]
	s_add_i32 m0, s14, 0x2000
	s_nop 0
	global_load_lds_dwordx4 v[240:241], off
	v_lshl_add_u64 v[240:241], s[60:61], 0, v[128:129]
	s_mov_b32 m0, s26
	s_nop 0
	global_load_lds_dwordx4 v[240:241], off
	s_mov_b32 m0, s27
	s_nop 0
	global_load_lds_dwordx4 v[242:243], off
	s_waitcnt vmcnt(8)
	s_waitcnt lgkmcnt(0)
	s_barrier
; #define PG8_STAGE(bufoff, gbase, voff) do { _Pragma("unroll") for (int _i = 0; _i < 2; ++_i) \
;         __builtin_amdgcn_global_load_lds((const unsigned*)((const char*)(gbase) + (voff)[_i]), (LAS unsigned*)(lds + (bufoff) + ldsw + _i * 8192), 16, 0, 0); } while (0)
; #define PG8_LDA(dst, b, h) do { _Pragma("unroll") for (int m = 0; m < 4; ++m) _Pragma("unroll") for (int k = 0; k < 2; ++k) dst[m][k] = *(const LAS bf16x8*)(lds + PG8_SA(b, h) + aoff + m * 2048 + k * 1024); } while (0)
; #define PG8_LDB(dst, b, h) do { _Pragma("unroll") for (int n = 0; n < 2; ++n) _Pragma("unroll") for (int k = 0; k < 2; ++k) dst[n][k] = *(const LAS bf16x8*)(lds + PG8_SB(b, h) + boff + n * 2048 + k * 1024); } while (0)
; #define PG8_MMA(ai, bj, At, Bt) do { __builtin_amdgcn_s_setprio(1); _Pragma("unroll") for (int m = 0; m < 4; ++m) _Pragma("unroll") for (int n = 0; n < 2; ++n) _Pragma("unroll") for (int k = 0; k < 2; ++k) \
;         acc[ai][bj][m][n] = __builtin_amdgcn_mfma_f32_16x16x32_bf16(Bt[n][k], At[m][k], acc[ai][bj][m][n], 0, 0, 0); __builtin_amdgcn_s_setprio(0); } while (0)
; #define PG8_WAIT_V(n) asm volatile("s_waitcnt vmcnt(" #n ")" ::: "memory")
; #define PG8_WAIT_L(n) asm volatile("s_waitcnt lgkmcnt(" #n ")" ::: "memory")
; #define PG8_BAR __builtin_amdgcn_s_barrier()
; #define PG8_SCHED __builtin_amdgcn_sched_barrier(0)
; template <class Epi, class Sched>
; __device__ __forceinline__ void gemm_phase(const int tid, LAS unsigned char* lds, const int lda, const int ldb, const int K, const Sched& S, const Epi& E) {
;     ...
;             PG8_WAIT_V(8); PG8_WAIT_L(0); PG8_BAR; if (!cur.half) { PG8_MMA(1, 0, At, B0); PG8_MMA(1, 1, At, B1); } PG8_BAR; PG8_SCHED;
;             PG8_LDB(B0, 1, 0); PG8_LDB(B1, 1, 1); PG8_SCHED; PG8_LDA(At, 1, 0); PG8_STAGE(PG8_SA(0, 1), a2 + hstepA, voffA);
;             PG8_WAIT_V(8); PG8_WAIT_L(0); PG8_BAR; PG8_MMA(0, 0, At, B0); PG8_MMA(0, 1, At, B1); PG8_BAR; PG8_SCHED;
	s_setprio 1
	v_mfma_f32_16x16x32_bf16 v[60:63], v[142:145], v[206:209], v[60:63]
	v_mfma_f32_16x16x32_bf16 v[56:59], v[158:161], v[206:209], v[56:59]
	v_mfma_f32_16x16x32_bf16 v[44:47], v[142:145], v[214:217], v[44:47]
	v_mfma_f32_16x16x32_bf16 v[40:43], v[158:161], v[214:217], v[40:43]
	v_mfma_f32_16x16x32_bf16 v[28:31], v[142:145], v[222:225], v[28:31]
	v_mfma_f32_16x16x32_bf16 v[24:27], v[158:161], v[222:225], v[24:27]
	v_mfma_f32_16x16x32_bf16 v[12:15], v[142:145], v[230:233], v[12:15]
	v_mfma_f32_16x16x32_bf16 v[8:11], v[158:161], v[230:233], v[8:11]
	v_mfma_f32_16x16x32_bf16 v[60:63], v[154:157], v[210:213], v[60:63]
	v_mfma_f32_16x16x32_bf16 v[56:59], v[162:165], v[210:213], v[56:59]
	v_mfma_f32_16x16x32_bf16 v[44:47], v[154:157], v[218:221], v[44:47]
	v_mfma_f32_16x16x32_bf16 v[40:43], v[162:165], v[218:221], v[40:43]
	v_mfma_f32_16x16x32_bf16 v[28:31], v[154:157], v[226:229], v[28:31]
	v_mfma_f32_16x16x32_bf16 v[24:27], v[162:165], v[226:229], v[24:27]
	v_mfma_f32_16x16x32_bf16 v[12:15], v[154:157], v[234:237], v[12:15]
	v_mfma_f32_16x16x32_bf16 v[8:11], v[162:165], v[234:237], v[8:11]
	v_mfma_f32_16x16x32_bf16 v[52:55], v[180:183], v[206:209], v[52:55]
	v_mfma_f32_16x16x32_bf16 v[48:51], v[190:193], v[206:209], v[48:51]
	v_mfma_f32_16x16x32_bf16 v[36:39], v[180:183], v[214:217], v[36:39]
	v_mfma_f32_16x16x32_bf16 v[32:35], v[190:193], v[214:217], v[32:35]
	v_mfma_f32_16x16x32_bf16 v[20:23], v[180:183], v[222:225], v[20:23]
	v_mfma_f32_16x16x32_bf16 v[16:19], v[190:193], v[222:225], v[16:19]
	v_mfma_f32_16x16x32_bf16 v[4:7], v[180:183], v[230:233], v[4:7]
	v_mfma_f32_16x16x32_bf16 v[0:3], v[190:193], v[230:233], v[0:3]
	v_mfma_f32_16x16x32_bf16 v[52:55], v[184:187], v[210:213], v[52:55]
	v_mfma_f32_16x16x32_bf16 v[48:51], v[194:197], v[210:213], v[48:51]
	v_mfma_f32_16x16x32_bf16 v[36:39], v[184:187], v[218:221], v[36:39]
	v_mfma_f32_16x16x32_bf16 v[32:35], v[194:197], v[218:221], v[32:35]
	v_mfma_f32_16x16x32_bf16 v[20:23], v[184:187], v[226:229], v[20:23]
	v_mfma_f32_16x16x32_bf16 v[16:19], v[194:197], v[226:229], v[16:19]
	v_mfma_f32_16x16x32_bf16 v[4:7], v[184:187], v[234:237], v[4:7]
	v_mfma_f32_16x16x32_bf16 v[0:3], v[194:197], v[234:237], v[0:3]
	s_setprio 0
	s_barrier
	s_add_i32 s14, 0, 0x18000
	v_add_u32_e32 v153, s14, v137
	s_add_i32 s15, 0, 0x1c000
	ds_read_b128 v[142:145], v153
	ds_read_b128 v[154:157], v153 offset:1024
	ds_read_b128 v[158:161], v153 offset:2048
	ds_read_b128 v[162:165], v153 offset:3072
	v_add_u32_e32 v153, s15, v137
	ds_read_b128 v[180:183], v153
	ds_read_b128 v[184:187], v153 offset:1024
	ds_read_b128 v[190:193], v153 offset:2048
	ds_read_b128 v[194:197], v153 offset:3072
	s_add_u32 s50, s60, 0xb0000
	s_addc_u32 s51, s61, 0
	s_mov_b32 m0, s62
	v_lshl_add_u64 v[244:245], s[50:51], 0, v[128:129]
	ds_read_b128 v[206:209], v152 offset:32768
	ds_read_b128 v[210:213], v152 offset:33792
	ds_read_b128 v[214:217], v152 offset:34816
	ds_read_b128 v[218:221], v152 offset:35840
	ds_read_b128 v[222:225], v152 offset:36864
	ds_read_b128 v[226:229], v152 offset:37888
	ds_read_b128 v[230:233], v152 offset:38912
	ds_read_b128 v[234:237], v152 offset:39936
	global_load_lds_dwordx4 v[244:245], off
	v_lshl_add_u64 v[244:245], s[50:51], 0, v[132:133]
	s_mov_b32 m0, s63
	s_nop 0
	global_load_lds_dwordx4 v[244:245], off
	s_waitcnt vmcnt(8)
	s_waitcnt lgkmcnt(0)
	s_barrier
	s_setprio 1
	v_mfma_f32_16x16x32_bf16 v[124:127], v[142:145], v[206:209], v[124:127]
	v_mfma_f32_16x16x32_bf16 v[120:123], v[158:161], v[206:209], v[120:123]
	v_mfma_f32_16x16x32_bf16 v[108:111], v[142:145], v[214:217], v[108:111]
	v_mfma_f32_16x16x32_bf16 v[104:107], v[158:161], v[214:217], v[104:107]
	v_mfma_f32_16x16x32_bf16 v[92:95], v[142:145], v[222:225], v[92:95]
	v_mfma_f32_16x16x32_bf16 v[88:91], v[158:161], v[222:225], v[88:91]
	v_mfma_f32_16x16x32_bf16 v[76:79], v[142:145], v[230:233], v[76:79]
	v_mfma_f32_16x16x32_bf16 v[72:75], v[158:161], v[230:233], v[72:75]
	v_mfma_f32_16x16x32_bf16 v[124:127], v[154:157], v[210:213], v[124:127]
	v_mfma_f32_16x16x32_bf16 v[120:123], v[162:165], v[210:213], v[120:123]
	v_mfma_f32_16x16x32_bf16 v[108:111], v[154:157], v[218:221], v[108:111]
	v_mfma_f32_16x16x32_bf16 v[104:107], v[162:165], v[218:221], v[104:107]
	v_mfma_f32_16x16x32_bf16 v[92:95], v[154:157], v[226:229], v[92:95]
	v_mfma_f32_16x16x32_bf16 v[88:91], v[162:165], v[226:229], v[88:91]
	v_mfma_f32_16x16x32_bf16 v[76:79], v[154:157], v[234:237], v[76:79]
	v_mfma_f32_16x16x32_bf16 v[72:75], v[162:165], v[234:237], v[72:75]
	v_mfma_f32_16x16x32_bf16 v[116:119], v[180:183], v[206:209], v[116:119]
	v_mfma_f32_16x16x32_bf16 v[112:115], v[190:193], v[206:209], v[112:115]
	v_mfma_f32_16x16x32_bf16 v[100:103], v[180:183], v[214:217], v[100:103]
	v_mfma_f32_16x16x32_bf16 v[96:99], v[190:193], v[214:217], v[96:99]
	v_mfma_f32_16x16x32_bf16 v[84:87], v[180:183], v[222:225], v[84:87]
	v_mfma_f32_16x16x32_bf16 v[80:83], v[190:193], v[222:225], v[80:83]
	v_mfma_f32_16x16x32_bf16 v[68:71], v[180:183], v[230:233], v[68:71]
	v_mfma_f32_16x16x32_bf16 v[64:67], v[190:193], v[230:233], v[64:67]
	v_mfma_f32_16x16x32_bf16 v[116:119], v[184:187], v[210:213], v[116:119]
	v_mfma_f32_16x16x32_bf16 v[112:115], v[194:197], v[210:213], v[112:115]
	v_mfma_f32_16x16x32_bf16 v[100:103], v[184:187], v[218:221], v[100:103]
	v_mfma_f32_16x16x32_bf16 v[96:99], v[194:197], v[218:221], v[96:99]
	v_mfma_f32_16x16x32_bf16 v[84:87], v[184:187], v[226:229], v[84:87]
	v_mfma_f32_16x16x32_bf16 v[80:83], v[194:197], v[226:229], v[80:83]
	v_mfma_f32_16x16x32_bf16 v[68:71], v[184:187], v[234:237], v[68:71]
	v_mfma_f32_16x16x32_bf16 v[64:67], v[194:197], v[234:237], v[64:67]
	s_setprio 0
	s_barrier
; #define PG8_STAGE(bufoff, gbase, voff) do { _Pragma("unroll") for (int _i = 0; _i < 2; ++_i) \
;         __builtin_amdgcn_global_load_lds((const unsigned*)((const char*)(gbase) + (voff)[_i]), (LAS unsigned*)(lds + (bufoff) + ldsw + _i * 8192), 16, 0, 0); } while (0)
; #define PG8_LDA(dst, b, h) do { _Pragma("unroll") for (int m = 0; m < 4; ++m) _Pragma("unroll") for (int k = 0; k < 2; ++k) dst[m][k] = *(const LAS bf16x8*)(lds + PG8_SA(b, h) + aoff + m * 2048 + k * 1024); } while (0)
; #define PG8_MMA(ai, bj, At, Bt) do { __builtin_amdgcn_s_setprio(1); _Pragma("unroll") for (int m = 0; m < 4; ++m) _Pragma("unroll") for (int n = 0; n < 2; ++n) _Pragma("unroll") for (int k = 0; k < 2; ++k) \
;         acc[ai][bj][m][n] = __builtin_amdgcn_mfma_f32_16x16x32_bf16(Bt[n][k], At[m][k], acc[ai][bj][m][n], 0, 0, 0); __builtin_amdgcn_s_setprio(0); } while (0)
; #define PG8_WAIT_V(n) asm volatile("s_waitcnt vmcnt(" #n ")" ::: "memory")
; #define PG8_WAIT_L(n) asm volatile("s_waitcnt lgkmcnt(" #n ")" ::: "memory")
; #define PG8_BAR __builtin_amdgcn_s_barrier()
; #define PG8_SCHED __builtin_amdgcn_sched_barrier(0)
; template <class Epi, class Sched>
; __device__ __forceinline__ void gemm_phase(const int tid, LAS unsigned char* lds, const int lda, const int ldb, const int K, const Sched& S, const Epi& E) {
;     ...
;             PG8_LDA(At, 1, 1); PG8_STAGE(PG8_SB(1, 0), b3, voffB); PG8_STAGE(PG8_SB(1, 1), b3 + hstepB, voffB); PG8_STAGE(PG8_SA(1, 0), a3, voffA);
;             PG8_WAIT_V(8); PG8_WAIT_L(0); PG8_BAR; if (!cur.half) { PG8_MMA(1, 0, At, B0); PG8_MMA(1, 1, At, B1); } PG8_BAR; PG8_SCHED;
;         }
	s_add_i32 s14, s14, s31
	v_lshl_add_u64 v[166:167], v[166:167], 0, s[6:7]
	s_mov_b32 m0, s14
	ds_read_b128 v[206:209], v152 offset:49152
	ds_read_b128 v[210:213], v152 offset:50176
	ds_read_b128 v[214:217], v152 offset:51200
	ds_read_b128 v[218:221], v152 offset:52224
	ds_read_b128 v[222:225], v152 offset:53248
	ds_read_b128 v[226:229], v152 offset:54272
	ds_read_b128 v[230:233], v152 offset:55296
	ds_read_b128 v[234:237], v152 offset:56320
	global_load_lds_dwordx4 v[166:167], off
	s_add_i32 m0, s14, 0x2000
	s_add_u32 s50, s58, 0xb0080
	v_lshl_add_u64 v[166:167], v[238:239], 0, s[6:7]
	s_addc_u32 s51, s59, 0
	s_add_i32 s14, s15, s31
	global_load_lds_dwordx4 v[166:167], off
	v_lshl_add_u64 v[166:167], s[50:51], 0, v[130:131]
	s_mov_b32 m0, s14
	s_nop 0
	global_load_lds_dwordx4 v[166:167], off
	v_lshl_add_u64 v[166:167], s[50:51], 0, v[134:135]
	s_add_i32 m0, s14, 0x2000
	s_nop 0
	global_load_lds_dwordx4 v[166:167], off
	v_lshl_add_u64 v[166:167], v[240:241], 0, s[6:7]
	s_mov_b32 m0, s65
	s_nop 0
	global_load_lds_dwordx4 v[166:167], off
	v_lshl_add_u64 v[166:167], v[242:243], 0, s[6:7]
	s_mov_b32 m0, s66
	s_nop 0
	global_load_lds_dwordx4 v[166:167], off
	s_waitcnt vmcnt(8)
	s_waitcnt lgkmcnt(0)
	s_barrier
	s_setprio 1
	v_mfma_f32_16x16x32_bf16 v[60:63], v[142:145], v[206:209], v[60:63]
	v_mfma_f32_16x16x32_bf16 v[56:59], v[158:161], v[206:209], v[56:59]
	v_mfma_f32_16x16x32_bf16 v[44:47], v[142:145], v[214:217], v[44:47]
	v_mfma_f32_16x16x32_bf16 v[40:43], v[158:161], v[214:217], v[40:43]
	v_mfma_f32_16x16x32_bf16 v[28:31], v[142:145], v[222:225], v[28:31]
	v_mfma_f32_16x16x32_bf16 v[24:27], v[158:161], v[222:225], v[24:27]
	v_mfma_f32_16x16x32_bf16 v[12:15], v[142:145], v[230:233], v[12:15]
	v_mfma_f32_16x16x32_bf16 v[8:11], v[158:161], v[230:233], v[8:11]
	v_mfma_f32_16x16x32_bf16 v[60:63], v[154:157], v[210:213], v[60:63]
	v_mfma_f32_16x16x32_bf16 v[56:59], v[162:165], v[210:213], v[56:59]
	v_mfma_f32_16x16x32_bf16 v[44:47], v[154:157], v[218:221], v[44:47]
	v_mfma_f32_16x16x32_bf16 v[40:43], v[162:165], v[218:221], v[40:43]
	v_mfma_f32_16x16x32_bf16 v[28:31], v[154:157], v[226:229], v[28:31]
	v_mfma_f32_16x16x32_bf16 v[24:27], v[162:165], v[226:229], v[24:27]
	v_mfma_f32_16x16x32_bf16 v[12:15], v[154:157], v[234:237], v[12:15]
	v_mfma_f32_16x16x32_bf16 v[8:11], v[162:165], v[234:237], v[8:11]
	v_mfma_f32_16x16x32_bf16 v[52:55], v[180:183], v[206:209], v[52:55]
	v_mfma_f32_16x16x32_bf16 v[48:51], v[190:193], v[206:209], v[48:51]
	v_mfma_f32_16x16x32_bf16 v[36:39], v[180:183], v[214:217], v[36:39]
	v_mfma_f32_16x16x32_bf16 v[32:35], v[190:193], v[214:217], v[32:35]
	v_mfma_f32_16x16x32_bf16 v[20:23], v[180:183], v[222:225], v[20:23]
	v_mfma_f32_16x16x32_bf16 v[16:19], v[190:193], v[222:225], v[16:19]
	v_mfma_f32_16x16x32_bf16 v[4:7], v[180:183], v[230:233], v[4:7]
	v_mfma_f32_16x16x32_bf16 v[0:3], v[190:193], v[230:233], v[0:3]
	v_mfma_f32_16x16x32_bf16 v[52:55], v[184:187], v[210:213], v[52:55]
	v_mfma_f32_16x16x32_bf16 v[48:51], v[194:197], v[210:213], v[48:51]
	v_mfma_f32_16x16x32_bf16 v[36:39], v[184:187], v[218:221], v[36:39]
	v_mfma_f32_16x16x32_bf16 v[32:35], v[194:197], v[218:221], v[32:35]
	v_mfma_f32_16x16x32_bf16 v[20:23], v[184:187], v[226:229], v[20:23]
	v_mfma_f32_16x16x32_bf16 v[16:19], v[194:197], v[226:229], v[16:19]
	v_mfma_f32_16x16x32_bf16 v[4:7], v[184:187], v[234:237], v[4:7]
	v_mfma_f32_16x16x32_bf16 v[0:3], v[194:197], v[234:237], v[0:3]
	s_setprio 0
	s_barrier
	s_add_u32 vcc_lo, vcc_lo, 0x100
	s_addc_u32 vcc_hi, vcc_hi, 0
	s_cmp_ge_i32 s24, s21
	s_mov_b64 s[50:51], s[52:53]
	s_mov_b32 s58, s24
	s_cbranch_scc0 .LBB0_53
	v_readlane_b32 s60, v254, 56
	v_readlane_b32 s61, v254, 57

; #define PG8_STAGE(bufoff, gbase, voff) do { _Pragma("unroll") for (int _i = 0; _i < 2; ++_i) \
;         __builtin_amdgcn_global_load_lds((const unsigned*)((const char*)(gbase) + (voff)[_i]), (LAS unsigned*)(lds + (bufoff) + ldsw + _i * 8192), 16, 0, 0); } while (0)
; #define PG8_LDA(dst, b, h) do { _Pragma("unroll") for (int m = 0; m < 4; ++m) _Pragma("unroll") for (int k = 0; k < 2; ++k) dst[m][k] = *(const LAS bf16x8*)(lds + PG8_SA(b, h) + aoff + m * 2048 + k * 1024); } while (0)
; #define PG8_LDB(dst, b, h) do { _Pragma("unroll") for (int n = 0; n < 2; ++n) _Pragma("unroll") for (int k = 0; k < 2; ++k) dst[n][k] = *(const LAS bf16x8*)(lds + PG8_SB(b, h) + boff + n * 2048 + k * 1024); } while (0)
; #define PG8_MMA(ai, bj, At, Bt) do { __builtin_amdgcn_s_setprio(1); _Pragma("unroll") for (int m = 0; m < 4; ++m) _Pragma("unroll") for (int n = 0; n < 2; ++n) _Pragma("unroll") for (int k = 0; k < 2; ++k) \
;         acc[ai][bj][m][n] = __builtin_amdgcn_mfma_f32_16x16x32_bf16(Bt[n][k], At[m][k], acc[ai][bj][m][n], 0, 0, 0); __builtin_amdgcn_s_setprio(0); } while (0)
; #define PG8_WAIT_V(n) asm volatile("s_waitcnt vmcnt(" #n ")" ::: "memory")
; template <class Epi, class Sched>
; __device__ __forceinline__ void gemm_phase(const int tid, LAS unsigned char* lds, const int lda, const int ldb, const int K, const Sched& S, const Epi& E) {
;     ...
;         const bool has_next = S.next(ui + 1, nxt);
;         const char* nA = has_next ? nxt.a : cA; const char* nB = has_next ? nxt.b : cB;
;         for (int t = 0; t < nt; t += 2) {
;             const bool last = (t == nt - 2);
;             const char* a1 = cA + (size_t)(t + 1) * kstep;
;             const char* a2 = last ? nA : cA + (size_t)(t + 2) * kstep; const char* b2 = last ? nB : cB + (size_t)(t + 2) * kstep;
;             const char* a3 = a2 + kstep; const char* b3 = b2 + kstep;
;             PG8_LDB(B0, 0, 0); PG8_LDB(B1, 0, 1); PG8_SCHED; PG8_LDA(At, 0, 0); PG8_STAGE(PG8_SA(1, 1), a1 + hstepA, voffA);
;             PG8_WAIT_V(8); PG8_WAIT_L(0); PG8_BAR; PG8_MMA(0, 0, At, B0); PG8_MMA(0, 1, At, B1); PG8_BAR; PG8_SCHED;
;             PG8_LDA(At, 0, 1); PG8_STAGE(PG8_SB(0, 0), b2, voffB); PG8_STAGE(PG8_SB(0, 1), b2 + hstepB, voffB); PG8_STAGE(PG8_SA(0, 0), a2, voffA);
;             PG8_WAIT_V(8); PG8_WAIT_L(0); PG8_BAR; if (!cur.half) { PG8_MMA(1, 0, At, B0); PG8_MMA(1, 1, At, B1); } PG8_BAR; PG8_SCHED;
.LBB0_122:
	s_add_i32 vcc_lo, s24, 2
	s_add_u32 s14, s2, 0xfffc0080
	s_addc_u32 s15, s3, -1
	s_add_i32 s22, 0, 0x10000
	s_cmp_eq_u32 s68, s24
	s_cselect_b32 s57, s53, s15
	s_cselect_b32 s56, s52, s14
	v_add_u32_e32 v153, s22, v137
	s_cselect_b32 s51, s55, s75
	s_cselect_b32 s50, s54, s45
	s_add_i32 s14, 0, 0x14000
	ds_read_b128 v[142:145], v153
	ds_read_b128 v[154:157], v153 offset:1024
	ds_read_b128 v[158:161], v153 offset:2048
	ds_read_b128 v[162:165], v153 offset:3072
	v_add_u32_e32 v153, s14, v137
	ds_read_b128 v[180:183], v153
	ds_read_b128 v[184:187], v153 offset:1024
	ds_read_b128 v[190:193], v153 offset:2048
	ds_read_b128 v[194:197], v153 offset:3072
	v_lshl_add_u64 v[166:167], s[2:3], 0, v[138:139]
	s_add_i32 m0, s26, 0xc000
	ds_read_b128 v[206:209], v152
	ds_read_b128 v[210:213], v152 offset:1024
	ds_read_b128 v[214:217], v152 offset:2048
	ds_read_b128 v[218:221], v152 offset:3072
	ds_read_b128 v[222:225], v152 offset:4096
	ds_read_b128 v[226:229], v152 offset:5120
	ds_read_b128 v[230:233], v152 offset:6144
	ds_read_b128 v[234:237], v152 offset:7168
	global_load_lds_dwordx4 v[166:167], off
	v_lshl_add_u64 v[166:167], s[2:3], 0, v[140:141]
	s_add_i32 m0, s26, 0xe000
	s_nop 0
	global_load_lds_dwordx4 v[166:167], off
	s_waitcnt vmcnt(8)
	s_waitcnt lgkmcnt(0)
	s_barrier
	s_setprio 1
	v_mfma_f32_16x16x32_bf16 v[124:127], v[142:145], v[206:209], v[124:127]
	v_mfma_f32_16x16x32_bf16 v[120:123], v[158:161], v[206:209], v[120:123]
	v_mfma_f32_16x16x32_bf16 v[108:111], v[142:145], v[214:217], v[108:111]
	v_mfma_f32_16x16x32_bf16 v[104:107], v[158:161], v[214:217], v[104:107]
	v_mfma_f32_16x16x32_bf16 v[92:95], v[142:145], v[222:225], v[92:95]
	v_mfma_f32_16x16x32_bf16 v[88:91], v[158:161], v[222:225], v[88:91]
	v_mfma_f32_16x16x32_bf16 v[76:79], v[142:145], v[230:233], v[76:79]
	v_mfma_f32_16x16x32_bf16 v[72:75], v[158:161], v[230:233], v[72:75]
	v_mfma_f32_16x16x32_bf16 v[124:127], v[154:157], v[210:213], v[124:127]
	v_mfma_f32_16x16x32_bf16 v[120:123], v[162:165], v[210:213], v[120:123]
	v_mfma_f32_16x16x32_bf16 v[108:111], v[154:157], v[218:221], v[108:111]
	v_mfma_f32_16x16x32_bf16 v[104:107], v[162:165], v[218:221], v[104:107]
	v_mfma_f32_16x16x32_bf16 v[92:95], v[154:157], v[226:229], v[92:95]
	v_mfma_f32_16x16x32_bf16 v[88:91], v[162:165], v[226:229], v[88:91]
	v_mfma_f32_16x16x32_bf16 v[76:79], v[154:157], v[234:237], v[76:79]
	v_mfma_f32_16x16x32_bf16 v[72:75], v[162:165], v[234:237], v[72:75]
	v_mfma_f32_16x16x32_bf16 v[116:119], v[180:183], v[206:209], v[116:119]
	v_mfma_f32_16x16x32_bf16 v[112:115], v[190:193], v[206:209], v[112:115]
	v_mfma_f32_16x16x32_bf16 v[100:103], v[180:183], v[214:217], v[100:103]
	v_mfma_f32_16x16x32_bf16 v[96:99], v[190:193], v[214:217], v[96:99]
	v_mfma_f32_16x16x32_bf16 v[84:87], v[180:183], v[222:225], v[84:87]
	v_mfma_f32_16x16x32_bf16 v[80:83], v[190:193], v[222:225], v[80:83]
	v_mfma_f32_16x16x32_bf16 v[68:71], v[180:183], v[230:233], v[68:71]
	v_mfma_f32_16x16x32_bf16 v[64:67], v[190:193], v[230:233], v[64:67]
	v_mfma_f32_16x16x32_bf16 v[116:119], v[184:187], v[210:213], v[116:119]
	v_mfma_f32_16x16x32_bf16 v[112:115], v[194:197], v[210:213], v[112:115]
	v_mfma_f32_16x16x32_bf16 v[100:103], v[184:187], v[218:221], v[100:103]
	v_mfma_f32_16x16x32_bf16 v[96:99], v[194:197], v[218:221], v[96:99]
	v_mfma_f32_16x16x32_bf16 v[84:87], v[184:187], v[226:229], v[84:87]
	v_mfma_f32_16x16x32_bf16 v[80:83], v[194:197], v[226:229], v[80:83]
	v_mfma_f32_16x16x32_bf16 v[68:71], v[184:187], v[234:237], v[68:71]
	v_mfma_f32_16x16x32_bf16 v[64:67], v[194:197], v[234:237], v[64:67]
	s_setprio 0
	s_barrier
	s_add_i32 s15, s22, s61
	v_lshl_add_u64 v[166:167], s[50:51], 0, v[130:131]
	s_mov_b32 m0, s15
	ds_read_b128 v[206:209], v152 offset:16384
	ds_read_b128 v[210:213], v152 offset:17408
	ds_read_b128 v[214:217], v152 offset:18432
	ds_read_b128 v[218:221], v152 offset:19456
	ds_read_b128 v[222:225], v152 offset:20480
	ds_read_b128 v[226:229], v152 offset:21504
	ds_read_b128 v[230:233], v152 offset:22528
	ds_read_b128 v[234:237], v152 offset:23552
	global_load_lds_dwordx4 v[166:167], off
	s_add_i32 m0, s15, 0x2000
	s_add_u32 s22, s50, 0x40000
	v_lshl_add_u64 v[176:177], s[50:51], 0, v[134:135]
	s_addc_u32 s23, s51, 0
	s_add_i32 s14, s14, s61
	global_load_lds_dwordx4 v[176:177], off
	v_lshl_add_u64 v[238:239], s[22:23], 0, v[130:131]
	s_mov_b32 m0, s14
	v_lshl_add_u64 v[240:241], s[56:57], 0, v[132:133]
	global_load_lds_dwordx4 v[238:239], off
	v_lshl_add_u64 v[238:239], s[22:23], 0, v[134:135]
	s_add_i32 m0, s14, 0x2000
	s_nop 0
	global_load_lds_dwordx4 v[238:239], off
	v_lshl_add_u64 v[238:239], s[56:57], 0, v[128:129]
	s_mov_b32 m0, s26
	s_nop 0
	global_load_lds_dwordx4 v[238:239], off
	s_mov_b32 m0, s27
	s_nop 0
	global_load_lds_dwordx4 v[240:241], off
	s_waitcnt vmcnt(8)
	s_waitcnt lgkmcnt(0)
	s_barrier
; #define PG8_STAGE(bufoff, gbase, voff) do { _Pragma("unroll") for (int _i = 0; _i < 2; ++_i) \
;         __builtin_amdgcn_global_load_lds((const unsigned*)((const char*)(gbase) + (voff)[_i]), (LAS unsigned*)(lds + (bufoff) + ldsw + _i * 8192), 16, 0, 0); } while (0)
; #define PG8_LDA(dst, b, h) do { _Pragma("unroll") for (int m = 0; m < 4; ++m) _Pragma("unroll") for (int k = 0; k < 2; ++k) dst[m][k] = *(const LAS bf16x8*)(lds + PG8_SA(b, h) + aoff + m * 2048 + k * 1024); } while (0)
; #define PG8_LDB(dst, b, h) do { _Pragma("unroll") for (int n = 0; n < 2; ++n) _Pragma("unroll") for (int k = 0; k < 2; ++k) dst[n][k] = *(const LAS bf16x8*)(lds + PG8_SB(b, h) + boff + n * 2048 + k * 1024); } while (0)
; #define PG8_MMA(ai, bj, At, Bt) do { __builtin_amdgcn_s_setprio(1); _Pragma("unroll") for (int m = 0; m < 4; ++m) _Pragma("unroll") for (int n = 0; n < 2; ++n) _Pragma("unroll") for (int k = 0; k < 2; ++k) \
;         acc[ai][bj][m][n] = __builtin_amdgcn_mfma_f32_16x16x32_bf16(Bt[n][k], At[m][k], acc[ai][bj][m][n], 0, 0, 0); __builtin_amdgcn_s_setprio(0); } while (0)
; #define PG8_WAIT_V(n) asm volatile("s_waitcnt vmcnt(" #n ")" ::: "memory")
; #define PG8_WAIT_L(n) asm volatile("s_waitcnt lgkmcnt(" #n ")" ::: "memory")
; #define PG8_BAR __builtin_amdgcn_s_barrier()
; #define PG8_SCHED __builtin_amdgcn_sched_barrier(0)
; template <class Epi, class Sched>
; __device__ __forceinline__ void gemm_phase(const int tid, LAS unsigned char* lds, const int lda, const int ldb, const int K, const Sched& S, const Epi& E) {
;     ...
;             PG8_WAIT_V(8); PG8_WAIT_L(0); PG8_BAR; if (!cur.half) { PG8_MMA(1, 0, At, B0); PG8_MMA(1, 1, At, B1); } PG8_BAR; PG8_SCHED;
;             PG8_LDB(B0, 1, 0); PG8_LDB(B1, 1, 1); PG8_SCHED; PG8_LDA(At, 1, 0); PG8_STAGE(PG8_SA(0, 1), a2 + hstepA, voffA);
;             PG8_WAIT_V(8); PG8_WAIT_L(0); PG8_BAR; PG8_MMA(0, 0, At, B0); PG8_MMA(0, 1, At, B1); PG8_BAR; PG8_SCHED;
	s_setprio 1
	v_mfma_f32_16x16x32_bf16 v[60:63], v[142:145], v[206:209], v[60:63]
	v_mfma_f32_16x16x32_bf16 v[56:59], v[158:161], v[206:209], v[56:59]
	v_mfma_f32_16x16x32_bf16 v[44:47], v[142:145], v[214:217], v[44:47]
	v_mfma_f32_16x16x32_bf16 v[40:43], v[158:161], v[214:217], v[40:43]
	v_mfma_f32_16x16x32_bf16 v[28:31], v[142:145], v[222:225], v[28:31]
	v_mfma_f32_16x16x32_bf16 v[24:27], v[158:161], v[222:225], v[24:27]
	v_mfma_f32_16x16x32_bf16 v[12:15], v[142:145], v[230:233], v[12:15]
	v_mfma_f32_16x16x32_bf16 v[8:11], v[158:161], v[230:233], v[8:11]
	v_mfma_f32_16x16x32_bf16 v[60:63], v[154:157], v[210:213], v[60:63]
	v_mfma_f32_16x16x32_bf16 v[56:59], v[162:165], v[210:213], v[56:59]
	v_mfma_f32_16x16x32_bf16 v[44:47], v[154:157], v[218:221], v[44:47]
	v_mfma_f32_16x16x32_bf16 v[40:43], v[162:165], v[218:221], v[40:43]
	v_mfma_f32_16x16x32_bf16 v[28:31], v[154:157], v[226:229], v[28:31]
	v_mfma_f32_16x16x32_bf16 v[24:27], v[162:165], v[226:229], v[24:27]
	v_mfma_f32_16x16x32_bf16 v[12:15], v[154:157], v[234:237], v[12:15]
	v_mfma_f32_16x16x32_bf16 v[8:11], v[162:165], v[234:237], v[8:11]
	v_mfma_f32_16x16x32_bf16 v[52:55], v[180:183], v[206:209], v[52:55]
	v_mfma_f32_16x16x32_bf16 v[48:51], v[190:193], v[206:209], v[48:51]
	v_mfma_f32_16x16x32_bf16 v[36:39], v[180:183], v[214:217], v[36:39]
	v_mfma_f32_16x16x32_bf16 v[32:35], v[190:193], v[214:217], v[32:35]
	v_mfma_f32_16x16x32_bf16 v[20:23], v[180:183], v[222:225], v[20:23]
	v_mfma_f32_16x16x32_bf16 v[16:19], v[190:193], v[222:225], v[16:19]
	v_mfma_f32_16x16x32_bf16 v[4:7], v[180:183], v[230:233], v[4:7]
	v_mfma_f32_16x16x32_bf16 v[0:3], v[190:193], v[230:233], v[0:3]
	v_mfma_f32_16x16x32_bf16 v[52:55], v[184:187], v[210:213], v[52:55]
	v_mfma_f32_16x16x32_bf16 v[48:51], v[194:197], v[210:213], v[48:51]
	v_mfma_f32_16x16x32_bf16 v[36:39], v[184:187], v[218:221], v[36:39]
	v_mfma_f32_16x16x32_bf16 v[32:35], v[194:197], v[218:221], v[32:35]
	v_mfma_f32_16x16x32_bf16 v[20:23], v[184:187], v[226:229], v[20:23]
	v_mfma_f32_16x16x32_bf16 v[16:19], v[194:197], v[226:229], v[16:19]
	v_mfma_f32_16x16x32_bf16 v[4:7], v[184:187], v[234:237], v[4:7]
	v_mfma_f32_16x16x32_bf16 v[0:3], v[194:197], v[234:237], v[0:3]
	s_setprio 0
	s_barrier
	s_add_i32 s14, 0, 0x18000
	v_add_u32_e32 v153, s14, v137
	s_add_i32 s15, 0, 0x1c000
	ds_read_b128 v[142:145], v153
	ds_read_b128 v[154:157], v153 offset:1024
	ds_read_b128 v[158:161], v153 offset:2048
	ds_read_b128 v[162:165], v153 offset:3072
	v_add_u32_e32 v153, s15, v137
	ds_read_b128 v[180:183], v153
	ds_read_b128 v[184:187], v153 offset:1024
	ds_read_b128 v[190:193], v153 offset:2048
	ds_read_b128 v[194:197], v153 offset:3072
	s_add_u32 s22, s56, 0x40000
	s_addc_u32 s23, s57, 0
	s_mov_b32 m0, s62
	v_lshl_add_u64 v[242:243], s[22:23], 0, v[128:129]
	ds_read_b128 v[206:209], v152 offset:32768
	ds_read_b128 v[210:213], v152 offset:33792
	ds_read_b128 v[214:217], v152 offset:34816
	ds_read_b128 v[218:221], v152 offset:35840
	ds_read_b128 v[222:225], v152 offset:36864
	ds_read_b128 v[226:229], v152 offset:37888
	ds_read_b128 v[230:233], v152 offset:38912
	ds_read_b128 v[234:237], v152 offset:39936
	global_load_lds_dwordx4 v[242:243], off
	v_lshl_add_u64 v[242:243], s[22:23], 0, v[132:133]
	s_mov_b32 m0, s63
	s_nop 0
	global_load_lds_dwordx4 v[242:243], off
	s_waitcnt vmcnt(8)
	s_waitcnt lgkmcnt(0)
	s_barrier
	s_setprio 1
	v_mfma_f32_16x16x32_bf16 v[124:127], v[142:145], v[206:209], v[124:127]
	v_mfma_f32_16x16x32_bf16 v[120:123], v[158:161], v[206:209], v[120:123]
	v_mfma_f32_16x16x32_bf16 v[108:111], v[142:145], v[214:217], v[108:111]
	v_mfma_f32_16x16x32_bf16 v[104:107], v[158:161], v[214:217], v[104:107]
	v_mfma_f32_16x16x32_bf16 v[92:95], v[142:145], v[222:225], v[92:95]
	v_mfma_f32_16x16x32_bf16 v[88:91], v[158:161], v[222:225], v[88:91]
	v_mfma_f32_16x16x32_bf16 v[76:79], v[142:145], v[230:233], v[76:79]
	v_mfma_f32_16x16x32_bf16 v[72:75], v[158:161], v[230:233], v[72:75]
	v_mfma_f32_16x16x32_bf16 v[124:127], v[154:157], v[210:213], v[124:127]
	v_mfma_f32_16x16x32_bf16 v[120:123], v[162:165], v[210:213], v[120:123]
	v_mfma_f32_16x16x32_bf16 v[108:111], v[154:157], v[218:221], v[108:111]
	v_mfma_f32_16x16x32_bf16 v[104:107], v[162:165], v[218:221], v[104:107]
	v_mfma_f32_16x16x32_bf16 v[92:95], v[154:157], v[226:229], v[92:95]
	v_mfma_f32_16x16x32_bf16 v[88:91], v[162:165], v[226:229], v[88:91]
	v_mfma_f32_16x16x32_bf16 v[76:79], v[154:157], v[234:237], v[76:79]
	v_mfma_f32_16x16x32_bf16 v[72:75], v[162:165], v[234:237], v[72:75]
	v_mfma_f32_16x16x32_bf16 v[116:119], v[180:183], v[206:209], v[116:119]
	v_mfma_f32_16x16x32_bf16 v[112:115], v[190:193], v[206:209], v[112:115]
	v_mfma_f32_16x16x32_bf16 v[100:103], v[180:183], v[214:217], v[100:103]
	v_mfma_f32_16x16x32_bf16 v[96:99], v[190:193], v[214:217], v[96:99]
	v_mfma_f32_16x16x32_bf16 v[84:87], v[180:183], v[222:225], v[84:87]
	v_mfma_f32_16x16x32_bf16 v[80:83], v[190:193], v[222:225], v[80:83]
	v_mfma_f32_16x16x32_bf16 v[68:71], v[180:183], v[230:233], v[68:71]
	v_mfma_f32_16x16x32_bf16 v[64:67], v[190:193], v[230:233], v[64:67]
	v_mfma_f32_16x16x32_bf16 v[116:119], v[184:187], v[210:213], v[116:119]
	v_mfma_f32_16x16x32_bf16 v[112:115], v[194:197], v[210:213], v[112:115]
	v_mfma_f32_16x16x32_bf16 v[100:103], v[184:187], v[218:221], v[100:103]
	v_mfma_f32_16x16x32_bf16 v[96:99], v[194:197], v[218:221], v[96:99]
	v_mfma_f32_16x16x32_bf16 v[84:87], v[184:187], v[226:229], v[84:87]
	v_mfma_f32_16x16x32_bf16 v[80:83], v[194:197], v[226:229], v[80:83]
	v_mfma_f32_16x16x32_bf16 v[68:71], v[184:187], v[234:237], v[68:71]
	v_mfma_f32_16x16x32_bf16 v[64:67], v[194:197], v[234:237], v[64:67]
	s_setprio 0
	s_barrier
; #define PG8_STAGE(bufoff, gbase, voff) do { _Pragma("unroll") for (int _i = 0; _i < 2; ++_i) \
;         __builtin_amdgcn_global_load_lds((const unsigned*)((const char*)(gbase) + (voff)[_i]), (LAS unsigned*)(lds + (bufoff) + ldsw + _i * 8192), 16, 0, 0); } while (0)
; #define PG8_LDA(dst, b, h) do { _Pragma("unroll") for (int m = 0; m < 4; ++m) _Pragma("unroll") for (int k = 0; k < 2; ++k) dst[m][k] = *(const LAS bf16x8*)(lds + PG8_SA(b, h) + aoff + m * 2048 + k * 1024); } while (0)
; #define PG8_MMA(ai, bj, At, Bt) do { __builtin_amdgcn_s_setprio(1); _Pragma("unroll") for (int m = 0; m < 4; ++m) _Pragma("unroll") for (int n = 0; n < 2; ++n) _Pragma("unroll") for (int k = 0; k < 2; ++k) \
;         acc[ai][bj][m][n] = __builtin_amdgcn_mfma_f32_16x16x32_bf16(Bt[n][k], At[m][k], acc[ai][bj][m][n], 0, 0, 0); __builtin_amdgcn_s_setprio(0); } while (0)
; #define PG8_WAIT_V(n) asm volatile("s_waitcnt vmcnt(" #n ")" ::: "memory")
; #define PG8_WAIT_L(n) asm volatile("s_waitcnt lgkmcnt(" #n ")" ::: "memory")
; #define PG8_BAR __builtin_amdgcn_s_barrier()
; #define PG8_SCHED __builtin_amdgcn_sched_barrier(0)
; template <class Epi, class Sched>
; __device__ __forceinline__ void gemm_phase(const int tid, LAS unsigned char* lds, const int lda, const int ldb, const int K, const Sched& S, const Epi& E) {
;     ...
;             PG8_LDA(At, 1, 1); PG8_STAGE(PG8_SB(1, 0), b3, voffB); PG8_STAGE(PG8_SB(1, 1), b3 + hstepB, voffB); PG8_STAGE(PG8_SA(1, 0), a3, voffA);
;             PG8_WAIT_V(8); PG8_WAIT_L(0); PG8_BAR; if (!cur.half) { PG8_MMA(1, 0, At, B0); PG8_MMA(1, 1, At, B1); } PG8_BAR; PG8_SCHED;
;         }
	s_add_i32 s14, s14, s61
	v_lshl_add_u64 v[166:167], v[166:167], 0, s[6:7]
	s_mov_b32 m0, s14
	ds_read_b128 v[206:209], v152 offset:49152
	ds_read_b128 v[210:213], v152 offset:50176
	ds_read_b128 v[214:217], v152 offset:51200
	ds_read_b128 v[218:221], v152 offset:52224
	ds_read_b128 v[222:225], v152 offset:53248
	ds_read_b128 v[226:229], v152 offset:54272
	ds_read_b128 v[230:233], v152 offset:55296
	ds_read_b128 v[234:237], v152 offset:56320
	global_load_lds_dwordx4 v[166:167], off
	s_add_i32 m0, s14, 0x2000
	s_add_u32 s22, s50, 0x40080
	v_lshl_add_u64 v[166:167], v[176:177], 0, s[6:7]
	s_addc_u32 s23, s51, 0
	s_add_i32 s14, s15, s61
	global_load_lds_dwordx4 v[166:167], off
	v_lshl_add_u64 v[166:167], s[22:23], 0, v[130:131]
	s_mov_b32 m0, s14
	s_nop 0
	global_load_lds_dwordx4 v[166:167], off
	v_lshl_add_u64 v[166:167], s[22:23], 0, v[134:135]
	s_add_i32 m0, s14, 0x2000
	s_nop 0
	global_load_lds_dwordx4 v[166:167], off
	v_lshl_add_u64 v[166:167], v[238:239], 0, s[6:7]
	s_mov_b32 m0, s65
	s_nop 0
	global_load_lds_dwordx4 v[166:167], off
	v_lshl_add_u64 v[166:167], v[240:241], 0, s[6:7]
	s_mov_b32 m0, s66
	s_nop 0
	global_load_lds_dwordx4 v[166:167], off
	s_waitcnt vmcnt(8)
	s_waitcnt lgkmcnt(0)
	s_barrier
	s_setprio 1
	v_mfma_f32_16x16x32_bf16 v[60:63], v[142:145], v[206:209], v[60:63]
	v_mfma_f32_16x16x32_bf16 v[56:59], v[158:161], v[206:209], v[56:59]
	v_mfma_f32_16x16x32_bf16 v[44:47], v[142:145], v[214:217], v[44:47]
	v_mfma_f32_16x16x32_bf16 v[40:43], v[158:161], v[214:217], v[40:43]
	v_mfma_f32_16x16x32_bf16 v[28:31], v[142:145], v[222:225], v[28:31]
	v_mfma_f32_16x16x32_bf16 v[24:27], v[158:161], v[222:225], v[24:27]
	v_mfma_f32_16x16x32_bf16 v[12:15], v[142:145], v[230:233], v[12:15]
	v_mfma_f32_16x16x32_bf16 v[8:11], v[158:161], v[230:233], v[8:11]
	v_mfma_f32_16x16x32_bf16 v[60:63], v[154:157], v[210:213], v[60:63]
	v_mfma_f32_16x16x32_bf16 v[56:59], v[162:165], v[210:213], v[56:59]
	v_mfma_f32_16x16x32_bf16 v[44:47], v[154:157], v[218:221], v[44:47]
	v_mfma_f32_16x16x32_bf16 v[40:43], v[162:165], v[218:221], v[40:43]
	v_mfma_f32_16x16x32_bf16 v[28:31], v[154:157], v[226:229], v[28:31]
	v_mfma_f32_16x16x32_bf16 v[24:27], v[162:165], v[226:229], v[24:27]
	v_mfma_f32_16x16x32_bf16 v[12:15], v[154:157], v[234:237], v[12:15]
	v_mfma_f32_16x16x32_bf16 v[8:11], v[162:165], v[234:237], v[8:11]
	v_mfma_f32_16x16x32_bf16 v[52:55], v[180:183], v[206:209], v[52:55]
	v_mfma_f32_16x16x32_bf16 v[48:51], v[190:193], v[206:209], v[48:51]
	v_mfma_f32_16x16x32_bf16 v[36:39], v[180:183], v[214:217], v[36:39]
	v_mfma_f32_16x16x32_bf16 v[32:35], v[190:193], v[214:217], v[32:35]
	v_mfma_f32_16x16x32_bf16 v[20:23], v[180:183], v[222:225], v[20:23]
	v_mfma_f32_16x16x32_bf16 v[16:19], v[190:193], v[222:225], v[16:19]
	v_mfma_f32_16x16x32_bf16 v[4:7], v[180:183], v[230:233], v[4:7]
	v_mfma_f32_16x16x32_bf16 v[0:3], v[190:193], v[230:233], v[0:3]
	v_mfma_f32_16x16x32_bf16 v[52:55], v[184:187], v[210:213], v[52:55]
	v_mfma_f32_16x16x32_bf16 v[48:51], v[194:197], v[210:213], v[48:51]
	v_mfma_f32_16x16x32_bf16 v[36:39], v[184:187], v[218:221], v[36:39]
	v_mfma_f32_16x16x32_bf16 v[32:35], v[194:197], v[218:221], v[32:35]
	v_mfma_f32_16x16x32_bf16 v[20:23], v[184:187], v[226:229], v[20:23]
	v_mfma_f32_16x16x32_bf16 v[16:19], v[194:197], v[226:229], v[16:19]
	v_mfma_f32_16x16x32_bf16 v[4:7], v[184:187], v[234:237], v[4:7]
	v_mfma_f32_16x16x32_bf16 v[0:3], v[194:197], v[234:237], v[0:3]
	s_setprio 0
	s_barrier
	s_add_u32 s2, s2, 0x100
	s_addc_u32 s3, s3, 0
	s_add_u32 s45, s45, 0x100
	s_addc_u32 s75, s75, 0
	s_cmp_ge_i32 vcc_lo, s59
	s_mov_b32 s24, vcc_lo
	s_cbranch_scc0 .LBB0_122
	v_readlane_b32 s75, v254, 55

; #define PG8_STAGE(bufoff, gbase, voff) do { _Pragma("unroll") for (int _i = 0; _i < 2; ++_i) \
;         __builtin_amdgcn_global_load_lds((const unsigned*)((const char*)(gbase) + (voff)[_i]), (LAS unsigned*)(lds + (bufoff) + ldsw + _i * 8192), 16, 0, 0); } while (0)
; #define PG8_LDA(dst, b, h) do { _Pragma("unroll") for (int m = 0; m < 4; ++m) _Pragma("unroll") for (int k = 0; k < 2; ++k) dst[m][k] = *(const LAS bf16x8*)(lds + PG8_SA(b, h) + aoff + m * 2048 + k * 1024); } while (0)
; #define PG8_LDB(dst, b, h) do { _Pragma("unroll") for (int n = 0; n < 2; ++n) _Pragma("unroll") for (int k = 0; k < 2; ++k) dst[n][k] = *(const LAS bf16x8*)(lds + PG8_SB(b, h) + boff + n * 2048 + k * 1024); } while (0)
; #define PG8_MMA(ai, bj, At, Bt) do { __builtin_amdgcn_s_setprio(1); _Pragma("unroll") for (int m = 0; m < 4; ++m) _Pragma("unroll") for (int n = 0; n < 2; ++n) _Pragma("unroll") for (int k = 0; k < 2; ++k) \
;         acc[ai][bj][m][n] = __builtin_amdgcn_mfma_f32_16x16x32_bf16(Bt[n][k], At[m][k], acc[ai][bj][m][n], 0, 0, 0); __builtin_amdgcn_s_setprio(0); } while (0)
; #define PG8_WAIT_V(n) asm volatile("s_waitcnt vmcnt(" #n ")" ::: "memory")
; template <class Epi, class Sched>
; __device__ __forceinline__ void gemm_phase(const int tid, LAS unsigned char* lds, const int lda, const int ldb, const int K, const Sched& S, const Epi& E) {
;     ...
;         const bool has_next = S.next(ui + 1, nxt);
;         const char* nA = has_next ? nxt.a : cA; const char* nB = has_next ? nxt.b : cB;
;         for (int t = 0; t < nt; t += 2) {
;             const bool last = (t == nt - 2);
;             const char* a1 = cA + (size_t)(t + 1) * kstep;
;             const char* a2 = last ? nA : cA + (size_t)(t + 2) * kstep; const char* b2 = last ? nB : cB + (size_t)(t + 2) * kstep;
;             const char* a3 = a2 + kstep; const char* b3 = b2 + kstep;
;             PG8_LDB(B0, 0, 0); PG8_LDB(B1, 0, 1); PG8_SCHED; PG8_LDA(At, 0, 0); PG8_STAGE(PG8_SA(1, 1), a1 + hstepA, voffA);
;             PG8_WAIT_V(8); PG8_WAIT_L(0); PG8_BAR; PG8_MMA(0, 0, At, B0); PG8_MMA(0, 1, At, B1); PG8_BAR; PG8_SCHED;
;             PG8_LDA(At, 0, 1); PG8_STAGE(PG8_SB(0, 0), b2, voffB); PG8_STAGE(PG8_SB(0, 1), b2 + hstepB, voffB); PG8_STAGE(PG8_SA(0, 0), a2, voffA);
;             PG8_WAIT_V(8); PG8_WAIT_L(0); PG8_BAR; if (!cur.half) { PG8_MMA(1, 0, At, B0); PG8_MMA(1, 1, At, B1); } PG8_BAR; PG8_SCHED;
.LBB0_195:
	s_andn2_b64 vcc, exec, s[42:43]
	s_cbranch_vccnz .LBB0_203
	s_add_u32 s38, s38, 0x40080
	s_addc_u32 s39, s39, 0
	s_add_u32 s47, s52, 0x100
	s_addc_u32 s67, s53, 0
	s_mov_b32 s52, 0
	s_add_i32 s68, s52, 2
	s_add_u32 s14, s38, 0xfffc0080
	s_addc_u32 s15, s39, -1
	s_add_i32 s24, 0, 0x10000
	s_cmp_eq_u32 s64, s52
	s_cselect_b32 s55, s3, s15
	s_cselect_b32 s54, s2, s14
	v_add_u32_e32 v155, s24, v146
	s_cselect_b32 s53, s23, s67
	s_cselect_b32 s52, s22, s47
	s_add_i32 s14, 0, 0x14000
	ds_read_b128 v[156:159], v155
	ds_read_b128 v[160:163], v155 offset:1024
	ds_read_b128 v[164:167], v155 offset:2048
	ds_read_b128 v[180:183], v155 offset:3072
	v_add_u32_e32 v155, s14, v146
	ds_read_b128 v[184:187], v155
	ds_read_b128 v[190:193], v155 offset:1024
	ds_read_b128 v[194:197], v155 offset:2048
	ds_read_b128 v[206:209], v155 offset:3072
	v_lshl_add_u64 v[242:243], s[38:39], 0, v[136:137]
	s_add_i32 m0, s57, 0xc000
	ds_read_b128 v[210:213], v154
	ds_read_b128 v[214:217], v154 offset:1024
	ds_read_b128 v[218:221], v154 offset:2048
	ds_read_b128 v[222:225], v154 offset:3072
	ds_read_b128 v[226:229], v154 offset:4096
	ds_read_b128 v[230:233], v154 offset:5120
	ds_read_b128 v[234:237], v154 offset:6144
	ds_read_b128 v[238:241], v154 offset:7168
	global_load_lds_dwordx4 v[242:243], off
	v_lshl_add_u64 v[242:243], s[38:39], 0, v[138:139]
	s_add_i32 m0, s57, 0xe000
	s_nop 0
	global_load_lds_dwordx4 v[242:243], off
	s_waitcnt vmcnt(8)
	s_waitcnt lgkmcnt(0)
	s_barrier
	s_setprio 1
	v_mfma_f32_16x16x32_bf16 v[124:127], v[156:159], v[210:213], 0
	v_mfma_f32_16x16x32_bf16 v[120:123], v[164:167], v[210:213], 0
	v_mfma_f32_16x16x32_bf16 v[108:111], v[156:159], v[218:221], 0
	v_mfma_f32_16x16x32_bf16 v[104:107], v[164:167], v[218:221], 0
	v_mfma_f32_16x16x32_bf16 v[92:95], v[156:159], v[226:229], 0
	v_mfma_f32_16x16x32_bf16 v[88:91], v[164:167], v[226:229], 0
	v_mfma_f32_16x16x32_bf16 v[76:79], v[156:159], v[234:237], 0
	v_mfma_f32_16x16x32_bf16 v[72:75], v[164:167], v[234:237], 0
	v_mfma_f32_16x16x32_bf16 v[124:127], v[160:163], v[214:217], v[124:127]
	v_mfma_f32_16x16x32_bf16 v[120:123], v[180:183], v[214:217], v[120:123]
	v_mfma_f32_16x16x32_bf16 v[108:111], v[160:163], v[222:225], v[108:111]
	v_mfma_f32_16x16x32_bf16 v[104:107], v[180:183], v[222:225], v[104:107]
	v_mfma_f32_16x16x32_bf16 v[92:95], v[160:163], v[230:233], v[92:95]
	v_mfma_f32_16x16x32_bf16 v[88:91], v[180:183], v[230:233], v[88:91]
	v_mfma_f32_16x16x32_bf16 v[76:79], v[160:163], v[238:241], v[76:79]
	v_mfma_f32_16x16x32_bf16 v[72:75], v[180:183], v[238:241], v[72:75]
	v_mfma_f32_16x16x32_bf16 v[116:119], v[184:187], v[210:213], 0
	v_mfma_f32_16x16x32_bf16 v[112:115], v[194:197], v[210:213], 0
	v_mfma_f32_16x16x32_bf16 v[100:103], v[184:187], v[218:221], 0
	v_mfma_f32_16x16x32_bf16 v[96:99], v[194:197], v[218:221], 0
	v_mfma_f32_16x16x32_bf16 v[84:87], v[184:187], v[226:229], 0
	v_mfma_f32_16x16x32_bf16 v[80:83], v[194:197], v[226:229], 0
	v_mfma_f32_16x16x32_bf16 v[68:71], v[184:187], v[234:237], 0
	v_mfma_f32_16x16x32_bf16 v[64:67], v[194:197], v[234:237], 0
	v_mfma_f32_16x16x32_bf16 v[116:119], v[190:193], v[214:217], v[116:119]
	v_mfma_f32_16x16x32_bf16 v[112:115], v[206:209], v[214:217], v[112:115]
	v_mfma_f32_16x16x32_bf16 v[100:103], v[190:193], v[222:225], v[100:103]
	v_mfma_f32_16x16x32_bf16 v[96:99], v[206:209], v[222:225], v[96:99]
	v_mfma_f32_16x16x32_bf16 v[84:87], v[190:193], v[230:233], v[84:87]
	v_mfma_f32_16x16x32_bf16 v[80:83], v[206:209], v[230:233], v[80:83]
	v_mfma_f32_16x16x32_bf16 v[68:71], v[190:193], v[238:241], v[68:71]
	v_mfma_f32_16x16x32_bf16 v[64:67], v[206:209], v[238:241], v[64:67]
	s_setprio 0
	s_barrier
	s_add_i32 s15, s24, s56
	v_lshl_add_u64 v[242:243], s[52:53], 0, v[130:131]
	s_mov_b32 m0, s15
	ds_read_b128 v[210:213], v154 offset:16384
	ds_read_b128 v[214:217], v154 offset:17408
	ds_read_b128 v[218:221], v154 offset:18432
	ds_read_b128 v[222:225], v154 offset:19456
	ds_read_b128 v[226:229], v154 offset:20480
	ds_read_b128 v[230:233], v154 offset:21504
	ds_read_b128 v[234:237], v154 offset:22528
	ds_read_b128 v[238:241], v154 offset:23552
	global_load_lds_dwordx4 v[242:243], off
	s_add_i32 m0, s15, 0x2000
	s_add_u32 s70, s52, 0x40000
	v_lshl_add_u64 v[244:245], s[52:53], 0, v[134:135]
	s_addc_u32 s71, s53, 0
	s_add_i32 s14, s14, s56
	global_load_lds_dwordx4 v[244:245], off
	v_lshl_add_u64 v[246:247], s[70:71], 0, v[130:131]
	s_mov_b32 m0, s14
	v_lshl_add_u64 v[248:249], s[54:55], 0, v[132:133]
	global_load_lds_dwordx4 v[246:247], off
	v_lshl_add_u64 v[246:247], s[70:71], 0, v[134:135]
	s_add_i32 m0, s14, 0x2000
	s_nop 0
	global_load_lds_dwordx4 v[246:247], off
	v_lshl_add_u64 v[246:247], s[54:55], 0, v[128:129]
	s_mov_b32 m0, s57
	s_nop 0
	global_load_lds_dwordx4 v[246:247], off
	s_mov_b32 m0, s58
	s_nop 0
	global_load_lds_dwordx4 v[248:249], off
	s_waitcnt vmcnt(8)
	s_waitcnt lgkmcnt(0)
	s_barrier
; #define PG8_STAGE(bufoff, gbase, voff) do { _Pragma("unroll") for (int _i = 0; _i < 2; ++_i) \
;         __builtin_amdgcn_global_load_lds((const unsigned*)((const char*)(gbase) + (voff)[_i]), (LAS unsigned*)(lds + (bufoff) + ldsw + _i * 8192), 16, 0, 0); } while (0)
; #define PG8_LDA(dst, b, h) do { _Pragma("unroll") for (int m = 0; m < 4; ++m) _Pragma("unroll") for (int k = 0; k < 2; ++k) dst[m][k] = *(const LAS bf16x8*)(lds + PG8_SA(b, h) + aoff + m * 2048 + k * 1024); } while (0)
; #define PG8_LDB(dst, b, h) do { _Pragma("unroll") for (int n = 0; n < 2; ++n) _Pragma("unroll") for (int k = 0; k < 2; ++k) dst[n][k] = *(const LAS bf16x8*)(lds + PG8_SB(b, h) + boff + n * 2048 + k * 1024); } while (0)
; #define PG8_MMA(ai, bj, At, Bt) do { __builtin_amdgcn_s_setprio(1); _Pragma("unroll") for (int m = 0; m < 4; ++m) _Pragma("unroll") for (int n = 0; n < 2; ++n) _Pragma("unroll") for (int k = 0; k < 2; ++k) \
;         acc[ai][bj][m][n] = __builtin_amdgcn_mfma_f32_16x16x32_bf16(Bt[n][k], At[m][k], acc[ai][bj][m][n], 0, 0, 0); __builtin_amdgcn_s_setprio(0); } while (0)
; #define PG8_WAIT_V(n) asm volatile("s_waitcnt vmcnt(" #n ")" ::: "memory")
; #define PG8_WAIT_L(n) asm volatile("s_waitcnt lgkmcnt(" #n ")" ::: "memory")
; #define PG8_BAR __builtin_amdgcn_s_barrier()
; #define PG8_SCHED __builtin_amdgcn_sched_barrier(0)
; template <class Epi, class Sched>
; __device__ __forceinline__ void gemm_phase(const int tid, LAS unsigned char* lds, const int lda, const int ldb, const int K, const Sched& S, const Epi& E) {
;     ...
;             PG8_WAIT_V(8); PG8_WAIT_L(0); PG8_BAR; if (!cur.half) { PG8_MMA(1, 0, At, B0); PG8_MMA(1, 1, At, B1); } PG8_BAR; PG8_SCHED;
;             PG8_LDB(B0, 1, 0); PG8_LDB(B1, 1, 1); PG8_SCHED; PG8_LDA(At, 1, 0); PG8_STAGE(PG8_SA(0, 1), a2 + hstepA, voffA);
;             PG8_WAIT_V(8); PG8_WAIT_L(0); PG8_BAR; PG8_MMA(0, 0, At, B0); PG8_MMA(0, 1, At, B1); PG8_BAR; PG8_SCHED;
	s_setprio 1
	v_mfma_f32_16x16x32_bf16 v[60:63], v[156:159], v[210:213], 0
	v_mfma_f32_16x16x32_bf16 v[56:59], v[164:167], v[210:213], 0
	v_mfma_f32_16x16x32_bf16 v[44:47], v[156:159], v[218:221], 0
	v_mfma_f32_16x16x32_bf16 v[40:43], v[164:167], v[218:221], 0
	v_mfma_f32_16x16x32_bf16 v[28:31], v[156:159], v[226:229], 0
	v_mfma_f32_16x16x32_bf16 v[24:27], v[164:167], v[226:229], 0
	v_mfma_f32_16x16x32_bf16 v[12:15], v[156:159], v[234:237], 0
	v_mfma_f32_16x16x32_bf16 v[8:11], v[164:167], v[234:237], 0
	v_mfma_f32_16x16x32_bf16 v[60:63], v[160:163], v[214:217], v[60:63]
	v_mfma_f32_16x16x32_bf16 v[56:59], v[180:183], v[214:217], v[56:59]
	v_mfma_f32_16x16x32_bf16 v[44:47], v[160:163], v[222:225], v[44:47]
	v_mfma_f32_16x16x32_bf16 v[40:43], v[180:183], v[222:225], v[40:43]
	v_mfma_f32_16x16x32_bf16 v[28:31], v[160:163], v[230:233], v[28:31]
	v_mfma_f32_16x16x32_bf16 v[24:27], v[180:183], v[230:233], v[24:27]
	v_mfma_f32_16x16x32_bf16 v[12:15], v[160:163], v[238:241], v[12:15]
	v_mfma_f32_16x16x32_bf16 v[8:11], v[180:183], v[238:241], v[8:11]
	v_mfma_f32_16x16x32_bf16 v[52:55], v[184:187], v[210:213], 0
	v_mfma_f32_16x16x32_bf16 v[48:51], v[194:197], v[210:213], 0
	v_mfma_f32_16x16x32_bf16 v[36:39], v[184:187], v[218:221], 0
	v_mfma_f32_16x16x32_bf16 v[32:35], v[194:197], v[218:221], 0
	v_mfma_f32_16x16x32_bf16 v[20:23], v[184:187], v[226:229], 0
	v_mfma_f32_16x16x32_bf16 v[16:19], v[194:197], v[226:229], 0
	v_mfma_f32_16x16x32_bf16 v[4:7], v[184:187], v[234:237], 0
	v_mfma_f32_16x16x32_bf16 v[0:3], v[194:197], v[234:237], 0
	v_mfma_f32_16x16x32_bf16 v[52:55], v[190:193], v[214:217], v[52:55]
	v_mfma_f32_16x16x32_bf16 v[48:51], v[206:209], v[214:217], v[48:51]
	v_mfma_f32_16x16x32_bf16 v[36:39], v[190:193], v[222:225], v[36:39]
	v_mfma_f32_16x16x32_bf16 v[32:35], v[206:209], v[222:225], v[32:35]
	v_mfma_f32_16x16x32_bf16 v[20:23], v[190:193], v[230:233], v[20:23]
	v_mfma_f32_16x16x32_bf16 v[16:19], v[206:209], v[230:233], v[16:19]
	v_mfma_f32_16x16x32_bf16 v[4:7], v[190:193], v[238:241], v[4:7]
	v_mfma_f32_16x16x32_bf16 v[0:3], v[206:209], v[238:241], v[0:3]
	s_setprio 0
	s_barrier
	s_add_i32 s14, 0, 0x18000
	v_add_u32_e32 v155, s14, v146
	s_add_i32 s15, 0, 0x1c000
	ds_read_b128 v[156:159], v155
	ds_read_b128 v[160:163], v155 offset:1024
	ds_read_b128 v[164:167], v155 offset:2048
	ds_read_b128 v[180:183], v155 offset:3072
	v_add_u32_e32 v155, s15, v146
	ds_read_b128 v[184:187], v155
	ds_read_b128 v[190:193], v155 offset:1024
	ds_read_b128 v[194:197], v155 offset:2048
	ds_read_b128 v[206:209], v155 offset:3072
	s_add_u32 s54, s54, 0x40000
	s_addc_u32 s55, s55, 0
	s_mov_b32 m0, s59
	v_lshl_add_u64 v[250:251], s[54:55], 0, v[128:129]
	ds_read_b128 v[210:213], v154 offset:32768
	ds_read_b128 v[214:217], v154 offset:33792
	ds_read_b128 v[218:221], v154 offset:34816
	ds_read_b128 v[222:225], v154 offset:35840
	ds_read_b128 v[226:229], v154 offset:36864
	ds_read_b128 v[230:233], v154 offset:37888
	ds_read_b128 v[234:237], v154 offset:38912
	ds_read_b128 v[238:241], v154 offset:39936
	global_load_lds_dwordx4 v[250:251], off
	v_lshl_add_u64 v[250:251], s[54:55], 0, v[132:133]
	s_mov_b32 m0, s60
	s_nop 0
	global_load_lds_dwordx4 v[250:251], off
	s_waitcnt vmcnt(8)
	s_waitcnt lgkmcnt(0)
	s_barrier
	s_setprio 1
	v_mfma_f32_16x16x32_bf16 v[124:127], v[156:159], v[210:213], v[124:127]
	v_mfma_f32_16x16x32_bf16 v[120:123], v[164:167], v[210:213], v[120:123]
	v_mfma_f32_16x16x32_bf16 v[108:111], v[156:159], v[218:221], v[108:111]
	v_mfma_f32_16x16x32_bf16 v[104:107], v[164:167], v[218:221], v[104:107]
	v_mfma_f32_16x16x32_bf16 v[92:95], v[156:159], v[226:229], v[92:95]
	v_mfma_f32_16x16x32_bf16 v[88:91], v[164:167], v[226:229], v[88:91]
	v_mfma_f32_16x16x32_bf16 v[76:79], v[156:159], v[234:237], v[76:79]
	v_mfma_f32_16x16x32_bf16 v[72:75], v[164:167], v[234:237], v[72:75]
	v_mfma_f32_16x16x32_bf16 v[124:127], v[160:163], v[214:217], v[124:127]
	v_mfma_f32_16x16x32_bf16 v[120:123], v[180:183], v[214:217], v[120:123]
	v_mfma_f32_16x16x32_bf16 v[108:111], v[160:163], v[222:225], v[108:111]
	v_mfma_f32_16x16x32_bf16 v[104:107], v[180:183], v[222:225], v[104:107]
	v_mfma_f32_16x16x32_bf16 v[92:95], v[160:163], v[230:233], v[92:95]
	v_mfma_f32_16x16x32_bf16 v[88:91], v[180:183], v[230:233], v[88:91]
	v_mfma_f32_16x16x32_bf16 v[76:79], v[160:163], v[238:241], v[76:79]
	v_mfma_f32_16x16x32_bf16 v[72:75], v[180:183], v[238:241], v[72:75]
	v_mfma_f32_16x16x32_bf16 v[116:119], v[184:187], v[210:213], v[116:119]
	v_mfma_f32_16x16x32_bf16 v[112:115], v[194:197], v[210:213], v[112:115]
	v_mfma_f32_16x16x32_bf16 v[100:103], v[184:187], v[218:221], v[100:103]
	v_mfma_f32_16x16x32_bf16 v[96:99], v[194:197], v[218:221], v[96:99]
	v_mfma_f32_16x16x32_bf16 v[84:87], v[184:187], v[226:229], v[84:87]
	v_mfma_f32_16x16x32_bf16 v[80:83], v[194:197], v[226:229], v[80:83]
	v_mfma_f32_16x16x32_bf16 v[68:71], v[184:187], v[234:237], v[68:71]
	v_mfma_f32_16x16x32_bf16 v[64:67], v[194:197], v[234:237], v[64:67]
	v_mfma_f32_16x16x32_bf16 v[116:119], v[190:193], v[214:217], v[116:119]
	v_mfma_f32_16x16x32_bf16 v[112:115], v[206:209], v[214:217], v[112:115]
	v_mfma_f32_16x16x32_bf16 v[100:103], v[190:193], v[222:225], v[100:103]
	v_mfma_f32_16x16x32_bf16 v[96:99], v[206:209], v[222:225], v[96:99]
	v_mfma_f32_16x16x32_bf16 v[84:87], v[190:193], v[230:233], v[84:87]
	v_mfma_f32_16x16x32_bf16 v[80:83], v[206:209], v[230:233], v[80:83]
	v_mfma_f32_16x16x32_bf16 v[68:71], v[190:193], v[238:241], v[68:71]
	v_mfma_f32_16x16x32_bf16 v[64:67], v[206:209], v[238:241], v[64:67]
	s_setprio 0
	s_barrier
; #define PG8_STAGE(bufoff, gbase, voff) do { _Pragma("unroll") for (int _i = 0; _i < 2; ++_i) \
;         __builtin_amdgcn_global_load_lds((const unsigned*)((const char*)(gbase) + (voff)[_i]), (LAS unsigned*)(lds + (bufoff) + ldsw + _i * 8192), 16, 0, 0); } while (0)
; #define PG8_LDA(dst, b, h) do { _Pragma("unroll") for (int m = 0; m < 4; ++m) _Pragma("unroll") for (int k = 0; k < 2; ++k) dst[m][k] = *(const LAS bf16x8*)(lds + PG8_SA(b, h) + aoff + m * 2048 + k * 1024); } while (0)
; #define PG8_LDB(dst, b, h) do { _Pragma("unroll") for (int n = 0; n < 2; ++n) _Pragma("unroll") for (int k = 0; k < 2; ++k) dst[n][k] = *(const LAS bf16x8*)(lds + PG8_SB(b, h) + boff + n * 2048 + k * 1024); } while (0)
; #define PG8_WAIT_V(n) asm volatile("s_waitcnt vmcnt(" #n ")" ::: "memory")
; template <class Epi, class Sched>
; __device__ __forceinline__ void gemm_phase(const int tid, LAS unsigned char* lds, const int lda, const int ldb, const int K, const Sched& S, const Epi& E) {
;     ...
;             const bool last = (t == nt - 2);
;             const char* a1 = cA + (size_t)(t + 1) * kstep;
;             const char* a2 = last ? nA : cA + (size_t)(t + 2) * kstep; const char* b2 = last ? nB : cB + (size_t)(t + 2) * kstep;
;             const char* a3 = a2 + kstep; const char* b3 = b2 + kstep;
;             PG8_LDB(B0, 0, 0); PG8_LDB(B1, 0, 1); PG8_SCHED; PG8_LDA(At, 0, 0); PG8_STAGE(PG8_SA(1, 1), a1 + hstepA, voffA);
;             PG8_WAIT_V(8); PG8_WAIT_L(0); PG8_BAR; PG8_MMA(0, 0, At, B0); PG8_MMA(0, 1, At, B1); PG8_BAR; PG8_SCHED;
;             PG8_LDA(At, 0, 1); PG8_STAGE(PG8_SB(0, 0), b2, voffB); PG8_STAGE(PG8_SB(0, 1), b2 + hstepB, voffB); PG8_STAGE(PG8_SA(0, 0), a2, voffA);
;             PG8_WAIT_V(8); PG8_WAIT_L(0); PG8_BAR; if (!cur.half) { PG8_MMA(1, 0, At, B0); PG8_MMA(1, 1, At, B1); } PG8_BAR; PG8_SCHED;
;             PG8_LDB(B0, 1, 0); PG8_LDB(B1, 1, 1); PG8_SCHED; PG8_LDA(At, 1, 0); PG8_STAGE(PG8_SA(0, 1), a2 + hstepA, voffA);
;             PG8_WAIT_V(8); PG8_WAIT_L(0); PG8_BAR; PG8_MMA(0, 0, At, B0); PG8_MMA(0, 1, At, B1); PG8_BAR; PG8_SCHED;
;             PG8_LDA(At, 1, 1); PG8_STAGE(PG8_SB(1, 0), b3, voffB); PG8_STAGE(PG8_SB(1, 1), b3 + hstepB, voffB); PG8_STAGE(PG8_SA(1, 0), a3, voffA);
;             PG8_WAIT_V(8); PG8_WAIT_L(0); PG8_BAR; if (!cur.half) { PG8_MMA(1, 0, At, B0); PG8_MMA(1, 1, At, B1); } PG8_BAR; PG8_SCHED;
	s_add_i32 s14, s14, s56
	v_lshl_add_u64 v[242:243], v[242:243], 0, s[6:7]
	s_mov_b32 m0, s14
	ds_read_b128 v[210:213], v154 offset:49152
	ds_read_b128 v[214:217], v154 offset:50176
	ds_read_b128 v[218:221], v154 offset:51200
	ds_read_b128 v[222:225], v154 offset:52224
	ds_read_b128 v[226:229], v154 offset:53248
	ds_read_b128 v[230:233], v154 offset:54272
	ds_read_b128 v[234:237], v154 offset:55296
	ds_read_b128 v[238:241], v154 offset:56320
	global_load_lds_dwordx4 v[242:243], off
	s_add_i32 m0, s14, 0x2000
	s_add_u32 s52, s52, 0x40080
	v_lshl_add_u64 v[242:243], v[244:245], 0, s[6:7]
	s_addc_u32 s53, s53, 0
	s_add_i32 s14, s15, s56
	global_load_lds_dwordx4 v[242:243], off
	v_lshl_add_u64 v[242:243], s[52:53], 0, v[130:131]
	s_mov_b32 m0, s14
	s_nop 0
	global_load_lds_dwordx4 v[242:243], off
	v_lshl_add_u64 v[242:243], s[52:53], 0, v[134:135]
	s_add_i32 m0, s14, 0x2000
	s_nop 0
	global_load_lds_dwordx4 v[242:243], off
	v_lshl_add_u64 v[242:243], v[246:247], 0, s[6:7]
	s_mov_b32 m0, s61
	s_nop 0
	global_load_lds_dwordx4 v[242:243], off
	v_lshl_add_u64 v[242:243], v[248:249], 0, s[6:7]
	s_mov_b32 m0, s62
	s_nop 0
	global_load_lds_dwordx4 v[242:243], off
	s_waitcnt vmcnt(8)
	s_waitcnt lgkmcnt(0)
	s_barrier
	s_setprio 1
	v_mfma_f32_16x16x32_bf16 v[60:63], v[156:159], v[210:213], v[60:63]
	v_mfma_f32_16x16x32_bf16 v[56:59], v[164:167], v[210:213], v[56:59]
	v_mfma_f32_16x16x32_bf16 v[44:47], v[156:159], v[218:221], v[44:47]
	v_mfma_f32_16x16x32_bf16 v[40:43], v[164:167], v[218:221], v[40:43]
	v_mfma_f32_16x16x32_bf16 v[28:31], v[156:159], v[226:229], v[28:31]
	v_mfma_f32_16x16x32_bf16 v[24:27], v[164:167], v[226:229], v[24:27]
	v_mfma_f32_16x16x32_bf16 v[12:15], v[156:159], v[234:237], v[12:15]
	v_mfma_f32_16x16x32_bf16 v[8:11], v[164:167], v[234:237], v[8:11]
	v_mfma_f32_16x16x32_bf16 v[60:63], v[160:163], v[214:217], v[60:63]
	v_mfma_f32_16x16x32_bf16 v[56:59], v[180:183], v[214:217], v[56:59]
	v_mfma_f32_16x16x32_bf16 v[44:47], v[160:163], v[222:225], v[44:47]
	v_mfma_f32_16x16x32_bf16 v[40:43], v[180:183], v[222:225], v[40:43]
	v_mfma_f32_16x16x32_bf16 v[28:31], v[160:163], v[230:233], v[28:31]
	v_mfma_f32_16x16x32_bf16 v[24:27], v[180:183], v[230:233], v[24:27]
	v_mfma_f32_16x16x32_bf16 v[12:15], v[160:163], v[238:241], v[12:15]
	v_mfma_f32_16x16x32_bf16 v[8:11], v[180:183], v[238:241], v[8:11]
	v_mfma_f32_16x16x32_bf16 v[52:55], v[184:187], v[210:213], v[52:55]
	v_mfma_f32_16x16x32_bf16 v[48:51], v[194:197], v[210:213], v[48:51]
	v_mfma_f32_16x16x32_bf16 v[36:39], v[184:187], v[218:221], v[36:39]
	v_mfma_f32_16x16x32_bf16 v[32:35], v[194:197], v[218:221], v[32:35]
	v_mfma_f32_16x16x32_bf16 v[20:23], v[184:187], v[226:229], v[20:23]
	v_mfma_f32_16x16x32_bf16 v[16:19], v[194:197], v[226:229], v[16:19]
	v_mfma_f32_16x16x32_bf16 v[4:7], v[184:187], v[234:237], v[4:7]
	v_mfma_f32_16x16x32_bf16 v[0:3], v[194:197], v[234:237], v[0:3]
	v_mfma_f32_16x16x32_bf16 v[52:55], v[190:193], v[214:217], v[52:55]
	v_mfma_f32_16x16x32_bf16 v[48:51], v[206:209], v[214:217], v[48:51]
	v_mfma_f32_16x16x32_bf16 v[36:39], v[190:193], v[222:225], v[36:39]
	v_mfma_f32_16x16x32_bf16 v[32:35], v[206:209], v[222:225], v[32:35]
	v_mfma_f32_16x16x32_bf16 v[20:23], v[190:193], v[230:233], v[20:23]
	v_mfma_f32_16x16x32_bf16 v[16:19], v[206:209], v[230:233], v[16:19]
	v_mfma_f32_16x16x32_bf16 v[4:7], v[190:193], v[238:241], v[4:7]
	v_mfma_f32_16x16x32_bf16 v[0:3], v[206:209], v[238:241], v[0:3]
	s_setprio 0
	s_barrier
	s_add_u32 s38, s38, 0x100
	s_addc_u32 s39, s39, 0
	s_add_u32 s47, s47, 0x100
	s_addc_u32 s67, s67, 0
	s_cmp_ge_i32 s68, s4
	s_mov_b32 s52, s68
	s_cbranch_scc1 .Lkexit_197
.LBB0_197:
	s_add_i32 s68, s52, 2
	s_add_u32 s14, s38, 0xfffc0080
	s_addc_u32 s15, s39, -1
	s_add_i32 s24, 0, 0x10000
	s_cmp_eq_u32 s64, s52
	s_cselect_b32 s55, s3, s15
	s_cselect_b32 s54, s2, s14
	v_add_u32_e32 v155, s24, v146
	s_cselect_b32 s53, s23, s67
	s_cselect_b32 s52, s22, s47
	s_add_i32 s14, 0, 0x14000
	ds_read_b128 v[156:159], v155
	ds_read_b128 v[160:163], v155 offset:1024
	ds_read_b128 v[164:167], v155 offset:2048
	ds_read_b128 v[180:183], v155 offset:3072
	v_add_u32_e32 v155, s14, v146
	ds_read_b128 v[184:187], v155
	ds_read_b128 v[190:193], v155 offset:1024
	ds_read_b128 v[194:197], v155 offset:2048
	ds_read_b128 v[206:209], v155 offset:3072
	v_lshl_add_u64 v[242:243], s[38:39], 0, v[136:137]
	s_add_i32 m0, s57, 0xc000
	ds_read_b128 v[210:213], v154
	ds_read_b128 v[214:217], v154 offset:1024
	ds_read_b128 v[218:221], v154 offset:2048
	ds_read_b128 v[222:225], v154 offset:3072
	ds_read_b128 v[226:229], v154 offset:4096
	ds_read_b128 v[230:233], v154 offset:5120
	ds_read_b128 v[234:237], v154 offset:6144
	ds_read_b128 v[238:241], v154 offset:7168
	global_load_lds_dwordx4 v[242:243], off
	v_lshl_add_u64 v[242:243], s[38:39], 0, v[138:139]
	s_add_i32 m0, s57, 0xe000
	s_nop 0
	global_load_lds_dwordx4 v[242:243], off
	s_waitcnt vmcnt(8)
	s_waitcnt lgkmcnt(0)
	s_barrier
; #define PG8_STAGE(bufoff, gbase, voff) do { _Pragma("unroll") for (int _i = 0; _i < 2; ++_i) \
;         __builtin_amdgcn_global_load_lds((const unsigned*)((const char*)(gbase) + (voff)[_i]), (LAS unsigned*)(lds + (bufoff) + ldsw + _i * 8192), 16, 0, 0); } while (0)
; #define PG8_LDA(dst, b, h) do { _Pragma("unroll") for (int m = 0; m < 4; ++m) _Pragma("unroll") for (int k = 0; k < 2; ++k) dst[m][k] = *(const LAS bf16x8*)(lds + PG8_SA(b, h) + aoff + m * 2048 + k * 1024); } while (0)
; #define PG8_LDB(dst, b, h) do { _Pragma("unroll") for (int n = 0; n < 2; ++n) _Pragma("unroll") for (int k = 0; k < 2; ++k) dst[n][k] = *(const LAS bf16x8*)(lds + PG8_SB(b, h) + boff + n * 2048 + k * 1024); } while (0)
; #define PG8_MMA(ai, bj, At, Bt) do { __builtin_amdgcn_s_setprio(1); _Pragma("unroll") for (int m = 0; m < 4; ++m) _Pragma("unroll") for (int n = 0; n < 2; ++n) _Pragma("unroll") for (int k = 0; k < 2; ++k) \
;         acc[ai][bj][m][n] = __builtin_amdgcn_mfma_f32_16x16x32_bf16(Bt[n][k], At[m][k], acc[ai][bj][m][n], 0, 0, 0); __builtin_amdgcn_s_setprio(0); } while (0)
; #define PG8_WAIT_V(n) asm volatile("s_waitcnt vmcnt(" #n ")" ::: "memory")
; #define PG8_WAIT_L(n) asm volatile("s_waitcnt lgkmcnt(" #n ")" ::: "memory")
; #define PG8_BAR __builtin_amdgcn_s_barrier()
; #define PG8_SCHED __builtin_amdgcn_sched_barrier(0)
; template <class Epi, class Sched>
; __device__ __forceinline__ void gemm_phase(const int tid, LAS unsigned char* lds, const int lda, const int ldb, const int K, const Sched& S, const Epi& E) {
;     ...
;             PG8_WAIT_V(8); PG8_WAIT_L(0); PG8_BAR; PG8_MMA(0, 0, At, B0); PG8_MMA(0, 1, At, B1); PG8_BAR; PG8_SCHED;
;             PG8_LDA(At, 0, 1); PG8_STAGE(PG8_SB(0, 0), b2, voffB); PG8_STAGE(PG8_SB(0, 1), b2 + hstepB, voffB); PG8_STAGE(PG8_SA(0, 0), a2, voffA);
;             PG8_WAIT_V(8); PG8_WAIT_L(0); PG8_BAR; if (!cur.half) { PG8_MMA(1, 0, At, B0); PG8_MMA(1, 1, At, B1); } PG8_BAR; PG8_SCHED;
;             PG8_LDB(B0, 1, 0); PG8_LDB(B1, 1, 1); PG8_SCHED; PG8_LDA(At, 1, 0); PG8_STAGE(PG8_SA(0, 1), a2 + hstepA, voffA);
;             PG8_WAIT_V(8); PG8_WAIT_L(0); PG8_BAR; PG8_MMA(0, 0, At, B0); PG8_MMA(0, 1, At, B1); PG8_BAR; PG8_SCHED;
	s_setprio 1
	v_mfma_f32_16x16x32_bf16 v[124:127], v[156:159], v[210:213], v[124:127]
	v_mfma_f32_16x16x32_bf16 v[120:123], v[164:167], v[210:213], v[120:123]
	v_mfma_f32_16x16x32_bf16 v[108:111], v[156:159], v[218:221], v[108:111]
	v_mfma_f32_16x16x32_bf16 v[104:107], v[164:167], v[218:221], v[104:107]
	v_mfma_f32_16x16x32_bf16 v[92:95], v[156:159], v[226:229], v[92:95]
	v_mfma_f32_16x16x32_bf16 v[88:91], v[164:167], v[226:229], v[88:91]
	v_mfma_f32_16x16x32_bf16 v[76:79], v[156:159], v[234:237], v[76:79]
	v_mfma_f32_16x16x32_bf16 v[72:75], v[164:167], v[234:237], v[72:75]
	v_mfma_f32_16x16x32_bf16 v[124:127], v[160:163], v[214:217], v[124:127]
	v_mfma_f32_16x16x32_bf16 v[120:123], v[180:183], v[214:217], v[120:123]
	v_mfma_f32_16x16x32_bf16 v[108:111], v[160:163], v[222:225], v[108:111]
	v_mfma_f32_16x16x32_bf16 v[104:107], v[180:183], v[222:225], v[104:107]
	v_mfma_f32_16x16x32_bf16 v[92:95], v[160:163], v[230:233], v[92:95]
	v_mfma_f32_16x16x32_bf16 v[88:91], v[180:183], v[230:233], v[88:91]
	v_mfma_f32_16x16x32_bf16 v[76:79], v[160:163], v[238:241], v[76:79]
	v_mfma_f32_16x16x32_bf16 v[72:75], v[180:183], v[238:241], v[72:75]
	v_mfma_f32_16x16x32_bf16 v[116:119], v[184:187], v[210:213], v[116:119]
	v_mfma_f32_16x16x32_bf16 v[112:115], v[194:197], v[210:213], v[112:115]
	v_mfma_f32_16x16x32_bf16 v[100:103], v[184:187], v[218:221], v[100:103]
	v_mfma_f32_16x16x32_bf16 v[96:99], v[194:197], v[218:221], v[96:99]
	v_mfma_f32_16x16x32_bf16 v[84:87], v[184:187], v[226:229], v[84:87]
	v_mfma_f32_16x16x32_bf16 v[80:83], v[194:197], v[226:229], v[80:83]
	v_mfma_f32_16x16x32_bf16 v[68:71], v[184:187], v[234:237], v[68:71]
	v_mfma_f32_16x16x32_bf16 v[64:67], v[194:197], v[234:237], v[64:67]
	v_mfma_f32_16x16x32_bf16 v[116:119], v[190:193], v[214:217], v[116:119]
	v_mfma_f32_16x16x32_bf16 v[112:115], v[206:209], v[214:217], v[112:115]
	v_mfma_f32_16x16x32_bf16 v[100:103], v[190:193], v[222:225], v[100:103]
	v_mfma_f32_16x16x32_bf16 v[96:99], v[206:209], v[222:225], v[96:99]
	v_mfma_f32_16x16x32_bf16 v[84:87], v[190:193], v[230:233], v[84:87]
	v_mfma_f32_16x16x32_bf16 v[80:83], v[206:209], v[230:233], v[80:83]
	v_mfma_f32_16x16x32_bf16 v[68:71], v[190:193], v[238:241], v[68:71]
	v_mfma_f32_16x16x32_bf16 v[64:67], v[206:209], v[238:241], v[64:67]
	s_setprio 0
	s_barrier
	s_add_i32 s15, s24, s56
	v_lshl_add_u64 v[242:243], s[52:53], 0, v[130:131]
	s_mov_b32 m0, s15
	ds_read_b128 v[210:213], v154 offset:16384
	ds_read_b128 v[214:217], v154 offset:17408
	ds_read_b128 v[218:221], v154 offset:18432
	ds_read_b128 v[222:225], v154 offset:19456
	ds_read_b128 v[226:229], v154 offset:20480
	ds_read_b128 v[230:233], v154 offset:21504
	ds_read_b128 v[234:237], v154 offset:22528
	ds_read_b128 v[238:241], v154 offset:23552
	global_load_lds_dwordx4 v[242:243], off
	s_add_i32 m0, s15, 0x2000
	s_add_u32 s70, s52, 0x40000
	v_lshl_add_u64 v[244:245], s[52:53], 0, v[134:135]
	s_addc_u32 s71, s53, 0
	s_add_i32 s14, s14, s56
	global_load_lds_dwordx4 v[244:245], off
	v_lshl_add_u64 v[246:247], s[70:71], 0, v[130:131]
	s_mov_b32 m0, s14
	v_lshl_add_u64 v[248:249], s[54:55], 0, v[132:133]
	global_load_lds_dwordx4 v[246:247], off
	v_lshl_add_u64 v[246:247], s[70:71], 0, v[134:135]
	s_add_i32 m0, s14, 0x2000
	s_nop 0
	global_load_lds_dwordx4 v[246:247], off
	v_lshl_add_u64 v[246:247], s[54:55], 0, v[128:129]
	s_mov_b32 m0, s57
	s_nop 0
	global_load_lds_dwordx4 v[246:247], off
	s_mov_b32 m0, s58
	s_nop 0
	global_load_lds_dwordx4 v[248:249], off
	s_waitcnt vmcnt(8)
	s_waitcnt lgkmcnt(0)
	s_barrier
	s_setprio 1
	v_mfma_f32_16x16x32_bf16 v[60:63], v[156:159], v[210:213], v[60:63]
	v_mfma_f32_16x16x32_bf16 v[56:59], v[164:167], v[210:213], v[56:59]
	v_mfma_f32_16x16x32_bf16 v[44:47], v[156:159], v[218:221], v[44:47]
	v_mfma_f32_16x16x32_bf16 v[40:43], v[164:167], v[218:221], v[40:43]
	v_mfma_f32_16x16x32_bf16 v[28:31], v[156:159], v[226:229], v[28:31]
	v_mfma_f32_16x16x32_bf16 v[24:27], v[164:167], v[226:229], v[24:27]
	v_mfma_f32_16x16x32_bf16 v[12:15], v[156:159], v[234:237], v[12:15]
	v_mfma_f32_16x16x32_bf16 v[8:11], v[164:167], v[234:237], v[8:11]
	v_mfma_f32_16x16x32_bf16 v[60:63], v[160:163], v[214:217], v[60:63]
	v_mfma_f32_16x16x32_bf16 v[56:59], v[180:183], v[214:217], v[56:59]
	v_mfma_f32_16x16x32_bf16 v[44:47], v[160:163], v[222:225], v[44:47]
	v_mfma_f32_16x16x32_bf16 v[40:43], v[180:183], v[222:225], v[40:43]
	v_mfma_f32_16x16x32_bf16 v[28:31], v[160:163], v[230:233], v[28:31]
	v_mfma_f32_16x16x32_bf16 v[24:27], v[180:183], v[230:233], v[24:27]
	v_mfma_f32_16x16x32_bf16 v[12:15], v[160:163], v[238:241], v[12:15]
	v_mfma_f32_16x16x32_bf16 v[8:11], v[180:183], v[238:241], v[8:11]
	v_mfma_f32_16x16x32_bf16 v[52:55], v[184:187], v[210:213], v[52:55]
	v_mfma_f32_16x16x32_bf16 v[48:51], v[194:197], v[210:213], v[48:51]
	v_mfma_f32_16x16x32_bf16 v[36:39], v[184:187], v[218:221], v[36:39]
	v_mfma_f32_16x16x32_bf16 v[32:35], v[194:197], v[218:221], v[32:35]
	v_mfma_f32_16x16x32_bf16 v[20:23], v[184:187], v[226:229], v[20:23]
	v_mfma_f32_16x16x32_bf16 v[16:19], v[194:197], v[226:229], v[16:19]
	v_mfma_f32_16x16x32_bf16 v[4:7], v[184:187], v[234:237], v[4:7]
	v_mfma_f32_16x16x32_bf16 v[0:3], v[194:197], v[234:237], v[0:3]
	v_mfma_f32_16x16x32_bf16 v[52:55], v[190:193], v[214:217], v[52:55]
	v_mfma_f32_16x16x32_bf16 v[48:51], v[206:209], v[214:217], v[48:51]
	v_mfma_f32_16x16x32_bf16 v[36:39], v[190:193], v[222:225], v[36:39]
	v_mfma_f32_16x16x32_bf16 v[32:35], v[206:209], v[222:225], v[32:35]
	v_mfma_f32_16x16x32_bf16 v[20:23], v[190:193], v[230:233], v[20:23]
	v_mfma_f32_16x16x32_bf16 v[16:19], v[206:209], v[230:233], v[16:19]
	v_mfma_f32_16x16x32_bf16 v[4:7], v[190:193], v[238:241], v[4:7]
	v_mfma_f32_16x16x32_bf16 v[0:3], v[206:209], v[238:241], v[0:3]
	s_setprio 0
	s_barrier
; #define PG8_STAGE(bufoff, gbase, voff) do { _Pragma("unroll") for (int _i = 0; _i < 2; ++_i) \
;         __builtin_amdgcn_global_load_lds((const unsigned*)((const char*)(gbase) + (voff)[_i]), (LAS unsigned*)(lds + (bufoff) + ldsw + _i * 8192), 16, 0, 0); } while (0)
; #define PG8_LDA(dst, b, h) do { _Pragma("unroll") for (int m = 0; m < 4; ++m) _Pragma("unroll") for (int k = 0; k < 2; ++k) dst[m][k] = *(const LAS bf16x8*)(lds + PG8_SA(b, h) + aoff + m * 2048 + k * 1024); } while (0)
; #define PG8_LDB(dst, b, h) do { _Pragma("unroll") for (int n = 0; n < 2; ++n) _Pragma("unroll") for (int k = 0; k < 2; ++k) dst[n][k] = *(const LAS bf16x8*)(lds + PG8_SB(b, h) + boff + n * 2048 + k * 1024); } while (0)
; #define PG8_MMA(ai, bj, At, Bt) do { __builtin_amdgcn_s_setprio(1); _Pragma("unroll") for (int m = 0; m < 4; ++m) _Pragma("unroll") for (int n = 0; n < 2; ++n) _Pragma("unroll") for (int k = 0; k < 2; ++k) \
;         acc[ai][bj][m][n] = __builtin_amdgcn_mfma_f32_16x16x32_bf16(Bt[n][k], At[m][k], acc[ai][bj][m][n], 0, 0, 0); __builtin_amdgcn_s_setprio(0); } while (0)
; #define PG8_WAIT_V(n) asm volatile("s_waitcnt vmcnt(" #n ")" ::: "memory")
; #define PG8_WAIT_L(n) asm volatile("s_waitcnt lgkmcnt(" #n ")" ::: "memory")
; #define PG8_BAR __builtin_amdgcn_s_barrier()
; #define PG8_SCHED __builtin_amdgcn_sched_barrier(0)
; template <class Epi, class Sched>
; __device__ __forceinline__ void gemm_phase(const int tid, LAS unsigned char* lds, const int lda, const int ldb, const int K, const Sched& S, const Epi& E) {
;     ...
;             PG8_LDB(B0, 1, 0); PG8_LDB(B1, 1, 1); PG8_SCHED; PG8_LDA(At, 1, 0); PG8_STAGE(PG8_SA(0, 1), a2 + hstepA, voffA);
;             PG8_WAIT_V(8); PG8_WAIT_L(0); PG8_BAR; PG8_MMA(0, 0, At, B0); PG8_MMA(0, 1, At, B1); PG8_BAR; PG8_SCHED;
;             PG8_LDA(At, 1, 1); PG8_STAGE(PG8_SB(1, 0), b3, voffB); PG8_STAGE(PG8_SB(1, 1), b3 + hstepB, voffB); PG8_STAGE(PG8_SA(1, 0), a3, voffA);
;             PG8_WAIT_V(8); PG8_WAIT_L(0); PG8_BAR; if (!cur.half) { PG8_MMA(1, 0, At, B0); PG8_MMA(1, 1, At, B1); } PG8_BAR; PG8_SCHED;
;         }
	s_add_i32 s14, 0, 0x18000
	v_add_u32_e32 v155, s14, v146
	s_add_i32 s15, 0, 0x1c000
	ds_read_b128 v[156:159], v155
	ds_read_b128 v[160:163], v155 offset:1024
	ds_read_b128 v[164:167], v155 offset:2048
	ds_read_b128 v[180:183], v155 offset:3072
	v_add_u32_e32 v155, s15, v146
	ds_read_b128 v[184:187], v155
	ds_read_b128 v[190:193], v155 offset:1024
	ds_read_b128 v[194:197], v155 offset:2048
	ds_read_b128 v[206:209], v155 offset:3072
	s_add_u32 s54, s54, 0x40000
	s_addc_u32 s55, s55, 0
	s_mov_b32 m0, s59
	v_lshl_add_u64 v[250:251], s[54:55], 0, v[128:129]
	ds_read_b128 v[210:213], v154 offset:32768
	ds_read_b128 v[214:217], v154 offset:33792
	ds_read_b128 v[218:221], v154 offset:34816
	ds_read_b128 v[222:225], v154 offset:35840
	ds_read_b128 v[226:229], v154 offset:36864
	ds_read_b128 v[230:233], v154 offset:37888
	ds_read_b128 v[234:237], v154 offset:38912
	ds_read_b128 v[238:241], v154 offset:39936
	global_load_lds_dwordx4 v[250:251], off
	v_lshl_add_u64 v[250:251], s[54:55], 0, v[132:133]
	s_mov_b32 m0, s60
	s_nop 0
	global_load_lds_dwordx4 v[250:251], off
	s_waitcnt vmcnt(8)
	s_waitcnt lgkmcnt(0)
	s_barrier
	s_setprio 1
	v_mfma_f32_16x16x32_bf16 v[124:127], v[156:159], v[210:213], v[124:127]
	v_mfma_f32_16x16x32_bf16 v[120:123], v[164:167], v[210:213], v[120:123]
	v_mfma_f32_16x16x32_bf16 v[108:111], v[156:159], v[218:221], v[108:111]
	v_mfma_f32_16x16x32_bf16 v[104:107], v[164:167], v[218:221], v[104:107]
	v_mfma_f32_16x16x32_bf16 v[92:95], v[156:159], v[226:229], v[92:95]
	v_mfma_f32_16x16x32_bf16 v[88:91], v[164:167], v[226:229], v[88:91]
	v_mfma_f32_16x16x32_bf16 v[76:79], v[156:159], v[234:237], v[76:79]
	v_mfma_f32_16x16x32_bf16 v[72:75], v[164:167], v[234:237], v[72:75]
	v_mfma_f32_16x16x32_bf16 v[124:127], v[160:163], v[214:217], v[124:127]
	v_mfma_f32_16x16x32_bf16 v[120:123], v[180:183], v[214:217], v[120:123]
	v_mfma_f32_16x16x32_bf16 v[108:111], v[160:163], v[222:225], v[108:111]
	v_mfma_f32_16x16x32_bf16 v[104:107], v[180:183], v[222:225], v[104:107]
	v_mfma_f32_16x16x32_bf16 v[92:95], v[160:163], v[230:233], v[92:95]
	v_mfma_f32_16x16x32_bf16 v[88:91], v[180:183], v[230:233], v[88:91]
	v_mfma_f32_16x16x32_bf16 v[76:79], v[160:163], v[238:241], v[76:79]
	v_mfma_f32_16x16x32_bf16 v[72:75], v[180:183], v[238:241], v[72:75]
	v_mfma_f32_16x16x32_bf16 v[116:119], v[184:187], v[210:213], v[116:119]
	v_mfma_f32_16x16x32_bf16 v[112:115], v[194:197], v[210:213], v[112:115]
	v_mfma_f32_16x16x32_bf16 v[100:103], v[184:187], v[218:221], v[100:103]
	v_mfma_f32_16x16x32_bf16 v[96:99], v[194:197], v[218:221], v[96:99]
	v_mfma_f32_16x16x32_bf16 v[84:87], v[184:187], v[226:229], v[84:87]
	v_mfma_f32_16x16x32_bf16 v[80:83], v[194:197], v[226:229], v[80:83]
	v_mfma_f32_16x16x32_bf16 v[68:71], v[184:187], v[234:237], v[68:71]
	v_mfma_f32_16x16x32_bf16 v[64:67], v[194:197], v[234:237], v[64:67]
	v_mfma_f32_16x16x32_bf16 v[116:119], v[190:193], v[214:217], v[116:119]
	v_mfma_f32_16x16x32_bf16 v[112:115], v[206:209], v[214:217], v[112:115]
	v_mfma_f32_16x16x32_bf16 v[100:103], v[190:193], v[222:225], v[100:103]
	v_mfma_f32_16x16x32_bf16 v[96:99], v[206:209], v[222:225], v[96:99]
	v_mfma_f32_16x16x32_bf16 v[84:87], v[190:193], v[230:233], v[84:87]
	v_mfma_f32_16x16x32_bf16 v[80:83], v[206:209], v[230:233], v[80:83]
	v_mfma_f32_16x16x32_bf16 v[68:71], v[190:193], v[238:241], v[68:71]
	v_mfma_f32_16x16x32_bf16 v[64:67], v[206:209], v[238:241], v[64:67]
	s_setprio 0
	s_barrier
	s_add_i32 s14, s14, s56
	v_lshl_add_u64 v[242:243], v[242:243], 0, s[6:7]
	s_mov_b32 m0, s14
	ds_read_b128 v[210:213], v154 offset:49152
	ds_read_b128 v[214:217], v154 offset:50176
	ds_read_b128 v[218:221], v154 offset:51200
	ds_read_b128 v[222:225], v154 offset:52224
	ds_read_b128 v[226:229], v154 offset:53248
	ds_read_b128 v[230:233], v154 offset:54272
	ds_read_b128 v[234:237], v154 offset:55296
	ds_read_b128 v[238:241], v154 offset:56320
	global_load_lds_dwordx4 v[242:243], off
	s_add_i32 m0, s14, 0x2000
	s_add_u32 s52, s52, 0x40080
	v_lshl_add_u64 v[242:243], v[244:245], 0, s[6:7]
	s_addc_u32 s53, s53, 0
	s_add_i32 s14, s15, s56
	global_load_lds_dwordx4 v[242:243], off
	v_lshl_add_u64 v[242:243], s[52:53], 0, v[130:131]
	s_mov_b32 m0, s14
	s_nop 0
	global_load_lds_dwordx4 v[242:243], off
	v_lshl_add_u64 v[242:243], s[52:53], 0, v[134:135]
	s_add_i32 m0, s14, 0x2000
	s_nop 0
	global_load_lds_dwordx4 v[242:243], off
	v_lshl_add_u64 v[242:243], v[246:247], 0, s[6:7]
	s_mov_b32 m0, s61
	s_nop 0
	global_load_lds_dwordx4 v[242:243], off
	v_lshl_add_u64 v[242:243], v[248:249], 0, s[6:7]
	s_mov_b32 m0, s62
	s_nop 0
	global_load_lds_dwordx4 v[242:243], off
	s_waitcnt vmcnt(8)
	s_waitcnt lgkmcnt(0)
	s_barrier
	s_setprio 1
	v_mfma_f32_16x16x32_bf16 v[60:63], v[156:159], v[210:213], v[60:63]
	v_mfma_f32_16x16x32_bf16 v[56:59], v[164:167], v[210:213], v[56:59]
	v_mfma_f32_16x16x32_bf16 v[44:47], v[156:159], v[218:221], v[44:47]
	v_mfma_f32_16x16x32_bf16 v[40:43], v[164:167], v[218:221], v[40:43]
	v_mfma_f32_16x16x32_bf16 v[28:31], v[156:159], v[226:229], v[28:31]
	v_mfma_f32_16x16x32_bf16 v[24:27], v[164:167], v[226:229], v[24:27]
	v_mfma_f32_16x16x32_bf16 v[12:15], v[156:159], v[234:237], v[12:15]
	v_mfma_f32_16x16x32_bf16 v[8:11], v[164:167], v[234:237], v[8:11]
	v_mfma_f32_16x16x32_bf16 v[60:63], v[160:163], v[214:217], v[60:63]
	v_mfma_f32_16x16x32_bf16 v[56:59], v[180:183], v[214:217], v[56:59]
	v_mfma_f32_16x16x32_bf16 v[44:47], v[160:163], v[222:225], v[44:47]
	v_mfma_f32_16x16x32_bf16 v[40:43], v[180:183], v[222:225], v[40:43]
	v_mfma_f32_16x16x32_bf16 v[28:31], v[160:163], v[230:233], v[28:31]
	v_mfma_f32_16x16x32_bf16 v[24:27], v[180:183], v[230:233], v[24:27]
	v_mfma_f32_16x16x32_bf16 v[12:15], v[160:163], v[238:241], v[12:15]
	v_mfma_f32_16x16x32_bf16 v[8:11], v[180:183], v[238:241], v[8:11]
	v_mfma_f32_16x16x32_bf16 v[52:55], v[184:187], v[210:213], v[52:55]
	v_mfma_f32_16x16x32_bf16 v[48:51], v[194:197], v[210:213], v[48:51]
	v_mfma_f32_16x16x32_bf16 v[36:39], v[184:187], v[218:221], v[36:39]
	v_mfma_f32_16x16x32_bf16 v[32:35], v[194:197], v[218:221], v[32:35]
	v_mfma_f32_16x16x32_bf16 v[20:23], v[184:187], v[226:229], v[20:23]
	v_mfma_f32_16x16x32_bf16 v[16:19], v[194:197], v[226:229], v[16:19]
	v_mfma_f32_16x16x32_bf16 v[4:7], v[184:187], v[234:237], v[4:7]
	v_mfma_f32_16x16x32_bf16 v[0:3], v[194:197], v[234:237], v[0:3]
	v_mfma_f32_16x16x32_bf16 v[52:55], v[190:193], v[214:217], v[52:55]
	v_mfma_f32_16x16x32_bf16 v[48:51], v[206:209], v[214:217], v[48:51]
	v_mfma_f32_16x16x32_bf16 v[36:39], v[190:193], v[222:225], v[36:39]
	v_mfma_f32_16x16x32_bf16 v[32:35], v[206:209], v[222:225], v[32:35]
	v_mfma_f32_16x16x32_bf16 v[20:23], v[190:193], v[230:233], v[20:23]
	v_mfma_f32_16x16x32_bf16 v[16:19], v[206:209], v[230:233], v[16:19]
	v_mfma_f32_16x16x32_bf16 v[4:7], v[190:193], v[238:241], v[4:7]
	v_mfma_f32_16x16x32_bf16 v[0:3], v[206:209], v[238:241], v[0:3]
	s_setprio 0
	s_barrier
	s_add_u32 s38, s38, 0x100
	s_addc_u32 s39, s39, 0
	s_add_u32 s47, s47, 0x100
	s_addc_u32 s67, s67, 0
	s_cmp_ge_i32 s68, s4
	s_mov_b32 s52, s68
	s_cbranch_scc0 .LBB0_197

; #define PG8_STAGE(bufoff, gbase, voff) do { _Pragma("unroll") for (int _i = 0; _i < 2; ++_i) \
;         __builtin_amdgcn_global_load_lds((const unsigned*)((const char*)(gbase) + (voff)[_i]), (LAS unsigned*)(lds + (bufoff) + ldsw + _i * 8192), 16, 0, 0); } while (0)
; #define PG8_LDA(dst, b, h) do { _Pragma("unroll") for (int m = 0; m < 4; ++m) _Pragma("unroll") for (int k = 0; k < 2; ++k) dst[m][k] = *(const LAS bf16x8*)(lds + PG8_SA(b, h) + aoff + m * 2048 + k * 1024); } while (0)
; #define PG8_LDB(dst, b, h) do { _Pragma("unroll") for (int n = 0; n < 2; ++n) _Pragma("unroll") for (int k = 0; k < 2; ++k) dst[n][k] = *(const LAS bf16x8*)(lds + PG8_SB(b, h) + boff + n * 2048 + k * 1024); } while (0)
; #define PG8_MMA(ai, bj, At, Bt) do { __builtin_amdgcn_s_setprio(1); _Pragma("unroll") for (int m = 0; m < 4; ++m) _Pragma("unroll") for (int n = 0; n < 2; ++n) _Pragma("unroll") for (int k = 0; k < 2; ++k) \
;         acc[ai][bj][m][n] = __builtin_amdgcn_mfma_f32_16x16x32_bf16(Bt[n][k], At[m][k], acc[ai][bj][m][n], 0, 0, 0); __builtin_amdgcn_s_setprio(0); } while (0)
; #define PG8_WAIT_V(n) asm volatile("s_waitcnt vmcnt(" #n ")" ::: "memory")
; template <class Epi, class Sched>
; __device__ __forceinline__ void gemm_phase(const int tid, LAS unsigned char* lds, const int lda, const int ldb, const int K, const Sched& S, const Epi& E) {
;     ...
;         const bool has_next = S.next(ui + 1, nxt);
;         const char* nA = has_next ? nxt.a : cA; const char* nB = has_next ? nxt.b : cB;
;         for (int t = 0; t < nt; t += 2) {
;             const bool last = (t == nt - 2);
;             const char* a1 = cA + (size_t)(t + 1) * kstep;
;             const char* a2 = last ? nA : cA + (size_t)(t + 2) * kstep; const char* b2 = last ? nB : cB + (size_t)(t + 2) * kstep;
;             const char* a3 = a2 + kstep; const char* b3 = b2 + kstep;
;             PG8_LDB(B0, 0, 0); PG8_LDB(B1, 0, 1); PG8_SCHED; PG8_LDA(At, 0, 0); PG8_STAGE(PG8_SA(1, 1), a1 + hstepA, voffA);
;             PG8_WAIT_V(8); PG8_WAIT_L(0); PG8_BAR; PG8_MMA(0, 0, At, B0); PG8_MMA(0, 1, At, B1); PG8_BAR; PG8_SCHED;
;             PG8_LDA(At, 0, 1); PG8_STAGE(PG8_SB(0, 0), b2, voffB); PG8_STAGE(PG8_SB(0, 1), b2 + hstepB, voffB); PG8_STAGE(PG8_SA(0, 0), a2, voffA);
;             PG8_WAIT_V(8); PG8_WAIT_L(0); PG8_BAR; if (!cur.half) { PG8_MMA(1, 0, At, B0); PG8_MMA(1, 1, At, B1); } PG8_BAR; PG8_SCHED;
.LBB0_213:
	s_andn2_b64 vcc, exec, s[40:41]
	s_cbranch_vccnz .LBB0_221
	s_add_u32 s54, s54, 0x40080
	s_addc_u32 s55, s55, 0
	s_add_u32 s23, s56, 0x100
	v_mov_b64_e32 v[204:205], 0xff
	v_mov_b64_e32 v[174:175], 0x100
	v_mov_b64_e32 v[172:173], 0x1ff
	v_mov_b64_e32 v[178:179], 0x200
	s_addc_u32 s27, s57, 0
	s_mov_b32 s45, 0
	s_add_i32 s69, s45, 2
	s_add_u32 s14, s54, 0xfffc0080
	s_addc_u32 s15, s55, -1
	s_add_i32 s24, 0, 0x10000
	s_cmp_eq_u32 s68, s45
	s_cselect_b32 s59, s53, s15
	s_cselect_b32 s58, s52, s14
	v_add_u32_e32 v176, s24, v151
	s_cselect_b32 s57, s3, s27
	s_cselect_b32 s56, s2, s23
	s_add_i32 s14, 0, 0x14000
	ds_read_b128 v[140:143], v176
	ds_read_b128 v[144:147], v176 offset:1024
	ds_read_b128 v[180:183], v176 offset:2048
	ds_read_b128 v[184:187], v176 offset:3072
	v_add_u32_e32 v176, s14, v151
	ds_read_b128 v[190:193], v176
	ds_read_b128 v[194:197], v176 offset:1024
	ds_read_b128 v[206:209], v176 offset:2048
	ds_read_b128 v[210:213], v176 offset:3072
	v_lshl_add_u64 v[246:247], s[54:55], 0, v[136:137]
	s_add_i32 m0, s51, 0xc000
	ds_read_b128 v[214:217], v166
	ds_read_b128 v[218:221], v166 offset:1024
	ds_read_b128 v[222:225], v166 offset:2048
	ds_read_b128 v[226:229], v166 offset:3072
	ds_read_b128 v[230:233], v166 offset:4096
	ds_read_b128 v[234:237], v166 offset:5120
	ds_read_b128 v[238:241], v166 offset:6144
	ds_read_b128 v[242:245], v166 offset:7168
	global_load_lds_dwordx4 v[246:247], off
	v_lshl_add_u64 v[246:247], s[54:55], 0, v[138:139]
	s_add_i32 m0, s51, 0xe000
	s_nop 0
	global_load_lds_dwordx4 v[246:247], off
	s_waitcnt vmcnt(8)
	s_waitcnt lgkmcnt(0)
	s_barrier
	s_setprio 1
	v_mfma_f32_16x16x32_bf16 v[124:127], v[140:143], v[214:217], 0
	v_mfma_f32_16x16x32_bf16 v[120:123], v[180:183], v[214:217], 0
	v_mfma_f32_16x16x32_bf16 v[116:119], v[140:143], v[222:225], 0
	v_mfma_f32_16x16x32_bf16 v[112:115], v[180:183], v[222:225], 0
	v_mfma_f32_16x16x32_bf16 v[108:111], v[140:143], v[230:233], 0
	v_mfma_f32_16x16x32_bf16 v[104:107], v[180:183], v[230:233], 0
	v_mfma_f32_16x16x32_bf16 v[100:103], v[140:143], v[238:241], 0
	v_mfma_f32_16x16x32_bf16 v[96:99], v[180:183], v[238:241], 0
	v_mfma_f32_16x16x32_bf16 v[124:127], v[144:147], v[218:221], v[124:127]
	v_mfma_f32_16x16x32_bf16 v[120:123], v[184:187], v[218:221], v[120:123]
	v_mfma_f32_16x16x32_bf16 v[116:119], v[144:147], v[226:229], v[116:119]
	v_mfma_f32_16x16x32_bf16 v[112:115], v[184:187], v[226:229], v[112:115]
	v_mfma_f32_16x16x32_bf16 v[108:111], v[144:147], v[234:237], v[108:111]
	v_mfma_f32_16x16x32_bf16 v[104:107], v[184:187], v[234:237], v[104:107]
	v_mfma_f32_16x16x32_bf16 v[100:103], v[144:147], v[242:245], v[100:103]
	v_mfma_f32_16x16x32_bf16 v[96:99], v[184:187], v[242:245], v[96:99]
	v_mfma_f32_16x16x32_bf16 v[60:63], v[190:193], v[214:217], 0
	v_mfma_f32_16x16x32_bf16 v[56:59], v[206:209], v[214:217], 0
	v_mfma_f32_16x16x32_bf16 v[52:55], v[190:193], v[222:225], 0
	v_mfma_f32_16x16x32_bf16 v[48:51], v[206:209], v[222:225], 0
	v_mfma_f32_16x16x32_bf16 v[44:47], v[190:193], v[230:233], 0
	v_mfma_f32_16x16x32_bf16 v[40:43], v[206:209], v[230:233], 0
	v_mfma_f32_16x16x32_bf16 v[36:39], v[190:193], v[238:241], 0
	v_mfma_f32_16x16x32_bf16 v[32:35], v[206:209], v[238:241], 0
	v_mfma_f32_16x16x32_bf16 v[60:63], v[194:197], v[218:221], v[60:63]
	v_mfma_f32_16x16x32_bf16 v[56:59], v[210:213], v[218:221], v[56:59]
	v_mfma_f32_16x16x32_bf16 v[52:55], v[194:197], v[226:229], v[52:55]
	v_mfma_f32_16x16x32_bf16 v[48:51], v[210:213], v[226:229], v[48:51]
	v_mfma_f32_16x16x32_bf16 v[44:47], v[194:197], v[234:237], v[44:47]
	v_mfma_f32_16x16x32_bf16 v[40:43], v[210:213], v[234:237], v[40:43]
	v_mfma_f32_16x16x32_bf16 v[36:39], v[194:197], v[242:245], v[36:39]
	v_mfma_f32_16x16x32_bf16 v[32:35], v[210:213], v[242:245], v[32:35]
	s_setprio 0
	s_barrier
	s_add_i32 s15, s24, s60
	v_lshl_add_u64 v[246:247], s[56:57], 0, v[132:133]
	s_mov_b32 m0, s15
	ds_read_b128 v[214:217], v166 offset:16384
	ds_read_b128 v[218:221], v166 offset:17408
	ds_read_b128 v[222:225], v166 offset:18432
	ds_read_b128 v[226:229], v166 offset:19456
	ds_read_b128 v[230:233], v166 offset:20480
	ds_read_b128 v[234:237], v166 offset:21504
	ds_read_b128 v[238:241], v166 offset:22528
	ds_read_b128 v[242:245], v166 offset:23552
	global_load_lds_dwordx4 v[246:247], off
	s_add_i32 m0, s15, 0x2000
	s_add_u32 s70, s56, 0x40000
	v_lshl_add_u64 v[248:249], s[56:57], 0, v[128:129]
	s_addc_u32 s71, s57, 0
	s_add_i32 s14, s14, s60
	global_load_lds_dwordx4 v[248:249], off
	v_lshl_add_u64 v[250:251], s[70:71], 0, v[132:133]
	s_mov_b32 m0, s14
	v_lshl_add_u64 v[252:253], s[58:59], 0, v[130:131]
	global_load_lds_dwordx4 v[250:251], off
	v_lshl_add_u64 v[250:251], s[70:71], 0, v[128:129]
	s_add_i32 m0, s14, 0x2000
	s_nop 0
	global_load_lds_dwordx4 v[250:251], off
	v_lshl_add_u64 v[250:251], s[58:59], 0, v[134:135]
	s_mov_b32 m0, s51
	s_nop 0
	global_load_lds_dwordx4 v[250:251], off
	s_mov_b32 m0, s62
	s_nop 0
	global_load_lds_dwordx4 v[252:253], off
	s_waitcnt vmcnt(8)
	s_waitcnt lgkmcnt(0)
	s_barrier
; #define PG8_STAGE(bufoff, gbase, voff) do { _Pragma("unroll") for (int _i = 0; _i < 2; ++_i) \
;         __builtin_amdgcn_global_load_lds((const unsigned*)((const char*)(gbase) + (voff)[_i]), (LAS unsigned*)(lds + (bufoff) + ldsw + _i * 8192), 16, 0, 0); } while (0)
; #define PG8_LDA(dst, b, h) do { _Pragma("unroll") for (int m = 0; m < 4; ++m) _Pragma("unroll") for (int k = 0; k < 2; ++k) dst[m][k] = *(const LAS bf16x8*)(lds + PG8_SA(b, h) + aoff + m * 2048 + k * 1024); } while (0)
; #define PG8_LDB(dst, b, h) do { _Pragma("unroll") for (int n = 0; n < 2; ++n) _Pragma("unroll") for (int k = 0; k < 2; ++k) dst[n][k] = *(const LAS bf16x8*)(lds + PG8_SB(b, h) + boff + n * 2048 + k * 1024); } while (0)
; #define PG8_MMA(ai, bj, At, Bt) do { __builtin_amdgcn_s_setprio(1); _Pragma("unroll") for (int m = 0; m < 4; ++m) _Pragma("unroll") for (int n = 0; n < 2; ++n) _Pragma("unroll") for (int k = 0; k < 2; ++k) \
;         acc[ai][bj][m][n] = __builtin_amdgcn_mfma_f32_16x16x32_bf16(Bt[n][k], At[m][k], acc[ai][bj][m][n], 0, 0, 0); __builtin_amdgcn_s_setprio(0); } while (0)
; #define PG8_WAIT_V(n) asm volatile("s_waitcnt vmcnt(" #n ")" ::: "memory")
; #define PG8_WAIT_L(n) asm volatile("s_waitcnt lgkmcnt(" #n ")" ::: "memory")
; #define PG8_BAR __builtin_amdgcn_s_barrier()
; #define PG8_SCHED __builtin_amdgcn_sched_barrier(0)
; template <class Epi, class Sched>
; __device__ __forceinline__ void gemm_phase(const int tid, LAS unsigned char* lds, const int lda, const int ldb, const int K, const Sched& S, const Epi& E) {
;     ...
;             PG8_WAIT_V(8); PG8_WAIT_L(0); PG8_BAR; if (!cur.half) { PG8_MMA(1, 0, At, B0); PG8_MMA(1, 1, At, B1); } PG8_BAR; PG8_SCHED;
;             PG8_LDB(B0, 1, 0); PG8_LDB(B1, 1, 1); PG8_SCHED; PG8_LDA(At, 1, 0); PG8_STAGE(PG8_SA(0, 1), a2 + hstepA, voffA);
;             PG8_WAIT_V(8); PG8_WAIT_L(0); PG8_BAR; PG8_MMA(0, 0, At, B0); PG8_MMA(0, 1, At, B1); PG8_BAR; PG8_SCHED;
	s_setprio 1
	v_mfma_f32_16x16x32_bf16 v[92:95], v[140:143], v[214:217], 0
	v_mfma_f32_16x16x32_bf16 v[88:91], v[180:183], v[214:217], 0
	v_mfma_f32_16x16x32_bf16 v[84:87], v[140:143], v[222:225], 0
	v_mfma_f32_16x16x32_bf16 v[80:83], v[180:183], v[222:225], 0
	v_mfma_f32_16x16x32_bf16 v[76:79], v[140:143], v[230:233], 0
	v_mfma_f32_16x16x32_bf16 v[72:75], v[180:183], v[230:233], 0
	v_mfma_f32_16x16x32_bf16 v[68:71], v[140:143], v[238:241], 0
	v_mfma_f32_16x16x32_bf16 v[64:67], v[180:183], v[238:241], 0
	v_mfma_f32_16x16x32_bf16 v[92:95], v[144:147], v[218:221], v[92:95]
	v_mfma_f32_16x16x32_bf16 v[88:91], v[184:187], v[218:221], v[88:91]
	v_mfma_f32_16x16x32_bf16 v[84:87], v[144:147], v[226:229], v[84:87]
	v_mfma_f32_16x16x32_bf16 v[80:83], v[184:187], v[226:229], v[80:83]
	v_mfma_f32_16x16x32_bf16 v[76:79], v[144:147], v[234:237], v[76:79]
	v_mfma_f32_16x16x32_bf16 v[72:75], v[184:187], v[234:237], v[72:75]
	v_mfma_f32_16x16x32_bf16 v[68:71], v[144:147], v[242:245], v[68:71]
	v_mfma_f32_16x16x32_bf16 v[64:67], v[184:187], v[242:245], v[64:67]
	v_mfma_f32_16x16x32_bf16 v[28:31], v[190:193], v[214:217], 0
	v_mfma_f32_16x16x32_bf16 v[24:27], v[206:209], v[214:217], 0
	v_mfma_f32_16x16x32_bf16 v[20:23], v[190:193], v[222:225], 0
	v_mfma_f32_16x16x32_bf16 v[16:19], v[206:209], v[222:225], 0
	v_mfma_f32_16x16x32_bf16 v[12:15], v[190:193], v[230:233], 0
	v_mfma_f32_16x16x32_bf16 v[8:11], v[206:209], v[230:233], 0
	v_mfma_f32_16x16x32_bf16 v[4:7], v[190:193], v[238:241], 0
	v_mfma_f32_16x16x32_bf16 v[0:3], v[206:209], v[238:241], 0
	v_mfma_f32_16x16x32_bf16 v[28:31], v[194:197], v[218:221], v[28:31]
	v_mfma_f32_16x16x32_bf16 v[24:27], v[210:213], v[218:221], v[24:27]
	v_mfma_f32_16x16x32_bf16 v[20:23], v[194:197], v[226:229], v[20:23]
	v_mfma_f32_16x16x32_bf16 v[16:19], v[210:213], v[226:229], v[16:19]
	v_mfma_f32_16x16x32_bf16 v[12:15], v[194:197], v[234:237], v[12:15]
	v_mfma_f32_16x16x32_bf16 v[8:11], v[210:213], v[234:237], v[8:11]
	v_mfma_f32_16x16x32_bf16 v[4:7], v[194:197], v[242:245], v[4:7]
	v_mfma_f32_16x16x32_bf16 v[0:3], v[210:213], v[242:245], v[0:3]
	s_setprio 0
	s_barrier
	s_add_i32 s14, 0, 0x18000
	v_add_u32_e32 v176, s14, v151
	s_add_i32 s15, 0, 0x1c000
	ds_read_b128 v[140:143], v176
	ds_read_b128 v[144:147], v176 offset:1024
	ds_read_b128 v[180:183], v176 offset:2048
	ds_read_b128 v[184:187], v176 offset:3072
	v_add_u32_e32 v176, s15, v151
	ds_read_b128 v[190:193], v176
	ds_read_b128 v[194:197], v176 offset:1024
	ds_read_b128 v[206:209], v176 offset:2048
	ds_read_b128 v[210:213], v176 offset:3072
	s_add_u32 s58, s58, 0x40000
	s_addc_u32 s59, s59, 0
	s_mov_b32 m0, s63
	v_lshl_add_u64 v[176:177], s[58:59], 0, v[134:135]
	ds_read_b128 v[214:217], v166 offset:32768
	ds_read_b128 v[218:221], v166 offset:33792
	ds_read_b128 v[222:225], v166 offset:34816
	ds_read_b128 v[226:229], v166 offset:35840
	ds_read_b128 v[230:233], v166 offset:36864
	ds_read_b128 v[234:237], v166 offset:37888
	ds_read_b128 v[238:241], v166 offset:38912
	ds_read_b128 v[242:245], v166 offset:39936
	global_load_lds_dwordx4 v[176:177], off
	v_lshl_add_u64 v[176:177], s[58:59], 0, v[130:131]
	s_mov_b32 m0, s64
	s_nop 0
	global_load_lds_dwordx4 v[176:177], off
	s_waitcnt vmcnt(8)
	s_waitcnt lgkmcnt(0)
	s_barrier
	s_setprio 1
	v_mfma_f32_16x16x32_bf16 v[124:127], v[140:143], v[214:217], v[124:127]
	v_mfma_f32_16x16x32_bf16 v[120:123], v[180:183], v[214:217], v[120:123]
	v_mfma_f32_16x16x32_bf16 v[116:119], v[140:143], v[222:225], v[116:119]
	v_mfma_f32_16x16x32_bf16 v[112:115], v[180:183], v[222:225], v[112:115]
	v_mfma_f32_16x16x32_bf16 v[108:111], v[140:143], v[230:233], v[108:111]
	v_mfma_f32_16x16x32_bf16 v[104:107], v[180:183], v[230:233], v[104:107]
	v_mfma_f32_16x16x32_bf16 v[100:103], v[140:143], v[238:241], v[100:103]
	v_mfma_f32_16x16x32_bf16 v[96:99], v[180:183], v[238:241], v[96:99]
	v_mfma_f32_16x16x32_bf16 v[124:127], v[144:147], v[218:221], v[124:127]
	v_mfma_f32_16x16x32_bf16 v[120:123], v[184:187], v[218:221], v[120:123]
	v_mfma_f32_16x16x32_bf16 v[116:119], v[144:147], v[226:229], v[116:119]
	v_mfma_f32_16x16x32_bf16 v[112:115], v[184:187], v[226:229], v[112:115]
	v_mfma_f32_16x16x32_bf16 v[108:111], v[144:147], v[234:237], v[108:111]
	v_mfma_f32_16x16x32_bf16 v[104:107], v[184:187], v[234:237], v[104:107]
	v_mfma_f32_16x16x32_bf16 v[100:103], v[144:147], v[242:245], v[100:103]
	v_mfma_f32_16x16x32_bf16 v[96:99], v[184:187], v[242:245], v[96:99]
	v_mfma_f32_16x16x32_bf16 v[60:63], v[190:193], v[214:217], v[60:63]
	v_mfma_f32_16x16x32_bf16 v[56:59], v[206:209], v[214:217], v[56:59]
	v_mfma_f32_16x16x32_bf16 v[52:55], v[190:193], v[222:225], v[52:55]
	v_mfma_f32_16x16x32_bf16 v[48:51], v[206:209], v[222:225], v[48:51]
	v_mfma_f32_16x16x32_bf16 v[44:47], v[190:193], v[230:233], v[44:47]
	v_mfma_f32_16x16x32_bf16 v[40:43], v[206:209], v[230:233], v[40:43]
	v_mfma_f32_16x16x32_bf16 v[36:39], v[190:193], v[238:241], v[36:39]
	v_mfma_f32_16x16x32_bf16 v[32:35], v[206:209], v[238:241], v[32:35]
	v_mfma_f32_16x16x32_bf16 v[60:63], v[194:197], v[218:221], v[60:63]
	v_mfma_f32_16x16x32_bf16 v[56:59], v[210:213], v[218:221], v[56:59]
	v_mfma_f32_16x16x32_bf16 v[52:55], v[194:197], v[226:229], v[52:55]
	v_mfma_f32_16x16x32_bf16 v[48:51], v[210:213], v[226:229], v[48:51]
	v_mfma_f32_16x16x32_bf16 v[44:47], v[194:197], v[234:237], v[44:47]
	v_mfma_f32_16x16x32_bf16 v[40:43], v[210:213], v[234:237], v[40:43]
	v_mfma_f32_16x16x32_bf16 v[36:39], v[194:197], v[242:245], v[36:39]
	v_mfma_f32_16x16x32_bf16 v[32:35], v[210:213], v[242:245], v[32:35]
	s_setprio 0
	s_barrier
; #define PG8_STAGE(bufoff, gbase, voff) do { _Pragma("unroll") for (int _i = 0; _i < 2; ++_i) \
;         __builtin_amdgcn_global_load_lds((const unsigned*)((const char*)(gbase) + (voff)[_i]), (LAS unsigned*)(lds + (bufoff) + ldsw + _i * 8192), 16, 0, 0); } while (0)
; #define PG8_LDA(dst, b, h) do { _Pragma("unroll") for (int m = 0; m < 4; ++m) _Pragma("unroll") for (int k = 0; k < 2; ++k) dst[m][k] = *(const LAS bf16x8*)(lds + PG8_SA(b, h) + aoff + m * 2048 + k * 1024); } while (0)
; #define PG8_LDB(dst, b, h) do { _Pragma("unroll") for (int n = 0; n < 2; ++n) _Pragma("unroll") for (int k = 0; k < 2; ++k) dst[n][k] = *(const LAS bf16x8*)(lds + PG8_SB(b, h) + boff + n * 2048 + k * 1024); } while (0)
; #define PG8_WAIT_V(n) asm volatile("s_waitcnt vmcnt(" #n ")" ::: "memory")
; template <class Epi, class Sched>
; __device__ __forceinline__ void gemm_phase(const int tid, LAS unsigned char* lds, const int lda, const int ldb, const int K, const Sched& S, const Epi& E) {
;     ...
;             const bool last = (t == nt - 2);
;             const char* a1 = cA + (size_t)(t + 1) * kstep;
;             const char* a2 = last ? nA : cA + (size_t)(t + 2) * kstep; const char* b2 = last ? nB : cB + (size_t)(t + 2) * kstep;
;             const char* a3 = a2 + kstep; const char* b3 = b2 + kstep;
;             PG8_LDB(B0, 0, 0); PG8_LDB(B1, 0, 1); PG8_SCHED; PG8_LDA(At, 0, 0); PG8_STAGE(PG8_SA(1, 1), a1 + hstepA, voffA);
;             PG8_WAIT_V(8); PG8_WAIT_L(0); PG8_BAR; PG8_MMA(0, 0, At, B0); PG8_MMA(0, 1, At, B1); PG8_BAR; PG8_SCHED;
;             PG8_LDA(At, 0, 1); PG8_STAGE(PG8_SB(0, 0), b2, voffB); PG8_STAGE(PG8_SB(0, 1), b2 + hstepB, voffB); PG8_STAGE(PG8_SA(0, 0), a2, voffA);
;             PG8_WAIT_V(8); PG8_WAIT_L(0); PG8_BAR; if (!cur.half) { PG8_MMA(1, 0, At, B0); PG8_MMA(1, 1, At, B1); } PG8_BAR; PG8_SCHED;
;             PG8_LDB(B0, 1, 0); PG8_LDB(B1, 1, 1); PG8_SCHED; PG8_LDA(At, 1, 0); PG8_STAGE(PG8_SA(0, 1), a2 + hstepA, voffA);
;             PG8_WAIT_V(8); PG8_WAIT_L(0); PG8_BAR; PG8_MMA(0, 0, At, B0); PG8_MMA(0, 1, At, B1); PG8_BAR; PG8_SCHED;
;             PG8_LDA(At, 1, 1); PG8_STAGE(PG8_SB(1, 0), b3, voffB); PG8_STAGE(PG8_SB(1, 1), b3 + hstepB, voffB); PG8_STAGE(PG8_SA(1, 0), a3, voffA);
;             PG8_WAIT_V(8); PG8_WAIT_L(0); PG8_BAR; if (!cur.half) { PG8_MMA(1, 0, At, B0); PG8_MMA(1, 1, At, B1); } PG8_BAR; PG8_SCHED;
	s_add_i32 s14, s14, s60
	v_lshl_add_u64 v[176:177], v[246:247], 0, s[6:7]
	s_mov_b32 m0, s14
	ds_read_b128 v[214:217], v166 offset:49152
	ds_read_b128 v[218:221], v166 offset:50176
	ds_read_b128 v[222:225], v166 offset:51200
	ds_read_b128 v[226:229], v166 offset:52224
	ds_read_b128 v[230:233], v166 offset:53248
	ds_read_b128 v[234:237], v166 offset:54272
	ds_read_b128 v[238:241], v166 offset:55296
	ds_read_b128 v[242:245], v166 offset:56320
	global_load_lds_dwordx4 v[176:177], off
	s_add_i32 m0, s14, 0x2000
	s_add_u32 s56, s56, 0x40080
	v_lshl_add_u64 v[176:177], v[248:249], 0, s[6:7]
	s_addc_u32 s57, s57, 0
	s_add_i32 s14, s15, s60
	global_load_lds_dwordx4 v[176:177], off
	v_lshl_add_u64 v[176:177], s[56:57], 0, v[132:133]
	s_mov_b32 m0, s14
	s_nop 0
	global_load_lds_dwordx4 v[176:177], off
	v_lshl_add_u64 v[176:177], s[56:57], 0, v[128:129]
	s_add_i32 m0, s14, 0x2000
	s_nop 0
	global_load_lds_dwordx4 v[176:177], off
	v_lshl_add_u64 v[176:177], v[250:251], 0, s[6:7]
	s_mov_b32 m0, s65
	s_nop 0
	global_load_lds_dwordx4 v[176:177], off
	v_lshl_add_u64 v[176:177], v[252:253], 0, s[6:7]
	s_mov_b32 m0, s66
	s_nop 0
	global_load_lds_dwordx4 v[176:177], off
	s_waitcnt vmcnt(8)
	s_waitcnt lgkmcnt(0)
	s_barrier
	s_setprio 1
	v_mfma_f32_16x16x32_bf16 v[92:95], v[140:143], v[214:217], v[92:95]
	v_mfma_f32_16x16x32_bf16 v[88:91], v[180:183], v[214:217], v[88:91]
	v_mfma_f32_16x16x32_bf16 v[84:87], v[140:143], v[222:225], v[84:87]
	v_mfma_f32_16x16x32_bf16 v[80:83], v[180:183], v[222:225], v[80:83]
	v_mfma_f32_16x16x32_bf16 v[76:79], v[140:143], v[230:233], v[76:79]
	v_mfma_f32_16x16x32_bf16 v[72:75], v[180:183], v[230:233], v[72:75]
	v_mfma_f32_16x16x32_bf16 v[68:71], v[140:143], v[238:241], v[68:71]
	v_mfma_f32_16x16x32_bf16 v[64:67], v[180:183], v[238:241], v[64:67]
	v_mfma_f32_16x16x32_bf16 v[92:95], v[144:147], v[218:221], v[92:95]
	v_mfma_f32_16x16x32_bf16 v[88:91], v[184:187], v[218:221], v[88:91]
	v_mfma_f32_16x16x32_bf16 v[84:87], v[144:147], v[226:229], v[84:87]
	v_mfma_f32_16x16x32_bf16 v[80:83], v[184:187], v[226:229], v[80:83]
	v_mfma_f32_16x16x32_bf16 v[76:79], v[144:147], v[234:237], v[76:79]
	v_mfma_f32_16x16x32_bf16 v[72:75], v[184:187], v[234:237], v[72:75]
	v_mfma_f32_16x16x32_bf16 v[68:71], v[144:147], v[242:245], v[68:71]
	v_mfma_f32_16x16x32_bf16 v[64:67], v[184:187], v[242:245], v[64:67]
	v_mfma_f32_16x16x32_bf16 v[28:31], v[190:193], v[214:217], v[28:31]
	v_mfma_f32_16x16x32_bf16 v[24:27], v[206:209], v[214:217], v[24:27]
	v_mfma_f32_16x16x32_bf16 v[20:23], v[190:193], v[222:225], v[20:23]
	v_mfma_f32_16x16x32_bf16 v[16:19], v[206:209], v[222:225], v[16:19]
	v_mfma_f32_16x16x32_bf16 v[12:15], v[190:193], v[230:233], v[12:15]
	v_mfma_f32_16x16x32_bf16 v[8:11], v[206:209], v[230:233], v[8:11]
	v_mfma_f32_16x16x32_bf16 v[4:7], v[190:193], v[238:241], v[4:7]
	v_mfma_f32_16x16x32_bf16 v[0:3], v[206:209], v[238:241], v[0:3]
	v_mfma_f32_16x16x32_bf16 v[28:31], v[194:197], v[218:221], v[28:31]
	v_mfma_f32_16x16x32_bf16 v[24:27], v[210:213], v[218:221], v[24:27]
	v_mfma_f32_16x16x32_bf16 v[20:23], v[194:197], v[226:229], v[20:23]
	v_mfma_f32_16x16x32_bf16 v[16:19], v[210:213], v[226:229], v[16:19]
	v_mfma_f32_16x16x32_bf16 v[12:15], v[194:197], v[234:237], v[12:15]
	v_mfma_f32_16x16x32_bf16 v[8:11], v[210:213], v[234:237], v[8:11]
	v_mfma_f32_16x16x32_bf16 v[4:7], v[194:197], v[242:245], v[4:7]
	v_mfma_f32_16x16x32_bf16 v[0:3], v[210:213], v[242:245], v[0:3]
	s_setprio 0
	s_barrier
	s_add_u32 s54, s54, 0x100
	s_addc_u32 s55, s55, 0
	s_add_u32 s23, s23, 0x100
	s_addc_u32 s27, s27, 0
	s_cmp_ge_i32 s69, s13
	s_mov_b32 s45, s69
	s_cbranch_scc1 .Lkexit_215
.LBB0_215:
	s_add_i32 s69, s45, 2
	s_add_u32 s14, s54, 0xfffc0080
	s_addc_u32 s15, s55, -1
	s_add_i32 s24, 0, 0x10000
	s_cmp_eq_u32 s68, s45
	s_cselect_b32 s59, s53, s15
	s_cselect_b32 s58, s52, s14
	v_add_u32_e32 v176, s24, v151
	s_cselect_b32 s57, s3, s27
	s_cselect_b32 s56, s2, s23
	s_add_i32 s14, 0, 0x14000
	ds_read_b128 v[140:143], v176
	ds_read_b128 v[144:147], v176 offset:1024
	ds_read_b128 v[180:183], v176 offset:2048
	ds_read_b128 v[184:187], v176 offset:3072
	v_add_u32_e32 v176, s14, v151
	ds_read_b128 v[190:193], v176
	ds_read_b128 v[194:197], v176 offset:1024
	ds_read_b128 v[206:209], v176 offset:2048
	ds_read_b128 v[210:213], v176 offset:3072
	v_lshl_add_u64 v[246:247], s[54:55], 0, v[136:137]
	s_add_i32 m0, s51, 0xc000
	ds_read_b128 v[214:217], v166
	ds_read_b128 v[218:221], v166 offset:1024
	ds_read_b128 v[222:225], v166 offset:2048
	ds_read_b128 v[226:229], v166 offset:3072
	ds_read_b128 v[230:233], v166 offset:4096
	ds_read_b128 v[234:237], v166 offset:5120
	ds_read_b128 v[238:241], v166 offset:6144
	ds_read_b128 v[242:245], v166 offset:7168
	global_load_lds_dwordx4 v[246:247], off
	v_lshl_add_u64 v[246:247], s[54:55], 0, v[138:139]
	s_add_i32 m0, s51, 0xe000
	s_nop 0
	global_load_lds_dwordx4 v[246:247], off
	s_waitcnt vmcnt(8)
	s_waitcnt lgkmcnt(0)
	s_barrier
; #define PG8_STAGE(bufoff, gbase, voff) do { _Pragma("unroll") for (int _i = 0; _i < 2; ++_i) \
;         __builtin_amdgcn_global_load_lds((const unsigned*)((const char*)(gbase) + (voff)[_i]), (LAS unsigned*)(lds + (bufoff) + ldsw + _i * 8192), 16, 0, 0); } while (0)
; #define PG8_LDA(dst, b, h) do { _Pragma("unroll") for (int m = 0; m < 4; ++m) _Pragma("unroll") for (int k = 0; k < 2; ++k) dst[m][k] = *(const LAS bf16x8*)(lds + PG8_SA(b, h) + aoff + m * 2048 + k * 1024); } while (0)
; #define PG8_LDB(dst, b, h) do { _Pragma("unroll") for (int n = 0; n < 2; ++n) _Pragma("unroll") for (int k = 0; k < 2; ++k) dst[n][k] = *(const LAS bf16x8*)(lds + PG8_SB(b, h) + boff + n * 2048 + k * 1024); } while (0)
; #define PG8_MMA(ai, bj, At, Bt) do { __builtin_amdgcn_s_setprio(1); _Pragma("unroll") for (int m = 0; m < 4; ++m) _Pragma("unroll") for (int n = 0; n < 2; ++n) _Pragma("unroll") for (int k = 0; k < 2; ++k) \
;         acc[ai][bj][m][n] = __builtin_amdgcn_mfma_f32_16x16x32_bf16(Bt[n][k], At[m][k], acc[ai][bj][m][n], 0, 0, 0); __builtin_amdgcn_s_setprio(0); } while (0)
; #define PG8_WAIT_V(n) asm volatile("s_waitcnt vmcnt(" #n ")" ::: "memory")
; #define PG8_WAIT_L(n) asm volatile("s_waitcnt lgkmcnt(" #n ")" ::: "memory")
; #define PG8_BAR __builtin_amdgcn_s_barrier()
; #define PG8_SCHED __builtin_amdgcn_sched_barrier(0)
; template <class Epi, class Sched>
; __device__ __forceinline__ void gemm_phase(const int tid, LAS unsigned char* lds, const int lda, const int ldb, const int K, const Sched& S, const Epi& E) {
;     ...
;             PG8_WAIT_V(8); PG8_WAIT_L(0); PG8_BAR; PG8_MMA(0, 0, At, B0); PG8_MMA(0, 1, At, B1); PG8_BAR; PG8_SCHED;
;             PG8_LDA(At, 0, 1); PG8_STAGE(PG8_SB(0, 0), b2, voffB); PG8_STAGE(PG8_SB(0, 1), b2 + hstepB, voffB); PG8_STAGE(PG8_SA(0, 0), a2, voffA);
;             PG8_WAIT_V(8); PG8_WAIT_L(0); PG8_BAR; if (!cur.half) { PG8_MMA(1, 0, At, B0); PG8_MMA(1, 1, At, B1); } PG8_BAR; PG8_SCHED;
;             PG8_LDB(B0, 1, 0); PG8_LDB(B1, 1, 1); PG8_SCHED; PG8_LDA(At, 1, 0); PG8_STAGE(PG8_SA(0, 1), a2 + hstepA, voffA);
;             PG8_WAIT_V(8); PG8_WAIT_L(0); PG8_BAR; PG8_MMA(0, 0, At, B0); PG8_MMA(0, 1, At, B1); PG8_BAR; PG8_SCHED;
	s_setprio 1
	v_mfma_f32_16x16x32_bf16 v[124:127], v[140:143], v[214:217], v[124:127]
	v_mfma_f32_16x16x32_bf16 v[120:123], v[180:183], v[214:217], v[120:123]
	v_mfma_f32_16x16x32_bf16 v[116:119], v[140:143], v[222:225], v[116:119]
	v_mfma_f32_16x16x32_bf16 v[112:115], v[180:183], v[222:225], v[112:115]
	v_mfma_f32_16x16x32_bf16 v[108:111], v[140:143], v[230:233], v[108:111]
	v_mfma_f32_16x16x32_bf16 v[104:107], v[180:183], v[230:233], v[104:107]
	v_mfma_f32_16x16x32_bf16 v[100:103], v[140:143], v[238:241], v[100:103]
	v_mfma_f32_16x16x32_bf16 v[96:99], v[180:183], v[238:241], v[96:99]
	v_mfma_f32_16x16x32_bf16 v[124:127], v[144:147], v[218:221], v[124:127]
	v_mfma_f32_16x16x32_bf16 v[120:123], v[184:187], v[218:221], v[120:123]
	v_mfma_f32_16x16x32_bf16 v[116:119], v[144:147], v[226:229], v[116:119]
	v_mfma_f32_16x16x32_bf16 v[112:115], v[184:187], v[226:229], v[112:115]
	v_mfma_f32_16x16x32_bf16 v[108:111], v[144:147], v[234:237], v[108:111]
	v_mfma_f32_16x16x32_bf16 v[104:107], v[184:187], v[234:237], v[104:107]
	v_mfma_f32_16x16x32_bf16 v[100:103], v[144:147], v[242:245], v[100:103]
	v_mfma_f32_16x16x32_bf16 v[96:99], v[184:187], v[242:245], v[96:99]
	v_mfma_f32_16x16x32_bf16 v[60:63], v[190:193], v[214:217], v[60:63]
	v_mfma_f32_16x16x32_bf16 v[56:59], v[206:209], v[214:217], v[56:59]
	v_mfma_f32_16x16x32_bf16 v[52:55], v[190:193], v[222:225], v[52:55]
	v_mfma_f32_16x16x32_bf16 v[48:51], v[206:209], v[222:225], v[48:51]
	v_mfma_f32_16x16x32_bf16 v[44:47], v[190:193], v[230:233], v[44:47]
	v_mfma_f32_16x16x32_bf16 v[40:43], v[206:209], v[230:233], v[40:43]
	v_mfma_f32_16x16x32_bf16 v[36:39], v[190:193], v[238:241], v[36:39]
	v_mfma_f32_16x16x32_bf16 v[32:35], v[206:209], v[238:241], v[32:35]
	v_mfma_f32_16x16x32_bf16 v[60:63], v[194:197], v[218:221], v[60:63]
	v_mfma_f32_16x16x32_bf16 v[56:59], v[210:213], v[218:221], v[56:59]
	v_mfma_f32_16x16x32_bf16 v[52:55], v[194:197], v[226:229], v[52:55]
	v_mfma_f32_16x16x32_bf16 v[48:51], v[210:213], v[226:229], v[48:51]
	v_mfma_f32_16x16x32_bf16 v[44:47], v[194:197], v[234:237], v[44:47]
	v_mfma_f32_16x16x32_bf16 v[40:43], v[210:213], v[234:237], v[40:43]
	v_mfma_f32_16x16x32_bf16 v[36:39], v[194:197], v[242:245], v[36:39]
	v_mfma_f32_16x16x32_bf16 v[32:35], v[210:213], v[242:245], v[32:35]
	s_setprio 0
	s_barrier
	s_add_i32 s15, s24, s60
	v_lshl_add_u64 v[246:247], s[56:57], 0, v[132:133]
	s_mov_b32 m0, s15
	ds_read_b128 v[214:217], v166 offset:16384
	ds_read_b128 v[218:221], v166 offset:17408
	ds_read_b128 v[222:225], v166 offset:18432
	ds_read_b128 v[226:229], v166 offset:19456
	ds_read_b128 v[230:233], v166 offset:20480
	ds_read_b128 v[234:237], v166 offset:21504
	ds_read_b128 v[238:241], v166 offset:22528
	ds_read_b128 v[242:245], v166 offset:23552
	global_load_lds_dwordx4 v[246:247], off
	s_add_i32 m0, s15, 0x2000
	s_add_u32 s70, s56, 0x40000
	v_lshl_add_u64 v[248:249], s[56:57], 0, v[128:129]
	s_addc_u32 s71, s57, 0
	s_add_i32 s14, s14, s60
	global_load_lds_dwordx4 v[248:249], off
	v_lshl_add_u64 v[250:251], s[70:71], 0, v[132:133]
	s_mov_b32 m0, s14
	v_lshl_add_u64 v[252:253], s[58:59], 0, v[130:131]
	global_load_lds_dwordx4 v[250:251], off
	v_lshl_add_u64 v[250:251], s[70:71], 0, v[128:129]
	s_add_i32 m0, s14, 0x2000
	s_nop 0
	global_load_lds_dwordx4 v[250:251], off
	v_lshl_add_u64 v[250:251], s[58:59], 0, v[134:135]
	s_mov_b32 m0, s51
	s_nop 0
	global_load_lds_dwordx4 v[250:251], off
	s_mov_b32 m0, s62
	s_nop 0
	global_load_lds_dwordx4 v[252:253], off
	s_waitcnt vmcnt(8)
	s_waitcnt lgkmcnt(0)
	s_barrier
	s_setprio 1
	v_mfma_f32_16x16x32_bf16 v[92:95], v[140:143], v[214:217], v[92:95]
	v_mfma_f32_16x16x32_bf16 v[88:91], v[180:183], v[214:217], v[88:91]
	v_mfma_f32_16x16x32_bf16 v[84:87], v[140:143], v[222:225], v[84:87]
	v_mfma_f32_16x16x32_bf16 v[80:83], v[180:183], v[222:225], v[80:83]
	v_mfma_f32_16x16x32_bf16 v[76:79], v[140:143], v[230:233], v[76:79]
	v_mfma_f32_16x16x32_bf16 v[72:75], v[180:183], v[230:233], v[72:75]
	v_mfma_f32_16x16x32_bf16 v[68:71], v[140:143], v[238:241], v[68:71]
	v_mfma_f32_16x16x32_bf16 v[64:67], v[180:183], v[238:241], v[64:67]
	v_mfma_f32_16x16x32_bf16 v[92:95], v[144:147], v[218:221], v[92:95]
	v_mfma_f32_16x16x32_bf16 v[88:91], v[184:187], v[218:221], v[88:91]
	v_mfma_f32_16x16x32_bf16 v[84:87], v[144:147], v[226:229], v[84:87]
	v_mfma_f32_16x16x32_bf16 v[80:83], v[184:187], v[226:229], v[80:83]
	v_mfma_f32_16x16x32_bf16 v[76:79], v[144:147], v[234:237], v[76:79]
	v_mfma_f32_16x16x32_bf16 v[72:75], v[184:187], v[234:237], v[72:75]
	v_mfma_f32_16x16x32_bf16 v[68:71], v[144:147], v[242:245], v[68:71]
	v_mfma_f32_16x16x32_bf16 v[64:67], v[184:187], v[242:245], v[64:67]
	v_mfma_f32_16x16x32_bf16 v[28:31], v[190:193], v[214:217], v[28:31]
	v_mfma_f32_16x16x32_bf16 v[24:27], v[206:209], v[214:217], v[24:27]
	v_mfma_f32_16x16x32_bf16 v[20:23], v[190:193], v[222:225], v[20:23]
	v_mfma_f32_16x16x32_bf16 v[16:19], v[206:209], v[222:225], v[16:19]
	v_mfma_f32_16x16x32_bf16 v[12:15], v[190:193], v[230:233], v[12:15]
	v_mfma_f32_16x16x32_bf16 v[8:11], v[206:209], v[230:233], v[8:11]
	v_mfma_f32_16x16x32_bf16 v[4:7], v[190:193], v[238:241], v[4:7]
	v_mfma_f32_16x16x32_bf16 v[0:3], v[206:209], v[238:241], v[0:3]
	v_mfma_f32_16x16x32_bf16 v[28:31], v[194:197], v[218:221], v[28:31]
	v_mfma_f32_16x16x32_bf16 v[24:27], v[210:213], v[218:221], v[24:27]
	v_mfma_f32_16x16x32_bf16 v[20:23], v[194:197], v[226:229], v[20:23]
	v_mfma_f32_16x16x32_bf16 v[16:19], v[210:213], v[226:229], v[16:19]
	v_mfma_f32_16x16x32_bf16 v[12:15], v[194:197], v[234:237], v[12:15]
	v_mfma_f32_16x16x32_bf16 v[8:11], v[210:213], v[234:237], v[8:11]
	v_mfma_f32_16x16x32_bf16 v[4:7], v[194:197], v[242:245], v[4:7]
	v_mfma_f32_16x16x32_bf16 v[0:3], v[210:213], v[242:245], v[0:3]
	s_setprio 0
	s_barrier
; #define PG8_STAGE(bufoff, gbase, voff) do { _Pragma("unroll") for (int _i = 0; _i < 2; ++_i) \
;         __builtin_amdgcn_global_load_lds((const unsigned*)((const char*)(gbase) + (voff)[_i]), (LAS unsigned*)(lds + (bufoff) + ldsw + _i * 8192), 16, 0, 0); } while (0)
; #define PG8_LDA(dst, b, h) do { _Pragma("unroll") for (int m = 0; m < 4; ++m) _Pragma("unroll") for (int k = 0; k < 2; ++k) dst[m][k] = *(const LAS bf16x8*)(lds + PG8_SA(b, h) + aoff + m * 2048 + k * 1024); } while (0)
; #define PG8_LDB(dst, b, h) do { _Pragma("unroll") for (int n = 0; n < 2; ++n) _Pragma("unroll") for (int k = 0; k < 2; ++k) dst[n][k] = *(const LAS bf16x8*)(lds + PG8_SB(b, h) + boff + n * 2048 + k * 1024); } while (0)
; #define PG8_MMA(ai, bj, At, Bt) do { __builtin_amdgcn_s_setprio(1); _Pragma("unroll") for (int m = 0; m < 4; ++m) _Pragma("unroll") for (int n = 0; n < 2; ++n) _Pragma("unroll") for (int k = 0; k < 2; ++k) \
;         acc[ai][bj][m][n] = __builtin_amdgcn_mfma_f32_16x16x32_bf16(Bt[n][k], At[m][k], acc[ai][bj][m][n], 0, 0, 0); __builtin_amdgcn_s_setprio(0); } while (0)
; #define PG8_WAIT_V(n) asm volatile("s_waitcnt vmcnt(" #n ")" ::: "memory")
; #define PG8_WAIT_L(n) asm volatile("s_waitcnt lgkmcnt(" #n ")" ::: "memory")
; #define PG8_BAR __builtin_amdgcn_s_barrier()
; #define PG8_SCHED __builtin_amdgcn_sched_barrier(0)
; template <class Epi, class Sched>
; __device__ __forceinline__ void gemm_phase(const int tid, LAS unsigned char* lds, const int lda, const int ldb, const int K, const Sched& S, const Epi& E) {
;     ...
;             PG8_LDB(B0, 1, 0); PG8_LDB(B1, 1, 1); PG8_SCHED; PG8_LDA(At, 1, 0); PG8_STAGE(PG8_SA(0, 1), a2 + hstepA, voffA);
;             PG8_WAIT_V(8); PG8_WAIT_L(0); PG8_BAR; PG8_MMA(0, 0, At, B0); PG8_MMA(0, 1, At, B1); PG8_BAR; PG8_SCHED;
;             PG8_LDA(At, 1, 1); PG8_STAGE(PG8_SB(1, 0), b3, voffB); PG8_STAGE(PG8_SB(1, 1), b3 + hstepB, voffB); PG8_STAGE(PG8_SA(1, 0), a3, voffA);
;             PG8_WAIT_V(8); PG8_WAIT_L(0); PG8_BAR; if (!cur.half) { PG8_MMA(1, 0, At, B0); PG8_MMA(1, 1, At, B1); } PG8_BAR; PG8_SCHED;
;         }
	s_add_i32 s14, 0, 0x18000
	v_add_u32_e32 v176, s14, v151
	s_add_i32 s15, 0, 0x1c000
	ds_read_b128 v[140:143], v176
	ds_read_b128 v[144:147], v176 offset:1024
	ds_read_b128 v[180:183], v176 offset:2048
	ds_read_b128 v[184:187], v176 offset:3072
	v_add_u32_e32 v176, s15, v151
	ds_read_b128 v[190:193], v176
	ds_read_b128 v[194:197], v176 offset:1024
	ds_read_b128 v[206:209], v176 offset:2048
	ds_read_b128 v[210:213], v176 offset:3072
	s_add_u32 s58, s58, 0x40000
	s_addc_u32 s59, s59, 0
	s_mov_b32 m0, s63
	v_lshl_add_u64 v[176:177], s[58:59], 0, v[134:135]
	ds_read_b128 v[214:217], v166 offset:32768
	ds_read_b128 v[218:221], v166 offset:33792
	ds_read_b128 v[222:225], v166 offset:34816
	ds_read_b128 v[226:229], v166 offset:35840
	ds_read_b128 v[230:233], v166 offset:36864
	ds_read_b128 v[234:237], v166 offset:37888
	ds_read_b128 v[238:241], v166 offset:38912
	ds_read_b128 v[242:245], v166 offset:39936
	global_load_lds_dwordx4 v[176:177], off
	v_lshl_add_u64 v[176:177], s[58:59], 0, v[130:131]
	s_mov_b32 m0, s64
	s_nop 0
	global_load_lds_dwordx4 v[176:177], off
	s_waitcnt vmcnt(8)
	s_waitcnt lgkmcnt(0)
	s_barrier
	s_setprio 1
	v_mfma_f32_16x16x32_bf16 v[124:127], v[140:143], v[214:217], v[124:127]
	v_mfma_f32_16x16x32_bf16 v[120:123], v[180:183], v[214:217], v[120:123]
	v_mfma_f32_16x16x32_bf16 v[116:119], v[140:143], v[222:225], v[116:119]
	v_mfma_f32_16x16x32_bf16 v[112:115], v[180:183], v[222:225], v[112:115]
	v_mfma_f32_16x16x32_bf16 v[108:111], v[140:143], v[230:233], v[108:111]
	v_mfma_f32_16x16x32_bf16 v[104:107], v[180:183], v[230:233], v[104:107]
	v_mfma_f32_16x16x32_bf16 v[100:103], v[140:143], v[238:241], v[100:103]
	v_mfma_f32_16x16x32_bf16 v[96:99], v[180:183], v[238:241], v[96:99]
	v_mfma_f32_16x16x32_bf16 v[124:127], v[144:147], v[218:221], v[124:127]
	v_mfma_f32_16x16x32_bf16 v[120:123], v[184:187], v[218:221], v[120:123]
	v_mfma_f32_16x16x32_bf16 v[116:119], v[144:147], v[226:229], v[116:119]
	v_mfma_f32_16x16x32_bf16 v[112:115], v[184:187], v[226:229], v[112:115]
	v_mfma_f32_16x16x32_bf16 v[108:111], v[144:147], v[234:237], v[108:111]
	v_mfma_f32_16x16x32_bf16 v[104:107], v[184:187], v[234:237], v[104:107]
	v_mfma_f32_16x16x32_bf16 v[100:103], v[144:147], v[242:245], v[100:103]
	v_mfma_f32_16x16x32_bf16 v[96:99], v[184:187], v[242:245], v[96:99]
	v_mfma_f32_16x16x32_bf16 v[60:63], v[190:193], v[214:217], v[60:63]
	v_mfma_f32_16x16x32_bf16 v[56:59], v[206:209], v[214:217], v[56:59]
	v_mfma_f32_16x16x32_bf16 v[52:55], v[190:193], v[222:225], v[52:55]
	v_mfma_f32_16x16x32_bf16 v[48:51], v[206:209], v[222:225], v[48:51]
	v_mfma_f32_16x16x32_bf16 v[44:47], v[190:193], v[230:233], v[44:47]
	v_mfma_f32_16x16x32_bf16 v[40:43], v[206:209], v[230:233], v[40:43]
	v_mfma_f32_16x16x32_bf16 v[36:39], v[190:193], v[238:241], v[36:39]
	v_mfma_f32_16x16x32_bf16 v[32:35], v[206:209], v[238:241], v[32:35]
	v_mfma_f32_16x16x32_bf16 v[60:63], v[194:197], v[218:221], v[60:63]
	v_mfma_f32_16x16x32_bf16 v[56:59], v[210:213], v[218:221], v[56:59]
	v_mfma_f32_16x16x32_bf16 v[52:55], v[194:197], v[226:229], v[52:55]
	v_mfma_f32_16x16x32_bf16 v[48:51], v[210:213], v[226:229], v[48:51]
	v_mfma_f32_16x16x32_bf16 v[44:47], v[194:197], v[234:237], v[44:47]
	v_mfma_f32_16x16x32_bf16 v[40:43], v[210:213], v[234:237], v[40:43]
	v_mfma_f32_16x16x32_bf16 v[36:39], v[194:197], v[242:245], v[36:39]
	v_mfma_f32_16x16x32_bf16 v[32:35], v[210:213], v[242:245], v[32:35]
	s_setprio 0
	s_barrier
	s_add_i32 s14, s14, s60
	v_lshl_add_u64 v[176:177], v[246:247], 0, s[6:7]
	s_mov_b32 m0, s14
	ds_read_b128 v[214:217], v166 offset:49152
	ds_read_b128 v[218:221], v166 offset:50176
	ds_read_b128 v[222:225], v166 offset:51200
	ds_read_b128 v[226:229], v166 offset:52224
	ds_read_b128 v[230:233], v166 offset:53248
	ds_read_b128 v[234:237], v166 offset:54272
	ds_read_b128 v[238:241], v166 offset:55296
	ds_read_b128 v[242:245], v166 offset:56320
	global_load_lds_dwordx4 v[176:177], off
	s_add_i32 m0, s14, 0x2000
	s_add_u32 s56, s56, 0x40080
	v_lshl_add_u64 v[176:177], v[248:249], 0, s[6:7]
	s_addc_u32 s57, s57, 0
	s_add_i32 s14, s15, s60
	global_load_lds_dwordx4 v[176:177], off
	v_lshl_add_u64 v[176:177], s[56:57], 0, v[132:133]
	s_mov_b32 m0, s14
	s_nop 0
	global_load_lds_dwordx4 v[176:177], off
	v_lshl_add_u64 v[176:177], s[56:57], 0, v[128:129]
	s_add_i32 m0, s14, 0x2000
	s_nop 0
	global_load_lds_dwordx4 v[176:177], off
	v_lshl_add_u64 v[176:177], v[250:251], 0, s[6:7]
	s_mov_b32 m0, s65
	s_nop 0
	global_load_lds_dwordx4 v[176:177], off
	v_lshl_add_u64 v[176:177], v[252:253], 0, s[6:7]
	s_mov_b32 m0, s66
	s_nop 0
	global_load_lds_dwordx4 v[176:177], off
	s_waitcnt vmcnt(8)
	s_waitcnt lgkmcnt(0)
	s_barrier
	s_setprio 1
	v_mfma_f32_16x16x32_bf16 v[92:95], v[140:143], v[214:217], v[92:95]
	v_mfma_f32_16x16x32_bf16 v[88:91], v[180:183], v[214:217], v[88:91]
	v_mfma_f32_16x16x32_bf16 v[84:87], v[140:143], v[222:225], v[84:87]
	v_mfma_f32_16x16x32_bf16 v[80:83], v[180:183], v[222:225], v[80:83]
	v_mfma_f32_16x16x32_bf16 v[76:79], v[140:143], v[230:233], v[76:79]
	v_mfma_f32_16x16x32_bf16 v[72:75], v[180:183], v[230:233], v[72:75]
	v_mfma_f32_16x16x32_bf16 v[68:71], v[140:143], v[238:241], v[68:71]
	v_mfma_f32_16x16x32_bf16 v[64:67], v[180:183], v[238:241], v[64:67]
	v_mfma_f32_16x16x32_bf16 v[92:95], v[144:147], v[218:221], v[92:95]
	v_mfma_f32_16x16x32_bf16 v[88:91], v[184:187], v[218:221], v[88:91]
	v_mfma_f32_16x16x32_bf16 v[84:87], v[144:147], v[226:229], v[84:87]
	v_mfma_f32_16x16x32_bf16 v[80:83], v[184:187], v[226:229], v[80:83]
	v_mfma_f32_16x16x32_bf16 v[76:79], v[144:147], v[234:237], v[76:79]
	v_mfma_f32_16x16x32_bf16 v[72:75], v[184:187], v[234:237], v[72:75]
	v_mfma_f32_16x16x32_bf16 v[68:71], v[144:147], v[242:245], v[68:71]
	v_mfma_f32_16x16x32_bf16 v[64:67], v[184:187], v[242:245], v[64:67]
	v_mfma_f32_16x16x32_bf16 v[28:31], v[190:193], v[214:217], v[28:31]
	v_mfma_f32_16x16x32_bf16 v[24:27], v[206:209], v[214:217], v[24:27]
	v_mfma_f32_16x16x32_bf16 v[20:23], v[190:193], v[222:225], v[20:23]
	v_mfma_f32_16x16x32_bf16 v[16:19], v[206:209], v[222:225], v[16:19]
	v_mfma_f32_16x16x32_bf16 v[12:15], v[190:193], v[230:233], v[12:15]
	v_mfma_f32_16x16x32_bf16 v[8:11], v[206:209], v[230:233], v[8:11]
	v_mfma_f32_16x16x32_bf16 v[4:7], v[190:193], v[238:241], v[4:7]
	v_mfma_f32_16x16x32_bf16 v[0:3], v[206:209], v[238:241], v[0:3]
	v_mfma_f32_16x16x32_bf16 v[28:31], v[194:197], v[218:221], v[28:31]
	v_mfma_f32_16x16x32_bf16 v[24:27], v[210:213], v[218:221], v[24:27]
	v_mfma_f32_16x16x32_bf16 v[20:23], v[194:197], v[226:229], v[20:23]
	v_mfma_f32_16x16x32_bf16 v[16:19], v[210:213], v[226:229], v[16:19]
	v_mfma_f32_16x16x32_bf16 v[12:15], v[194:197], v[234:237], v[12:15]
	v_mfma_f32_16x16x32_bf16 v[8:11], v[210:213], v[234:237], v[8:11]
	v_mfma_f32_16x16x32_bf16 v[4:7], v[194:197], v[242:245], v[4:7]
	v_mfma_f32_16x16x32_bf16 v[0:3], v[210:213], v[242:245], v[0:3]
	s_setprio 0
	s_barrier
	s_add_u32 s54, s54, 0x100
	s_addc_u32 s55, s55, 0
	s_add_u32 s23, s23, 0x100
	s_addc_u32 s27, s27, 0
	s_cmp_ge_i32 s69, s13
	s_mov_b32 s45, s69
	s_cbranch_scc0 .LBB0_215

; #define PG8_STAGE(bufoff, gbase, voff) do { _Pragma("unroll") for (int _i = 0; _i < 2; ++_i) \
;         __builtin_amdgcn_global_load_lds((const unsigned*)((const char*)(gbase) + (voff)[_i]), (LAS unsigned*)(lds + (bufoff) + ldsw + _i * 8192), 16, 0, 0); } while (0)
; #define PG8_LDA(dst, b, h) do { _Pragma("unroll") for (int m = 0; m < 4; ++m) _Pragma("unroll") for (int k = 0; k < 2; ++k) dst[m][k] = *(const LAS bf16x8*)(lds + PG8_SA(b, h) + aoff + m * 2048 + k * 1024); } while (0)
; #define PG8_LDB(dst, b, h) do { _Pragma("unroll") for (int n = 0; n < 2; ++n) _Pragma("unroll") for (int k = 0; k < 2; ++k) dst[n][k] = *(const LAS bf16x8*)(lds + PG8_SB(b, h) + boff + n * 2048 + k * 1024); } while (0)
; #define PG8_MMA(ai, bj, At, Bt) do { __builtin_amdgcn_s_setprio(1); _Pragma("unroll") for (int m = 0; m < 4; ++m) _Pragma("unroll") for (int n = 0; n < 2; ++n) _Pragma("unroll") for (int k = 0; k < 2; ++k) \
;         acc[ai][bj][m][n] = __builtin_amdgcn_mfma_f32_16x16x32_bf16(Bt[n][k], At[m][k], acc[ai][bj][m][n], 0, 0, 0); __builtin_amdgcn_s_setprio(0); } while (0)
; #define PG8_WAIT_V(n) asm volatile("s_waitcnt vmcnt(" #n ")" ::: "memory")
; template <class Epi, class Sched>
; __device__ __forceinline__ void gemm_phase(const int tid, LAS unsigned char* lds, const int lda, const int ldb, const int K, const Sched& S, const Epi& E) {
;     ...
;         const bool has_next = S.next(ui + 1, nxt);
;         const char* nA = has_next ? nxt.a : cA; const char* nB = has_next ? nxt.b : cB;
;         for (int t = 0; t < nt; t += 2) {
;             const bool last = (t == nt - 2);
;             const char* a1 = cA + (size_t)(t + 1) * kstep;
;             const char* a2 = last ? nA : cA + (size_t)(t + 2) * kstep; const char* b2 = last ? nB : cB + (size_t)(t + 2) * kstep;
;             const char* a3 = a2 + kstep; const char* b3 = b2 + kstep;
;             PG8_LDB(B0, 0, 0); PG8_LDB(B1, 0, 1); PG8_SCHED; PG8_LDA(At, 0, 0); PG8_STAGE(PG8_SA(1, 1), a1 + hstepA, voffA);
;             PG8_WAIT_V(8); PG8_WAIT_L(0); PG8_BAR; PG8_MMA(0, 0, At, B0); PG8_MMA(0, 1, At, B1); PG8_BAR; PG8_SCHED;
;             PG8_LDA(At, 0, 1); PG8_STAGE(PG8_SB(0, 0), b2, voffB); PG8_STAGE(PG8_SB(0, 1), b2 + hstepB, voffB); PG8_STAGE(PG8_SA(0, 0), a2, voffA);
;             PG8_WAIT_V(8); PG8_WAIT_L(0); PG8_BAR; if (!cur.half) { PG8_MMA(1, 0, At, B0); PG8_MMA(1, 1, At, B1); } PG8_BAR; PG8_SCHED;
.LBB0_309:
	s_andn2_b64 vcc, exec, s[56:57]
	s_cbranch_vccnz .LBB0_312
	s_add_u32 s66, s66, 0x40080
	s_addc_u32 s67, s67, 0
	s_add_u32 s53, s68, 0x100
	s_addc_u32 s61, s69, 0
	s_mov_b32 s68, 0
	s_add_i32 vcc_lo, s68, 2
	s_add_u32 s14, s66, 0xfffc0080
	s_addc_u32 s15, s67, -1
	s_add_i32 s24, 0, 0x10000
	s_cmp_eq_u32 s45, s68
	s_cselect_b32 s71, s3, s15
	s_cselect_b32 s70, s2, s14
	s_cselect_b32 s69, s39, s61
	s_cselect_b32 s68, s38, s53
	s_add_i32 s14, 0, 0x14000
	v_add_u32_e32 v150, s24, v163
	v_add_u32_e32 v176, s14, v163
	ds_read_b128 v[104:107], v150
	ds_read_b128 v[112:115], v150 offset:1024
	ds_read_b128 v[136:139], v150 offset:2048
	ds_read_b128 v[150:153], v150 offset:3072
	ds_read_b128 v[154:157], v176
	ds_read_b128 v[158:161], v176 offset:1024
	ds_read_b128 v[182:185], v176 offset:2048
	ds_read_b128 v[190:193], v176 offset:3072
	v_lshl_add_u64 v[176:177], s[66:67], 0, v[146:147]
	s_add_i32 m0, s72, 0xc000
	ds_read_b128 v[194:197], v180
	ds_read_b128 v[206:209], v180 offset:1024
	ds_read_b128 v[210:213], v180 offset:2048
	ds_read_b128 v[214:217], v180 offset:3072
	ds_read_b128 v[218:221], v180 offset:4096
	ds_read_b128 v[222:225], v180 offset:5120
	ds_read_b128 v[226:229], v180 offset:6144
	ds_read_b128 v[230:233], v180 offset:7168
	global_load_lds_dwordx4 v[176:177], off
	v_lshl_add_u64 v[176:177], s[66:67], 0, v[148:149]
	s_add_i32 m0, s72, 0xe000
	s_nop 0
	global_load_lds_dwordx4 v[176:177], off
	s_waitcnt vmcnt(8)
	s_waitcnt lgkmcnt(0)
	s_barrier
	s_setprio 1
	v_mfma_f32_16x16x32_bf16 v[132:135], v[104:107], v[194:197], 0
	v_mfma_f32_16x16x32_bf16 v[60:63], v[136:139], v[194:197], 0
	v_mfma_f32_16x16x32_bf16 v[124:127], v[104:107], v[210:213], 0
	v_mfma_f32_16x16x32_bf16 v[52:55], v[136:139], v[210:213], 0
	v_mfma_f32_16x16x32_bf16 v[116:119], v[104:107], v[218:221], 0
	v_mfma_f32_16x16x32_bf16 v[44:47], v[136:139], v[218:221], 0
	v_mfma_f32_16x16x32_bf16 v[100:103], v[104:107], v[226:229], 0
	v_mfma_f32_16x16x32_bf16 v[36:39], v[136:139], v[226:229], 0
	v_mfma_f32_16x16x32_bf16 v[132:135], v[112:115], v[206:209], v[132:135]
	v_mfma_f32_16x16x32_bf16 v[60:63], v[150:153], v[206:209], v[60:63]
	v_mfma_f32_16x16x32_bf16 v[124:127], v[112:115], v[214:217], v[124:127]
	v_mfma_f32_16x16x32_bf16 v[52:55], v[150:153], v[214:217], v[52:55]
	v_mfma_f32_16x16x32_bf16 v[116:119], v[112:115], v[222:225], v[116:119]
	v_mfma_f32_16x16x32_bf16 v[44:47], v[150:153], v[222:225], v[44:47]
	v_mfma_f32_16x16x32_bf16 v[100:103], v[112:115], v[230:233], v[100:103]
	v_mfma_f32_16x16x32_bf16 v[36:39], v[150:153], v[230:233], v[36:39]
	v_mfma_f32_16x16x32_bf16 v[128:131], v[154:157], v[194:197], 0
	v_mfma_f32_16x16x32_bf16 v[56:59], v[182:185], v[194:197], 0
	v_mfma_f32_16x16x32_bf16 v[120:123], v[154:157], v[210:213], 0
	v_mfma_f32_16x16x32_bf16 v[48:51], v[182:185], v[210:213], 0
	v_mfma_f32_16x16x32_bf16 v[108:111], v[154:157], v[218:221], 0
	v_mfma_f32_16x16x32_bf16 v[40:43], v[182:185], v[218:221], 0
	v_mfma_f32_16x16x32_bf16 v[96:99], v[154:157], v[226:229], 0
	v_mfma_f32_16x16x32_bf16 v[32:35], v[182:185], v[226:229], 0
	v_mfma_f32_16x16x32_bf16 v[128:131], v[158:161], v[206:209], v[128:131]
	v_mfma_f32_16x16x32_bf16 v[56:59], v[190:193], v[206:209], v[56:59]
	v_mfma_f32_16x16x32_bf16 v[120:123], v[158:161], v[214:217], v[120:123]
	v_mfma_f32_16x16x32_bf16 v[48:51], v[190:193], v[214:217], v[48:51]
	v_mfma_f32_16x16x32_bf16 v[108:111], v[158:161], v[222:225], v[108:111]
	v_mfma_f32_16x16x32_bf16 v[40:43], v[190:193], v[222:225], v[40:43]
	v_mfma_f32_16x16x32_bf16 v[96:99], v[158:161], v[230:233], v[96:99]
	v_mfma_f32_16x16x32_bf16 v[32:35], v[190:193], v[230:233], v[32:35]
	s_setprio 0
	s_barrier
	s_add_i32 s15, s24, s31
	v_lshl_add_u64 v[176:177], s[68:69], 0, v[168:169]
	s_mov_b32 m0, s15
	ds_read_b128 v[194:197], v180 offset:16384
	ds_read_b128 v[206:209], v180 offset:17408
	ds_read_b128 v[210:213], v180 offset:18432
	ds_read_b128 v[214:217], v180 offset:19456
	ds_read_b128 v[218:221], v180 offset:20480
	ds_read_b128 v[222:225], v180 offset:21504
	ds_read_b128 v[226:229], v180 offset:22528
	ds_read_b128 v[230:233], v180 offset:23552
	global_load_lds_dwordx4 v[176:177], off
	s_add_i32 m0, s15, 0x2000
	s_add_u32 s42, s68, 0x10000
	v_lshl_add_u64 v[186:187], s[68:69], 0, v[144:145]
	s_addc_u32 s43, s69, 0
	s_add_i32 s14, s14, s31
	global_load_lds_dwordx4 v[186:187], off
	v_lshl_add_u64 v[234:235], s[42:43], 0, v[168:169]
	s_mov_b32 m0, s14
	v_lshl_add_u64 v[236:237], s[70:71], 0, v[142:143]
	global_load_lds_dwordx4 v[234:235], off
	v_lshl_add_u64 v[234:235], s[42:43], 0, v[144:145]
	s_add_i32 m0, s14, 0x2000
	s_nop 0
	global_load_lds_dwordx4 v[234:235], off
	v_lshl_add_u64 v[234:235], s[70:71], 0, v[140:141]
	s_mov_b32 m0, s72
	s_nop 0
	global_load_lds_dwordx4 v[234:235], off
	s_mov_b32 m0, s73
	s_nop 0
	global_load_lds_dwordx4 v[236:237], off
	s_waitcnt vmcnt(8)
	s_waitcnt lgkmcnt(0)
	s_barrier
; #define PG8_STAGE(bufoff, gbase, voff) do { _Pragma("unroll") for (int _i = 0; _i < 2; ++_i) \
;         __builtin_amdgcn_global_load_lds((const unsigned*)((const char*)(gbase) + (voff)[_i]), (LAS unsigned*)(lds + (bufoff) + ldsw + _i * 8192), 16, 0, 0); } while (0)
; #define PG8_LDA(dst, b, h) do { _Pragma("unroll") for (int m = 0; m < 4; ++m) _Pragma("unroll") for (int k = 0; k < 2; ++k) dst[m][k] = *(const LAS bf16x8*)(lds + PG8_SA(b, h) + aoff + m * 2048 + k * 1024); } while (0)
; #define PG8_LDB(dst, b, h) do { _Pragma("unroll") for (int n = 0; n < 2; ++n) _Pragma("unroll") for (int k = 0; k < 2; ++k) dst[n][k] = *(const LAS bf16x8*)(lds + PG8_SB(b, h) + boff + n * 2048 + k * 1024); } while (0)
; #define PG8_MMA(ai, bj, At, Bt) do { __builtin_amdgcn_s_setprio(1); _Pragma("unroll") for (int m = 0; m < 4; ++m) _Pragma("unroll") for (int n = 0; n < 2; ++n) _Pragma("unroll") for (int k = 0; k < 2; ++k) \
;         acc[ai][bj][m][n] = __builtin_amdgcn_mfma_f32_16x16x32_bf16(Bt[n][k], At[m][k], acc[ai][bj][m][n], 0, 0, 0); __builtin_amdgcn_s_setprio(0); } while (0)
; #define PG8_WAIT_V(n) asm volatile("s_waitcnt vmcnt(" #n ")" ::: "memory")
; #define PG8_WAIT_L(n) asm volatile("s_waitcnt lgkmcnt(" #n ")" ::: "memory")
; #define PG8_BAR __builtin_amdgcn_s_barrier()
; #define PG8_SCHED __builtin_amdgcn_sched_barrier(0)
; template <class Epi, class Sched>
; __device__ __forceinline__ void gemm_phase(const int tid, LAS unsigned char* lds, const int lda, const int ldb, const int K, const Sched& S, const Epi& E) {
;     ...
;             PG8_WAIT_V(8); PG8_WAIT_L(0); PG8_BAR; if (!cur.half) { PG8_MMA(1, 0, At, B0); PG8_MMA(1, 1, At, B1); } PG8_BAR; PG8_SCHED;
;             PG8_LDB(B0, 1, 0); PG8_LDB(B1, 1, 1); PG8_SCHED; PG8_LDA(At, 1, 0); PG8_STAGE(PG8_SA(0, 1), a2 + hstepA, voffA);
;             PG8_WAIT_V(8); PG8_WAIT_L(0); PG8_BAR; PG8_MMA(0, 0, At, B0); PG8_MMA(0, 1, At, B1); PG8_BAR; PG8_SCHED;
	s_setprio 1
	v_mfma_f32_16x16x32_bf16 v[92:95], v[104:107], v[194:197], 0
	v_mfma_f32_16x16x32_bf16 v[28:31], v[136:139], v[194:197], 0
	v_mfma_f32_16x16x32_bf16 v[84:87], v[104:107], v[210:213], 0
	v_mfma_f32_16x16x32_bf16 v[20:23], v[136:139], v[210:213], 0
	v_mfma_f32_16x16x32_bf16 v[76:79], v[104:107], v[218:221], 0
	v_mfma_f32_16x16x32_bf16 v[12:15], v[136:139], v[218:221], 0
	v_mfma_f32_16x16x32_bf16 v[68:71], v[104:107], v[226:229], 0
	v_mfma_f32_16x16x32_bf16 v[4:7], v[136:139], v[226:229], 0
	v_mfma_f32_16x16x32_bf16 v[92:95], v[112:115], v[206:209], v[92:95]
	v_mfma_f32_16x16x32_bf16 v[28:31], v[150:153], v[206:209], v[28:31]
	v_mfma_f32_16x16x32_bf16 v[84:87], v[112:115], v[214:217], v[84:87]
	v_mfma_f32_16x16x32_bf16 v[20:23], v[150:153], v[214:217], v[20:23]
	v_mfma_f32_16x16x32_bf16 v[76:79], v[112:115], v[222:225], v[76:79]
	v_mfma_f32_16x16x32_bf16 v[12:15], v[150:153], v[222:225], v[12:15]
	v_mfma_f32_16x16x32_bf16 v[68:71], v[112:115], v[230:233], v[68:71]
	v_mfma_f32_16x16x32_bf16 v[4:7], v[150:153], v[230:233], v[4:7]
	v_mfma_f32_16x16x32_bf16 v[88:91], v[154:157], v[194:197], 0
	v_mfma_f32_16x16x32_bf16 v[24:27], v[182:185], v[194:197], 0
	v_mfma_f32_16x16x32_bf16 v[80:83], v[154:157], v[210:213], 0
	v_mfma_f32_16x16x32_bf16 v[16:19], v[182:185], v[210:213], 0
	v_mfma_f32_16x16x32_bf16 v[72:75], v[154:157], v[218:221], 0
	v_mfma_f32_16x16x32_bf16 v[8:11], v[182:185], v[218:221], 0
	v_mfma_f32_16x16x32_bf16 v[64:67], v[154:157], v[226:229], 0
	v_mfma_f32_16x16x32_bf16 v[0:3], v[182:185], v[226:229], 0
	v_mfma_f32_16x16x32_bf16 v[88:91], v[158:161], v[206:209], v[88:91]
	v_mfma_f32_16x16x32_bf16 v[24:27], v[190:193], v[206:209], v[24:27]
	v_mfma_f32_16x16x32_bf16 v[80:83], v[158:161], v[214:217], v[80:83]
	v_mfma_f32_16x16x32_bf16 v[16:19], v[190:193], v[214:217], v[16:19]
	v_mfma_f32_16x16x32_bf16 v[72:75], v[158:161], v[222:225], v[72:75]
	v_mfma_f32_16x16x32_bf16 v[8:11], v[190:193], v[222:225], v[8:11]
	v_mfma_f32_16x16x32_bf16 v[64:67], v[158:161], v[230:233], v[64:67]
	v_mfma_f32_16x16x32_bf16 v[0:3], v[190:193], v[230:233], v[0:3]
	s_setprio 0
	s_barrier
	s_add_i32 s14, 0, 0x18000
	s_add_i32 s15, 0, 0x1c000
	v_add_u32_e32 v150, s14, v163
	v_add_u32_e32 v181, s15, v163
	ds_read_b128 v[104:107], v150
	ds_read_b128 v[112:115], v150 offset:1024
	ds_read_b128 v[136:139], v150 offset:2048
	ds_read_b128 v[150:153], v150 offset:3072
	ds_read_b128 v[154:157], v181
	ds_read_b128 v[158:161], v181 offset:1024
	ds_read_b128 v[182:185], v181 offset:2048
	ds_read_b128 v[190:193], v181 offset:3072
	s_add_u32 s42, s70, 0x40000
	s_addc_u32 s43, s71, 0
	s_mov_b32 m0, s74
	v_lshl_add_u64 v[238:239], s[42:43], 0, v[140:141]
	ds_read_b128 v[194:197], v180 offset:32768
	ds_read_b128 v[206:209], v180 offset:33792
	ds_read_b128 v[210:213], v180 offset:34816
	ds_read_b128 v[214:217], v180 offset:35840
	ds_read_b128 v[218:221], v180 offset:36864
	ds_read_b128 v[222:225], v180 offset:37888
	ds_read_b128 v[226:229], v180 offset:38912
	ds_read_b128 v[230:233], v180 offset:39936
	global_load_lds_dwordx4 v[238:239], off
	v_lshl_add_u64 v[238:239], s[42:43], 0, v[142:143]
	s_mov_b32 m0, s75
	s_nop 0
	global_load_lds_dwordx4 v[238:239], off
	s_waitcnt vmcnt(8)
	s_waitcnt lgkmcnt(0)
	s_barrier
	s_setprio 1
	v_mfma_f32_16x16x32_bf16 v[132:135], v[104:107], v[194:197], v[132:135]
	v_mfma_f32_16x16x32_bf16 v[60:63], v[136:139], v[194:197], v[60:63]
	v_mfma_f32_16x16x32_bf16 v[124:127], v[104:107], v[210:213], v[124:127]
	v_mfma_f32_16x16x32_bf16 v[52:55], v[136:139], v[210:213], v[52:55]
	v_mfma_f32_16x16x32_bf16 v[116:119], v[104:107], v[218:221], v[116:119]
	v_mfma_f32_16x16x32_bf16 v[44:47], v[136:139], v[218:221], v[44:47]
	v_mfma_f32_16x16x32_bf16 v[100:103], v[104:107], v[226:229], v[100:103]
	v_mfma_f32_16x16x32_bf16 v[36:39], v[136:139], v[226:229], v[36:39]
	v_mfma_f32_16x16x32_bf16 v[132:135], v[112:115], v[206:209], v[132:135]
	v_mfma_f32_16x16x32_bf16 v[60:63], v[150:153], v[206:209], v[60:63]
	v_mfma_f32_16x16x32_bf16 v[124:127], v[112:115], v[214:217], v[124:127]
	v_mfma_f32_16x16x32_bf16 v[52:55], v[150:153], v[214:217], v[52:55]
	v_mfma_f32_16x16x32_bf16 v[116:119], v[112:115], v[222:225], v[116:119]
	v_mfma_f32_16x16x32_bf16 v[44:47], v[150:153], v[222:225], v[44:47]
	v_mfma_f32_16x16x32_bf16 v[100:103], v[112:115], v[230:233], v[100:103]
	v_mfma_f32_16x16x32_bf16 v[36:39], v[150:153], v[230:233], v[36:39]
	v_mfma_f32_16x16x32_bf16 v[128:131], v[154:157], v[194:197], v[128:131]
	v_mfma_f32_16x16x32_bf16 v[56:59], v[182:185], v[194:197], v[56:59]
	v_mfma_f32_16x16x32_bf16 v[120:123], v[154:157], v[210:213], v[120:123]
	v_mfma_f32_16x16x32_bf16 v[48:51], v[182:185], v[210:213], v[48:51]
	v_mfma_f32_16x16x32_bf16 v[108:111], v[154:157], v[218:221], v[108:111]
	v_mfma_f32_16x16x32_bf16 v[40:43], v[182:185], v[218:221], v[40:43]
	v_mfma_f32_16x16x32_bf16 v[96:99], v[154:157], v[226:229], v[96:99]
	v_mfma_f32_16x16x32_bf16 v[32:35], v[182:185], v[226:229], v[32:35]
	v_mfma_f32_16x16x32_bf16 v[128:131], v[158:161], v[206:209], v[128:131]
	v_mfma_f32_16x16x32_bf16 v[56:59], v[190:193], v[206:209], v[56:59]
	v_mfma_f32_16x16x32_bf16 v[120:123], v[158:161], v[214:217], v[120:123]
	v_mfma_f32_16x16x32_bf16 v[48:51], v[190:193], v[214:217], v[48:51]
	v_mfma_f32_16x16x32_bf16 v[108:111], v[158:161], v[222:225], v[108:111]
	v_mfma_f32_16x16x32_bf16 v[40:43], v[190:193], v[222:225], v[40:43]
	v_mfma_f32_16x16x32_bf16 v[96:99], v[158:161], v[230:233], v[96:99]
	v_mfma_f32_16x16x32_bf16 v[32:35], v[190:193], v[230:233], v[32:35]
	s_setprio 0
	s_barrier
; #define PG8_STAGE(bufoff, gbase, voff) do { _Pragma("unroll") for (int _i = 0; _i < 2; ++_i) \
;         __builtin_amdgcn_global_load_lds((const unsigned*)((const char*)(gbase) + (voff)[_i]), (LAS unsigned*)(lds + (bufoff) + ldsw + _i * 8192), 16, 0, 0); } while (0)
; #define PG8_LDA(dst, b, h) do { _Pragma("unroll") for (int m = 0; m < 4; ++m) _Pragma("unroll") for (int k = 0; k < 2; ++k) dst[m][k] = *(const LAS bf16x8*)(lds + PG8_SA(b, h) + aoff + m * 2048 + k * 1024); } while (0)
; #define PG8_LDB(dst, b, h) do { _Pragma("unroll") for (int n = 0; n < 2; ++n) _Pragma("unroll") for (int k = 0; k < 2; ++k) dst[n][k] = *(const LAS bf16x8*)(lds + PG8_SB(b, h) + boff + n * 2048 + k * 1024); } while (0)
; #define PG8_WAIT_V(n) asm volatile("s_waitcnt vmcnt(" #n ")" ::: "memory")
; template <class Epi, class Sched>
; __device__ __forceinline__ void gemm_phase(const int tid, LAS unsigned char* lds, const int lda, const int ldb, const int K, const Sched& S, const Epi& E) {
;     ...
;             const bool last = (t == nt - 2);
;             const char* a1 = cA + (size_t)(t + 1) * kstep;
;             const char* a2 = last ? nA : cA + (size_t)(t + 2) * kstep; const char* b2 = last ? nB : cB + (size_t)(t + 2) * kstep;
;             const char* a3 = a2 + kstep; const char* b3 = b2 + kstep;
;             PG8_LDB(B0, 0, 0); PG8_LDB(B1, 0, 1); PG8_SCHED; PG8_LDA(At, 0, 0); PG8_STAGE(PG8_SA(1, 1), a1 + hstepA, voffA);
;             PG8_WAIT_V(8); PG8_WAIT_L(0); PG8_BAR; PG8_MMA(0, 0, At, B0); PG8_MMA(0, 1, At, B1); PG8_BAR; PG8_SCHED;
;             PG8_LDA(At, 0, 1); PG8_STAGE(PG8_SB(0, 0), b2, voffB); PG8_STAGE(PG8_SB(0, 1), b2 + hstepB, voffB); PG8_STAGE(PG8_SA(0, 0), a2, voffA);
;             PG8_WAIT_V(8); PG8_WAIT_L(0); PG8_BAR; if (!cur.half) { PG8_MMA(1, 0, At, B0); PG8_MMA(1, 1, At, B1); } PG8_BAR; PG8_SCHED;
;             PG8_LDB(B0, 1, 0); PG8_LDB(B1, 1, 1); PG8_SCHED; PG8_LDA(At, 1, 0); PG8_STAGE(PG8_SA(0, 1), a2 + hstepA, voffA);
;             PG8_WAIT_V(8); PG8_WAIT_L(0); PG8_BAR; PG8_MMA(0, 0, At, B0); PG8_MMA(0, 1, At, B1); PG8_BAR; PG8_SCHED;
;             PG8_LDA(At, 1, 1); PG8_STAGE(PG8_SB(1, 0), b3, voffB); PG8_STAGE(PG8_SB(1, 1), b3 + hstepB, voffB); PG8_STAGE(PG8_SA(1, 0), a3, voffA);
;             PG8_WAIT_V(8); PG8_WAIT_L(0); PG8_BAR; if (!cur.half) { PG8_MMA(1, 0, At, B0); PG8_MMA(1, 1, At, B1); } PG8_BAR; PG8_SCHED;
	s_add_i32 s14, s14, s31
	v_lshl_add_u64 v[176:177], v[176:177], 0, s[6:7]
	s_mov_b32 m0, s14
	ds_read_b128 v[194:197], v180 offset:49152
	ds_read_b128 v[206:209], v180 offset:50176
	ds_read_b128 v[210:213], v180 offset:51200
	ds_read_b128 v[214:217], v180 offset:52224
	ds_read_b128 v[218:221], v180 offset:53248
	ds_read_b128 v[222:225], v180 offset:54272
	ds_read_b128 v[226:229], v180 offset:55296
	ds_read_b128 v[230:233], v180 offset:56320
	global_load_lds_dwordx4 v[176:177], off
	s_add_i32 m0, s14, 0x2000
	s_add_u32 s42, s68, 0x10080
	v_lshl_add_u64 v[176:177], v[186:187], 0, s[6:7]
	s_addc_u32 s43, s69, 0
	s_add_i32 s14, s15, s31
	global_load_lds_dwordx4 v[176:177], off
	v_lshl_add_u64 v[176:177], s[42:43], 0, v[168:169]
	s_mov_b32 m0, s14
	s_nop 0
	global_load_lds_dwordx4 v[176:177], off
	v_lshl_add_u64 v[176:177], s[42:43], 0, v[144:145]
	s_add_i32 m0, s14, 0x2000
	s_nop 0
	global_load_lds_dwordx4 v[176:177], off
	v_lshl_add_u64 v[176:177], v[234:235], 0, s[6:7]
	s_mov_b32 m0, s20
	s_nop 0
	global_load_lds_dwordx4 v[176:177], off
	v_lshl_add_u64 v[176:177], v[236:237], 0, s[6:7]
	s_mov_b32 m0, s13
	s_nop 0
	global_load_lds_dwordx4 v[176:177], off
	s_waitcnt vmcnt(8)
	s_waitcnt lgkmcnt(0)
	s_barrier
	s_setprio 1
	v_mfma_f32_16x16x32_bf16 v[92:95], v[104:107], v[194:197], v[92:95]
	v_mfma_f32_16x16x32_bf16 v[28:31], v[136:139], v[194:197], v[28:31]
	v_mfma_f32_16x16x32_bf16 v[84:87], v[104:107], v[210:213], v[84:87]
	v_mfma_f32_16x16x32_bf16 v[20:23], v[136:139], v[210:213], v[20:23]
	v_mfma_f32_16x16x32_bf16 v[76:79], v[104:107], v[218:221], v[76:79]
	v_mfma_f32_16x16x32_bf16 v[12:15], v[136:139], v[218:221], v[12:15]
	v_mfma_f32_16x16x32_bf16 v[68:71], v[104:107], v[226:229], v[68:71]
	v_mfma_f32_16x16x32_bf16 v[4:7], v[136:139], v[226:229], v[4:7]
	v_mfma_f32_16x16x32_bf16 v[92:95], v[112:115], v[206:209], v[92:95]
	v_mfma_f32_16x16x32_bf16 v[28:31], v[150:153], v[206:209], v[28:31]
	v_mfma_f32_16x16x32_bf16 v[84:87], v[112:115], v[214:217], v[84:87]
	v_mfma_f32_16x16x32_bf16 v[20:23], v[150:153], v[214:217], v[20:23]
	v_mfma_f32_16x16x32_bf16 v[76:79], v[112:115], v[222:225], v[76:79]
	v_mfma_f32_16x16x32_bf16 v[12:15], v[150:153], v[222:225], v[12:15]
	v_mfma_f32_16x16x32_bf16 v[68:71], v[112:115], v[230:233], v[68:71]
	v_mfma_f32_16x16x32_bf16 v[4:7], v[150:153], v[230:233], v[4:7]
	v_mfma_f32_16x16x32_bf16 v[88:91], v[154:157], v[194:197], v[88:91]
	v_mfma_f32_16x16x32_bf16 v[24:27], v[182:185], v[194:197], v[24:27]
	v_mfma_f32_16x16x32_bf16 v[80:83], v[154:157], v[210:213], v[80:83]
	v_mfma_f32_16x16x32_bf16 v[16:19], v[182:185], v[210:213], v[16:19]
	v_mfma_f32_16x16x32_bf16 v[72:75], v[154:157], v[218:221], v[72:75]
	v_mfma_f32_16x16x32_bf16 v[8:11], v[182:185], v[218:221], v[8:11]
	v_mfma_f32_16x16x32_bf16 v[64:67], v[154:157], v[226:229], v[64:67]
	v_mfma_f32_16x16x32_bf16 v[0:3], v[182:185], v[226:229], v[0:3]
	v_mfma_f32_16x16x32_bf16 v[88:91], v[158:161], v[206:209], v[88:91]
	v_mfma_f32_16x16x32_bf16 v[24:27], v[190:193], v[206:209], v[24:27]
	v_mfma_f32_16x16x32_bf16 v[80:83], v[158:161], v[214:217], v[80:83]
	v_mfma_f32_16x16x32_bf16 v[16:19], v[190:193], v[214:217], v[16:19]
	v_mfma_f32_16x16x32_bf16 v[72:75], v[158:161], v[222:225], v[72:75]
	v_mfma_f32_16x16x32_bf16 v[8:11], v[190:193], v[222:225], v[8:11]
	v_mfma_f32_16x16x32_bf16 v[64:67], v[158:161], v[230:233], v[64:67]
	v_mfma_f32_16x16x32_bf16 v[0:3], v[190:193], v[230:233], v[0:3]
	s_setprio 0
	s_barrier
	s_add_u32 s66, s66, 0x100
	s_addc_u32 s67, s67, 0
	s_add_u32 s53, s53, 0x100
	s_addc_u32 s61, s61, 0
	s_cmp_ge_i32 vcc_lo, s29
	s_mov_b32 s68, vcc_lo
	s_cbranch_scc1 .Lkexit_311
.LBB0_311:
	s_add_i32 vcc_lo, s68, 2
	s_add_u32 s14, s66, 0xfffc0080
	s_addc_u32 s15, s67, -1
	s_add_i32 s24, 0, 0x10000
	s_cmp_eq_u32 s45, s68
	s_cselect_b32 s71, s3, s15
	s_cselect_b32 s70, s2, s14
	s_cselect_b32 s69, s39, s61
	s_cselect_b32 s68, s38, s53
	s_add_i32 s14, 0, 0x14000
	v_add_u32_e32 v150, s24, v163
	v_add_u32_e32 v176, s14, v163
	ds_read_b128 v[104:107], v150
	ds_read_b128 v[112:115], v150 offset:1024
	ds_read_b128 v[136:139], v150 offset:2048
	ds_read_b128 v[150:153], v150 offset:3072
	ds_read_b128 v[154:157], v176
	ds_read_b128 v[158:161], v176 offset:1024
	ds_read_b128 v[182:185], v176 offset:2048
	ds_read_b128 v[190:193], v176 offset:3072
	v_lshl_add_u64 v[176:177], s[66:67], 0, v[146:147]
	s_add_i32 m0, s72, 0xc000
	ds_read_b128 v[194:197], v180
	ds_read_b128 v[206:209], v180 offset:1024
	ds_read_b128 v[210:213], v180 offset:2048
	ds_read_b128 v[214:217], v180 offset:3072
	ds_read_b128 v[218:221], v180 offset:4096
	ds_read_b128 v[222:225], v180 offset:5120
	ds_read_b128 v[226:229], v180 offset:6144
	ds_read_b128 v[230:233], v180 offset:7168
	global_load_lds_dwordx4 v[176:177], off
	v_lshl_add_u64 v[176:177], s[66:67], 0, v[148:149]
	s_add_i32 m0, s72, 0xe000
	s_nop 0
	global_load_lds_dwordx4 v[176:177], off
	s_waitcnt vmcnt(8)
	s_waitcnt lgkmcnt(0)
	s_barrier
; #define PG8_STAGE(bufoff, gbase, voff) do { _Pragma("unroll") for (int _i = 0; _i < 2; ++_i) \
;         __builtin_amdgcn_global_load_lds((const unsigned*)((const char*)(gbase) + (voff)[_i]), (LAS unsigned*)(lds + (bufoff) + ldsw + _i * 8192), 16, 0, 0); } while (0)
; #define PG8_LDA(dst, b, h) do { _Pragma("unroll") for (int m = 0; m < 4; ++m) _Pragma("unroll") for (int k = 0; k < 2; ++k) dst[m][k] = *(const LAS bf16x8*)(lds + PG8_SA(b, h) + aoff + m * 2048 + k * 1024); } while (0)
; #define PG8_LDB(dst, b, h) do { _Pragma("unroll") for (int n = 0; n < 2; ++n) _Pragma("unroll") for (int k = 0; k < 2; ++k) dst[n][k] = *(const LAS bf16x8*)(lds + PG8_SB(b, h) + boff + n * 2048 + k * 1024); } while (0)
; #define PG8_MMA(ai, bj, At, Bt) do { __builtin_amdgcn_s_setprio(1); _Pragma("unroll") for (int m = 0; m < 4; ++m) _Pragma("unroll") for (int n = 0; n < 2; ++n) _Pragma("unroll") for (int k = 0; k < 2; ++k) \
;         acc[ai][bj][m][n] = __builtin_amdgcn_mfma_f32_16x16x32_bf16(Bt[n][k], At[m][k], acc[ai][bj][m][n], 0, 0, 0); __builtin_amdgcn_s_setprio(0); } while (0)
; #define PG8_WAIT_V(n) asm volatile("s_waitcnt vmcnt(" #n ")" ::: "memory")
; #define PG8_WAIT_L(n) asm volatile("s_waitcnt lgkmcnt(" #n ")" ::: "memory")
; #define PG8_BAR __builtin_amdgcn_s_barrier()
; #define PG8_SCHED __builtin_amdgcn_sched_barrier(0)
; template <class Epi, class Sched>
; __device__ __forceinline__ void gemm_phase(const int tid, LAS unsigned char* lds, const int lda, const int ldb, const int K, const Sched& S, const Epi& E) {
;     ...
;             PG8_WAIT_V(8); PG8_WAIT_L(0); PG8_BAR; PG8_MMA(0, 0, At, B0); PG8_MMA(0, 1, At, B1); PG8_BAR; PG8_SCHED;
;             PG8_LDA(At, 0, 1); PG8_STAGE(PG8_SB(0, 0), b2, voffB); PG8_STAGE(PG8_SB(0, 1), b2 + hstepB, voffB); PG8_STAGE(PG8_SA(0, 0), a2, voffA);
;             PG8_WAIT_V(8); PG8_WAIT_L(0); PG8_BAR; if (!cur.half) { PG8_MMA(1, 0, At, B0); PG8_MMA(1, 1, At, B1); } PG8_BAR; PG8_SCHED;
;             PG8_LDB(B0, 1, 0); PG8_LDB(B1, 1, 1); PG8_SCHED; PG8_LDA(At, 1, 0); PG8_STAGE(PG8_SA(0, 1), a2 + hstepA, voffA);
;             PG8_WAIT_V(8); PG8_WAIT_L(0); PG8_BAR; PG8_MMA(0, 0, At, B0); PG8_MMA(0, 1, At, B1); PG8_BAR; PG8_SCHED;
	s_setprio 1
	v_mfma_f32_16x16x32_bf16 v[132:135], v[104:107], v[194:197], v[132:135]
	v_mfma_f32_16x16x32_bf16 v[60:63], v[136:139], v[194:197], v[60:63]
	v_mfma_f32_16x16x32_bf16 v[124:127], v[104:107], v[210:213], v[124:127]
	v_mfma_f32_16x16x32_bf16 v[52:55], v[136:139], v[210:213], v[52:55]
	v_mfma_f32_16x16x32_bf16 v[116:119], v[104:107], v[218:221], v[116:119]
	v_mfma_f32_16x16x32_bf16 v[44:47], v[136:139], v[218:221], v[44:47]
	v_mfma_f32_16x16x32_bf16 v[100:103], v[104:107], v[226:229], v[100:103]
	v_mfma_f32_16x16x32_bf16 v[36:39], v[136:139], v[226:229], v[36:39]
	v_mfma_f32_16x16x32_bf16 v[132:135], v[112:115], v[206:209], v[132:135]
	v_mfma_f32_16x16x32_bf16 v[60:63], v[150:153], v[206:209], v[60:63]
	v_mfma_f32_16x16x32_bf16 v[124:127], v[112:115], v[214:217], v[124:127]
	v_mfma_f32_16x16x32_bf16 v[52:55], v[150:153], v[214:217], v[52:55]
	v_mfma_f32_16x16x32_bf16 v[116:119], v[112:115], v[222:225], v[116:119]
	v_mfma_f32_16x16x32_bf16 v[44:47], v[150:153], v[222:225], v[44:47]
	v_mfma_f32_16x16x32_bf16 v[100:103], v[112:115], v[230:233], v[100:103]
	v_mfma_f32_16x16x32_bf16 v[36:39], v[150:153], v[230:233], v[36:39]
	v_mfma_f32_16x16x32_bf16 v[128:131], v[154:157], v[194:197], v[128:131]
	v_mfma_f32_16x16x32_bf16 v[56:59], v[182:185], v[194:197], v[56:59]
	v_mfma_f32_16x16x32_bf16 v[120:123], v[154:157], v[210:213], v[120:123]
	v_mfma_f32_16x16x32_bf16 v[48:51], v[182:185], v[210:213], v[48:51]
	v_mfma_f32_16x16x32_bf16 v[108:111], v[154:157], v[218:221], v[108:111]
	v_mfma_f32_16x16x32_bf16 v[40:43], v[182:185], v[218:221], v[40:43]
	v_mfma_f32_16x16x32_bf16 v[96:99], v[154:157], v[226:229], v[96:99]
	v_mfma_f32_16x16x32_bf16 v[32:35], v[182:185], v[226:229], v[32:35]
	v_mfma_f32_16x16x32_bf16 v[128:131], v[158:161], v[206:209], v[128:131]
	v_mfma_f32_16x16x32_bf16 v[56:59], v[190:193], v[206:209], v[56:59]
	v_mfma_f32_16x16x32_bf16 v[120:123], v[158:161], v[214:217], v[120:123]
	v_mfma_f32_16x16x32_bf16 v[48:51], v[190:193], v[214:217], v[48:51]
	v_mfma_f32_16x16x32_bf16 v[108:111], v[158:161], v[222:225], v[108:111]
	v_mfma_f32_16x16x32_bf16 v[40:43], v[190:193], v[222:225], v[40:43]
	v_mfma_f32_16x16x32_bf16 v[96:99], v[158:161], v[230:233], v[96:99]
	v_mfma_f32_16x16x32_bf16 v[32:35], v[190:193], v[230:233], v[32:35]
	s_setprio 0
	s_barrier
	s_add_i32 s15, s24, s31
	v_lshl_add_u64 v[176:177], s[68:69], 0, v[168:169]
	s_mov_b32 m0, s15
	ds_read_b128 v[194:197], v180 offset:16384
	ds_read_b128 v[206:209], v180 offset:17408
	ds_read_b128 v[210:213], v180 offset:18432
	ds_read_b128 v[214:217], v180 offset:19456
	ds_read_b128 v[218:221], v180 offset:20480
	ds_read_b128 v[222:225], v180 offset:21504
	ds_read_b128 v[226:229], v180 offset:22528
	ds_read_b128 v[230:233], v180 offset:23552
	global_load_lds_dwordx4 v[176:177], off
	s_add_i32 m0, s15, 0x2000
	s_add_u32 s42, s68, 0x10000
	v_lshl_add_u64 v[186:187], s[68:69], 0, v[144:145]
	s_addc_u32 s43, s69, 0
	s_add_i32 s14, s14, s31
	global_load_lds_dwordx4 v[186:187], off
	v_lshl_add_u64 v[234:235], s[42:43], 0, v[168:169]
	s_mov_b32 m0, s14
	v_lshl_add_u64 v[236:237], s[70:71], 0, v[142:143]
	global_load_lds_dwordx4 v[234:235], off
	v_lshl_add_u64 v[234:235], s[42:43], 0, v[144:145]
	s_add_i32 m0, s14, 0x2000
	s_nop 0
	global_load_lds_dwordx4 v[234:235], off
	v_lshl_add_u64 v[234:235], s[70:71], 0, v[140:141]
	s_mov_b32 m0, s72
	s_nop 0
	global_load_lds_dwordx4 v[234:235], off
	s_mov_b32 m0, s73
	s_nop 0
	global_load_lds_dwordx4 v[236:237], off
	s_waitcnt vmcnt(8)
	s_waitcnt lgkmcnt(0)
	s_barrier
	s_setprio 1
	v_mfma_f32_16x16x32_bf16 v[92:95], v[104:107], v[194:197], v[92:95]
	v_mfma_f32_16x16x32_bf16 v[28:31], v[136:139], v[194:197], v[28:31]
	v_mfma_f32_16x16x32_bf16 v[84:87], v[104:107], v[210:213], v[84:87]
	v_mfma_f32_16x16x32_bf16 v[20:23], v[136:139], v[210:213], v[20:23]
	v_mfma_f32_16x16x32_bf16 v[76:79], v[104:107], v[218:221], v[76:79]
	v_mfma_f32_16x16x32_bf16 v[12:15], v[136:139], v[218:221], v[12:15]
	v_mfma_f32_16x16x32_bf16 v[68:71], v[104:107], v[226:229], v[68:71]
	v_mfma_f32_16x16x32_bf16 v[4:7], v[136:139], v[226:229], v[4:7]
	v_mfma_f32_16x16x32_bf16 v[92:95], v[112:115], v[206:209], v[92:95]
	v_mfma_f32_16x16x32_bf16 v[28:31], v[150:153], v[206:209], v[28:31]
	v_mfma_f32_16x16x32_bf16 v[84:87], v[112:115], v[214:217], v[84:87]
	v_mfma_f32_16x16x32_bf16 v[20:23], v[150:153], v[214:217], v[20:23]
	v_mfma_f32_16x16x32_bf16 v[76:79], v[112:115], v[222:225], v[76:79]
	v_mfma_f32_16x16x32_bf16 v[12:15], v[150:153], v[222:225], v[12:15]
	v_mfma_f32_16x16x32_bf16 v[68:71], v[112:115], v[230:233], v[68:71]
	v_mfma_f32_16x16x32_bf16 v[4:7], v[150:153], v[230:233], v[4:7]
	v_mfma_f32_16x16x32_bf16 v[88:91], v[154:157], v[194:197], v[88:91]
	v_mfma_f32_16x16x32_bf16 v[24:27], v[182:185], v[194:197], v[24:27]
	v_mfma_f32_16x16x32_bf16 v[80:83], v[154:157], v[210:213], v[80:83]
	v_mfma_f32_16x16x32_bf16 v[16:19], v[182:185], v[210:213], v[16:19]
	v_mfma_f32_16x16x32_bf16 v[72:75], v[154:157], v[218:221], v[72:75]
	v_mfma_f32_16x16x32_bf16 v[8:11], v[182:185], v[218:221], v[8:11]
	v_mfma_f32_16x16x32_bf16 v[64:67], v[154:157], v[226:229], v[64:67]
	v_mfma_f32_16x16x32_bf16 v[0:3], v[182:185], v[226:229], v[0:3]
	v_mfma_f32_16x16x32_bf16 v[88:91], v[158:161], v[206:209], v[88:91]
	v_mfma_f32_16x16x32_bf16 v[24:27], v[190:193], v[206:209], v[24:27]
	v_mfma_f32_16x16x32_bf16 v[80:83], v[158:161], v[214:217], v[80:83]
	v_mfma_f32_16x16x32_bf16 v[16:19], v[190:193], v[214:217], v[16:19]
	v_mfma_f32_16x16x32_bf16 v[72:75], v[158:161], v[222:225], v[72:75]
	v_mfma_f32_16x16x32_bf16 v[8:11], v[190:193], v[222:225], v[8:11]
	v_mfma_f32_16x16x32_bf16 v[64:67], v[158:161], v[230:233], v[64:67]
	v_mfma_f32_16x16x32_bf16 v[0:3], v[190:193], v[230:233], v[0:3]
	s_setprio 0
	s_barrier
; #define PG8_STAGE(bufoff, gbase, voff) do { _Pragma("unroll") for (int _i = 0; _i < 2; ++_i) \
;         __builtin_amdgcn_global_load_lds((const unsigned*)((const char*)(gbase) + (voff)[_i]), (LAS unsigned*)(lds + (bufoff) + ldsw + _i * 8192), 16, 0, 0); } while (0)
; #define PG8_LDA(dst, b, h) do { _Pragma("unroll") for (int m = 0; m < 4; ++m) _Pragma("unroll") for (int k = 0; k < 2; ++k) dst[m][k] = *(const LAS bf16x8*)(lds + PG8_SA(b, h) + aoff + m * 2048 + k * 1024); } while (0)
; #define PG8_LDB(dst, b, h) do { _Pragma("unroll") for (int n = 0; n < 2; ++n) _Pragma("unroll") for (int k = 0; k < 2; ++k) dst[n][k] = *(const LAS bf16x8*)(lds + PG8_SB(b, h) + boff + n * 2048 + k * 1024); } while (0)
; #define PG8_MMA(ai, bj, At, Bt) do { __builtin_amdgcn_s_setprio(1); _Pragma("unroll") for (int m = 0; m < 4; ++m) _Pragma("unroll") for (int n = 0; n < 2; ++n) _Pragma("unroll") for (int k = 0; k < 2; ++k) \
;         acc[ai][bj][m][n] = __builtin_amdgcn_mfma_f32_16x16x32_bf16(Bt[n][k], At[m][k], acc[ai][bj][m][n], 0, 0, 0); __builtin_amdgcn_s_setprio(0); } while (0)
; #define PG8_WAIT_V(n) asm volatile("s_waitcnt vmcnt(" #n ")" ::: "memory")
; #define PG8_WAIT_L(n) asm volatile("s_waitcnt lgkmcnt(" #n ")" ::: "memory")
; #define PG8_BAR __builtin_amdgcn_s_barrier()
; #define PG8_SCHED __builtin_amdgcn_sched_barrier(0)
; template <class Epi, class Sched>
; __device__ __forceinline__ void gemm_phase(const int tid, LAS unsigned char* lds, const int lda, const int ldb, const int K, const Sched& S, const Epi& E) {
;     ...
;             PG8_LDB(B0, 1, 0); PG8_LDB(B1, 1, 1); PG8_SCHED; PG8_LDA(At, 1, 0); PG8_STAGE(PG8_SA(0, 1), a2 + hstepA, voffA);
;             PG8_WAIT_V(8); PG8_WAIT_L(0); PG8_BAR; PG8_MMA(0, 0, At, B0); PG8_MMA(0, 1, At, B1); PG8_BAR; PG8_SCHED;
	s_add_i32 s14, 0, 0x18000
	s_add_i32 s15, 0, 0x1c000
	v_add_u32_e32 v150, s14, v163
	v_add_u32_e32 v181, s15, v163
	ds_read_b128 v[104:107], v150
	ds_read_b128 v[112:115], v150 offset:1024
	ds_read_b128 v[136:139], v150 offset:2048
	ds_read_b128 v[150:153], v150 offset:3072
	ds_read_b128 v[154:157], v181
	ds_read_b128 v[158:161], v181 offset:1024
	ds_read_b128 v[182:185], v181 offset:2048
	ds_read_b128 v[190:193], v181 offset:3072
	s_add_u32 s42, s70, 0x40000
	s_addc_u32 s43, s71, 0
	s_mov_b32 m0, s74
	v_lshl_add_u64 v[238:239], s[42:43], 0, v[140:141]
	ds_read_b128 v[194:197], v180 offset:32768
	ds_read_b128 v[206:209], v180 offset:33792
	ds_read_b128 v[210:213], v180 offset:34816
	ds_read_b128 v[214:217], v180 offset:35840
	ds_read_b128 v[218:221], v180 offset:36864
	ds_read_b128 v[222:225], v180 offset:37888
	ds_read_b128 v[226:229], v180 offset:38912
	ds_read_b128 v[230:233], v180 offset:39936
	global_load_lds_dwordx4 v[238:239], off
	v_lshl_add_u64 v[238:239], s[42:43], 0, v[142:143]
	s_mov_b32 m0, s75
	s_nop 0
	global_load_lds_dwordx4 v[238:239], off
	s_waitcnt vmcnt(8)
	s_waitcnt lgkmcnt(0)
	s_barrier
	s_setprio 1
	v_mfma_f32_16x16x32_bf16 v[132:135], v[104:107], v[194:197], v[132:135]
	v_mfma_f32_16x16x32_bf16 v[60:63], v[136:139], v[194:197], v[60:63]
	v_mfma_f32_16x16x32_bf16 v[124:127], v[104:107], v[210:213], v[124:127]
	v_mfma_f32_16x16x32_bf16 v[52:55], v[136:139], v[210:213], v[52:55]
	v_mfma_f32_16x16x32_bf16 v[116:119], v[104:107], v[218:221], v[116:119]
	v_mfma_f32_16x16x32_bf16 v[44:47], v[136:139], v[218:221], v[44:47]
	v_mfma_f32_16x16x32_bf16 v[100:103], v[104:107], v[226:229], v[100:103]
	v_mfma_f32_16x16x32_bf16 v[36:39], v[136:139], v[226:229], v[36:39]
	v_mfma_f32_16x16x32_bf16 v[132:135], v[112:115], v[206:209], v[132:135]
	v_mfma_f32_16x16x32_bf16 v[60:63], v[150:153], v[206:209], v[60:63]
	v_mfma_f32_16x16x32_bf16 v[124:127], v[112:115], v[214:217], v[124:127]
	v_mfma_f32_16x16x32_bf16 v[52:55], v[150:153], v[214:217], v[52:55]
	v_mfma_f32_16x16x32_bf16 v[116:119], v[112:115], v[222:225], v[116:119]
	v_mfma_f32_16x16x32_bf16 v[44:47], v[150:153], v[222:225], v[44:47]
	v_mfma_f32_16x16x32_bf16 v[100:103], v[112:115], v[230:233], v[100:103]
	v_mfma_f32_16x16x32_bf16 v[36:39], v[150:153], v[230:233], v[36:39]
	v_mfma_f32_16x16x32_bf16 v[128:131], v[154:157], v[194:197], v[128:131]
	v_mfma_f32_16x16x32_bf16 v[56:59], v[182:185], v[194:197], v[56:59]
	v_mfma_f32_16x16x32_bf16 v[120:123], v[154:157], v[210:213], v[120:123]
	v_mfma_f32_16x16x32_bf16 v[48:51], v[182:185], v[210:213], v[48:51]
	v_mfma_f32_16x16x32_bf16 v[108:111], v[154:157], v[218:221], v[108:111]
	v_mfma_f32_16x16x32_bf16 v[40:43], v[182:185], v[218:221], v[40:43]
	v_mfma_f32_16x16x32_bf16 v[96:99], v[154:157], v[226:229], v[96:99]
	v_mfma_f32_16x16x32_bf16 v[32:35], v[182:185], v[226:229], v[32:35]
	v_mfma_f32_16x16x32_bf16 v[128:131], v[158:161], v[206:209], v[128:131]
	v_mfma_f32_16x16x32_bf16 v[56:59], v[190:193], v[206:209], v[56:59]
	v_mfma_f32_16x16x32_bf16 v[120:123], v[158:161], v[214:217], v[120:123]
	v_mfma_f32_16x16x32_bf16 v[48:51], v[190:193], v[214:217], v[48:51]
	v_mfma_f32_16x16x32_bf16 v[108:111], v[158:161], v[222:225], v[108:111]
	v_mfma_f32_16x16x32_bf16 v[40:43], v[190:193], v[222:225], v[40:43]
	v_mfma_f32_16x16x32_bf16 v[96:99], v[158:161], v[230:233], v[96:99]
	v_mfma_f32_16x16x32_bf16 v[32:35], v[190:193], v[230:233], v[32:35]
	s_setprio 0
	s_barrier
; #define PG8_STAGE(bufoff, gbase, voff) do { _Pragma("unroll") for (int _i = 0; _i < 2; ++_i) \
;         __builtin_amdgcn_global_load_lds((const unsigned*)((const char*)(gbase) + (voff)[_i]), (LAS unsigned*)(lds + (bufoff) + ldsw + _i * 8192), 16, 0, 0); } while (0)
; #define PG8_LDA(dst, b, h) do { _Pragma("unroll") for (int m = 0; m < 4; ++m) _Pragma("unroll") for (int k = 0; k < 2; ++k) dst[m][k] = *(const LAS bf16x8*)(lds + PG8_SA(b, h) + aoff + m * 2048 + k * 1024); } while (0)
; #define PG8_MMA(ai, bj, At, Bt) do { __builtin_amdgcn_s_setprio(1); _Pragma("unroll") for (int m = 0; m < 4; ++m) _Pragma("unroll") for (int n = 0; n < 2; ++n) _Pragma("unroll") for (int k = 0; k < 2; ++k) \
;         acc[ai][bj][m][n] = __builtin_amdgcn_mfma_f32_16x16x32_bf16(Bt[n][k], At[m][k], acc[ai][bj][m][n], 0, 0, 0); __builtin_amdgcn_s_setprio(0); } while (0)
; #define PG8_WAIT_V(n) asm volatile("s_waitcnt vmcnt(" #n ")" ::: "memory")
; #define PG8_WAIT_L(n) asm volatile("s_waitcnt lgkmcnt(" #n ")" ::: "memory")
; #define PG8_BAR __builtin_amdgcn_s_barrier()
; #define PG8_SCHED __builtin_amdgcn_sched_barrier(0)
; template <class Epi, class Sched>
; __device__ __forceinline__ void gemm_phase(const int tid, LAS unsigned char* lds, const int lda, const int ldb, const int K, const Sched& S, const Epi& E) {
;     ...
;             PG8_LDA(At, 1, 1); PG8_STAGE(PG8_SB(1, 0), b3, voffB); PG8_STAGE(PG8_SB(1, 1), b3 + hstepB, voffB); PG8_STAGE(PG8_SA(1, 0), a3, voffA);
;             PG8_WAIT_V(8); PG8_WAIT_L(0); PG8_BAR; if (!cur.half) { PG8_MMA(1, 0, At, B0); PG8_MMA(1, 1, At, B1); } PG8_BAR; PG8_SCHED;
;         }
	s_add_i32 s14, s14, s31
	v_lshl_add_u64 v[176:177], v[176:177], 0, s[6:7]
	s_mov_b32 m0, s14
	ds_read_b128 v[194:197], v180 offset:49152
	ds_read_b128 v[206:209], v180 offset:50176
	ds_read_b128 v[210:213], v180 offset:51200
	ds_read_b128 v[214:217], v180 offset:52224
	ds_read_b128 v[218:221], v180 offset:53248
	ds_read_b128 v[222:225], v180 offset:54272
	ds_read_b128 v[226:229], v180 offset:55296
	ds_read_b128 v[230:233], v180 offset:56320
	global_load_lds_dwordx4 v[176:177], off
	s_add_i32 m0, s14, 0x2000
	s_add_u32 s42, s68, 0x10080
	v_lshl_add_u64 v[176:177], v[186:187], 0, s[6:7]
	s_addc_u32 s43, s69, 0
	s_add_i32 s14, s15, s31
	global_load_lds_dwordx4 v[176:177], off
	v_lshl_add_u64 v[176:177], s[42:43], 0, v[168:169]
	s_mov_b32 m0, s14
	s_nop 0
	global_load_lds_dwordx4 v[176:177], off
	v_lshl_add_u64 v[176:177], s[42:43], 0, v[144:145]
	s_add_i32 m0, s14, 0x2000
	s_nop 0
	global_load_lds_dwordx4 v[176:177], off
	v_lshl_add_u64 v[176:177], v[234:235], 0, s[6:7]
	s_mov_b32 m0, s20
	s_nop 0
	global_load_lds_dwordx4 v[176:177], off
	v_lshl_add_u64 v[176:177], v[236:237], 0, s[6:7]
	s_mov_b32 m0, s13
	s_nop 0
	global_load_lds_dwordx4 v[176:177], off
	s_waitcnt vmcnt(8)
	s_waitcnt lgkmcnt(0)
	s_barrier
	s_setprio 1
	v_mfma_f32_16x16x32_bf16 v[92:95], v[104:107], v[194:197], v[92:95]
	v_mfma_f32_16x16x32_bf16 v[28:31], v[136:139], v[194:197], v[28:31]
	v_mfma_f32_16x16x32_bf16 v[84:87], v[104:107], v[210:213], v[84:87]
	v_mfma_f32_16x16x32_bf16 v[20:23], v[136:139], v[210:213], v[20:23]
	v_mfma_f32_16x16x32_bf16 v[76:79], v[104:107], v[218:221], v[76:79]
	v_mfma_f32_16x16x32_bf16 v[12:15], v[136:139], v[218:221], v[12:15]
	v_mfma_f32_16x16x32_bf16 v[68:71], v[104:107], v[226:229], v[68:71]
	v_mfma_f32_16x16x32_bf16 v[4:7], v[136:139], v[226:229], v[4:7]
	v_mfma_f32_16x16x32_bf16 v[92:95], v[112:115], v[206:209], v[92:95]
	v_mfma_f32_16x16x32_bf16 v[28:31], v[150:153], v[206:209], v[28:31]
	v_mfma_f32_16x16x32_bf16 v[84:87], v[112:115], v[214:217], v[84:87]
	v_mfma_f32_16x16x32_bf16 v[20:23], v[150:153], v[214:217], v[20:23]
	v_mfma_f32_16x16x32_bf16 v[76:79], v[112:115], v[222:225], v[76:79]
	v_mfma_f32_16x16x32_bf16 v[12:15], v[150:153], v[222:225], v[12:15]
	v_mfma_f32_16x16x32_bf16 v[68:71], v[112:115], v[230:233], v[68:71]
	v_mfma_f32_16x16x32_bf16 v[4:7], v[150:153], v[230:233], v[4:7]
	v_mfma_f32_16x16x32_bf16 v[88:91], v[154:157], v[194:197], v[88:91]
	v_mfma_f32_16x16x32_bf16 v[24:27], v[182:185], v[194:197], v[24:27]
	v_mfma_f32_16x16x32_bf16 v[80:83], v[154:157], v[210:213], v[80:83]
	v_mfma_f32_16x16x32_bf16 v[16:19], v[182:185], v[210:213], v[16:19]
	v_mfma_f32_16x16x32_bf16 v[72:75], v[154:157], v[218:221], v[72:75]
	v_mfma_f32_16x16x32_bf16 v[8:11], v[182:185], v[218:221], v[8:11]
	v_mfma_f32_16x16x32_bf16 v[64:67], v[154:157], v[226:229], v[64:67]
	v_mfma_f32_16x16x32_bf16 v[0:3], v[182:185], v[226:229], v[0:3]
	v_mfma_f32_16x16x32_bf16 v[88:91], v[158:161], v[206:209], v[88:91]
	v_mfma_f32_16x16x32_bf16 v[24:27], v[190:193], v[206:209], v[24:27]
	v_mfma_f32_16x16x32_bf16 v[80:83], v[158:161], v[214:217], v[80:83]
	v_mfma_f32_16x16x32_bf16 v[16:19], v[190:193], v[214:217], v[16:19]
	v_mfma_f32_16x16x32_bf16 v[72:75], v[158:161], v[222:225], v[72:75]
	v_mfma_f32_16x16x32_bf16 v[8:11], v[190:193], v[222:225], v[8:11]
	v_mfma_f32_16x16x32_bf16 v[64:67], v[158:161], v[230:233], v[64:67]
	v_mfma_f32_16x16x32_bf16 v[0:3], v[190:193], v[230:233], v[0:3]
	s_setprio 0
	s_barrier
	s_add_u32 s66, s66, 0x100
	s_addc_u32 s67, s67, 0
	s_add_u32 s53, s53, 0x100
	s_addc_u32 s61, s61, 0
	s_cmp_ge_i32 vcc_lo, s29
	s_mov_b32 s68, vcc_lo
	s_cbranch_scc0 .LBB0_311

; #define PG8_STAGE(bufoff, gbase, voff) do { _Pragma("unroll") for (int _i = 0; _i < 2; ++_i) \
;         __builtin_amdgcn_global_load_lds((const unsigned*)((const char*)(gbase) + (voff)[_i]), (LAS unsigned*)(lds + (bufoff) + ldsw + _i * 8192), 16, 0, 0); } while (0)
; #define PG8_LDA(dst, b, h) do { _Pragma("unroll") for (int m = 0; m < 4; ++m) _Pragma("unroll") for (int k = 0; k < 2; ++k) dst[m][k] = *(const LAS bf16x8*)(lds + PG8_SA(b, h) + aoff + m * 2048 + k * 1024); } while (0)
; #define PG8_LDB(dst, b, h) do { _Pragma("unroll") for (int n = 0; n < 2; ++n) _Pragma("unroll") for (int k = 0; k < 2; ++k) dst[n][k] = *(const LAS bf16x8*)(lds + PG8_SB(b, h) + boff + n * 2048 + k * 1024); } while (0)
; #define PG8_MMA(ai, bj, At, Bt) do { __builtin_amdgcn_s_setprio(1); _Pragma("unroll") for (int m = 0; m < 4; ++m) _Pragma("unroll") for (int n = 0; n < 2; ++n) _Pragma("unroll") for (int k = 0; k < 2; ++k) \
;         acc[ai][bj][m][n] = __builtin_amdgcn_mfma_f32_16x16x32_bf16(Bt[n][k], At[m][k], acc[ai][bj][m][n], 0, 0, 0); __builtin_amdgcn_s_setprio(0); } while (0)
; #define PG8_WAIT_V(n) asm volatile("s_waitcnt vmcnt(" #n ")" ::: "memory")
; #define PG8_WAIT_L(n) asm volatile("s_waitcnt lgkmcnt(" #n ")" ::: "memory")
; #define PG8_BAR __builtin_amdgcn_s_barrier()
; template <class Epi, class Sched>
; __device__ __forceinline__ void gemm_phase(const int tid, LAS unsigned char* lds, const int lda, const int ldb, const int K, const Sched& S, const Epi& E) {
;     ...
;         for (int t = 0; t < nt; t += 2) {
;             const bool last = (t == nt - 2);
;             const char* a1 = cA + (size_t)(t + 1) * kstep;
;             const char* a2 = last ? nA : cA + (size_t)(t + 2) * kstep; const char* b2 = last ? nB : cB + (size_t)(t + 2) * kstep;
;             const char* a3 = a2 + kstep; const char* b3 = b2 + kstep;
;             PG8_LDB(B0, 0, 0); PG8_LDB(B1, 0, 1); PG8_SCHED; PG8_LDA(At, 0, 0); PG8_STAGE(PG8_SA(1, 1), a1 + hstepA, voffA);
;             PG8_WAIT_V(8); PG8_WAIT_L(0); PG8_BAR; PG8_MMA(0, 0, At, B0); PG8_MMA(0, 1, At, B1); PG8_BAR; PG8_SCHED;
;             PG8_LDA(At, 0, 1); PG8_STAGE(PG8_SB(0, 0), b2, voffB); PG8_STAGE(PG8_SB(0, 1), b2 + hstepB, voffB); PG8_STAGE(PG8_SA(0, 0), a2, voffA);
;             PG8_WAIT_V(8); PG8_WAIT_L(0); PG8_BAR; if (!cur.half) { PG8_MMA(1, 0, At, B0); PG8_MMA(1, 1, At, B1); } PG8_BAR; PG8_SCHED;
.LBB0_619:
	s_add_i32 s72, s24, 2
	s_add_u32 s14, s48, 0xfffc0080
	s_addc_u32 s15, s49, -1
	s_add_i32 s73, 0, 0x10000
	s_cmp_eq_u32 s66, s24
	s_cselect_b32 s57, s53, s15
	s_cselect_b32 s56, s52, s14
	v_add_u32_e32 v153, s73, v137
	s_cselect_b32 s51, s55, s71
	s_cselect_b32 s50, s54, s43
	s_add_i32 s14, 0, 0x14000
	ds_read_b128 v[142:145], v153
	ds_read_b128 v[154:157], v153 offset:1024
	ds_read_b128 v[158:161], v153 offset:2048
	ds_read_b128 v[162:165], v153 offset:3072
	v_add_u32_e32 v153, s14, v137
	ds_read_b128 v[180:183], v153
	ds_read_b128 v[184:187], v153 offset:1024
	ds_read_b128 v[190:193], v153 offset:2048
	ds_read_b128 v[194:197], v153 offset:3072
	v_lshl_add_u64 v[166:167], s[48:49], 0, v[138:139]
	s_add_i32 m0, s26, 0xc000
	ds_read_b128 v[206:209], v152
	ds_read_b128 v[210:213], v152 offset:1024
	ds_read_b128 v[214:217], v152 offset:2048
	ds_read_b128 v[218:221], v152 offset:3072
	ds_read_b128 v[222:225], v152 offset:4096
	ds_read_b128 v[226:229], v152 offset:5120
	ds_read_b128 v[230:233], v152 offset:6144
	ds_read_b128 v[234:237], v152 offset:7168
	global_load_lds_dwordx4 v[166:167], off
	v_lshl_add_u64 v[166:167], s[48:49], 0, v[140:141]
	s_add_i32 m0, s26, 0xe000
	s_nop 0
	global_load_lds_dwordx4 v[166:167], off
	s_waitcnt vmcnt(8)
	s_waitcnt lgkmcnt(0)
	s_barrier
	s_setprio 1
	v_mfma_f32_16x16x32_bf16 v[124:127], v[142:145], v[206:209], v[124:127]
	v_mfma_f32_16x16x32_bf16 v[120:123], v[158:161], v[206:209], v[120:123]
	v_mfma_f32_16x16x32_bf16 v[108:111], v[142:145], v[214:217], v[108:111]
	v_mfma_f32_16x16x32_bf16 v[104:107], v[158:161], v[214:217], v[104:107]
	v_mfma_f32_16x16x32_bf16 v[92:95], v[142:145], v[222:225], v[92:95]
	v_mfma_f32_16x16x32_bf16 v[88:91], v[158:161], v[222:225], v[88:91]
	v_mfma_f32_16x16x32_bf16 v[76:79], v[142:145], v[230:233], v[76:79]
	v_mfma_f32_16x16x32_bf16 v[72:75], v[158:161], v[230:233], v[72:75]
	v_mfma_f32_16x16x32_bf16 v[124:127], v[154:157], v[210:213], v[124:127]
	v_mfma_f32_16x16x32_bf16 v[120:123], v[162:165], v[210:213], v[120:123]
	v_mfma_f32_16x16x32_bf16 v[108:111], v[154:157], v[218:221], v[108:111]
	v_mfma_f32_16x16x32_bf16 v[104:107], v[162:165], v[218:221], v[104:107]
	v_mfma_f32_16x16x32_bf16 v[92:95], v[154:157], v[226:229], v[92:95]
	v_mfma_f32_16x16x32_bf16 v[88:91], v[162:165], v[226:229], v[88:91]
	v_mfma_f32_16x16x32_bf16 v[76:79], v[154:157], v[234:237], v[76:79]
	v_mfma_f32_16x16x32_bf16 v[72:75], v[162:165], v[234:237], v[72:75]
	v_mfma_f32_16x16x32_bf16 v[116:119], v[180:183], v[206:209], v[116:119]
	v_mfma_f32_16x16x32_bf16 v[112:115], v[190:193], v[206:209], v[112:115]
	v_mfma_f32_16x16x32_bf16 v[100:103], v[180:183], v[214:217], v[100:103]
	v_mfma_f32_16x16x32_bf16 v[96:99], v[190:193], v[214:217], v[96:99]
	v_mfma_f32_16x16x32_bf16 v[84:87], v[180:183], v[222:225], v[84:87]
	v_mfma_f32_16x16x32_bf16 v[80:83], v[190:193], v[222:225], v[80:83]
	v_mfma_f32_16x16x32_bf16 v[68:71], v[180:183], v[230:233], v[68:71]
	v_mfma_f32_16x16x32_bf16 v[64:67], v[190:193], v[230:233], v[64:67]
	v_mfma_f32_16x16x32_bf16 v[116:119], v[184:187], v[210:213], v[116:119]
	v_mfma_f32_16x16x32_bf16 v[112:115], v[194:197], v[210:213], v[112:115]
	v_mfma_f32_16x16x32_bf16 v[100:103], v[184:187], v[218:221], v[100:103]
	v_mfma_f32_16x16x32_bf16 v[96:99], v[194:197], v[218:221], v[96:99]
	v_mfma_f32_16x16x32_bf16 v[84:87], v[184:187], v[226:229], v[84:87]
	v_mfma_f32_16x16x32_bf16 v[80:83], v[194:197], v[226:229], v[80:83]
	v_mfma_f32_16x16x32_bf16 v[68:71], v[184:187], v[234:237], v[68:71]
	v_mfma_f32_16x16x32_bf16 v[64:67], v[194:197], v[234:237], v[64:67]
	s_setprio 0
	s_barrier
	s_add_i32 s15, s73, s59
	v_lshl_add_u64 v[166:167], s[50:51], 0, v[130:131]
	s_mov_b32 m0, s15
	ds_read_b128 v[206:209], v152 offset:16384
	ds_read_b128 v[210:213], v152 offset:17408
	ds_read_b128 v[214:217], v152 offset:18432
	ds_read_b128 v[218:221], v152 offset:19456
	ds_read_b128 v[222:225], v152 offset:20480
	ds_read_b128 v[226:229], v152 offset:21504
	ds_read_b128 v[230:233], v152 offset:22528
	ds_read_b128 v[234:237], v152 offset:23552
	global_load_lds_dwordx4 v[166:167], off
	s_add_i32 m0, s15, 0x2000
	s_add_u32 s74, s50, 0x40000
	v_lshl_add_u64 v[176:177], s[50:51], 0, v[134:135]
	s_addc_u32 s75, s51, 0
	s_add_i32 s14, s14, s59
	global_load_lds_dwordx4 v[176:177], off
	v_lshl_add_u64 v[238:239], s[74:75], 0, v[130:131]
	s_mov_b32 m0, s14
	v_lshl_add_u64 v[240:241], s[56:57], 0, v[132:133]
	global_load_lds_dwordx4 v[238:239], off
	v_lshl_add_u64 v[238:239], s[74:75], 0, v[134:135]
	s_add_i32 m0, s14, 0x2000
	s_nop 0
	global_load_lds_dwordx4 v[238:239], off
	v_lshl_add_u64 v[238:239], s[56:57], 0, v[128:129]
	s_mov_b32 m0, s26
	s_nop 0
	global_load_lds_dwordx4 v[238:239], off
	s_mov_b32 m0, s27
	s_nop 0
	global_load_lds_dwordx4 v[240:241], off
	s_waitcnt vmcnt(8)
	s_waitcnt lgkmcnt(0)
	s_barrier
; #define PG8_STAGE(bufoff, gbase, voff) do { _Pragma("unroll") for (int _i = 0; _i < 2; ++_i) \
;         __builtin_amdgcn_global_load_lds((const unsigned*)((const char*)(gbase) + (voff)[_i]), (LAS unsigned*)(lds + (bufoff) + ldsw + _i * 8192), 16, 0, 0); } while (0)
; #define PG8_LDA(dst, b, h) do { _Pragma("unroll") for (int m = 0; m < 4; ++m) _Pragma("unroll") for (int k = 0; k < 2; ++k) dst[m][k] = *(const LAS bf16x8*)(lds + PG8_SA(b, h) + aoff + m * 2048 + k * 1024); } while (0)
; #define PG8_LDB(dst, b, h) do { _Pragma("unroll") for (int n = 0; n < 2; ++n) _Pragma("unroll") for (int k = 0; k < 2; ++k) dst[n][k] = *(const LAS bf16x8*)(lds + PG8_SB(b, h) + boff + n * 2048 + k * 1024); } while (0)
; #define PG8_MMA(ai, bj, At, Bt) do { __builtin_amdgcn_s_setprio(1); _Pragma("unroll") for (int m = 0; m < 4; ++m) _Pragma("unroll") for (int n = 0; n < 2; ++n) _Pragma("unroll") for (int k = 0; k < 2; ++k) \
;         acc[ai][bj][m][n] = __builtin_amdgcn_mfma_f32_16x16x32_bf16(Bt[n][k], At[m][k], acc[ai][bj][m][n], 0, 0, 0); __builtin_amdgcn_s_setprio(0); } while (0)
; #define PG8_WAIT_V(n) asm volatile("s_waitcnt vmcnt(" #n ")" ::: "memory")
; #define PG8_WAIT_L(n) asm volatile("s_waitcnt lgkmcnt(" #n ")" ::: "memory")
; #define PG8_BAR __builtin_amdgcn_s_barrier()
; #define PG8_SCHED __builtin_amdgcn_sched_barrier(0)
; template <class Epi, class Sched>
; __device__ __forceinline__ void gemm_phase(const int tid, LAS unsigned char* lds, const int lda, const int ldb, const int K, const Sched& S, const Epi& E) {
;     ...
;             PG8_WAIT_V(8); PG8_WAIT_L(0); PG8_BAR; if (!cur.half) { PG8_MMA(1, 0, At, B0); PG8_MMA(1, 1, At, B1); } PG8_BAR; PG8_SCHED;
;             PG8_LDB(B0, 1, 0); PG8_LDB(B1, 1, 1); PG8_SCHED; PG8_LDA(At, 1, 0); PG8_STAGE(PG8_SA(0, 1), a2 + hstepA, voffA);
;             PG8_WAIT_V(8); PG8_WAIT_L(0); PG8_BAR; PG8_MMA(0, 0, At, B0); PG8_MMA(0, 1, At, B1); PG8_BAR; PG8_SCHED;
	s_setprio 1
	v_mfma_f32_16x16x32_bf16 v[60:63], v[142:145], v[206:209], v[60:63]
	v_mfma_f32_16x16x32_bf16 v[56:59], v[158:161], v[206:209], v[56:59]
	v_mfma_f32_16x16x32_bf16 v[44:47], v[142:145], v[214:217], v[44:47]
	v_mfma_f32_16x16x32_bf16 v[40:43], v[158:161], v[214:217], v[40:43]
	v_mfma_f32_16x16x32_bf16 v[28:31], v[142:145], v[222:225], v[28:31]
	v_mfma_f32_16x16x32_bf16 v[24:27], v[158:161], v[222:225], v[24:27]
	v_mfma_f32_16x16x32_bf16 v[12:15], v[142:145], v[230:233], v[12:15]
	v_mfma_f32_16x16x32_bf16 v[8:11], v[158:161], v[230:233], v[8:11]
	v_mfma_f32_16x16x32_bf16 v[60:63], v[154:157], v[210:213], v[60:63]
	v_mfma_f32_16x16x32_bf16 v[56:59], v[162:165], v[210:213], v[56:59]
	v_mfma_f32_16x16x32_bf16 v[44:47], v[154:157], v[218:221], v[44:47]
	v_mfma_f32_16x16x32_bf16 v[40:43], v[162:165], v[218:221], v[40:43]
	v_mfma_f32_16x16x32_bf16 v[28:31], v[154:157], v[226:229], v[28:31]
	v_mfma_f32_16x16x32_bf16 v[24:27], v[162:165], v[226:229], v[24:27]
	v_mfma_f32_16x16x32_bf16 v[12:15], v[154:157], v[234:237], v[12:15]
	v_mfma_f32_16x16x32_bf16 v[8:11], v[162:165], v[234:237], v[8:11]
	v_mfma_f32_16x16x32_bf16 v[52:55], v[180:183], v[206:209], v[52:55]
	v_mfma_f32_16x16x32_bf16 v[48:51], v[190:193], v[206:209], v[48:51]
	v_mfma_f32_16x16x32_bf16 v[36:39], v[180:183], v[214:217], v[36:39]
	v_mfma_f32_16x16x32_bf16 v[32:35], v[190:193], v[214:217], v[32:35]
	v_mfma_f32_16x16x32_bf16 v[20:23], v[180:183], v[222:225], v[20:23]
	v_mfma_f32_16x16x32_bf16 v[16:19], v[190:193], v[222:225], v[16:19]
	v_mfma_f32_16x16x32_bf16 v[4:7], v[180:183], v[230:233], v[4:7]
	v_mfma_f32_16x16x32_bf16 v[0:3], v[190:193], v[230:233], v[0:3]
	v_mfma_f32_16x16x32_bf16 v[52:55], v[184:187], v[210:213], v[52:55]
	v_mfma_f32_16x16x32_bf16 v[48:51], v[194:197], v[210:213], v[48:51]
	v_mfma_f32_16x16x32_bf16 v[36:39], v[184:187], v[218:221], v[36:39]
	v_mfma_f32_16x16x32_bf16 v[32:35], v[194:197], v[218:221], v[32:35]
	v_mfma_f32_16x16x32_bf16 v[20:23], v[184:187], v[226:229], v[20:23]
	v_mfma_f32_16x16x32_bf16 v[16:19], v[194:197], v[226:229], v[16:19]
	v_mfma_f32_16x16x32_bf16 v[4:7], v[184:187], v[234:237], v[4:7]
	v_mfma_f32_16x16x32_bf16 v[0:3], v[194:197], v[234:237], v[0:3]
	s_setprio 0
	s_barrier
	s_add_i32 s14, 0, 0x18000
	v_add_u32_e32 v153, s14, v137
	s_add_i32 s15, 0, 0x1c000
	ds_read_b128 v[142:145], v153
	ds_read_b128 v[154:157], v153 offset:1024
	ds_read_b128 v[158:161], v153 offset:2048
	ds_read_b128 v[162:165], v153 offset:3072
	v_add_u32_e32 v153, s15, v137
	ds_read_b128 v[180:183], v153
	ds_read_b128 v[184:187], v153 offset:1024
	ds_read_b128 v[190:193], v153 offset:2048
	ds_read_b128 v[194:197], v153 offset:3072
	s_add_u32 s56, s56, 0x40000
	s_addc_u32 s57, s57, 0
	s_mov_b32 m0, s60
	v_lshl_add_u64 v[242:243], s[56:57], 0, v[128:129]
	ds_read_b128 v[206:209], v152 offset:32768
	ds_read_b128 v[210:213], v152 offset:33792
	ds_read_b128 v[214:217], v152 offset:34816
	ds_read_b128 v[218:221], v152 offset:35840
	ds_read_b128 v[222:225], v152 offset:36864
	ds_read_b128 v[226:229], v152 offset:37888
	ds_read_b128 v[230:233], v152 offset:38912
	ds_read_b128 v[234:237], v152 offset:39936
	global_load_lds_dwordx4 v[242:243], off
	v_lshl_add_u64 v[242:243], s[56:57], 0, v[132:133]
	s_mov_b32 m0, s61
	s_nop 0
	global_load_lds_dwordx4 v[242:243], off
	s_waitcnt vmcnt(8)
	s_waitcnt lgkmcnt(0)
	s_barrier
	s_setprio 1
	v_mfma_f32_16x16x32_bf16 v[124:127], v[142:145], v[206:209], v[124:127]
	v_mfma_f32_16x16x32_bf16 v[120:123], v[158:161], v[206:209], v[120:123]
	v_mfma_f32_16x16x32_bf16 v[108:111], v[142:145], v[214:217], v[108:111]
	v_mfma_f32_16x16x32_bf16 v[104:107], v[158:161], v[214:217], v[104:107]
	v_mfma_f32_16x16x32_bf16 v[92:95], v[142:145], v[222:225], v[92:95]
	v_mfma_f32_16x16x32_bf16 v[88:91], v[158:161], v[222:225], v[88:91]
	v_mfma_f32_16x16x32_bf16 v[76:79], v[142:145], v[230:233], v[76:79]
	v_mfma_f32_16x16x32_bf16 v[72:75], v[158:161], v[230:233], v[72:75]
	v_mfma_f32_16x16x32_bf16 v[124:127], v[154:157], v[210:213], v[124:127]
	v_mfma_f32_16x16x32_bf16 v[120:123], v[162:165], v[210:213], v[120:123]
	v_mfma_f32_16x16x32_bf16 v[108:111], v[154:157], v[218:221], v[108:111]
	v_mfma_f32_16x16x32_bf16 v[104:107], v[162:165], v[218:221], v[104:107]
	v_mfma_f32_16x16x32_bf16 v[92:95], v[154:157], v[226:229], v[92:95]
	v_mfma_f32_16x16x32_bf16 v[88:91], v[162:165], v[226:229], v[88:91]
	v_mfma_f32_16x16x32_bf16 v[76:79], v[154:157], v[234:237], v[76:79]
	v_mfma_f32_16x16x32_bf16 v[72:75], v[162:165], v[234:237], v[72:75]
	v_mfma_f32_16x16x32_bf16 v[116:119], v[180:183], v[206:209], v[116:119]
	v_mfma_f32_16x16x32_bf16 v[112:115], v[190:193], v[206:209], v[112:115]
	v_mfma_f32_16x16x32_bf16 v[100:103], v[180:183], v[214:217], v[100:103]
	v_mfma_f32_16x16x32_bf16 v[96:99], v[190:193], v[214:217], v[96:99]
	v_mfma_f32_16x16x32_bf16 v[84:87], v[180:183], v[222:225], v[84:87]
	v_mfma_f32_16x16x32_bf16 v[80:83], v[190:193], v[222:225], v[80:83]
	v_mfma_f32_16x16x32_bf16 v[68:71], v[180:183], v[230:233], v[68:71]
	v_mfma_f32_16x16x32_bf16 v[64:67], v[190:193], v[230:233], v[64:67]
	v_mfma_f32_16x16x32_bf16 v[116:119], v[184:187], v[210:213], v[116:119]
	v_mfma_f32_16x16x32_bf16 v[112:115], v[194:197], v[210:213], v[112:115]
	v_mfma_f32_16x16x32_bf16 v[100:103], v[184:187], v[218:221], v[100:103]
	v_mfma_f32_16x16x32_bf16 v[96:99], v[194:197], v[218:221], v[96:99]
	v_mfma_f32_16x16x32_bf16 v[84:87], v[184:187], v[226:229], v[84:87]
	v_mfma_f32_16x16x32_bf16 v[80:83], v[194:197], v[226:229], v[80:83]
	v_mfma_f32_16x16x32_bf16 v[68:71], v[184:187], v[234:237], v[68:71]
	v_mfma_f32_16x16x32_bf16 v[64:67], v[194:197], v[234:237], v[64:67]
	s_setprio 0
	s_barrier
; #define PG8_STAGE(bufoff, gbase, voff) do { _Pragma("unroll") for (int _i = 0; _i < 2; ++_i) \
;         __builtin_amdgcn_global_load_lds((const unsigned*)((const char*)(gbase) + (voff)[_i]), (LAS unsigned*)(lds + (bufoff) + ldsw + _i * 8192), 16, 0, 0); } while (0)
; #define PG8_LDA(dst, b, h) do { _Pragma("unroll") for (int m = 0; m < 4; ++m) _Pragma("unroll") for (int k = 0; k < 2; ++k) dst[m][k] = *(const LAS bf16x8*)(lds + PG8_SA(b, h) + aoff + m * 2048 + k * 1024); } while (0)
; #define PG8_MMA(ai, bj, At, Bt) do { __builtin_amdgcn_s_setprio(1); _Pragma("unroll") for (int m = 0; m < 4; ++m) _Pragma("unroll") for (int n = 0; n < 2; ++n) _Pragma("unroll") for (int k = 0; k < 2; ++k) \
;         acc[ai][bj][m][n] = __builtin_amdgcn_mfma_f32_16x16x32_bf16(Bt[n][k], At[m][k], acc[ai][bj][m][n], 0, 0, 0); __builtin_amdgcn_s_setprio(0); } while (0)
; #define PG8_WAIT_V(n) asm volatile("s_waitcnt vmcnt(" #n ")" ::: "memory")
; #define PG8_WAIT_L(n) asm volatile("s_waitcnt lgkmcnt(" #n ")" ::: "memory")
; #define PG8_BAR __builtin_amdgcn_s_barrier()
; #define PG8_SCHED __builtin_amdgcn_sched_barrier(0)
; template <class Epi, class Sched>
; __device__ __forceinline__ void gemm_phase(const int tid, LAS unsigned char* lds, const int lda, const int ldb, const int K, const Sched& S, const Epi& E) {
;     ...
;             PG8_LDA(At, 1, 1); PG8_STAGE(PG8_SB(1, 0), b3, voffB); PG8_STAGE(PG8_SB(1, 1), b3 + hstepB, voffB); PG8_STAGE(PG8_SA(1, 0), a3, voffA);
;             PG8_WAIT_V(8); PG8_WAIT_L(0); PG8_BAR; if (!cur.half) { PG8_MMA(1, 0, At, B0); PG8_MMA(1, 1, At, B1); } PG8_BAR; PG8_SCHED;
;         }
	s_add_i32 s14, s14, s59
	v_lshl_add_u64 v[166:167], v[166:167], 0, s[6:7]
	s_mov_b32 m0, s14
	ds_read_b128 v[206:209], v152 offset:49152
	ds_read_b128 v[210:213], v152 offset:50176
	ds_read_b128 v[214:217], v152 offset:51200
	ds_read_b128 v[218:221], v152 offset:52224
	ds_read_b128 v[222:225], v152 offset:53248
	ds_read_b128 v[226:229], v152 offset:54272
	ds_read_b128 v[230:233], v152 offset:55296
	ds_read_b128 v[234:237], v152 offset:56320
	global_load_lds_dwordx4 v[166:167], off
	s_add_i32 m0, s14, 0x2000
	s_add_u32 s50, s50, 0x40080
	v_lshl_add_u64 v[166:167], v[176:177], 0, s[6:7]
	s_addc_u32 s51, s51, 0
	s_add_i32 s14, s15, s59
	global_load_lds_dwordx4 v[166:167], off
	v_lshl_add_u64 v[166:167], s[50:51], 0, v[130:131]
	s_mov_b32 m0, s14
	s_nop 0
	global_load_lds_dwordx4 v[166:167], off
	v_lshl_add_u64 v[166:167], s[50:51], 0, v[134:135]
	s_add_i32 m0, s14, 0x2000
	s_nop 0
	global_load_lds_dwordx4 v[166:167], off
	v_lshl_add_u64 v[166:167], v[238:239], 0, s[6:7]
	s_mov_b32 m0, s63
	s_nop 0
	global_load_lds_dwordx4 v[166:167], off
	v_lshl_add_u64 v[166:167], v[240:241], 0, s[6:7]
	s_mov_b32 m0, s64
	s_nop 0
	global_load_lds_dwordx4 v[166:167], off
	s_waitcnt vmcnt(8)
	s_waitcnt lgkmcnt(0)
	s_barrier
	s_setprio 1
	v_mfma_f32_16x16x32_bf16 v[60:63], v[142:145], v[206:209], v[60:63]
	v_mfma_f32_16x16x32_bf16 v[56:59], v[158:161], v[206:209], v[56:59]
	v_mfma_f32_16x16x32_bf16 v[44:47], v[142:145], v[214:217], v[44:47]
	v_mfma_f32_16x16x32_bf16 v[40:43], v[158:161], v[214:217], v[40:43]
	v_mfma_f32_16x16x32_bf16 v[28:31], v[142:145], v[222:225], v[28:31]
	v_mfma_f32_16x16x32_bf16 v[24:27], v[158:161], v[222:225], v[24:27]
	v_mfma_f32_16x16x32_bf16 v[12:15], v[142:145], v[230:233], v[12:15]
	v_mfma_f32_16x16x32_bf16 v[8:11], v[158:161], v[230:233], v[8:11]
	v_mfma_f32_16x16x32_bf16 v[60:63], v[154:157], v[210:213], v[60:63]
	v_mfma_f32_16x16x32_bf16 v[56:59], v[162:165], v[210:213], v[56:59]
	v_mfma_f32_16x16x32_bf16 v[44:47], v[154:157], v[218:221], v[44:47]
	v_mfma_f32_16x16x32_bf16 v[40:43], v[162:165], v[218:221], v[40:43]
	v_mfma_f32_16x16x32_bf16 v[28:31], v[154:157], v[226:229], v[28:31]
	v_mfma_f32_16x16x32_bf16 v[24:27], v[162:165], v[226:229], v[24:27]
	v_mfma_f32_16x16x32_bf16 v[12:15], v[154:157], v[234:237], v[12:15]
	v_mfma_f32_16x16x32_bf16 v[8:11], v[162:165], v[234:237], v[8:11]
	v_mfma_f32_16x16x32_bf16 v[52:55], v[180:183], v[206:209], v[52:55]
	v_mfma_f32_16x16x32_bf16 v[48:51], v[190:193], v[206:209], v[48:51]
	v_mfma_f32_16x16x32_bf16 v[36:39], v[180:183], v[214:217], v[36:39]
	v_mfma_f32_16x16x32_bf16 v[32:35], v[190:193], v[214:217], v[32:35]
	v_mfma_f32_16x16x32_bf16 v[20:23], v[180:183], v[222:225], v[20:23]
	v_mfma_f32_16x16x32_bf16 v[16:19], v[190:193], v[222:225], v[16:19]
	v_mfma_f32_16x16x32_bf16 v[4:7], v[180:183], v[230:233], v[4:7]
	v_mfma_f32_16x16x32_bf16 v[0:3], v[190:193], v[230:233], v[0:3]
	v_mfma_f32_16x16x32_bf16 v[52:55], v[184:187], v[210:213], v[52:55]
	v_mfma_f32_16x16x32_bf16 v[48:51], v[194:197], v[210:213], v[48:51]
	v_mfma_f32_16x16x32_bf16 v[36:39], v[184:187], v[218:221], v[36:39]
	v_mfma_f32_16x16x32_bf16 v[32:35], v[194:197], v[218:221], v[32:35]
	v_mfma_f32_16x16x32_bf16 v[20:23], v[184:187], v[226:229], v[20:23]
	v_mfma_f32_16x16x32_bf16 v[16:19], v[194:197], v[226:229], v[16:19]
	v_mfma_f32_16x16x32_bf16 v[4:7], v[184:187], v[234:237], v[4:7]
	v_mfma_f32_16x16x32_bf16 v[0:3], v[194:197], v[234:237], v[0:3]
	s_setprio 0
	s_barrier
	s_add_u32 s48, s48, 0x100
	s_addc_u32 s49, s49, 0
	s_add_u32 s43, s43, 0x100
	s_addc_u32 s71, s71, 0
	s_cmp_ge_i32 s72, s31
	s_mov_b32 s24, s72
	s_cbranch_scc0 .LBB0_619
	v_readlane_b32 s74, v254, 54
	v_readlane_b32 s75, v254, 55
	s_movk_i32 s71, 0x1600

; #define PG8_STAGE(bufoff, gbase, voff) do { _Pragma("unroll") for (int _i = 0; _i < 2; ++_i) \
;         __builtin_amdgcn_global_load_lds((const unsigned*)((const char*)(gbase) + (voff)[_i]), (LAS unsigned*)(lds + (bufoff) + ldsw + _i * 8192), 16, 0, 0); } while (0)
; #define PG8_LDA(dst, b, h) do { _Pragma("unroll") for (int m = 0; m < 4; ++m) _Pragma("unroll") for (int k = 0; k < 2; ++k) dst[m][k] = *(const LAS bf16x8*)(lds + PG8_SA(b, h) + aoff + m * 2048 + k * 1024); } while (0)
; #define PG8_LDB(dst, b, h) do { _Pragma("unroll") for (int n = 0; n < 2; ++n) _Pragma("unroll") for (int k = 0; k < 2; ++k) dst[n][k] = *(const LAS bf16x8*)(lds + PG8_SB(b, h) + boff + n * 2048 + k * 1024); } while (0)
; #define PG8_MMA(ai, bj, At, Bt) do { __builtin_amdgcn_s_setprio(1); _Pragma("unroll") for (int m = 0; m < 4; ++m) _Pragma("unroll") for (int n = 0; n < 2; ++n) _Pragma("unroll") for (int k = 0; k < 2; ++k) \
;         acc[ai][bj][m][n] = __builtin_amdgcn_mfma_f32_16x16x32_bf16(Bt[n][k], At[m][k], acc[ai][bj][m][n], 0, 0, 0); __builtin_amdgcn_s_setprio(0); } while (0)
; #define PG8_BAR __builtin_amdgcn_s_barrier()
; template <class Epi, class Sched>
; __device__ __forceinline__ void gemm_phase(const int tid, LAS unsigned char* lds, const int lda, const int ldb, const int K, const Sched& S, const Epi& E) {
;     ...
;     for (;;) {
;         const bool has_next = S.next(ui + 1, nxt);
;         const char* nA = has_next ? nxt.a : cA; const char* nB = has_next ? nxt.b : cB;
;         for (int t = 0; t < nt; t += 2) {
;             const bool last = (t == nt - 2);
;             const char* a1 = cA + (size_t)(t + 1) * kstep;
;             const char* a2 = last ? nA : cA + (size_t)(t + 2) * kstep; const char* b2 = last ? nB : cB + (size_t)(t + 2) * kstep;
;             const char* a3 = a2 + kstep; const char* b3 = b2 + kstep;
;             PG8_LDB(B0, 0, 0); PG8_LDB(B1, 0, 1); PG8_SCHED; PG8_LDA(At, 0, 0); PG8_STAGE(PG8_SA(1, 1), a1 + hstepA, voffA);
;             PG8_WAIT_V(8); PG8_WAIT_L(0); PG8_BAR; PG8_MMA(0, 0, At, B0); PG8_MMA(0, 1, At, B1); PG8_BAR; PG8_SCHED;
;             PG8_LDA(At, 0, 1); PG8_STAGE(PG8_SB(0, 0), b2, voffB); PG8_STAGE(PG8_SB(0, 1), b2 + hstepB, voffB); PG8_STAGE(PG8_SA(0, 0), a2, voffA);
;             PG8_WAIT_V(8); PG8_WAIT_L(0); PG8_BAR; if (!cur.half) { PG8_MMA(1, 0, At, B0); PG8_MMA(1, 1, At, B1); } PG8_BAR; PG8_SCHED;
.LBB0_679:
	s_andn2_b64 vcc, exec, s[40:41]
	s_cbranch_vccnz .LBB0_727
	s_add_u32 s50, s50, 0x40080
	s_addc_u32 s51, s51, 0
	s_add_u32 s26, s52, 0x100
	s_addc_u32 s27, s53, 0
	s_mov_b32 s45, 0
	s_add_i32 s67, s45, 2
	s_add_u32 s14, s50, 0xfffc0080
	s_addc_u32 s15, s51, -1
	s_add_i32 s24, 0, 0x10000
	s_cmp_eq_u32 s63, s45
	s_cselect_b32 s55, s3, s15
	s_cselect_b32 s54, s2, s14
	v_add_u32_e32 v146, s24, v152
	s_cselect_b32 s53, s39, s27
	s_cselect_b32 s52, s38, s26
	s_add_i32 s14, 0, 0x14000
	ds_read_b128 v[142:145], v146
	ds_read_b128 v[162:165], v146 offset:1024
	ds_read_b128 v[180:183], v146 offset:2048
	ds_read_b128 v[184:187], v146 offset:3072
	v_add_u32_e32 v146, s14, v152
	ds_read_b128 v[190:193], v146
	ds_read_b128 v[194:197], v146 offset:1024
	ds_read_b128 v[206:209], v146 offset:2048
	ds_read_b128 v[210:213], v146 offset:3072
	v_lshl_add_u64 v[146:147], s[50:51], 0, v[136:137]
	s_add_i32 m0, s56, 0xc000
	ds_read_b128 v[214:217], v160
	ds_read_b128 v[218:221], v160 offset:1024
	ds_read_b128 v[222:225], v160 offset:2048
	ds_read_b128 v[226:229], v160 offset:3072
	ds_read_b128 v[230:233], v160 offset:4096
	ds_read_b128 v[234:237], v160 offset:5120
	ds_read_b128 v[238:241], v160 offset:6144
	ds_read_b128 v[242:245], v160 offset:7168
	global_load_lds_dwordx4 v[146:147], off
	v_lshl_add_u64 v[146:147], s[50:51], 0, v[138:139]
	s_add_i32 m0, s56, 0xe000
	s_nop 0
	global_load_lds_dwordx4 v[146:147], off
	s_waitcnt vmcnt(8)
	s_waitcnt lgkmcnt(0)
	s_barrier
	s_setprio 1
	v_mfma_f32_16x16x32_bf16 v[124:127], v[142:145], v[214:217], 0
	v_mfma_f32_16x16x32_bf16 v[120:123], v[180:183], v[214:217], 0
	v_mfma_f32_16x16x32_bf16 v[108:111], v[142:145], v[222:225], 0
	v_mfma_f32_16x16x32_bf16 v[104:107], v[180:183], v[222:225], 0
	v_mfma_f32_16x16x32_bf16 v[92:95], v[142:145], v[230:233], 0
	v_mfma_f32_16x16x32_bf16 v[88:91], v[180:183], v[230:233], 0
	v_mfma_f32_16x16x32_bf16 v[76:79], v[142:145], v[238:241], 0
	v_mfma_f32_16x16x32_bf16 v[72:75], v[180:183], v[238:241], 0
	v_mfma_f32_16x16x32_bf16 v[124:127], v[162:165], v[218:221], v[124:127]
	v_mfma_f32_16x16x32_bf16 v[120:123], v[184:187], v[218:221], v[120:123]
	v_mfma_f32_16x16x32_bf16 v[108:111], v[162:165], v[226:229], v[108:111]
	v_mfma_f32_16x16x32_bf16 v[104:107], v[184:187], v[226:229], v[104:107]
	v_mfma_f32_16x16x32_bf16 v[92:95], v[162:165], v[234:237], v[92:95]
	v_mfma_f32_16x16x32_bf16 v[88:91], v[184:187], v[234:237], v[88:91]
	v_mfma_f32_16x16x32_bf16 v[76:79], v[162:165], v[242:245], v[76:79]
	v_mfma_f32_16x16x32_bf16 v[72:75], v[184:187], v[242:245], v[72:75]
	v_mfma_f32_16x16x32_bf16 v[116:119], v[190:193], v[214:217], 0
	v_mfma_f32_16x16x32_bf16 v[112:115], v[206:209], v[214:217], 0
	v_mfma_f32_16x16x32_bf16 v[100:103], v[190:193], v[222:225], 0
	v_mfma_f32_16x16x32_bf16 v[96:99], v[206:209], v[222:225], 0
	v_mfma_f32_16x16x32_bf16 v[84:87], v[190:193], v[230:233], 0
	v_mfma_f32_16x16x32_bf16 v[80:83], v[206:209], v[230:233], 0
	v_mfma_f32_16x16x32_bf16 v[68:71], v[190:193], v[238:241], 0
	v_mfma_f32_16x16x32_bf16 v[64:67], v[206:209], v[238:241], 0
	v_mfma_f32_16x16x32_bf16 v[116:119], v[194:197], v[218:221], v[116:119]
	v_mfma_f32_16x16x32_bf16 v[112:115], v[210:213], v[218:221], v[112:115]
	v_mfma_f32_16x16x32_bf16 v[100:103], v[194:197], v[226:229], v[100:103]
	v_mfma_f32_16x16x32_bf16 v[96:99], v[210:213], v[226:229], v[96:99]
	v_mfma_f32_16x16x32_bf16 v[84:87], v[194:197], v[234:237], v[84:87]
	v_mfma_f32_16x16x32_bf16 v[80:83], v[210:213], v[234:237], v[80:83]
	v_mfma_f32_16x16x32_bf16 v[68:71], v[194:197], v[242:245], v[68:71]
	v_mfma_f32_16x16x32_bf16 v[64:67], v[210:213], v[242:245], v[64:67]
	s_setprio 0
	s_barrier
	s_add_i32 s15, s24, s31
	v_lshl_add_u64 v[146:147], s[52:53], 0, v[130:131]
	s_mov_b32 m0, s15
	ds_read_b128 v[214:217], v160 offset:16384
	ds_read_b128 v[218:221], v160 offset:17408
	ds_read_b128 v[222:225], v160 offset:18432
	ds_read_b128 v[226:229], v160 offset:19456
	ds_read_b128 v[230:233], v160 offset:20480
	ds_read_b128 v[234:237], v160 offset:21504
	ds_read_b128 v[238:241], v160 offset:22528
	ds_read_b128 v[242:245], v160 offset:23552
	global_load_lds_dwordx4 v[146:147], off
	s_add_i32 m0, s15, 0x2000
	s_add_u32 s68, s52, 0x40000
	v_lshl_add_u64 v[166:167], s[52:53], 0, v[134:135]
	s_addc_u32 s69, s53, 0
	s_add_i32 s14, s14, s31
	global_load_lds_dwordx4 v[166:167], off
	v_lshl_add_u64 v[176:177], s[68:69], 0, v[130:131]
	s_mov_b32 m0, s14
	v_lshl_add_u64 v[246:247], s[54:55], 0, v[132:133]
	global_load_lds_dwordx4 v[176:177], off
	v_lshl_add_u64 v[176:177], s[68:69], 0, v[134:135]
	s_add_i32 m0, s14, 0x2000
	s_nop 0
	global_load_lds_dwordx4 v[176:177], off
	v_lshl_add_u64 v[176:177], s[54:55], 0, v[128:129]
	s_mov_b32 m0, s56
	s_nop 0
	global_load_lds_dwordx4 v[176:177], off
	s_mov_b32 m0, s57
	s_nop 0
	global_load_lds_dwordx4 v[246:247], off
	s_waitcnt vmcnt(8)
	s_waitcnt lgkmcnt(0)
	s_barrier
; #define PG8_STAGE(bufoff, gbase, voff) do { _Pragma("unroll") for (int _i = 0; _i < 2; ++_i) \
;         __builtin_amdgcn_global_load_lds((const unsigned*)((const char*)(gbase) + (voff)[_i]), (LAS unsigned*)(lds + (bufoff) + ldsw + _i * 8192), 16, 0, 0); } while (0)
; #define PG8_LDA(dst, b, h) do { _Pragma("unroll") for (int m = 0; m < 4; ++m) _Pragma("unroll") for (int k = 0; k < 2; ++k) dst[m][k] = *(const LAS bf16x8*)(lds + PG8_SA(b, h) + aoff + m * 2048 + k * 1024); } while (0)
; #define PG8_LDB(dst, b, h) do { _Pragma("unroll") for (int n = 0; n < 2; ++n) _Pragma("unroll") for (int k = 0; k < 2; ++k) dst[n][k] = *(const LAS bf16x8*)(lds + PG8_SB(b, h) + boff + n * 2048 + k * 1024); } while (0)
; #define PG8_MMA(ai, bj, At, Bt) do { __builtin_amdgcn_s_setprio(1); _Pragma("unroll") for (int m = 0; m < 4; ++m) _Pragma("unroll") for (int n = 0; n < 2; ++n) _Pragma("unroll") for (int k = 0; k < 2; ++k) \
;         acc[ai][bj][m][n] = __builtin_amdgcn_mfma_f32_16x16x32_bf16(Bt[n][k], At[m][k], acc[ai][bj][m][n], 0, 0, 0); __builtin_amdgcn_s_setprio(0); } while (0)
; #define PG8_WAIT_V(n) asm volatile("s_waitcnt vmcnt(" #n ")" ::: "memory")
; #define PG8_WAIT_L(n) asm volatile("s_waitcnt lgkmcnt(" #n ")" ::: "memory")
; #define PG8_BAR __builtin_amdgcn_s_barrier()
; #define PG8_SCHED __builtin_amdgcn_sched_barrier(0)
; template <class Epi, class Sched>
; __device__ __forceinline__ void gemm_phase(const int tid, LAS unsigned char* lds, const int lda, const int ldb, const int K, const Sched& S, const Epi& E) {
;     ...
;             PG8_WAIT_V(8); PG8_WAIT_L(0); PG8_BAR; if (!cur.half) { PG8_MMA(1, 0, At, B0); PG8_MMA(1, 1, At, B1); } PG8_BAR; PG8_SCHED;
;             PG8_LDB(B0, 1, 0); PG8_LDB(B1, 1, 1); PG8_SCHED; PG8_LDA(At, 1, 0); PG8_STAGE(PG8_SA(0, 1), a2 + hstepA, voffA);
;             PG8_WAIT_V(8); PG8_WAIT_L(0); PG8_BAR; PG8_MMA(0, 0, At, B0); PG8_MMA(0, 1, At, B1); PG8_BAR; PG8_SCHED;
	s_setprio 1
	v_mfma_f32_16x16x32_bf16 v[60:63], v[142:145], v[214:217], 0
	v_mfma_f32_16x16x32_bf16 v[56:59], v[180:183], v[214:217], 0
	v_mfma_f32_16x16x32_bf16 v[44:47], v[142:145], v[222:225], 0
	v_mfma_f32_16x16x32_bf16 v[40:43], v[180:183], v[222:225], 0
	v_mfma_f32_16x16x32_bf16 v[28:31], v[142:145], v[230:233], 0
	v_mfma_f32_16x16x32_bf16 v[24:27], v[180:183], v[230:233], 0
	v_mfma_f32_16x16x32_bf16 v[12:15], v[142:145], v[238:241], 0
	v_mfma_f32_16x16x32_bf16 v[8:11], v[180:183], v[238:241], 0
	v_mfma_f32_16x16x32_bf16 v[60:63], v[162:165], v[218:221], v[60:63]
	v_mfma_f32_16x16x32_bf16 v[56:59], v[184:187], v[218:221], v[56:59]
	v_mfma_f32_16x16x32_bf16 v[44:47], v[162:165], v[226:229], v[44:47]
	v_mfma_f32_16x16x32_bf16 v[40:43], v[184:187], v[226:229], v[40:43]
	v_mfma_f32_16x16x32_bf16 v[28:31], v[162:165], v[234:237], v[28:31]
	v_mfma_f32_16x16x32_bf16 v[24:27], v[184:187], v[234:237], v[24:27]
	v_mfma_f32_16x16x32_bf16 v[12:15], v[162:165], v[242:245], v[12:15]
	v_mfma_f32_16x16x32_bf16 v[8:11], v[184:187], v[242:245], v[8:11]
	v_mfma_f32_16x16x32_bf16 v[52:55], v[190:193], v[214:217], 0
	v_mfma_f32_16x16x32_bf16 v[48:51], v[206:209], v[214:217], 0
	v_mfma_f32_16x16x32_bf16 v[36:39], v[190:193], v[222:225], 0
	v_mfma_f32_16x16x32_bf16 v[32:35], v[206:209], v[222:225], 0
	v_mfma_f32_16x16x32_bf16 v[20:23], v[190:193], v[230:233], 0
	v_mfma_f32_16x16x32_bf16 v[16:19], v[206:209], v[230:233], 0
	v_mfma_f32_16x16x32_bf16 v[4:7], v[190:193], v[238:241], 0
	v_mfma_f32_16x16x32_bf16 v[0:3], v[206:209], v[238:241], 0
	v_mfma_f32_16x16x32_bf16 v[52:55], v[194:197], v[218:221], v[52:55]
	v_mfma_f32_16x16x32_bf16 v[48:51], v[210:213], v[218:221], v[48:51]
	v_mfma_f32_16x16x32_bf16 v[36:39], v[194:197], v[226:229], v[36:39]
	v_mfma_f32_16x16x32_bf16 v[32:35], v[210:213], v[226:229], v[32:35]
	v_mfma_f32_16x16x32_bf16 v[20:23], v[194:197], v[234:237], v[20:23]
	v_mfma_f32_16x16x32_bf16 v[16:19], v[210:213], v[234:237], v[16:19]
	v_mfma_f32_16x16x32_bf16 v[4:7], v[194:197], v[242:245], v[4:7]
	v_mfma_f32_16x16x32_bf16 v[0:3], v[210:213], v[242:245], v[0:3]
	s_setprio 0
	s_barrier
	s_add_i32 s14, 0, 0x18000
	v_add_u32_e32 v161, s14, v152
	s_add_i32 s15, 0, 0x1c000
	ds_read_b128 v[142:145], v161
	ds_read_b128 v[162:165], v161 offset:1024
	ds_read_b128 v[180:183], v161 offset:2048
	ds_read_b128 v[184:187], v161 offset:3072
	v_add_u32_e32 v161, s15, v152
	ds_read_b128 v[190:193], v161
	ds_read_b128 v[194:197], v161 offset:1024
	ds_read_b128 v[206:209], v161 offset:2048
	ds_read_b128 v[210:213], v161 offset:3072
	s_add_u32 s54, s54, 0x40000
	s_addc_u32 s55, s55, 0
	s_mov_b32 m0, s58
	v_lshl_add_u64 v[248:249], s[54:55], 0, v[128:129]
	ds_read_b128 v[214:217], v160 offset:32768
	ds_read_b128 v[218:221], v160 offset:33792
	ds_read_b128 v[222:225], v160 offset:34816
	ds_read_b128 v[226:229], v160 offset:35840
	ds_read_b128 v[230:233], v160 offset:36864
	ds_read_b128 v[234:237], v160 offset:37888
	ds_read_b128 v[238:241], v160 offset:38912
	ds_read_b128 v[242:245], v160 offset:39936
	global_load_lds_dwordx4 v[248:249], off
	v_lshl_add_u64 v[248:249], s[54:55], 0, v[132:133]
	s_mov_b32 m0, s59
	s_nop 0
	global_load_lds_dwordx4 v[248:249], off
	s_waitcnt vmcnt(8)
	s_waitcnt lgkmcnt(0)
	s_barrier
	s_setprio 1
	v_mfma_f32_16x16x32_bf16 v[124:127], v[142:145], v[214:217], v[124:127]
	v_mfma_f32_16x16x32_bf16 v[120:123], v[180:183], v[214:217], v[120:123]
	v_mfma_f32_16x16x32_bf16 v[108:111], v[142:145], v[222:225], v[108:111]
	v_mfma_f32_16x16x32_bf16 v[104:107], v[180:183], v[222:225], v[104:107]
	v_mfma_f32_16x16x32_bf16 v[92:95], v[142:145], v[230:233], v[92:95]
	v_mfma_f32_16x16x32_bf16 v[88:91], v[180:183], v[230:233], v[88:91]
	v_mfma_f32_16x16x32_bf16 v[76:79], v[142:145], v[238:241], v[76:79]
	v_mfma_f32_16x16x32_bf16 v[72:75], v[180:183], v[238:241], v[72:75]
	v_mfma_f32_16x16x32_bf16 v[124:127], v[162:165], v[218:221], v[124:127]
	v_mfma_f32_16x16x32_bf16 v[120:123], v[184:187], v[218:221], v[120:123]
	v_mfma_f32_16x16x32_bf16 v[108:111], v[162:165], v[226:229], v[108:111]
	v_mfma_f32_16x16x32_bf16 v[104:107], v[184:187], v[226:229], v[104:107]
	v_mfma_f32_16x16x32_bf16 v[92:95], v[162:165], v[234:237], v[92:95]
	v_mfma_f32_16x16x32_bf16 v[88:91], v[184:187], v[234:237], v[88:91]
	v_mfma_f32_16x16x32_bf16 v[76:79], v[162:165], v[242:245], v[76:79]
	v_mfma_f32_16x16x32_bf16 v[72:75], v[184:187], v[242:245], v[72:75]
	v_mfma_f32_16x16x32_bf16 v[116:119], v[190:193], v[214:217], v[116:119]
	v_mfma_f32_16x16x32_bf16 v[112:115], v[206:209], v[214:217], v[112:115]
	v_mfma_f32_16x16x32_bf16 v[100:103], v[190:193], v[222:225], v[100:103]
	v_mfma_f32_16x16x32_bf16 v[96:99], v[206:209], v[222:225], v[96:99]
	v_mfma_f32_16x16x32_bf16 v[84:87], v[190:193], v[230:233], v[84:87]
	v_mfma_f32_16x16x32_bf16 v[80:83], v[206:209], v[230:233], v[80:83]
	v_mfma_f32_16x16x32_bf16 v[68:71], v[190:193], v[238:241], v[68:71]
	v_mfma_f32_16x16x32_bf16 v[64:67], v[206:209], v[238:241], v[64:67]
	v_mfma_f32_16x16x32_bf16 v[116:119], v[194:197], v[218:221], v[116:119]
	v_mfma_f32_16x16x32_bf16 v[112:115], v[210:213], v[218:221], v[112:115]
	v_mfma_f32_16x16x32_bf16 v[100:103], v[194:197], v[226:229], v[100:103]
	v_mfma_f32_16x16x32_bf16 v[96:99], v[210:213], v[226:229], v[96:99]
	v_mfma_f32_16x16x32_bf16 v[84:87], v[194:197], v[234:237], v[84:87]
	v_mfma_f32_16x16x32_bf16 v[80:83], v[210:213], v[234:237], v[80:83]
	v_mfma_f32_16x16x32_bf16 v[68:71], v[194:197], v[242:245], v[68:71]
	v_mfma_f32_16x16x32_bf16 v[64:67], v[210:213], v[242:245], v[64:67]
	s_setprio 0
	s_barrier
; #define PG8_STAGE(bufoff, gbase, voff) do { _Pragma("unroll") for (int _i = 0; _i < 2; ++_i) \
;         __builtin_amdgcn_global_load_lds((const unsigned*)((const char*)(gbase) + (voff)[_i]), (LAS unsigned*)(lds + (bufoff) + ldsw + _i * 8192), 16, 0, 0); } while (0)
; #define PG8_LDA(dst, b, h) do { _Pragma("unroll") for (int m = 0; m < 4; ++m) _Pragma("unroll") for (int k = 0; k < 2; ++k) dst[m][k] = *(const LAS bf16x8*)(lds + PG8_SA(b, h) + aoff + m * 2048 + k * 1024); } while (0)
; #define PG8_LDB(dst, b, h) do { _Pragma("unroll") for (int n = 0; n < 2; ++n) _Pragma("unroll") for (int k = 0; k < 2; ++k) dst[n][k] = *(const LAS bf16x8*)(lds + PG8_SB(b, h) + boff + n * 2048 + k * 1024); } while (0)
; #define PG8_BAR __builtin_amdgcn_s_barrier()
; template <class Epi, class Sched>
; __device__ __forceinline__ void gemm_phase(const int tid, LAS unsigned char* lds, const int lda, const int ldb, const int K, const Sched& S, const Epi& E) {
;     ...
;         for (int t = 0; t < nt; t += 2) {
;             const bool last = (t == nt - 2);
;             const char* a1 = cA + (size_t)(t + 1) * kstep;
;             const char* a2 = last ? nA : cA + (size_t)(t + 2) * kstep; const char* b2 = last ? nB : cB + (size_t)(t + 2) * kstep;
;             const char* a3 = a2 + kstep; const char* b3 = b2 + kstep;
;             PG8_LDB(B0, 0, 0); PG8_LDB(B1, 0, 1); PG8_SCHED; PG8_LDA(At, 0, 0); PG8_STAGE(PG8_SA(1, 1), a1 + hstepA, voffA);
;             PG8_WAIT_V(8); PG8_WAIT_L(0); PG8_BAR; PG8_MMA(0, 0, At, B0); PG8_MMA(0, 1, At, B1); PG8_BAR; PG8_SCHED;
;             PG8_LDA(At, 0, 1); PG8_STAGE(PG8_SB(0, 0), b2, voffB); PG8_STAGE(PG8_SB(0, 1), b2 + hstepB, voffB); PG8_STAGE(PG8_SA(0, 0), a2, voffA);
;             PG8_WAIT_V(8); PG8_WAIT_L(0); PG8_BAR; if (!cur.half) { PG8_MMA(1, 0, At, B0); PG8_MMA(1, 1, At, B1); } PG8_BAR; PG8_SCHED;
;             PG8_LDB(B0, 1, 0); PG8_LDB(B1, 1, 1); PG8_SCHED; PG8_LDA(At, 1, 0); PG8_STAGE(PG8_SA(0, 1), a2 + hstepA, voffA);
;             PG8_WAIT_V(8); PG8_WAIT_L(0); PG8_BAR; PG8_MMA(0, 0, At, B0); PG8_MMA(0, 1, At, B1); PG8_BAR; PG8_SCHED;
;             PG8_LDA(At, 1, 1); PG8_STAGE(PG8_SB(1, 0), b3, voffB); PG8_STAGE(PG8_SB(1, 1), b3 + hstepB, voffB); PG8_STAGE(PG8_SA(1, 0), a3, voffA);
;             PG8_WAIT_V(8); PG8_WAIT_L(0); PG8_BAR; if (!cur.half) { PG8_MMA(1, 0, At, B0); PG8_MMA(1, 1, At, B1); } PG8_BAR; PG8_SCHED;
;         }
	s_add_i32 s14, s14, s31
	v_lshl_add_u64 v[146:147], v[146:147], 0, s[6:7]
	s_mov_b32 m0, s14
	ds_read_b128 v[214:217], v160 offset:49152
	ds_read_b128 v[218:221], v160 offset:50176
	ds_read_b128 v[222:225], v160 offset:51200
	ds_read_b128 v[226:229], v160 offset:52224
	ds_read_b128 v[230:233], v160 offset:53248
	ds_read_b128 v[234:237], v160 offset:54272
	ds_read_b128 v[238:241], v160 offset:55296
	ds_read_b128 v[242:245], v160 offset:56320
	global_load_lds_dwordx4 v[146:147], off
	s_add_i32 m0, s14, 0x2000
	s_add_u32 s52, s52, 0x40080
	v_lshl_add_u64 v[146:147], v[166:167], 0, s[6:7]
	s_addc_u32 s53, s53, 0
	s_add_i32 s14, s15, s31
	global_load_lds_dwordx4 v[146:147], off
	v_lshl_add_u64 v[146:147], s[52:53], 0, v[130:131]
	s_mov_b32 m0, s14
	s_nop 0
	global_load_lds_dwordx4 v[146:147], off
	v_lshl_add_u64 v[146:147], s[52:53], 0, v[134:135]
	s_add_i32 m0, s14, 0x2000
	s_nop 0
	global_load_lds_dwordx4 v[146:147], off
	v_lshl_add_u64 v[146:147], v[176:177], 0, s[6:7]
	s_mov_b32 m0, s60
	s_nop 0
	global_load_lds_dwordx4 v[146:147], off
	v_lshl_add_u64 v[146:147], v[246:247], 0, s[6:7]
	s_mov_b32 m0, s61
	s_nop 0
	global_load_lds_dwordx4 v[146:147], off
	s_waitcnt vmcnt(8)
	s_waitcnt lgkmcnt(0)
	s_barrier
	s_setprio 1
	v_mfma_f32_16x16x32_bf16 v[60:63], v[142:145], v[214:217], v[60:63]
	v_mfma_f32_16x16x32_bf16 v[56:59], v[180:183], v[214:217], v[56:59]
	v_mfma_f32_16x16x32_bf16 v[44:47], v[142:145], v[222:225], v[44:47]
	v_mfma_f32_16x16x32_bf16 v[40:43], v[180:183], v[222:225], v[40:43]
	v_mfma_f32_16x16x32_bf16 v[28:31], v[142:145], v[230:233], v[28:31]
	v_mfma_f32_16x16x32_bf16 v[24:27], v[180:183], v[230:233], v[24:27]
	v_mfma_f32_16x16x32_bf16 v[12:15], v[142:145], v[238:241], v[12:15]
	v_mfma_f32_16x16x32_bf16 v[8:11], v[180:183], v[238:241], v[8:11]
	v_mfma_f32_16x16x32_bf16 v[60:63], v[162:165], v[218:221], v[60:63]
	v_mfma_f32_16x16x32_bf16 v[56:59], v[184:187], v[218:221], v[56:59]
	v_mfma_f32_16x16x32_bf16 v[44:47], v[162:165], v[226:229], v[44:47]
	v_mfma_f32_16x16x32_bf16 v[40:43], v[184:187], v[226:229], v[40:43]
	v_mfma_f32_16x16x32_bf16 v[28:31], v[162:165], v[234:237], v[28:31]
	v_mfma_f32_16x16x32_bf16 v[24:27], v[184:187], v[234:237], v[24:27]
	v_mfma_f32_16x16x32_bf16 v[12:15], v[162:165], v[242:245], v[12:15]
	v_mfma_f32_16x16x32_bf16 v[8:11], v[184:187], v[242:245], v[8:11]
	v_mfma_f32_16x16x32_bf16 v[52:55], v[190:193], v[214:217], v[52:55]
	v_mfma_f32_16x16x32_bf16 v[48:51], v[206:209], v[214:217], v[48:51]
	v_mfma_f32_16x16x32_bf16 v[36:39], v[190:193], v[222:225], v[36:39]
	v_mfma_f32_16x16x32_bf16 v[32:35], v[206:209], v[222:225], v[32:35]
	v_mfma_f32_16x16x32_bf16 v[20:23], v[190:193], v[230:233], v[20:23]
	v_mfma_f32_16x16x32_bf16 v[16:19], v[206:209], v[230:233], v[16:19]
	v_mfma_f32_16x16x32_bf16 v[4:7], v[190:193], v[238:241], v[4:7]
	v_mfma_f32_16x16x32_bf16 v[0:3], v[206:209], v[238:241], v[0:3]
	v_mfma_f32_16x16x32_bf16 v[52:55], v[194:197], v[218:221], v[52:55]
	v_mfma_f32_16x16x32_bf16 v[48:51], v[210:213], v[218:221], v[48:51]
	v_mfma_f32_16x16x32_bf16 v[36:39], v[194:197], v[226:229], v[36:39]
	v_mfma_f32_16x16x32_bf16 v[32:35], v[210:213], v[226:229], v[32:35]
	v_mfma_f32_16x16x32_bf16 v[20:23], v[194:197], v[234:237], v[20:23]
	v_mfma_f32_16x16x32_bf16 v[16:19], v[210:213], v[234:237], v[16:19]
	v_mfma_f32_16x16x32_bf16 v[4:7], v[194:197], v[242:245], v[4:7]
	v_mfma_f32_16x16x32_bf16 v[0:3], v[210:213], v[242:245], v[0:3]
	s_setprio 0
	s_barrier
	s_add_u32 s50, s50, 0x100
	s_addc_u32 s51, s51, 0
	s_add_u32 s26, s26, 0x100
	s_addc_u32 s27, s27, 0
	s_cmp_ge_i32 s67, s29
	s_mov_b32 s45, s67
	s_cbranch_scc1 .Lkexit_681
.LBB0_681:
	s_add_i32 s67, s45, 2
	s_add_u32 s14, s50, 0xfffc0080
	s_addc_u32 s15, s51, -1
	s_add_i32 s24, 0, 0x10000
	s_cmp_eq_u32 s63, s45
	s_cselect_b32 s55, s3, s15
	s_cselect_b32 s54, s2, s14
	v_add_u32_e32 v146, s24, v152
	s_cselect_b32 s53, s39, s27
	s_cselect_b32 s52, s38, s26
	s_add_i32 s14, 0, 0x14000
	ds_read_b128 v[142:145], v146
	ds_read_b128 v[162:165], v146 offset:1024
	ds_read_b128 v[180:183], v146 offset:2048
	ds_read_b128 v[184:187], v146 offset:3072
	v_add_u32_e32 v146, s14, v152
	ds_read_b128 v[190:193], v146
	ds_read_b128 v[194:197], v146 offset:1024
	ds_read_b128 v[206:209], v146 offset:2048
	ds_read_b128 v[210:213], v146 offset:3072
	v_lshl_add_u64 v[146:147], s[50:51], 0, v[136:137]
	s_add_i32 m0, s56, 0xc000
	ds_read_b128 v[214:217], v160
	ds_read_b128 v[218:221], v160 offset:1024
	ds_read_b128 v[222:225], v160 offset:2048
	ds_read_b128 v[226:229], v160 offset:3072
	ds_read_b128 v[230:233], v160 offset:4096
	ds_read_b128 v[234:237], v160 offset:5120
	ds_read_b128 v[238:241], v160 offset:6144
	ds_read_b128 v[242:245], v160 offset:7168
	global_load_lds_dwordx4 v[146:147], off
	v_lshl_add_u64 v[146:147], s[50:51], 0, v[138:139]
	s_add_i32 m0, s56, 0xe000
	s_nop 0
	global_load_lds_dwordx4 v[146:147], off
	s_waitcnt vmcnt(8)
	s_waitcnt lgkmcnt(0)
	s_barrier
; #define PG8_STAGE(bufoff, gbase, voff) do { _Pragma("unroll") for (int _i = 0; _i < 2; ++_i) \
;         __builtin_amdgcn_global_load_lds((const unsigned*)((const char*)(gbase) + (voff)[_i]), (LAS unsigned*)(lds + (bufoff) + ldsw + _i * 8192), 16, 0, 0); } while (0)
; #define PG8_LDA(dst, b, h) do { _Pragma("unroll") for (int m = 0; m < 4; ++m) _Pragma("unroll") for (int k = 0; k < 2; ++k) dst[m][k] = *(const LAS bf16x8*)(lds + PG8_SA(b, h) + aoff + m * 2048 + k * 1024); } while (0)
; #define PG8_LDB(dst, b, h) do { _Pragma("unroll") for (int n = 0; n < 2; ++n) _Pragma("unroll") for (int k = 0; k < 2; ++k) dst[n][k] = *(const LAS bf16x8*)(lds + PG8_SB(b, h) + boff + n * 2048 + k * 1024); } while (0)
; #define PG8_MMA(ai, bj, At, Bt) do { __builtin_amdgcn_s_setprio(1); _Pragma("unroll") for (int m = 0; m < 4; ++m) _Pragma("unroll") for (int n = 0; n < 2; ++n) _Pragma("unroll") for (int k = 0; k < 2; ++k) \
;         acc[ai][bj][m][n] = __builtin_amdgcn_mfma_f32_16x16x32_bf16(Bt[n][k], At[m][k], acc[ai][bj][m][n], 0, 0, 0); __builtin_amdgcn_s_setprio(0); } while (0)
; #define PG8_WAIT_V(n) asm volatile("s_waitcnt vmcnt(" #n ")" ::: "memory")
; #define PG8_WAIT_L(n) asm volatile("s_waitcnt lgkmcnt(" #n ")" ::: "memory")
; #define PG8_BAR __builtin_amdgcn_s_barrier()
; #define PG8_SCHED __builtin_amdgcn_sched_barrier(0)
; template <class Epi, class Sched>
; __device__ __forceinline__ void gemm_phase(const int tid, LAS unsigned char* lds, const int lda, const int ldb, const int K, const Sched& S, const Epi& E) {
;     ...
;             PG8_WAIT_V(8); PG8_WAIT_L(0); PG8_BAR; PG8_MMA(0, 0, At, B0); PG8_MMA(0, 1, At, B1); PG8_BAR; PG8_SCHED;
;             PG8_LDA(At, 0, 1); PG8_STAGE(PG8_SB(0, 0), b2, voffB); PG8_STAGE(PG8_SB(0, 1), b2 + hstepB, voffB); PG8_STAGE(PG8_SA(0, 0), a2, voffA);
;             PG8_WAIT_V(8); PG8_WAIT_L(0); PG8_BAR; if (!cur.half) { PG8_MMA(1, 0, At, B0); PG8_MMA(1, 1, At, B1); } PG8_BAR; PG8_SCHED;
;             PG8_LDB(B0, 1, 0); PG8_LDB(B1, 1, 1); PG8_SCHED; PG8_LDA(At, 1, 0); PG8_STAGE(PG8_SA(0, 1), a2 + hstepA, voffA);
;             PG8_WAIT_V(8); PG8_WAIT_L(0); PG8_BAR; PG8_MMA(0, 0, At, B0); PG8_MMA(0, 1, At, B1); PG8_BAR; PG8_SCHED;
	s_setprio 1
	v_mfma_f32_16x16x32_bf16 v[124:127], v[142:145], v[214:217], v[124:127]
	v_mfma_f32_16x16x32_bf16 v[120:123], v[180:183], v[214:217], v[120:123]
	v_mfma_f32_16x16x32_bf16 v[108:111], v[142:145], v[222:225], v[108:111]
	v_mfma_f32_16x16x32_bf16 v[104:107], v[180:183], v[222:225], v[104:107]
	v_mfma_f32_16x16x32_bf16 v[92:95], v[142:145], v[230:233], v[92:95]
	v_mfma_f32_16x16x32_bf16 v[88:91], v[180:183], v[230:233], v[88:91]
	v_mfma_f32_16x16x32_bf16 v[76:79], v[142:145], v[238:241], v[76:79]
	v_mfma_f32_16x16x32_bf16 v[72:75], v[180:183], v[238:241], v[72:75]
	v_mfma_f32_16x16x32_bf16 v[124:127], v[162:165], v[218:221], v[124:127]
	v_mfma_f32_16x16x32_bf16 v[120:123], v[184:187], v[218:221], v[120:123]
	v_mfma_f32_16x16x32_bf16 v[108:111], v[162:165], v[226:229], v[108:111]
	v_mfma_f32_16x16x32_bf16 v[104:107], v[184:187], v[226:229], v[104:107]
	v_mfma_f32_16x16x32_bf16 v[92:95], v[162:165], v[234:237], v[92:95]
	v_mfma_f32_16x16x32_bf16 v[88:91], v[184:187], v[234:237], v[88:91]
	v_mfma_f32_16x16x32_bf16 v[76:79], v[162:165], v[242:245], v[76:79]
	v_mfma_f32_16x16x32_bf16 v[72:75], v[184:187], v[242:245], v[72:75]
	v_mfma_f32_16x16x32_bf16 v[116:119], v[190:193], v[214:217], v[116:119]
	v_mfma_f32_16x16x32_bf16 v[112:115], v[206:209], v[214:217], v[112:115]
	v_mfma_f32_16x16x32_bf16 v[100:103], v[190:193], v[222:225], v[100:103]
	v_mfma_f32_16x16x32_bf16 v[96:99], v[206:209], v[222:225], v[96:99]
	v_mfma_f32_16x16x32_bf16 v[84:87], v[190:193], v[230:233], v[84:87]
	v_mfma_f32_16x16x32_bf16 v[80:83], v[206:209], v[230:233], v[80:83]
	v_mfma_f32_16x16x32_bf16 v[68:71], v[190:193], v[238:241], v[68:71]
	v_mfma_f32_16x16x32_bf16 v[64:67], v[206:209], v[238:241], v[64:67]
	v_mfma_f32_16x16x32_bf16 v[116:119], v[194:197], v[218:221], v[116:119]
	v_mfma_f32_16x16x32_bf16 v[112:115], v[210:213], v[218:221], v[112:115]
	v_mfma_f32_16x16x32_bf16 v[100:103], v[194:197], v[226:229], v[100:103]
	v_mfma_f32_16x16x32_bf16 v[96:99], v[210:213], v[226:229], v[96:99]
	v_mfma_f32_16x16x32_bf16 v[84:87], v[194:197], v[234:237], v[84:87]
	v_mfma_f32_16x16x32_bf16 v[80:83], v[210:213], v[234:237], v[80:83]
	v_mfma_f32_16x16x32_bf16 v[68:71], v[194:197], v[242:245], v[68:71]
	v_mfma_f32_16x16x32_bf16 v[64:67], v[210:213], v[242:245], v[64:67]
	s_setprio 0
	s_barrier
	s_add_i32 s15, s24, s31
	v_lshl_add_u64 v[146:147], s[52:53], 0, v[130:131]
	s_mov_b32 m0, s15
	ds_read_b128 v[214:217], v160 offset:16384
	ds_read_b128 v[218:221], v160 offset:17408
	ds_read_b128 v[222:225], v160 offset:18432
	ds_read_b128 v[226:229], v160 offset:19456
	ds_read_b128 v[230:233], v160 offset:20480
	ds_read_b128 v[234:237], v160 offset:21504
	ds_read_b128 v[238:241], v160 offset:22528
	ds_read_b128 v[242:245], v160 offset:23552
	global_load_lds_dwordx4 v[146:147], off
	s_add_i32 m0, s15, 0x2000
	s_add_u32 s68, s52, 0x40000
	v_lshl_add_u64 v[166:167], s[52:53], 0, v[134:135]
	s_addc_u32 s69, s53, 0
	s_add_i32 s14, s14, s31
	global_load_lds_dwordx4 v[166:167], off
	v_lshl_add_u64 v[176:177], s[68:69], 0, v[130:131]
	s_mov_b32 m0, s14
	v_lshl_add_u64 v[246:247], s[54:55], 0, v[132:133]
	global_load_lds_dwordx4 v[176:177], off
	v_lshl_add_u64 v[176:177], s[68:69], 0, v[134:135]
	s_add_i32 m0, s14, 0x2000
	s_nop 0
	global_load_lds_dwordx4 v[176:177], off
	v_lshl_add_u64 v[176:177], s[54:55], 0, v[128:129]
	s_mov_b32 m0, s56
	s_nop 0
	global_load_lds_dwordx4 v[176:177], off
	s_mov_b32 m0, s57
	s_nop 0
	global_load_lds_dwordx4 v[246:247], off
	s_waitcnt vmcnt(8)
	s_waitcnt lgkmcnt(0)
	s_barrier
	s_setprio 1
	v_mfma_f32_16x16x32_bf16 v[60:63], v[142:145], v[214:217], v[60:63]
	v_mfma_f32_16x16x32_bf16 v[56:59], v[180:183], v[214:217], v[56:59]
	v_mfma_f32_16x16x32_bf16 v[44:47], v[142:145], v[222:225], v[44:47]
	v_mfma_f32_16x16x32_bf16 v[40:43], v[180:183], v[222:225], v[40:43]
	v_mfma_f32_16x16x32_bf16 v[28:31], v[142:145], v[230:233], v[28:31]
	v_mfma_f32_16x16x32_bf16 v[24:27], v[180:183], v[230:233], v[24:27]
	v_mfma_f32_16x16x32_bf16 v[12:15], v[142:145], v[238:241], v[12:15]
	v_mfma_f32_16x16x32_bf16 v[8:11], v[180:183], v[238:241], v[8:11]
	v_mfma_f32_16x16x32_bf16 v[60:63], v[162:165], v[218:221], v[60:63]
	v_mfma_f32_16x16x32_bf16 v[56:59], v[184:187], v[218:221], v[56:59]
	v_mfma_f32_16x16x32_bf16 v[44:47], v[162:165], v[226:229], v[44:47]
	v_mfma_f32_16x16x32_bf16 v[40:43], v[184:187], v[226:229], v[40:43]
	v_mfma_f32_16x16x32_bf16 v[28:31], v[162:165], v[234:237], v[28:31]
	v_mfma_f32_16x16x32_bf16 v[24:27], v[184:187], v[234:237], v[24:27]
	v_mfma_f32_16x16x32_bf16 v[12:15], v[162:165], v[242:245], v[12:15]
	v_mfma_f32_16x16x32_bf16 v[8:11], v[184:187], v[242:245], v[8:11]
	v_mfma_f32_16x16x32_bf16 v[52:55], v[190:193], v[214:217], v[52:55]
	v_mfma_f32_16x16x32_bf16 v[48:51], v[206:209], v[214:217], v[48:51]
	v_mfma_f32_16x16x32_bf16 v[36:39], v[190:193], v[222:225], v[36:39]
	v_mfma_f32_16x16x32_bf16 v[32:35], v[206:209], v[222:225], v[32:35]
	v_mfma_f32_16x16x32_bf16 v[20:23], v[190:193], v[230:233], v[20:23]
	v_mfma_f32_16x16x32_bf16 v[16:19], v[206:209], v[230:233], v[16:19]
	v_mfma_f32_16x16x32_bf16 v[4:7], v[190:193], v[238:241], v[4:7]
	v_mfma_f32_16x16x32_bf16 v[0:3], v[206:209], v[238:241], v[0:3]
	v_mfma_f32_16x16x32_bf16 v[52:55], v[194:197], v[218:221], v[52:55]
	v_mfma_f32_16x16x32_bf16 v[48:51], v[210:213], v[218:221], v[48:51]
	v_mfma_f32_16x16x32_bf16 v[36:39], v[194:197], v[226:229], v[36:39]
	v_mfma_f32_16x16x32_bf16 v[32:35], v[210:213], v[226:229], v[32:35]
	v_mfma_f32_16x16x32_bf16 v[20:23], v[194:197], v[234:237], v[20:23]
	v_mfma_f32_16x16x32_bf16 v[16:19], v[210:213], v[234:237], v[16:19]
	v_mfma_f32_16x16x32_bf16 v[4:7], v[194:197], v[242:245], v[4:7]
	v_mfma_f32_16x16x32_bf16 v[0:3], v[210:213], v[242:245], v[0:3]
	s_setprio 0
	s_barrier
; #define PG8_STAGE(bufoff, gbase, voff) do { _Pragma("unroll") for (int _i = 0; _i < 2; ++_i) \
;         __builtin_amdgcn_global_load_lds((const unsigned*)((const char*)(gbase) + (voff)[_i]), (LAS unsigned*)(lds + (bufoff) + ldsw + _i * 8192), 16, 0, 0); } while (0)
; #define PG8_LDA(dst, b, h) do { _Pragma("unroll") for (int m = 0; m < 4; ++m) _Pragma("unroll") for (int k = 0; k < 2; ++k) dst[m][k] = *(const LAS bf16x8*)(lds + PG8_SA(b, h) + aoff + m * 2048 + k * 1024); } while (0)
; #define PG8_LDB(dst, b, h) do { _Pragma("unroll") for (int n = 0; n < 2; ++n) _Pragma("unroll") for (int k = 0; k < 2; ++k) dst[n][k] = *(const LAS bf16x8*)(lds + PG8_SB(b, h) + boff + n * 2048 + k * 1024); } while (0)
; #define PG8_MMA(ai, bj, At, Bt) do { __builtin_amdgcn_s_setprio(1); _Pragma("unroll") for (int m = 0; m < 4; ++m) _Pragma("unroll") for (int n = 0; n < 2; ++n) _Pragma("unroll") for (int k = 0; k < 2; ++k) \
;         acc[ai][bj][m][n] = __builtin_amdgcn_mfma_f32_16x16x32_bf16(Bt[n][k], At[m][k], acc[ai][bj][m][n], 0, 0, 0); __builtin_amdgcn_s_setprio(0); } while (0)
; #define PG8_WAIT_V(n) asm volatile("s_waitcnt vmcnt(" #n ")" ::: "memory")
; #define PG8_WAIT_L(n) asm volatile("s_waitcnt lgkmcnt(" #n ")" ::: "memory")
; #define PG8_BAR __builtin_amdgcn_s_barrier()
; #define PG8_SCHED __builtin_amdgcn_sched_barrier(0)
; template <class Epi, class Sched>
; __device__ __forceinline__ void gemm_phase(const int tid, LAS unsigned char* lds, const int lda, const int ldb, const int K, const Sched& S, const Epi& E) {
;     ...
;             PG8_LDB(B0, 1, 0); PG8_LDB(B1, 1, 1); PG8_SCHED; PG8_LDA(At, 1, 0); PG8_STAGE(PG8_SA(0, 1), a2 + hstepA, voffA);
;             PG8_WAIT_V(8); PG8_WAIT_L(0); PG8_BAR; PG8_MMA(0, 0, At, B0); PG8_MMA(0, 1, At, B1); PG8_BAR; PG8_SCHED;
;             PG8_LDA(At, 1, 1); PG8_STAGE(PG8_SB(1, 0), b3, voffB); PG8_STAGE(PG8_SB(1, 1), b3 + hstepB, voffB); PG8_STAGE(PG8_SA(1, 0), a3, voffA);
;             PG8_WAIT_V(8); PG8_WAIT_L(0); PG8_BAR; if (!cur.half) { PG8_MMA(1, 0, At, B0); PG8_MMA(1, 1, At, B1); } PG8_BAR; PG8_SCHED;
;         }
	s_add_i32 s14, 0, 0x18000
	v_add_u32_e32 v161, s14, v152
	s_add_i32 s15, 0, 0x1c000
	ds_read_b128 v[142:145], v161
	ds_read_b128 v[162:165], v161 offset:1024
	ds_read_b128 v[180:183], v161 offset:2048
	ds_read_b128 v[184:187], v161 offset:3072
	v_add_u32_e32 v161, s15, v152
	ds_read_b128 v[190:193], v161
	ds_read_b128 v[194:197], v161 offset:1024
	ds_read_b128 v[206:209], v161 offset:2048
	ds_read_b128 v[210:213], v161 offset:3072
	s_add_u32 s54, s54, 0x40000
	s_addc_u32 s55, s55, 0
	s_mov_b32 m0, s58
	v_lshl_add_u64 v[248:249], s[54:55], 0, v[128:129]
	ds_read_b128 v[214:217], v160 offset:32768
	ds_read_b128 v[218:221], v160 offset:33792
	ds_read_b128 v[222:225], v160 offset:34816
	ds_read_b128 v[226:229], v160 offset:35840
	ds_read_b128 v[230:233], v160 offset:36864
	ds_read_b128 v[234:237], v160 offset:37888
	ds_read_b128 v[238:241], v160 offset:38912
	ds_read_b128 v[242:245], v160 offset:39936
	global_load_lds_dwordx4 v[248:249], off
	v_lshl_add_u64 v[248:249], s[54:55], 0, v[132:133]
	s_mov_b32 m0, s59
	s_nop 0
	global_load_lds_dwordx4 v[248:249], off
	s_waitcnt vmcnt(8)
	s_waitcnt lgkmcnt(0)
	s_barrier
	s_setprio 1
	v_mfma_f32_16x16x32_bf16 v[124:127], v[142:145], v[214:217], v[124:127]
	v_mfma_f32_16x16x32_bf16 v[120:123], v[180:183], v[214:217], v[120:123]
	v_mfma_f32_16x16x32_bf16 v[108:111], v[142:145], v[222:225], v[108:111]
	v_mfma_f32_16x16x32_bf16 v[104:107], v[180:183], v[222:225], v[104:107]
	v_mfma_f32_16x16x32_bf16 v[92:95], v[142:145], v[230:233], v[92:95]
	v_mfma_f32_16x16x32_bf16 v[88:91], v[180:183], v[230:233], v[88:91]
	v_mfma_f32_16x16x32_bf16 v[76:79], v[142:145], v[238:241], v[76:79]
	v_mfma_f32_16x16x32_bf16 v[72:75], v[180:183], v[238:241], v[72:75]
	v_mfma_f32_16x16x32_bf16 v[124:127], v[162:165], v[218:221], v[124:127]
	v_mfma_f32_16x16x32_bf16 v[120:123], v[184:187], v[218:221], v[120:123]
	v_mfma_f32_16x16x32_bf16 v[108:111], v[162:165], v[226:229], v[108:111]
	v_mfma_f32_16x16x32_bf16 v[104:107], v[184:187], v[226:229], v[104:107]
	v_mfma_f32_16x16x32_bf16 v[92:95], v[162:165], v[234:237], v[92:95]
	v_mfma_f32_16x16x32_bf16 v[88:91], v[184:187], v[234:237], v[88:91]
	v_mfma_f32_16x16x32_bf16 v[76:79], v[162:165], v[242:245], v[76:79]
	v_mfma_f32_16x16x32_bf16 v[72:75], v[184:187], v[242:245], v[72:75]
	v_mfma_f32_16x16x32_bf16 v[116:119], v[190:193], v[214:217], v[116:119]
	v_mfma_f32_16x16x32_bf16 v[112:115], v[206:209], v[214:217], v[112:115]
	v_mfma_f32_16x16x32_bf16 v[100:103], v[190:193], v[222:225], v[100:103]
	v_mfma_f32_16x16x32_bf16 v[96:99], v[206:209], v[222:225], v[96:99]
	v_mfma_f32_16x16x32_bf16 v[84:87], v[190:193], v[230:233], v[84:87]
	v_mfma_f32_16x16x32_bf16 v[80:83], v[206:209], v[230:233], v[80:83]
	v_mfma_f32_16x16x32_bf16 v[68:71], v[190:193], v[238:241], v[68:71]
	v_mfma_f32_16x16x32_bf16 v[64:67], v[206:209], v[238:241], v[64:67]
	v_mfma_f32_16x16x32_bf16 v[116:119], v[194:197], v[218:221], v[116:119]
	v_mfma_f32_16x16x32_bf16 v[112:115], v[210:213], v[218:221], v[112:115]
	v_mfma_f32_16x16x32_bf16 v[100:103], v[194:197], v[226:229], v[100:103]
	v_mfma_f32_16x16x32_bf16 v[96:99], v[210:213], v[226:229], v[96:99]
	v_mfma_f32_16x16x32_bf16 v[84:87], v[194:197], v[234:237], v[84:87]
	v_mfma_f32_16x16x32_bf16 v[80:83], v[210:213], v[234:237], v[80:83]
	v_mfma_f32_16x16x32_bf16 v[68:71], v[194:197], v[242:245], v[68:71]
	v_mfma_f32_16x16x32_bf16 v[64:67], v[210:213], v[242:245], v[64:67]
	s_setprio 0
	s_barrier
	s_add_i32 s14, s14, s31
	v_lshl_add_u64 v[146:147], v[146:147], 0, s[6:7]
	s_mov_b32 m0, s14
	ds_read_b128 v[214:217], v160 offset:49152
	ds_read_b128 v[218:221], v160 offset:50176
	ds_read_b128 v[222:225], v160 offset:51200
	ds_read_b128 v[226:229], v160 offset:52224
	ds_read_b128 v[230:233], v160 offset:53248
	ds_read_b128 v[234:237], v160 offset:54272
	ds_read_b128 v[238:241], v160 offset:55296
	ds_read_b128 v[242:245], v160 offset:56320
	global_load_lds_dwordx4 v[146:147], off
	s_add_i32 m0, s14, 0x2000
	s_add_u32 s52, s52, 0x40080
	v_lshl_add_u64 v[146:147], v[166:167], 0, s[6:7]
	s_addc_u32 s53, s53, 0
	s_add_i32 s14, s15, s31
	global_load_lds_dwordx4 v[146:147], off
	v_lshl_add_u64 v[146:147], s[52:53], 0, v[130:131]
	s_mov_b32 m0, s14
	s_nop 0
	global_load_lds_dwordx4 v[146:147], off
	v_lshl_add_u64 v[146:147], s[52:53], 0, v[134:135]
	s_add_i32 m0, s14, 0x2000
	s_nop 0
	global_load_lds_dwordx4 v[146:147], off
	v_lshl_add_u64 v[146:147], v[176:177], 0, s[6:7]
	s_mov_b32 m0, s60
	s_nop 0
	global_load_lds_dwordx4 v[146:147], off
	v_lshl_add_u64 v[146:147], v[246:247], 0, s[6:7]
	s_mov_b32 m0, s61
	s_nop 0
	global_load_lds_dwordx4 v[146:147], off
	s_waitcnt vmcnt(8)
	s_waitcnt lgkmcnt(0)
	s_barrier
	s_setprio 1
	v_mfma_f32_16x16x32_bf16 v[60:63], v[142:145], v[214:217], v[60:63]
	v_mfma_f32_16x16x32_bf16 v[56:59], v[180:183], v[214:217], v[56:59]
	v_mfma_f32_16x16x32_bf16 v[44:47], v[142:145], v[222:225], v[44:47]
	v_mfma_f32_16x16x32_bf16 v[40:43], v[180:183], v[222:225], v[40:43]
	v_mfma_f32_16x16x32_bf16 v[28:31], v[142:145], v[230:233], v[28:31]
	v_mfma_f32_16x16x32_bf16 v[24:27], v[180:183], v[230:233], v[24:27]
	v_mfma_f32_16x16x32_bf16 v[12:15], v[142:145], v[238:241], v[12:15]
	v_mfma_f32_16x16x32_bf16 v[8:11], v[180:183], v[238:241], v[8:11]
	v_mfma_f32_16x16x32_bf16 v[60:63], v[162:165], v[218:221], v[60:63]
	v_mfma_f32_16x16x32_bf16 v[56:59], v[184:187], v[218:221], v[56:59]
	v_mfma_f32_16x16x32_bf16 v[44:47], v[162:165], v[226:229], v[44:47]
	v_mfma_f32_16x16x32_bf16 v[40:43], v[184:187], v[226:229], v[40:43]
	v_mfma_f32_16x16x32_bf16 v[28:31], v[162:165], v[234:237], v[28:31]
	v_mfma_f32_16x16x32_bf16 v[24:27], v[184:187], v[234:237], v[24:27]
	v_mfma_f32_16x16x32_bf16 v[12:15], v[162:165], v[242:245], v[12:15]
	v_mfma_f32_16x16x32_bf16 v[8:11], v[184:187], v[242:245], v[8:11]
	v_mfma_f32_16x16x32_bf16 v[52:55], v[190:193], v[214:217], v[52:55]
	v_mfma_f32_16x16x32_bf16 v[48:51], v[206:209], v[214:217], v[48:51]
	v_mfma_f32_16x16x32_bf16 v[36:39], v[190:193], v[222:225], v[36:39]
	v_mfma_f32_16x16x32_bf16 v[32:35], v[206:209], v[222:225], v[32:35]
	v_mfma_f32_16x16x32_bf16 v[20:23], v[190:193], v[230:233], v[20:23]
	v_mfma_f32_16x16x32_bf16 v[16:19], v[206:209], v[230:233], v[16:19]
	v_mfma_f32_16x16x32_bf16 v[4:7], v[190:193], v[238:241], v[4:7]
	v_mfma_f32_16x16x32_bf16 v[0:3], v[206:209], v[238:241], v[0:3]
	v_mfma_f32_16x16x32_bf16 v[52:55], v[194:197], v[218:221], v[52:55]
	v_mfma_f32_16x16x32_bf16 v[48:51], v[210:213], v[218:221], v[48:51]
	v_mfma_f32_16x16x32_bf16 v[36:39], v[194:197], v[226:229], v[36:39]
	v_mfma_f32_16x16x32_bf16 v[32:35], v[210:213], v[226:229], v[32:35]
	v_mfma_f32_16x16x32_bf16 v[20:23], v[194:197], v[234:237], v[20:23]
	v_mfma_f32_16x16x32_bf16 v[16:19], v[210:213], v[234:237], v[16:19]
	v_mfma_f32_16x16x32_bf16 v[4:7], v[194:197], v[242:245], v[4:7]
	v_mfma_f32_16x16x32_bf16 v[0:3], v[210:213], v[242:245], v[0:3]
	s_setprio 0
	s_barrier
	s_add_u32 s50, s50, 0x100
	s_addc_u32 s51, s51, 0
	s_add_u32 s26, s26, 0x100
	s_addc_u32 s27, s27, 0
	s_cmp_ge_i32 s67, s29
	s_mov_b32 s45, s67
	s_cbranch_scc0 .LBB0_681

; #define PG8_STAGE(bufoff, gbase, voff) do { _Pragma("unroll") for (int _i = 0; _i < 2; ++_i) \
;         __builtin_amdgcn_global_load_lds((const unsigned*)((const char*)(gbase) + (voff)[_i]), (LAS unsigned*)(lds + (bufoff) + ldsw + _i * 8192), 16, 0, 0); } while (0)
; #define PG8_LDA(dst, b, h) do { _Pragma("unroll") for (int m = 0; m < 4; ++m) _Pragma("unroll") for (int k = 0; k < 2; ++k) dst[m][k] = *(const LAS bf16x8*)(lds + PG8_SA(b, h) + aoff + m * 2048 + k * 1024); } while (0)
; #define PG8_LDB(dst, b, h) do { _Pragma("unroll") for (int n = 0; n < 2; ++n) _Pragma("unroll") for (int k = 0; k < 2; ++k) dst[n][k] = *(const LAS bf16x8*)(lds + PG8_SB(b, h) + boff + n * 2048 + k * 1024); } while (0)
; #define PG8_MMA(ai, bj, At, Bt) do { __builtin_amdgcn_s_setprio(1); _Pragma("unroll") for (int m = 0; m < 4; ++m) _Pragma("unroll") for (int n = 0; n < 2; ++n) _Pragma("unroll") for (int k = 0; k < 2; ++k) \
;         acc[ai][bj][m][n] = __builtin_amdgcn_mfma_f32_16x16x32_bf16(Bt[n][k], At[m][k], acc[ai][bj][m][n], 0, 0, 0); __builtin_amdgcn_s_setprio(0); } while (0)
; #define PG8_BAR __builtin_amdgcn_s_barrier()
; template <class Epi, class Sched>
; __device__ __forceinline__ void gemm_phase(const int tid, LAS unsigned char* lds, const int lda, const int ldb, const int K, const Sched& S, const Epi& E) {
;     ...
;     for (;;) {
;         const bool has_next = S.next(ui + 1, nxt);
;         const char* nA = has_next ? nxt.a : cA; const char* nB = has_next ? nxt.b : cB;
;         for (int t = 0; t < nt; t += 2) {
;             const bool last = (t == nt - 2);
;             const char* a1 = cA + (size_t)(t + 1) * kstep;
;             const char* a2 = last ? nA : cA + (size_t)(t + 2) * kstep; const char* b2 = last ? nB : cB + (size_t)(t + 2) * kstep;
;             const char* a3 = a2 + kstep; const char* b3 = b2 + kstep;
;             PG8_LDB(B0, 0, 0); PG8_LDB(B1, 0, 1); PG8_SCHED; PG8_LDA(At, 0, 0); PG8_STAGE(PG8_SA(1, 1), a1 + hstepA, voffA);
;             PG8_WAIT_V(8); PG8_WAIT_L(0); PG8_BAR; PG8_MMA(0, 0, At, B0); PG8_MMA(0, 1, At, B1); PG8_BAR; PG8_SCHED;
;             PG8_LDA(At, 0, 1); PG8_STAGE(PG8_SB(0, 0), b2, voffB); PG8_STAGE(PG8_SB(0, 1), b2 + hstepB, voffB); PG8_STAGE(PG8_SA(0, 0), a2, voffA);
;             PG8_WAIT_V(8); PG8_WAIT_L(0); PG8_BAR; if (!cur.half) { PG8_MMA(1, 0, At, B0); PG8_MMA(1, 1, At, B1); } PG8_BAR; PG8_SCHED;
.LBB0_752:
	s_andn2_b64 vcc, exec, s[52:53]
	s_cbranch_vccnz .LBB0_755
	s_add_u32 s64, s64, 0x40080
	s_addc_u32 s65, s65, 0
	s_add_u32 s26, s66, 0x100
	s_addc_u32 s27, s67, 0
	s_mov_b32 s57, 0
	s_waitcnt lgkmcnt(0)
	s_add_i32 vcc_lo, s57, 2
	s_add_u32 s14, s64, 0xfffc0080
	s_addc_u32 s15, s65, -1
	s_add_i32 s24, 0, 0x10000
	s_cmp_eq_u32 s75, s57
	s_cselect_b32 s69, s3, s15
	s_cselect_b32 s68, s2, s14
	s_cselect_b32 s67, s63, s27
	s_cselect_b32 s66, s62, s26
	s_add_i32 s14, 0, 0x14000
	v_add_u32_e32 v140, s24, v182
	v_add_u32_e32 v166, s14, v182
	ds_read_b128 v[128:131], v140
	ds_read_b128 v[132:135], v140 offset:1024
	ds_read_b128 v[136:139], v140 offset:2048
	ds_read_b128 v[140:143], v140 offset:3072
	ds_read_b128 v[144:147], v166
	ds_read_b128 v[148:151], v166 offset:1024
	ds_read_b128 v[190:193], v166 offset:2048
	ds_read_b128 v[194:197], v166 offset:3072
	v_lshl_add_u64 v[166:167], s[64:65], 0, v[162:163]
	s_add_i32 m0, s31, 0xc000
	ds_read_b128 v[206:209], v188
	ds_read_b128 v[210:213], v188 offset:1024
	ds_read_b128 v[214:217], v188 offset:2048
	ds_read_b128 v[218:221], v188 offset:3072
	ds_read_b128 v[222:225], v188 offset:4096
	ds_read_b128 v[226:229], v188 offset:5120
	ds_read_b128 v[230:233], v188 offset:6144
	ds_read_b128 v[234:237], v188 offset:7168
	global_load_lds_dwordx4 v[166:167], off
	v_lshl_add_u64 v[166:167], s[64:65], 0, v[164:165]
	s_add_i32 m0, s31, 0xe000
	s_nop 0
	global_load_lds_dwordx4 v[166:167], off
	s_waitcnt vmcnt(8)
	s_waitcnt lgkmcnt(0)
	s_barrier
	s_setprio 1
	v_mfma_f32_16x16x32_bf16 v[116:119], v[128:131], v[206:209], 0
	v_mfma_f32_16x16x32_bf16 v[112:115], v[136:139], v[206:209], 0
	v_mfma_f32_16x16x32_bf16 v[100:103], v[128:131], v[214:217], 0
	v_mfma_f32_16x16x32_bf16 v[96:99], v[136:139], v[214:217], 0
	v_mfma_f32_16x16x32_bf16 v[84:87], v[128:131], v[222:225], 0
	v_mfma_f32_16x16x32_bf16 v[80:83], v[136:139], v[222:225], 0
	v_mfma_f32_16x16x32_bf16 v[68:71], v[128:131], v[230:233], 0
	v_mfma_f32_16x16x32_bf16 v[64:67], v[136:139], v[230:233], 0
	v_mfma_f32_16x16x32_bf16 v[116:119], v[132:135], v[210:213], v[116:119]
	v_mfma_f32_16x16x32_bf16 v[112:115], v[140:143], v[210:213], v[112:115]
	v_mfma_f32_16x16x32_bf16 v[100:103], v[132:135], v[218:221], v[100:103]
	v_mfma_f32_16x16x32_bf16 v[96:99], v[140:143], v[218:221], v[96:99]
	v_mfma_f32_16x16x32_bf16 v[84:87], v[132:135], v[226:229], v[84:87]
	v_mfma_f32_16x16x32_bf16 v[80:83], v[140:143], v[226:229], v[80:83]
	v_mfma_f32_16x16x32_bf16 v[68:71], v[132:135], v[234:237], v[68:71]
	v_mfma_f32_16x16x32_bf16 v[64:67], v[140:143], v[234:237], v[64:67]
	v_mfma_f32_16x16x32_bf16 v[124:127], v[144:147], v[206:209], 0
	v_mfma_f32_16x16x32_bf16 v[120:123], v[190:193], v[206:209], 0
	v_mfma_f32_16x16x32_bf16 v[108:111], v[144:147], v[214:217], 0
	v_mfma_f32_16x16x32_bf16 v[104:107], v[190:193], v[214:217], 0
	v_mfma_f32_16x16x32_bf16 v[92:95], v[144:147], v[222:225], 0
	v_mfma_f32_16x16x32_bf16 v[88:91], v[190:193], v[222:225], 0
	v_mfma_f32_16x16x32_bf16 v[76:79], v[144:147], v[230:233], 0
	v_mfma_f32_16x16x32_bf16 v[72:75], v[190:193], v[230:233], 0
	v_mfma_f32_16x16x32_bf16 v[124:127], v[148:151], v[210:213], v[124:127]
	v_mfma_f32_16x16x32_bf16 v[120:123], v[194:197], v[210:213], v[120:123]
	v_mfma_f32_16x16x32_bf16 v[108:111], v[148:151], v[218:221], v[108:111]
	v_mfma_f32_16x16x32_bf16 v[104:107], v[194:197], v[218:221], v[104:107]
	v_mfma_f32_16x16x32_bf16 v[92:95], v[148:151], v[226:229], v[92:95]
	v_mfma_f32_16x16x32_bf16 v[88:91], v[194:197], v[226:229], v[88:91]
	v_mfma_f32_16x16x32_bf16 v[76:79], v[148:151], v[234:237], v[76:79]
	v_mfma_f32_16x16x32_bf16 v[72:75], v[194:197], v[234:237], v[72:75]
	s_setprio 0
	s_barrier
	s_add_i32 s15, s24, s29
	v_lshl_add_u64 v[166:167], s[66:67], 0, v[168:169]
	s_mov_b32 m0, s15
	ds_read_b128 v[206:209], v188 offset:16384
	ds_read_b128 v[210:213], v188 offset:17408
	ds_read_b128 v[214:217], v188 offset:18432
	ds_read_b128 v[218:221], v188 offset:19456
	ds_read_b128 v[222:225], v188 offset:20480
	ds_read_b128 v[226:229], v188 offset:21504
	ds_read_b128 v[230:233], v188 offset:22528
	ds_read_b128 v[234:237], v188 offset:23552
	global_load_lds_dwordx4 v[166:167], off
	s_add_i32 m0, s15, 0x2000
	s_add_u32 s50, s66, 0x40000
	v_lshl_add_u64 v[180:181], s[66:67], 0, v[156:157]
	s_addc_u32 s51, s67, 0
	s_add_i32 s14, s14, s29
	global_load_lds_dwordx4 v[180:181], off
	v_lshl_add_u64 v[238:239], s[50:51], 0, v[168:169]
	s_mov_b32 m0, s14
	v_lshl_add_u64 v[240:241], s[68:69], 0, v[154:155]
	global_load_lds_dwordx4 v[238:239], off
	v_lshl_add_u64 v[238:239], s[50:51], 0, v[156:157]
	s_add_i32 m0, s14, 0x2000
	s_nop 0
	global_load_lds_dwordx4 v[238:239], off
	v_lshl_add_u64 v[238:239], s[68:69], 0, v[152:153]
	s_mov_b32 m0, s31
	s_nop 0
	global_load_lds_dwordx4 v[238:239], off
	s_mov_b32 m0, s41
	s_nop 0
	global_load_lds_dwordx4 v[240:241], off
	s_waitcnt vmcnt(8)
	s_waitcnt lgkmcnt(0)
	s_barrier
; #define PG8_STAGE(bufoff, gbase, voff) do { _Pragma("unroll") for (int _i = 0; _i < 2; ++_i) \
;         __builtin_amdgcn_global_load_lds((const unsigned*)((const char*)(gbase) + (voff)[_i]), (LAS unsigned*)(lds + (bufoff) + ldsw + _i * 8192), 16, 0, 0); } while (0)
; #define PG8_LDA(dst, b, h) do { _Pragma("unroll") for (int m = 0; m < 4; ++m) _Pragma("unroll") for (int k = 0; k < 2; ++k) dst[m][k] = *(const LAS bf16x8*)(lds + PG8_SA(b, h) + aoff + m * 2048 + k * 1024); } while (0)
; #define PG8_LDB(dst, b, h) do { _Pragma("unroll") for (int n = 0; n < 2; ++n) _Pragma("unroll") for (int k = 0; k < 2; ++k) dst[n][k] = *(const LAS bf16x8*)(lds + PG8_SB(b, h) + boff + n * 2048 + k * 1024); } while (0)
; #define PG8_MMA(ai, bj, At, Bt) do { __builtin_amdgcn_s_setprio(1); _Pragma("unroll") for (int m = 0; m < 4; ++m) _Pragma("unroll") for (int n = 0; n < 2; ++n) _Pragma("unroll") for (int k = 0; k < 2; ++k) \
;         acc[ai][bj][m][n] = __builtin_amdgcn_mfma_f32_16x16x32_bf16(Bt[n][k], At[m][k], acc[ai][bj][m][n], 0, 0, 0); __builtin_amdgcn_s_setprio(0); } while (0)
; #define PG8_WAIT_V(n) asm volatile("s_waitcnt vmcnt(" #n ")" ::: "memory")
; #define PG8_WAIT_L(n) asm volatile("s_waitcnt lgkmcnt(" #n ")" ::: "memory")
; #define PG8_BAR __builtin_amdgcn_s_barrier()
; #define PG8_SCHED __builtin_amdgcn_sched_barrier(0)
; template <class Epi, class Sched>
; __device__ __forceinline__ void gemm_phase(const int tid, LAS unsigned char* lds, const int lda, const int ldb, const int K, const Sched& S, const Epi& E) {
;     ...
;             PG8_WAIT_V(8); PG8_WAIT_L(0); PG8_BAR; if (!cur.half) { PG8_MMA(1, 0, At, B0); PG8_MMA(1, 1, At, B1); } PG8_BAR; PG8_SCHED;
;             PG8_LDB(B0, 1, 0); PG8_LDB(B1, 1, 1); PG8_SCHED; PG8_LDA(At, 1, 0); PG8_STAGE(PG8_SA(0, 1), a2 + hstepA, voffA);
;             PG8_WAIT_V(8); PG8_WAIT_L(0); PG8_BAR; PG8_MMA(0, 0, At, B0); PG8_MMA(0, 1, At, B1); PG8_BAR; PG8_SCHED;
	s_setprio 1
	v_mfma_f32_16x16x32_bf16 v[52:55], v[128:131], v[206:209], 0
	v_mfma_f32_16x16x32_bf16 v[48:51], v[136:139], v[206:209], 0
	v_mfma_f32_16x16x32_bf16 v[36:39], v[128:131], v[214:217], 0
	v_mfma_f32_16x16x32_bf16 v[32:35], v[136:139], v[214:217], 0
	v_mfma_f32_16x16x32_bf16 v[20:23], v[128:131], v[222:225], 0
	v_mfma_f32_16x16x32_bf16 v[16:19], v[136:139], v[222:225], 0
	v_mfma_f32_16x16x32_bf16 v[4:7], v[128:131], v[230:233], 0
	v_mfma_f32_16x16x32_bf16 v[0:3], v[136:139], v[230:233], 0
	v_mfma_f32_16x16x32_bf16 v[52:55], v[132:135], v[210:213], v[52:55]
	v_mfma_f32_16x16x32_bf16 v[48:51], v[140:143], v[210:213], v[48:51]
	v_mfma_f32_16x16x32_bf16 v[36:39], v[132:135], v[218:221], v[36:39]
	v_mfma_f32_16x16x32_bf16 v[32:35], v[140:143], v[218:221], v[32:35]
	v_mfma_f32_16x16x32_bf16 v[20:23], v[132:135], v[226:229], v[20:23]
	v_mfma_f32_16x16x32_bf16 v[16:19], v[140:143], v[226:229], v[16:19]
	v_mfma_f32_16x16x32_bf16 v[4:7], v[132:135], v[234:237], v[4:7]
	v_mfma_f32_16x16x32_bf16 v[0:3], v[140:143], v[234:237], v[0:3]
	v_mfma_f32_16x16x32_bf16 v[60:63], v[144:147], v[206:209], 0
	v_mfma_f32_16x16x32_bf16 v[56:59], v[190:193], v[206:209], 0
	v_mfma_f32_16x16x32_bf16 v[44:47], v[144:147], v[214:217], 0
	v_mfma_f32_16x16x32_bf16 v[40:43], v[190:193], v[214:217], 0
	v_mfma_f32_16x16x32_bf16 v[28:31], v[144:147], v[222:225], 0
	v_mfma_f32_16x16x32_bf16 v[24:27], v[190:193], v[222:225], 0
	v_mfma_f32_16x16x32_bf16 v[12:15], v[144:147], v[230:233], 0
	v_mfma_f32_16x16x32_bf16 v[8:11], v[190:193], v[230:233], 0
	v_mfma_f32_16x16x32_bf16 v[60:63], v[148:151], v[210:213], v[60:63]
	v_mfma_f32_16x16x32_bf16 v[56:59], v[194:197], v[210:213], v[56:59]
	v_mfma_f32_16x16x32_bf16 v[44:47], v[148:151], v[218:221], v[44:47]
	v_mfma_f32_16x16x32_bf16 v[40:43], v[194:197], v[218:221], v[40:43]
	v_mfma_f32_16x16x32_bf16 v[28:31], v[148:151], v[226:229], v[28:31]
	v_mfma_f32_16x16x32_bf16 v[24:27], v[194:197], v[226:229], v[24:27]
	v_mfma_f32_16x16x32_bf16 v[12:15], v[148:151], v[234:237], v[12:15]
	v_mfma_f32_16x16x32_bf16 v[8:11], v[194:197], v[234:237], v[8:11]
	s_setprio 0
	s_barrier
	s_add_i32 s14, 0, 0x18000
	s_add_i32 s15, 0, 0x1c000
	v_add_u32_e32 v140, s14, v182
	v_add_u32_e32 v176, s15, v182
	ds_read_b128 v[128:131], v140
	ds_read_b128 v[132:135], v140 offset:1024
	ds_read_b128 v[136:139], v140 offset:2048
	ds_read_b128 v[140:143], v140 offset:3072
	ds_read_b128 v[144:147], v176
	ds_read_b128 v[148:151], v176 offset:1024
	ds_read_b128 v[190:193], v176 offset:2048
	ds_read_b128 v[194:197], v176 offset:3072
	s_add_u32 s50, s68, 0x40000
	s_addc_u32 s51, s69, 0
	s_mov_b32 m0, s47
	v_lshl_add_u64 v[242:243], s[50:51], 0, v[152:153]
	ds_read_b128 v[206:209], v188 offset:32768
	ds_read_b128 v[210:213], v188 offset:33792
	ds_read_b128 v[214:217], v188 offset:34816
	ds_read_b128 v[218:221], v188 offset:35840
	ds_read_b128 v[222:225], v188 offset:36864
	ds_read_b128 v[226:229], v188 offset:37888
	ds_read_b128 v[230:233], v188 offset:38912
	ds_read_b128 v[234:237], v188 offset:39936
	global_load_lds_dwordx4 v[242:243], off
	v_lshl_add_u64 v[242:243], s[50:51], 0, v[154:155]
	s_mov_b32 m0, s70
	s_nop 0
	global_load_lds_dwordx4 v[242:243], off
	s_waitcnt vmcnt(8)
	s_waitcnt lgkmcnt(0)
	s_barrier
	s_setprio 1
	v_mfma_f32_16x16x32_bf16 v[116:119], v[128:131], v[206:209], v[116:119]
	v_mfma_f32_16x16x32_bf16 v[112:115], v[136:139], v[206:209], v[112:115]
	v_mfma_f32_16x16x32_bf16 v[100:103], v[128:131], v[214:217], v[100:103]
	v_mfma_f32_16x16x32_bf16 v[96:99], v[136:139], v[214:217], v[96:99]
	v_mfma_f32_16x16x32_bf16 v[84:87], v[128:131], v[222:225], v[84:87]
	v_mfma_f32_16x16x32_bf16 v[80:83], v[136:139], v[222:225], v[80:83]
	v_mfma_f32_16x16x32_bf16 v[68:71], v[128:131], v[230:233], v[68:71]
	v_mfma_f32_16x16x32_bf16 v[64:67], v[136:139], v[230:233], v[64:67]
	v_mfma_f32_16x16x32_bf16 v[116:119], v[132:135], v[210:213], v[116:119]
	v_mfma_f32_16x16x32_bf16 v[112:115], v[140:143], v[210:213], v[112:115]
	v_mfma_f32_16x16x32_bf16 v[100:103], v[132:135], v[218:221], v[100:103]
	v_mfma_f32_16x16x32_bf16 v[96:99], v[140:143], v[218:221], v[96:99]
	v_mfma_f32_16x16x32_bf16 v[84:87], v[132:135], v[226:229], v[84:87]
	v_mfma_f32_16x16x32_bf16 v[80:83], v[140:143], v[226:229], v[80:83]
	v_mfma_f32_16x16x32_bf16 v[68:71], v[132:135], v[234:237], v[68:71]
	v_mfma_f32_16x16x32_bf16 v[64:67], v[140:143], v[234:237], v[64:67]
	v_mfma_f32_16x16x32_bf16 v[124:127], v[144:147], v[206:209], v[124:127]
	v_mfma_f32_16x16x32_bf16 v[120:123], v[190:193], v[206:209], v[120:123]
	v_mfma_f32_16x16x32_bf16 v[108:111], v[144:147], v[214:217], v[108:111]
	v_mfma_f32_16x16x32_bf16 v[104:107], v[190:193], v[214:217], v[104:107]
	v_mfma_f32_16x16x32_bf16 v[92:95], v[144:147], v[222:225], v[92:95]
	v_mfma_f32_16x16x32_bf16 v[88:91], v[190:193], v[222:225], v[88:91]
	v_mfma_f32_16x16x32_bf16 v[76:79], v[144:147], v[230:233], v[76:79]
	v_mfma_f32_16x16x32_bf16 v[72:75], v[190:193], v[230:233], v[72:75]
	v_mfma_f32_16x16x32_bf16 v[124:127], v[148:151], v[210:213], v[124:127]
	v_mfma_f32_16x16x32_bf16 v[120:123], v[194:197], v[210:213], v[120:123]
	v_mfma_f32_16x16x32_bf16 v[108:111], v[148:151], v[218:221], v[108:111]
	v_mfma_f32_16x16x32_bf16 v[104:107], v[194:197], v[218:221], v[104:107]
	v_mfma_f32_16x16x32_bf16 v[92:95], v[148:151], v[226:229], v[92:95]
	v_mfma_f32_16x16x32_bf16 v[88:91], v[194:197], v[226:229], v[88:91]
	v_mfma_f32_16x16x32_bf16 v[76:79], v[148:151], v[234:237], v[76:79]
	v_mfma_f32_16x16x32_bf16 v[72:75], v[194:197], v[234:237], v[72:75]
	s_setprio 0
	s_barrier
; #define PG8_STAGE(bufoff, gbase, voff) do { _Pragma("unroll") for (int _i = 0; _i < 2; ++_i) \
;         __builtin_amdgcn_global_load_lds((const unsigned*)((const char*)(gbase) + (voff)[_i]), (LAS unsigned*)(lds + (bufoff) + ldsw + _i * 8192), 16, 0, 0); } while (0)
; #define PG8_LDA(dst, b, h) do { _Pragma("unroll") for (int m = 0; m < 4; ++m) _Pragma("unroll") for (int k = 0; k < 2; ++k) dst[m][k] = *(const LAS bf16x8*)(lds + PG8_SA(b, h) + aoff + m * 2048 + k * 1024); } while (0)
; #define PG8_LDB(dst, b, h) do { _Pragma("unroll") for (int n = 0; n < 2; ++n) _Pragma("unroll") for (int k = 0; k < 2; ++k) dst[n][k] = *(const LAS bf16x8*)(lds + PG8_SB(b, h) + boff + n * 2048 + k * 1024); } while (0)
; #define PG8_BAR __builtin_amdgcn_s_barrier()
; template <class Epi, class Sched>
; __device__ __forceinline__ void gemm_phase(const int tid, LAS unsigned char* lds, const int lda, const int ldb, const int K, const Sched& S, const Epi& E) {
;     ...
;         for (int t = 0; t < nt; t += 2) {
;             const bool last = (t == nt - 2);
;             const char* a1 = cA + (size_t)(t + 1) * kstep;
;             const char* a2 = last ? nA : cA + (size_t)(t + 2) * kstep; const char* b2 = last ? nB : cB + (size_t)(t + 2) * kstep;
;             const char* a3 = a2 + kstep; const char* b3 = b2 + kstep;
;             PG8_LDB(B0, 0, 0); PG8_LDB(B1, 0, 1); PG8_SCHED; PG8_LDA(At, 0, 0); PG8_STAGE(PG8_SA(1, 1), a1 + hstepA, voffA);
;             PG8_WAIT_V(8); PG8_WAIT_L(0); PG8_BAR; PG8_MMA(0, 0, At, B0); PG8_MMA(0, 1, At, B1); PG8_BAR; PG8_SCHED;
;             PG8_LDA(At, 0, 1); PG8_STAGE(PG8_SB(0, 0), b2, voffB); PG8_STAGE(PG8_SB(0, 1), b2 + hstepB, voffB); PG8_STAGE(PG8_SA(0, 0), a2, voffA);
;             PG8_WAIT_V(8); PG8_WAIT_L(0); PG8_BAR; if (!cur.half) { PG8_MMA(1, 0, At, B0); PG8_MMA(1, 1, At, B1); } PG8_BAR; PG8_SCHED;
;             PG8_LDB(B0, 1, 0); PG8_LDB(B1, 1, 1); PG8_SCHED; PG8_LDA(At, 1, 0); PG8_STAGE(PG8_SA(0, 1), a2 + hstepA, voffA);
;             PG8_WAIT_V(8); PG8_WAIT_L(0); PG8_BAR; PG8_MMA(0, 0, At, B0); PG8_MMA(0, 1, At, B1); PG8_BAR; PG8_SCHED;
;             PG8_LDA(At, 1, 1); PG8_STAGE(PG8_SB(1, 0), b3, voffB); PG8_STAGE(PG8_SB(1, 1), b3 + hstepB, voffB); PG8_STAGE(PG8_SA(1, 0), a3, voffA);
;             PG8_WAIT_V(8); PG8_WAIT_L(0); PG8_BAR; if (!cur.half) { PG8_MMA(1, 0, At, B0); PG8_MMA(1, 1, At, B1); } PG8_BAR; PG8_SCHED;
;         }
	s_add_i32 s14, s14, s29
	v_lshl_add_u64 v[166:167], v[166:167], 0, s[6:7]
	s_mov_b32 m0, s14
	ds_read_b128 v[206:209], v188 offset:49152
	ds_read_b128 v[210:213], v188 offset:50176
	ds_read_b128 v[214:217], v188 offset:51200
	ds_read_b128 v[218:221], v188 offset:52224
	ds_read_b128 v[222:225], v188 offset:53248
	ds_read_b128 v[226:229], v188 offset:54272
	ds_read_b128 v[230:233], v188 offset:55296
	ds_read_b128 v[234:237], v188 offset:56320
	global_load_lds_dwordx4 v[166:167], off
	s_add_i32 m0, s14, 0x2000
	s_add_u32 s50, s66, 0x40080
	v_lshl_add_u64 v[166:167], v[180:181], 0, s[6:7]
	s_addc_u32 s51, s67, 0
	s_add_i32 s14, s15, s29
	global_load_lds_dwordx4 v[166:167], off
	v_lshl_add_u64 v[166:167], s[50:51], 0, v[168:169]
	s_mov_b32 m0, s14
	s_nop 0
	global_load_lds_dwordx4 v[166:167], off
	v_lshl_add_u64 v[166:167], s[50:51], 0, v[156:157]
	s_add_i32 m0, s14, 0x2000
	s_nop 0
	global_load_lds_dwordx4 v[166:167], off
	v_lshl_add_u64 v[166:167], v[238:239], 0, s[6:7]
	s_mov_b32 m0, s72
	s_nop 0
	global_load_lds_dwordx4 v[166:167], off
	v_lshl_add_u64 v[166:167], v[240:241], 0, s[6:7]
	s_mov_b32 m0, s73
	s_nop 0
	global_load_lds_dwordx4 v[166:167], off
	s_waitcnt vmcnt(8)
	s_waitcnt lgkmcnt(0)
	s_barrier
	s_setprio 1
	v_mfma_f32_16x16x32_bf16 v[52:55], v[128:131], v[206:209], v[52:55]
	v_mfma_f32_16x16x32_bf16 v[48:51], v[136:139], v[206:209], v[48:51]
	v_mfma_f32_16x16x32_bf16 v[36:39], v[128:131], v[214:217], v[36:39]
	v_mfma_f32_16x16x32_bf16 v[32:35], v[136:139], v[214:217], v[32:35]
	v_mfma_f32_16x16x32_bf16 v[20:23], v[128:131], v[222:225], v[20:23]
	v_mfma_f32_16x16x32_bf16 v[16:19], v[136:139], v[222:225], v[16:19]
	v_mfma_f32_16x16x32_bf16 v[4:7], v[128:131], v[230:233], v[4:7]
	v_mfma_f32_16x16x32_bf16 v[0:3], v[136:139], v[230:233], v[0:3]
	v_mfma_f32_16x16x32_bf16 v[52:55], v[132:135], v[210:213], v[52:55]
	v_mfma_f32_16x16x32_bf16 v[48:51], v[140:143], v[210:213], v[48:51]
	v_mfma_f32_16x16x32_bf16 v[36:39], v[132:135], v[218:221], v[36:39]
	v_mfma_f32_16x16x32_bf16 v[32:35], v[140:143], v[218:221], v[32:35]
	v_mfma_f32_16x16x32_bf16 v[20:23], v[132:135], v[226:229], v[20:23]
	v_mfma_f32_16x16x32_bf16 v[16:19], v[140:143], v[226:229], v[16:19]
	v_mfma_f32_16x16x32_bf16 v[4:7], v[132:135], v[234:237], v[4:7]
	v_mfma_f32_16x16x32_bf16 v[0:3], v[140:143], v[234:237], v[0:3]
	v_mfma_f32_16x16x32_bf16 v[60:63], v[144:147], v[206:209], v[60:63]
	v_mfma_f32_16x16x32_bf16 v[56:59], v[190:193], v[206:209], v[56:59]
	v_mfma_f32_16x16x32_bf16 v[44:47], v[144:147], v[214:217], v[44:47]
	v_mfma_f32_16x16x32_bf16 v[40:43], v[190:193], v[214:217], v[40:43]
	v_mfma_f32_16x16x32_bf16 v[28:31], v[144:147], v[222:225], v[28:31]
	v_mfma_f32_16x16x32_bf16 v[24:27], v[190:193], v[222:225], v[24:27]
	v_mfma_f32_16x16x32_bf16 v[12:15], v[144:147], v[230:233], v[12:15]
	v_mfma_f32_16x16x32_bf16 v[8:11], v[190:193], v[230:233], v[8:11]
	v_mfma_f32_16x16x32_bf16 v[60:63], v[148:151], v[210:213], v[60:63]
	v_mfma_f32_16x16x32_bf16 v[56:59], v[194:197], v[210:213], v[56:59]
	v_mfma_f32_16x16x32_bf16 v[44:47], v[148:151], v[218:221], v[44:47]
	v_mfma_f32_16x16x32_bf16 v[40:43], v[194:197], v[218:221], v[40:43]
	v_mfma_f32_16x16x32_bf16 v[28:31], v[148:151], v[226:229], v[28:31]
	v_mfma_f32_16x16x32_bf16 v[24:27], v[194:197], v[226:229], v[24:27]
	v_mfma_f32_16x16x32_bf16 v[12:15], v[148:151], v[234:237], v[12:15]
	v_mfma_f32_16x16x32_bf16 v[8:11], v[194:197], v[234:237], v[8:11]
	s_setprio 0
	s_barrier
	s_add_u32 s64, s64, 0x100
	s_addc_u32 s65, s65, 0
	s_add_u32 s26, s26, 0x100
	s_addc_u32 s27, s27, 0
	s_cmp_ge_i32 vcc_lo, s21
	s_mov_b32 s57, vcc_lo
	s_cbranch_scc1 .Lkexit_754
.LBB0_754:
	s_add_i32 vcc_lo, s57, 2
	s_add_u32 s14, s64, 0xfffc0080
	s_addc_u32 s15, s65, -1
	s_add_i32 s24, 0, 0x10000
	s_cmp_eq_u32 s75, s57
	s_cselect_b32 s69, s3, s15
	s_cselect_b32 s68, s2, s14
	s_cselect_b32 s67, s63, s27
	s_cselect_b32 s66, s62, s26
	s_add_i32 s14, 0, 0x14000
	v_add_u32_e32 v140, s24, v182
	v_add_u32_e32 v166, s14, v182
	ds_read_b128 v[128:131], v140
	ds_read_b128 v[132:135], v140 offset:1024
	ds_read_b128 v[136:139], v140 offset:2048
	ds_read_b128 v[140:143], v140 offset:3072
	ds_read_b128 v[144:147], v166
	ds_read_b128 v[148:151], v166 offset:1024
	ds_read_b128 v[190:193], v166 offset:2048
	ds_read_b128 v[194:197], v166 offset:3072
	v_lshl_add_u64 v[166:167], s[64:65], 0, v[162:163]
	s_add_i32 m0, s31, 0xc000
	ds_read_b128 v[206:209], v188
	ds_read_b128 v[210:213], v188 offset:1024
	ds_read_b128 v[214:217], v188 offset:2048
	ds_read_b128 v[218:221], v188 offset:3072
	ds_read_b128 v[222:225], v188 offset:4096
	ds_read_b128 v[226:229], v188 offset:5120
	ds_read_b128 v[230:233], v188 offset:6144
	ds_read_b128 v[234:237], v188 offset:7168
	global_load_lds_dwordx4 v[166:167], off
	v_lshl_add_u64 v[166:167], s[64:65], 0, v[164:165]
	s_add_i32 m0, s31, 0xe000
	s_nop 0
	global_load_lds_dwordx4 v[166:167], off
	s_waitcnt vmcnt(8)
	s_waitcnt lgkmcnt(0)
	s_barrier
; #define PG8_STAGE(bufoff, gbase, voff) do { _Pragma("unroll") for (int _i = 0; _i < 2; ++_i) \
;         __builtin_amdgcn_global_load_lds((const unsigned*)((const char*)(gbase) + (voff)[_i]), (LAS unsigned*)(lds + (bufoff) + ldsw + _i * 8192), 16, 0, 0); } while (0)
; #define PG8_LDA(dst, b, h) do { _Pragma("unroll") for (int m = 0; m < 4; ++m) _Pragma("unroll") for (int k = 0; k < 2; ++k) dst[m][k] = *(const LAS bf16x8*)(lds + PG8_SA(b, h) + aoff + m * 2048 + k * 1024); } while (0)
; #define PG8_LDB(dst, b, h) do { _Pragma("unroll") for (int n = 0; n < 2; ++n) _Pragma("unroll") for (int k = 0; k < 2; ++k) dst[n][k] = *(const LAS bf16x8*)(lds + PG8_SB(b, h) + boff + n * 2048 + k * 1024); } while (0)
; #define PG8_MMA(ai, bj, At, Bt) do { __builtin_amdgcn_s_setprio(1); _Pragma("unroll") for (int m = 0; m < 4; ++m) _Pragma("unroll") for (int n = 0; n < 2; ++n) _Pragma("unroll") for (int k = 0; k < 2; ++k) \
;         acc[ai][bj][m][n] = __builtin_amdgcn_mfma_f32_16x16x32_bf16(Bt[n][k], At[m][k], acc[ai][bj][m][n], 0, 0, 0); __builtin_amdgcn_s_setprio(0); } while (0)
; #define PG8_WAIT_V(n) asm volatile("s_waitcnt vmcnt(" #n ")" ::: "memory")
; #define PG8_WAIT_L(n) asm volatile("s_waitcnt lgkmcnt(" #n ")" ::: "memory")
; #define PG8_BAR __builtin_amdgcn_s_barrier()
; #define PG8_SCHED __builtin_amdgcn_sched_barrier(0)
; template <class Epi, class Sched>
; __device__ __forceinline__ void gemm_phase(const int tid, LAS unsigned char* lds, const int lda, const int ldb, const int K, const Sched& S, const Epi& E) {
;     ...
;             PG8_WAIT_V(8); PG8_WAIT_L(0); PG8_BAR; PG8_MMA(0, 0, At, B0); PG8_MMA(0, 1, At, B1); PG8_BAR; PG8_SCHED;
;             PG8_LDA(At, 0, 1); PG8_STAGE(PG8_SB(0, 0), b2, voffB); PG8_STAGE(PG8_SB(0, 1), b2 + hstepB, voffB); PG8_STAGE(PG8_SA(0, 0), a2, voffA);
;             PG8_WAIT_V(8); PG8_WAIT_L(0); PG8_BAR; if (!cur.half) { PG8_MMA(1, 0, At, B0); PG8_MMA(1, 1, At, B1); } PG8_BAR; PG8_SCHED;
;             PG8_LDB(B0, 1, 0); PG8_LDB(B1, 1, 1); PG8_SCHED; PG8_LDA(At, 1, 0); PG8_STAGE(PG8_SA(0, 1), a2 + hstepA, voffA);
;             PG8_WAIT_V(8); PG8_WAIT_L(0); PG8_BAR; PG8_MMA(0, 0, At, B0); PG8_MMA(0, 1, At, B1); PG8_BAR; PG8_SCHED;
	s_setprio 1
	v_mfma_f32_16x16x32_bf16 v[116:119], v[128:131], v[206:209], v[116:119]
	v_mfma_f32_16x16x32_bf16 v[112:115], v[136:139], v[206:209], v[112:115]
	v_mfma_f32_16x16x32_bf16 v[100:103], v[128:131], v[214:217], v[100:103]
	v_mfma_f32_16x16x32_bf16 v[96:99], v[136:139], v[214:217], v[96:99]
	v_mfma_f32_16x16x32_bf16 v[84:87], v[128:131], v[222:225], v[84:87]
	v_mfma_f32_16x16x32_bf16 v[80:83], v[136:139], v[222:225], v[80:83]
	v_mfma_f32_16x16x32_bf16 v[68:71], v[128:131], v[230:233], v[68:71]
	v_mfma_f32_16x16x32_bf16 v[64:67], v[136:139], v[230:233], v[64:67]
	v_mfma_f32_16x16x32_bf16 v[116:119], v[132:135], v[210:213], v[116:119]
	v_mfma_f32_16x16x32_bf16 v[112:115], v[140:143], v[210:213], v[112:115]
	v_mfma_f32_16x16x32_bf16 v[100:103], v[132:135], v[218:221], v[100:103]
	v_mfma_f32_16x16x32_bf16 v[96:99], v[140:143], v[218:221], v[96:99]
	v_mfma_f32_16x16x32_bf16 v[84:87], v[132:135], v[226:229], v[84:87]
	v_mfma_f32_16x16x32_bf16 v[80:83], v[140:143], v[226:229], v[80:83]
	v_mfma_f32_16x16x32_bf16 v[68:71], v[132:135], v[234:237], v[68:71]
	v_mfma_f32_16x16x32_bf16 v[64:67], v[140:143], v[234:237], v[64:67]
	v_mfma_f32_16x16x32_bf16 v[124:127], v[144:147], v[206:209], v[124:127]
	v_mfma_f32_16x16x32_bf16 v[120:123], v[190:193], v[206:209], v[120:123]
	v_mfma_f32_16x16x32_bf16 v[108:111], v[144:147], v[214:217], v[108:111]
	v_mfma_f32_16x16x32_bf16 v[104:107], v[190:193], v[214:217], v[104:107]
	v_mfma_f32_16x16x32_bf16 v[92:95], v[144:147], v[222:225], v[92:95]
	v_mfma_f32_16x16x32_bf16 v[88:91], v[190:193], v[222:225], v[88:91]
	v_mfma_f32_16x16x32_bf16 v[76:79], v[144:147], v[230:233], v[76:79]
	v_mfma_f32_16x16x32_bf16 v[72:75], v[190:193], v[230:233], v[72:75]
	v_mfma_f32_16x16x32_bf16 v[124:127], v[148:151], v[210:213], v[124:127]
	v_mfma_f32_16x16x32_bf16 v[120:123], v[194:197], v[210:213], v[120:123]
	v_mfma_f32_16x16x32_bf16 v[108:111], v[148:151], v[218:221], v[108:111]
	v_mfma_f32_16x16x32_bf16 v[104:107], v[194:197], v[218:221], v[104:107]
	v_mfma_f32_16x16x32_bf16 v[92:95], v[148:151], v[226:229], v[92:95]
	v_mfma_f32_16x16x32_bf16 v[88:91], v[194:197], v[226:229], v[88:91]
	v_mfma_f32_16x16x32_bf16 v[76:79], v[148:151], v[234:237], v[76:79]
	v_mfma_f32_16x16x32_bf16 v[72:75], v[194:197], v[234:237], v[72:75]
	s_setprio 0
	s_barrier
	s_add_i32 s15, s24, s29
	v_lshl_add_u64 v[166:167], s[66:67], 0, v[168:169]
	s_mov_b32 m0, s15
	ds_read_b128 v[206:209], v188 offset:16384
	ds_read_b128 v[210:213], v188 offset:17408
	ds_read_b128 v[214:217], v188 offset:18432
	ds_read_b128 v[218:221], v188 offset:19456
	ds_read_b128 v[222:225], v188 offset:20480
	ds_read_b128 v[226:229], v188 offset:21504
	ds_read_b128 v[230:233], v188 offset:22528
	ds_read_b128 v[234:237], v188 offset:23552
	global_load_lds_dwordx4 v[166:167], off
	s_add_i32 m0, s15, 0x2000
	s_add_u32 s50, s66, 0x40000
	v_lshl_add_u64 v[180:181], s[66:67], 0, v[156:157]
	s_addc_u32 s51, s67, 0
	s_add_i32 s14, s14, s29
	global_load_lds_dwordx4 v[180:181], off
	v_lshl_add_u64 v[238:239], s[50:51], 0, v[168:169]
	s_mov_b32 m0, s14
	v_lshl_add_u64 v[240:241], s[68:69], 0, v[154:155]
	global_load_lds_dwordx4 v[238:239], off
	v_lshl_add_u64 v[238:239], s[50:51], 0, v[156:157]
	s_add_i32 m0, s14, 0x2000
	s_nop 0
	global_load_lds_dwordx4 v[238:239], off
	v_lshl_add_u64 v[238:239], s[68:69], 0, v[152:153]
	s_mov_b32 m0, s31
	s_nop 0
	global_load_lds_dwordx4 v[238:239], off
	s_mov_b32 m0, s41
	s_nop 0
	global_load_lds_dwordx4 v[240:241], off
	s_waitcnt vmcnt(8)
	s_waitcnt lgkmcnt(0)
	s_barrier
	s_setprio 1
	v_mfma_f32_16x16x32_bf16 v[52:55], v[128:131], v[206:209], v[52:55]
	v_mfma_f32_16x16x32_bf16 v[48:51], v[136:139], v[206:209], v[48:51]
	v_mfma_f32_16x16x32_bf16 v[36:39], v[128:131], v[214:217], v[36:39]
	v_mfma_f32_16x16x32_bf16 v[32:35], v[136:139], v[214:217], v[32:35]
	v_mfma_f32_16x16x32_bf16 v[20:23], v[128:131], v[222:225], v[20:23]
	v_mfma_f32_16x16x32_bf16 v[16:19], v[136:139], v[222:225], v[16:19]
	v_mfma_f32_16x16x32_bf16 v[4:7], v[128:131], v[230:233], v[4:7]
	v_mfma_f32_16x16x32_bf16 v[0:3], v[136:139], v[230:233], v[0:3]
	v_mfma_f32_16x16x32_bf16 v[52:55], v[132:135], v[210:213], v[52:55]
	v_mfma_f32_16x16x32_bf16 v[48:51], v[140:143], v[210:213], v[48:51]
	v_mfma_f32_16x16x32_bf16 v[36:39], v[132:135], v[218:221], v[36:39]
	v_mfma_f32_16x16x32_bf16 v[32:35], v[140:143], v[218:221], v[32:35]
	v_mfma_f32_16x16x32_bf16 v[20:23], v[132:135], v[226:229], v[20:23]
	v_mfma_f32_16x16x32_bf16 v[16:19], v[140:143], v[226:229], v[16:19]
	v_mfma_f32_16x16x32_bf16 v[4:7], v[132:135], v[234:237], v[4:7]
	v_mfma_f32_16x16x32_bf16 v[0:3], v[140:143], v[234:237], v[0:3]
	v_mfma_f32_16x16x32_bf16 v[60:63], v[144:147], v[206:209], v[60:63]
	v_mfma_f32_16x16x32_bf16 v[56:59], v[190:193], v[206:209], v[56:59]
	v_mfma_f32_16x16x32_bf16 v[44:47], v[144:147], v[214:217], v[44:47]
	v_mfma_f32_16x16x32_bf16 v[40:43], v[190:193], v[214:217], v[40:43]
	v_mfma_f32_16x16x32_bf16 v[28:31], v[144:147], v[222:225], v[28:31]
	v_mfma_f32_16x16x32_bf16 v[24:27], v[190:193], v[222:225], v[24:27]
	v_mfma_f32_16x16x32_bf16 v[12:15], v[144:147], v[230:233], v[12:15]
	v_mfma_f32_16x16x32_bf16 v[8:11], v[190:193], v[230:233], v[8:11]
	v_mfma_f32_16x16x32_bf16 v[60:63], v[148:151], v[210:213], v[60:63]
	v_mfma_f32_16x16x32_bf16 v[56:59], v[194:197], v[210:213], v[56:59]
	v_mfma_f32_16x16x32_bf16 v[44:47], v[148:151], v[218:221], v[44:47]
	v_mfma_f32_16x16x32_bf16 v[40:43], v[194:197], v[218:221], v[40:43]
	v_mfma_f32_16x16x32_bf16 v[28:31], v[148:151], v[226:229], v[28:31]
	v_mfma_f32_16x16x32_bf16 v[24:27], v[194:197], v[226:229], v[24:27]
	v_mfma_f32_16x16x32_bf16 v[12:15], v[148:151], v[234:237], v[12:15]
	v_mfma_f32_16x16x32_bf16 v[8:11], v[194:197], v[234:237], v[8:11]
	s_setprio 0
	s_barrier
; #define PG8_STAGE(bufoff, gbase, voff) do { _Pragma("unroll") for (int _i = 0; _i < 2; ++_i) \
;         __builtin_amdgcn_global_load_lds((const unsigned*)((const char*)(gbase) + (voff)[_i]), (LAS unsigned*)(lds + (bufoff) + ldsw + _i * 8192), 16, 0, 0); } while (0)
; #define PG8_LDA(dst, b, h) do { _Pragma("unroll") for (int m = 0; m < 4; ++m) _Pragma("unroll") for (int k = 0; k < 2; ++k) dst[m][k] = *(const LAS bf16x8*)(lds + PG8_SA(b, h) + aoff + m * 2048 + k * 1024); } while (0)
; #define PG8_LDB(dst, b, h) do { _Pragma("unroll") for (int n = 0; n < 2; ++n) _Pragma("unroll") for (int k = 0; k < 2; ++k) dst[n][k] = *(const LAS bf16x8*)(lds + PG8_SB(b, h) + boff + n * 2048 + k * 1024); } while (0)
; #define PG8_MMA(ai, bj, At, Bt) do { __builtin_amdgcn_s_setprio(1); _Pragma("unroll") for (int m = 0; m < 4; ++m) _Pragma("unroll") for (int n = 0; n < 2; ++n) _Pragma("unroll") for (int k = 0; k < 2; ++k) \
;         acc[ai][bj][m][n] = __builtin_amdgcn_mfma_f32_16x16x32_bf16(Bt[n][k], At[m][k], acc[ai][bj][m][n], 0, 0, 0); __builtin_amdgcn_s_setprio(0); } while (0)
; #define PG8_WAIT_V(n) asm volatile("s_waitcnt vmcnt(" #n ")" ::: "memory")
; #define PG8_WAIT_L(n) asm volatile("s_waitcnt lgkmcnt(" #n ")" ::: "memory")
; #define PG8_BAR __builtin_amdgcn_s_barrier()
; #define PG8_SCHED __builtin_amdgcn_sched_barrier(0)
; template <class Epi, class Sched>
; __device__ __forceinline__ void gemm_phase(const int tid, LAS unsigned char* lds, const int lda, const int ldb, const int K, const Sched& S, const Epi& E) {
;     ...
;             PG8_LDB(B0, 1, 0); PG8_LDB(B1, 1, 1); PG8_SCHED; PG8_LDA(At, 1, 0); PG8_STAGE(PG8_SA(0, 1), a2 + hstepA, voffA);
;             PG8_WAIT_V(8); PG8_WAIT_L(0); PG8_BAR; PG8_MMA(0, 0, At, B0); PG8_MMA(0, 1, At, B1); PG8_BAR; PG8_SCHED;
	s_add_i32 s14, 0, 0x18000
	s_add_i32 s15, 0, 0x1c000
	v_add_u32_e32 v140, s14, v182
	v_add_u32_e32 v176, s15, v182
	ds_read_b128 v[128:131], v140
	ds_read_b128 v[132:135], v140 offset:1024
	ds_read_b128 v[136:139], v140 offset:2048
	ds_read_b128 v[140:143], v140 offset:3072
	ds_read_b128 v[144:147], v176
	ds_read_b128 v[148:151], v176 offset:1024
	ds_read_b128 v[190:193], v176 offset:2048
	ds_read_b128 v[194:197], v176 offset:3072
	s_add_u32 s50, s68, 0x40000
	s_addc_u32 s51, s69, 0
	s_mov_b32 m0, s47
	v_lshl_add_u64 v[242:243], s[50:51], 0, v[152:153]
	ds_read_b128 v[206:209], v188 offset:32768
	ds_read_b128 v[210:213], v188 offset:33792
	ds_read_b128 v[214:217], v188 offset:34816
	ds_read_b128 v[218:221], v188 offset:35840
	ds_read_b128 v[222:225], v188 offset:36864
	ds_read_b128 v[226:229], v188 offset:37888
	ds_read_b128 v[230:233], v188 offset:38912
	ds_read_b128 v[234:237], v188 offset:39936
	global_load_lds_dwordx4 v[242:243], off
	v_lshl_add_u64 v[242:243], s[50:51], 0, v[154:155]
	s_mov_b32 m0, s70
	s_nop 0
	global_load_lds_dwordx4 v[242:243], off
	s_waitcnt vmcnt(8)
	s_waitcnt lgkmcnt(0)
	s_barrier
	s_setprio 1
	v_mfma_f32_16x16x32_bf16 v[116:119], v[128:131], v[206:209], v[116:119]
	v_mfma_f32_16x16x32_bf16 v[112:115], v[136:139], v[206:209], v[112:115]
	v_mfma_f32_16x16x32_bf16 v[100:103], v[128:131], v[214:217], v[100:103]
	v_mfma_f32_16x16x32_bf16 v[96:99], v[136:139], v[214:217], v[96:99]
	v_mfma_f32_16x16x32_bf16 v[84:87], v[128:131], v[222:225], v[84:87]
	v_mfma_f32_16x16x32_bf16 v[80:83], v[136:139], v[222:225], v[80:83]
	v_mfma_f32_16x16x32_bf16 v[68:71], v[128:131], v[230:233], v[68:71]
	v_mfma_f32_16x16x32_bf16 v[64:67], v[136:139], v[230:233], v[64:67]
	v_mfma_f32_16x16x32_bf16 v[116:119], v[132:135], v[210:213], v[116:119]
	v_mfma_f32_16x16x32_bf16 v[112:115], v[140:143], v[210:213], v[112:115]
	v_mfma_f32_16x16x32_bf16 v[100:103], v[132:135], v[218:221], v[100:103]
	v_mfma_f32_16x16x32_bf16 v[96:99], v[140:143], v[218:221], v[96:99]
	v_mfma_f32_16x16x32_bf16 v[84:87], v[132:135], v[226:229], v[84:87]
	v_mfma_f32_16x16x32_bf16 v[80:83], v[140:143], v[226:229], v[80:83]
	v_mfma_f32_16x16x32_bf16 v[68:71], v[132:135], v[234:237], v[68:71]
	v_mfma_f32_16x16x32_bf16 v[64:67], v[140:143], v[234:237], v[64:67]
	v_mfma_f32_16x16x32_bf16 v[124:127], v[144:147], v[206:209], v[124:127]
	v_mfma_f32_16x16x32_bf16 v[120:123], v[190:193], v[206:209], v[120:123]
	v_mfma_f32_16x16x32_bf16 v[108:111], v[144:147], v[214:217], v[108:111]
	v_mfma_f32_16x16x32_bf16 v[104:107], v[190:193], v[214:217], v[104:107]
	v_mfma_f32_16x16x32_bf16 v[92:95], v[144:147], v[222:225], v[92:95]
	v_mfma_f32_16x16x32_bf16 v[88:91], v[190:193], v[222:225], v[88:91]
	v_mfma_f32_16x16x32_bf16 v[76:79], v[144:147], v[230:233], v[76:79]
	v_mfma_f32_16x16x32_bf16 v[72:75], v[190:193], v[230:233], v[72:75]
	v_mfma_f32_16x16x32_bf16 v[124:127], v[148:151], v[210:213], v[124:127]
	v_mfma_f32_16x16x32_bf16 v[120:123], v[194:197], v[210:213], v[120:123]
	v_mfma_f32_16x16x32_bf16 v[108:111], v[148:151], v[218:221], v[108:111]
	v_mfma_f32_16x16x32_bf16 v[104:107], v[194:197], v[218:221], v[104:107]
	v_mfma_f32_16x16x32_bf16 v[92:95], v[148:151], v[226:229], v[92:95]
	v_mfma_f32_16x16x32_bf16 v[88:91], v[194:197], v[226:229], v[88:91]
	v_mfma_f32_16x16x32_bf16 v[76:79], v[148:151], v[234:237], v[76:79]
	v_mfma_f32_16x16x32_bf16 v[72:75], v[194:197], v[234:237], v[72:75]
	s_setprio 0
	s_barrier
; #define PG8_STAGE(bufoff, gbase, voff) do { _Pragma("unroll") for (int _i = 0; _i < 2; ++_i) \
;         __builtin_amdgcn_global_load_lds((const unsigned*)((const char*)(gbase) + (voff)[_i]), (LAS unsigned*)(lds + (bufoff) + ldsw + _i * 8192), 16, 0, 0); } while (0)
; #define PG8_LDA(dst, b, h) do { _Pragma("unroll") for (int m = 0; m < 4; ++m) _Pragma("unroll") for (int k = 0; k < 2; ++k) dst[m][k] = *(const LAS bf16x8*)(lds + PG8_SA(b, h) + aoff + m * 2048 + k * 1024); } while (0)
; #define PG8_MMA(ai, bj, At, Bt) do { __builtin_amdgcn_s_setprio(1); _Pragma("unroll") for (int m = 0; m < 4; ++m) _Pragma("unroll") for (int n = 0; n < 2; ++n) _Pragma("unroll") for (int k = 0; k < 2; ++k) \
;         acc[ai][bj][m][n] = __builtin_amdgcn_mfma_f32_16x16x32_bf16(Bt[n][k], At[m][k], acc[ai][bj][m][n], 0, 0, 0); __builtin_amdgcn_s_setprio(0); } while (0)
; #define PG8_WAIT_V(n) asm volatile("s_waitcnt vmcnt(" #n ")" ::: "memory")
; #define PG8_WAIT_L(n) asm volatile("s_waitcnt lgkmcnt(" #n ")" ::: "memory")
; #define PG8_BAR __builtin_amdgcn_s_barrier()
; #define PG8_SCHED __builtin_amdgcn_sched_barrier(0)
; template <class Epi, class Sched>
; __device__ __forceinline__ void gemm_phase(const int tid, LAS unsigned char* lds, const int lda, const int ldb, const int K, const Sched& S, const Epi& E) {
;     ...
;             PG8_LDA(At, 1, 1); PG8_STAGE(PG8_SB(1, 0), b3, voffB); PG8_STAGE(PG8_SB(1, 1), b3 + hstepB, voffB); PG8_STAGE(PG8_SA(1, 0), a3, voffA);
;             PG8_WAIT_V(8); PG8_WAIT_L(0); PG8_BAR; if (!cur.half) { PG8_MMA(1, 0, At, B0); PG8_MMA(1, 1, At, B1); } PG8_BAR; PG8_SCHED;
;         }
	s_add_i32 s14, s14, s29
	v_lshl_add_u64 v[166:167], v[166:167], 0, s[6:7]
	s_mov_b32 m0, s14
	ds_read_b128 v[206:209], v188 offset:49152
	ds_read_b128 v[210:213], v188 offset:50176
	ds_read_b128 v[214:217], v188 offset:51200
	ds_read_b128 v[218:221], v188 offset:52224
	ds_read_b128 v[222:225], v188 offset:53248
	ds_read_b128 v[226:229], v188 offset:54272
	ds_read_b128 v[230:233], v188 offset:55296
	ds_read_b128 v[234:237], v188 offset:56320
	global_load_lds_dwordx4 v[166:167], off
	s_add_i32 m0, s14, 0x2000
	s_add_u32 s50, s66, 0x40080
	v_lshl_add_u64 v[166:167], v[180:181], 0, s[6:7]
	s_addc_u32 s51, s67, 0
	s_add_i32 s14, s15, s29
	global_load_lds_dwordx4 v[166:167], off
	v_lshl_add_u64 v[166:167], s[50:51], 0, v[168:169]
	s_mov_b32 m0, s14
	s_nop 0
	global_load_lds_dwordx4 v[166:167], off
	v_lshl_add_u64 v[166:167], s[50:51], 0, v[156:157]
	s_add_i32 m0, s14, 0x2000
	s_nop 0
	global_load_lds_dwordx4 v[166:167], off
	v_lshl_add_u64 v[166:167], v[238:239], 0, s[6:7]
	s_mov_b32 m0, s72
	s_nop 0
	global_load_lds_dwordx4 v[166:167], off
	v_lshl_add_u64 v[166:167], v[240:241], 0, s[6:7]
	s_mov_b32 m0, s73
	s_nop 0
	global_load_lds_dwordx4 v[166:167], off
	s_waitcnt vmcnt(8)
	s_waitcnt lgkmcnt(0)
	s_barrier
	s_setprio 1
	v_mfma_f32_16x16x32_bf16 v[52:55], v[128:131], v[206:209], v[52:55]
	v_mfma_f32_16x16x32_bf16 v[48:51], v[136:139], v[206:209], v[48:51]
	v_mfma_f32_16x16x32_bf16 v[36:39], v[128:131], v[214:217], v[36:39]
	v_mfma_f32_16x16x32_bf16 v[32:35], v[136:139], v[214:217], v[32:35]
	v_mfma_f32_16x16x32_bf16 v[20:23], v[128:131], v[222:225], v[20:23]
	v_mfma_f32_16x16x32_bf16 v[16:19], v[136:139], v[222:225], v[16:19]
	v_mfma_f32_16x16x32_bf16 v[4:7], v[128:131], v[230:233], v[4:7]
	v_mfma_f32_16x16x32_bf16 v[0:3], v[136:139], v[230:233], v[0:3]
	v_mfma_f32_16x16x32_bf16 v[52:55], v[132:135], v[210:213], v[52:55]
	v_mfma_f32_16x16x32_bf16 v[48:51], v[140:143], v[210:213], v[48:51]
	v_mfma_f32_16x16x32_bf16 v[36:39], v[132:135], v[218:221], v[36:39]
	v_mfma_f32_16x16x32_bf16 v[32:35], v[140:143], v[218:221], v[32:35]
	v_mfma_f32_16x16x32_bf16 v[20:23], v[132:135], v[226:229], v[20:23]
	v_mfma_f32_16x16x32_bf16 v[16:19], v[140:143], v[226:229], v[16:19]
	v_mfma_f32_16x16x32_bf16 v[4:7], v[132:135], v[234:237], v[4:7]
	v_mfma_f32_16x16x32_bf16 v[0:3], v[140:143], v[234:237], v[0:3]
	v_mfma_f32_16x16x32_bf16 v[60:63], v[144:147], v[206:209], v[60:63]
	v_mfma_f32_16x16x32_bf16 v[56:59], v[190:193], v[206:209], v[56:59]
	v_mfma_f32_16x16x32_bf16 v[44:47], v[144:147], v[214:217], v[44:47]
	v_mfma_f32_16x16x32_bf16 v[40:43], v[190:193], v[214:217], v[40:43]
	v_mfma_f32_16x16x32_bf16 v[28:31], v[144:147], v[222:225], v[28:31]
	v_mfma_f32_16x16x32_bf16 v[24:27], v[190:193], v[222:225], v[24:27]
	v_mfma_f32_16x16x32_bf16 v[12:15], v[144:147], v[230:233], v[12:15]
	v_mfma_f32_16x16x32_bf16 v[8:11], v[190:193], v[230:233], v[8:11]
	v_mfma_f32_16x16x32_bf16 v[60:63], v[148:151], v[210:213], v[60:63]
	v_mfma_f32_16x16x32_bf16 v[56:59], v[194:197], v[210:213], v[56:59]
	v_mfma_f32_16x16x32_bf16 v[44:47], v[148:151], v[218:221], v[44:47]
	v_mfma_f32_16x16x32_bf16 v[40:43], v[194:197], v[218:221], v[40:43]
	v_mfma_f32_16x16x32_bf16 v[28:31], v[148:151], v[226:229], v[28:31]
	v_mfma_f32_16x16x32_bf16 v[24:27], v[194:197], v[226:229], v[24:27]
	v_mfma_f32_16x16x32_bf16 v[12:15], v[148:151], v[234:237], v[12:15]
	v_mfma_f32_16x16x32_bf16 v[8:11], v[194:197], v[234:237], v[8:11]
	s_setprio 0
	s_barrier
	s_add_u32 s64, s64, 0x100
	s_addc_u32 s65, s65, 0
	s_add_u32 s26, s26, 0x100
	s_addc_u32 s27, s27, 0
	s_cmp_ge_i32 vcc_lo, s21
	s_mov_b32 s57, vcc_lo
	s_cbranch_scc0 .LBB0_754

; #define PG8_STAGE(bufoff, gbase, voff) do { _Pragma("unroll") for (int _i = 0; _i < 2; ++_i) \
;         __builtin_amdgcn_global_load_lds((const unsigned*)((const char*)(gbase) + (voff)[_i]), (LAS unsigned*)(lds + (bufoff) + ldsw + _i * 8192), 16, 0, 0); } while (0)
; #define PG8_LDA(dst, b, h) do { _Pragma("unroll") for (int m = 0; m < 4; ++m) _Pragma("unroll") for (int k = 0; k < 2; ++k) dst[m][k] = *(const LAS bf16x8*)(lds + PG8_SA(b, h) + aoff + m * 2048 + k * 1024); } while (0)
; #define PG8_LDB(dst, b, h) do { _Pragma("unroll") for (int n = 0; n < 2; ++n) _Pragma("unroll") for (int k = 0; k < 2; ++k) dst[n][k] = *(const LAS bf16x8*)(lds + PG8_SB(b, h) + boff + n * 2048 + k * 1024); } while (0)
; #define PG8_MMA(ai, bj, At, Bt) do { __builtin_amdgcn_s_setprio(1); _Pragma("unroll") for (int m = 0; m < 4; ++m) _Pragma("unroll") for (int n = 0; n < 2; ++n) _Pragma("unroll") for (int k = 0; k < 2; ++k) \
;         acc[ai][bj][m][n] = __builtin_amdgcn_mfma_f32_16x16x32_bf16(Bt[n][k], At[m][k], acc[ai][bj][m][n], 0, 0, 0); __builtin_amdgcn_s_setprio(0); } while (0)
; #define PG8_BAR __builtin_amdgcn_s_barrier()
; template <class Epi, class Sched>
; __device__ __forceinline__ void gemm_phase(const int tid, LAS unsigned char* lds, const int lda, const int ldb, const int K, const Sched& S, const Epi& E) {
;     ...
;     for (;;) {
;         const bool has_next = S.next(ui + 1, nxt);
;         const char* nA = has_next ? nxt.a : cA; const char* nB = has_next ? nxt.b : cB;
;         for (int t = 0; t < nt; t += 2) {
;             const bool last = (t == nt - 2);
;             const char* a1 = cA + (size_t)(t + 1) * kstep;
;             const char* a2 = last ? nA : cA + (size_t)(t + 2) * kstep; const char* b2 = last ? nB : cB + (size_t)(t + 2) * kstep;
;             const char* a3 = a2 + kstep; const char* b3 = b2 + kstep;
;             PG8_LDB(B0, 0, 0); PG8_LDB(B1, 0, 1); PG8_SCHED; PG8_LDA(At, 0, 0); PG8_STAGE(PG8_SA(1, 1), a1 + hstepA, voffA);
;             PG8_WAIT_V(8); PG8_WAIT_L(0); PG8_BAR; PG8_MMA(0, 0, At, B0); PG8_MMA(0, 1, At, B1); PG8_BAR; PG8_SCHED;
;             PG8_LDA(At, 0, 1); PG8_STAGE(PG8_SB(0, 0), b2, voffB); PG8_STAGE(PG8_SB(0, 1), b2 + hstepB, voffB); PG8_STAGE(PG8_SA(0, 0), a2, voffA);
;             PG8_WAIT_V(8); PG8_WAIT_L(0); PG8_BAR; if (!cur.half) { PG8_MMA(1, 0, At, B0); PG8_MMA(1, 1, At, B1); } PG8_BAR; PG8_SCHED;
.LBB0_791:
	s_andn2_b64 vcc, exec, s[50:51]
	s_cbranch_vccnz .LBB0_799
	s_add_u32 s26, s64, 0x100
	s_addc_u32 s27, s65, 0
	s_mov_b32 s42, 0
	s_add_i32 s43, s42, 2
	s_add_u32 s64, s62, 0x100
	s_addc_u32 s65, s63, 0
	s_add_i32 s14, 0, 0x10000
	s_cmp_eq_u32 s72, s42
	s_cselect_b32 s69, s3, s65
	s_cselect_b32 s68, s2, s64
	s_cselect_b32 s67, s61, s27
	s_cselect_b32 s66, s60, s26
	s_add_i32 s15, 0, 0x14000
	v_add_u32_e32 v124, s14, v206
	v_add_u32_e32 v156, s15, v206
	ds_read_b128 v[104:107], v124
	ds_read_b128 v[108:111], v124 offset:1024
	ds_read_b128 v[120:123], v124 offset:2048
	ds_read_b128 v[124:127], v124 offset:3072
	ds_read_b128 v[136:139], v156
	ds_read_b128 v[144:147], v156 offset:1024
	ds_read_b128 v[152:155], v156 offset:2048
	ds_read_b128 v[156:159], v156 offset:3072
	v_lshl_add_u64 v[196:197], s[62:63], 0, v[192:193]
	s_add_i32 m0, s23, 0xc000
	ds_read_b128 v[160:163], v211
	ds_read_b128 v[164:167], v211 offset:1024
	ds_read_b128 v[212:215], v211 offset:2048
	ds_read_b128 v[216:219], v211 offset:3072
	ds_read_b128 v[220:223], v211 offset:4096
	ds_read_b128 v[224:227], v211 offset:5120
	ds_read_b128 v[228:231], v211 offset:6144
	ds_read_b128 v[232:235], v211 offset:7168
	global_load_lds_dwordx4 v[196:197], off
	v_lshl_add_u64 v[196:197], s[62:63], 0, v[194:195]
	s_add_i32 m0, s23, 0xe000
	s_nop 0
	global_load_lds_dwordx4 v[196:197], off
	s_waitcnt vmcnt(8)
	s_waitcnt lgkmcnt(0)
	s_barrier
	s_setprio 1
	v_mfma_f32_16x16x32_bf16 v[148:151], v[104:107], v[160:163], 0
	v_mfma_f32_16x16x32_bf16 v[140:143], v[120:123], v[160:163], 0
	v_mfma_f32_16x16x32_bf16 v[132:135], v[104:107], v[212:215], 0
	v_mfma_f32_16x16x32_bf16 v[128:131], v[120:123], v[212:215], 0
	v_mfma_f32_16x16x32_bf16 v[116:119], v[104:107], v[220:223], 0
	v_mfma_f32_16x16x32_bf16 v[112:115], v[120:123], v[220:223], 0
	v_mfma_f32_16x16x32_bf16 v[100:103], v[104:107], v[228:231], 0
	v_mfma_f32_16x16x32_bf16 v[96:99], v[120:123], v[228:231], 0
	v_mfma_f32_16x16x32_bf16 v[148:151], v[108:111], v[164:167], v[148:151]
	v_mfma_f32_16x16x32_bf16 v[140:143], v[124:127], v[164:167], v[140:143]
	v_mfma_f32_16x16x32_bf16 v[132:135], v[108:111], v[216:219], v[132:135]
	v_mfma_f32_16x16x32_bf16 v[128:131], v[124:127], v[216:219], v[128:131]
	v_mfma_f32_16x16x32_bf16 v[116:119], v[108:111], v[224:227], v[116:119]
	v_mfma_f32_16x16x32_bf16 v[112:115], v[124:127], v[224:227], v[112:115]
	v_mfma_f32_16x16x32_bf16 v[100:103], v[108:111], v[232:235], v[100:103]
	v_mfma_f32_16x16x32_bf16 v[96:99], v[124:127], v[232:235], v[96:99]
	v_mfma_f32_16x16x32_bf16 v[60:63], v[136:139], v[160:163], 0
	v_mfma_f32_16x16x32_bf16 v[56:59], v[152:155], v[160:163], 0
	v_mfma_f32_16x16x32_bf16 v[52:55], v[136:139], v[212:215], 0
	v_mfma_f32_16x16x32_bf16 v[48:51], v[152:155], v[212:215], 0
	v_mfma_f32_16x16x32_bf16 v[44:47], v[136:139], v[220:223], 0
	v_mfma_f32_16x16x32_bf16 v[40:43], v[152:155], v[220:223], 0
	v_mfma_f32_16x16x32_bf16 v[36:39], v[136:139], v[228:231], 0
	v_mfma_f32_16x16x32_bf16 v[32:35], v[152:155], v[228:231], 0
	v_mfma_f32_16x16x32_bf16 v[60:63], v[144:147], v[164:167], v[60:63]
	v_mfma_f32_16x16x32_bf16 v[56:59], v[156:159], v[164:167], v[56:59]
	v_mfma_f32_16x16x32_bf16 v[52:55], v[144:147], v[216:219], v[52:55]
	v_mfma_f32_16x16x32_bf16 v[48:51], v[156:159], v[216:219], v[48:51]
	v_mfma_f32_16x16x32_bf16 v[44:47], v[144:147], v[224:227], v[44:47]
	v_mfma_f32_16x16x32_bf16 v[40:43], v[156:159], v[224:227], v[40:43]
	v_mfma_f32_16x16x32_bf16 v[36:39], v[144:147], v[232:235], v[36:39]
	v_mfma_f32_16x16x32_bf16 v[32:35], v[156:159], v[232:235], v[32:35]
	s_setprio 0
	s_barrier
	s_add_i32 s14, s14, s21
	v_lshl_add_u64 v[196:197], s[66:67], 0, v[182:183]
	s_mov_b32 m0, s14
	ds_read_b128 v[160:163], v211 offset:16384
	ds_read_b128 v[164:167], v211 offset:17408
	ds_read_b128 v[212:215], v211 offset:18432
	ds_read_b128 v[216:219], v211 offset:19456
	ds_read_b128 v[220:223], v211 offset:20480
	ds_read_b128 v[224:227], v211 offset:21504
	ds_read_b128 v[228:231], v211 offset:22528
	ds_read_b128 v[232:235], v211 offset:23552
	global_load_lds_dwordx4 v[196:197], off
	s_add_i32 m0, s14, 0x2000
	s_add_u32 s62, s66, 0x28000
	v_lshl_add_u64 v[236:237], s[66:67], 0, v[186:187]
	s_addc_u32 s63, s67, 0
	s_add_i32 s14, s15, s21
	global_load_lds_dwordx4 v[236:237], off
	v_lshl_add_u64 v[238:239], s[62:63], 0, v[182:183]
	s_mov_b32 m0, s14
	v_lshl_add_u64 v[240:241], s[68:69], 0, v[184:185]
	global_load_lds_dwordx4 v[238:239], off
	v_lshl_add_u64 v[238:239], s[62:63], 0, v[186:187]
	s_add_i32 m0, s14, 0x2000
	s_nop 0
	global_load_lds_dwordx4 v[238:239], off
	v_lshl_add_u64 v[238:239], s[68:69], 0, v[180:181]
	s_mov_b32 m0, s23
	s_nop 0
	global_load_lds_dwordx4 v[238:239], off
	s_mov_b32 m0, s29
	s_nop 0
	global_load_lds_dwordx4 v[240:241], off
	s_waitcnt vmcnt(8)
	s_waitcnt lgkmcnt(0)
	s_barrier
; #define PG8_STAGE(bufoff, gbase, voff) do { _Pragma("unroll") for (int _i = 0; _i < 2; ++_i) \
;         __builtin_amdgcn_global_load_lds((const unsigned*)((const char*)(gbase) + (voff)[_i]), (LAS unsigned*)(lds + (bufoff) + ldsw + _i * 8192), 16, 0, 0); } while (0)
; #define PG8_LDA(dst, b, h) do { _Pragma("unroll") for (int m = 0; m < 4; ++m) _Pragma("unroll") for (int k = 0; k < 2; ++k) dst[m][k] = *(const LAS bf16x8*)(lds + PG8_SA(b, h) + aoff + m * 2048 + k * 1024); } while (0)
; #define PG8_LDB(dst, b, h) do { _Pragma("unroll") for (int n = 0; n < 2; ++n) _Pragma("unroll") for (int k = 0; k < 2; ++k) dst[n][k] = *(const LAS bf16x8*)(lds + PG8_SB(b, h) + boff + n * 2048 + k * 1024); } while (0)
; #define PG8_MMA(ai, bj, At, Bt) do { __builtin_amdgcn_s_setprio(1); _Pragma("unroll") for (int m = 0; m < 4; ++m) _Pragma("unroll") for (int n = 0; n < 2; ++n) _Pragma("unroll") for (int k = 0; k < 2; ++k) \
;         acc[ai][bj][m][n] = __builtin_amdgcn_mfma_f32_16x16x32_bf16(Bt[n][k], At[m][k], acc[ai][bj][m][n], 0, 0, 0); __builtin_amdgcn_s_setprio(0); } while (0)
; #define PG8_WAIT_V(n) asm volatile("s_waitcnt vmcnt(" #n ")" ::: "memory")
; #define PG8_WAIT_L(n) asm volatile("s_waitcnt lgkmcnt(" #n ")" ::: "memory")
; #define PG8_BAR __builtin_amdgcn_s_barrier()
; #define PG8_SCHED __builtin_amdgcn_sched_barrier(0)
; template <class Epi, class Sched>
; __device__ __forceinline__ void gemm_phase(const int tid, LAS unsigned char* lds, const int lda, const int ldb, const int K, const Sched& S, const Epi& E) {
;     ...
;             PG8_WAIT_V(8); PG8_WAIT_L(0); PG8_BAR; if (!cur.half) { PG8_MMA(1, 0, At, B0); PG8_MMA(1, 1, At, B1); } PG8_BAR; PG8_SCHED;
;             PG8_LDB(B0, 1, 0); PG8_LDB(B1, 1, 1); PG8_SCHED; PG8_LDA(At, 1, 0); PG8_STAGE(PG8_SA(0, 1), a2 + hstepA, voffA);
;             PG8_WAIT_V(8); PG8_WAIT_L(0); PG8_BAR; PG8_MMA(0, 0, At, B0); PG8_MMA(0, 1, At, B1); PG8_BAR; PG8_SCHED;
	s_setprio 1
	v_mfma_f32_16x16x32_bf16 v[92:95], v[104:107], v[160:163], 0
	v_mfma_f32_16x16x32_bf16 v[88:91], v[120:123], v[160:163], 0
	v_mfma_f32_16x16x32_bf16 v[84:87], v[104:107], v[212:215], 0
	v_mfma_f32_16x16x32_bf16 v[80:83], v[120:123], v[212:215], 0
	v_mfma_f32_16x16x32_bf16 v[76:79], v[104:107], v[220:223], 0
	v_mfma_f32_16x16x32_bf16 v[72:75], v[120:123], v[220:223], 0
	v_mfma_f32_16x16x32_bf16 v[68:71], v[104:107], v[228:231], 0
	v_mfma_f32_16x16x32_bf16 v[64:67], v[120:123], v[228:231], 0
	v_mfma_f32_16x16x32_bf16 v[92:95], v[108:111], v[164:167], v[92:95]
	v_mfma_f32_16x16x32_bf16 v[88:91], v[124:127], v[164:167], v[88:91]
	v_mfma_f32_16x16x32_bf16 v[84:87], v[108:111], v[216:219], v[84:87]
	v_mfma_f32_16x16x32_bf16 v[80:83], v[124:127], v[216:219], v[80:83]
	v_mfma_f32_16x16x32_bf16 v[76:79], v[108:111], v[224:227], v[76:79]
	v_mfma_f32_16x16x32_bf16 v[72:75], v[124:127], v[224:227], v[72:75]
	v_mfma_f32_16x16x32_bf16 v[68:71], v[108:111], v[232:235], v[68:71]
	v_mfma_f32_16x16x32_bf16 v[64:67], v[124:127], v[232:235], v[64:67]
	v_mfma_f32_16x16x32_bf16 v[28:31], v[136:139], v[160:163], 0
	v_mfma_f32_16x16x32_bf16 v[24:27], v[152:155], v[160:163], 0
	v_mfma_f32_16x16x32_bf16 v[20:23], v[136:139], v[212:215], 0
	v_mfma_f32_16x16x32_bf16 v[16:19], v[152:155], v[212:215], 0
	v_mfma_f32_16x16x32_bf16 v[12:15], v[136:139], v[220:223], 0
	v_mfma_f32_16x16x32_bf16 v[8:11], v[152:155], v[220:223], 0
	v_mfma_f32_16x16x32_bf16 v[4:7], v[136:139], v[228:231], 0
	v_mfma_f32_16x16x32_bf16 v[0:3], v[152:155], v[228:231], 0
	v_mfma_f32_16x16x32_bf16 v[28:31], v[144:147], v[164:167], v[28:31]
	v_mfma_f32_16x16x32_bf16 v[24:27], v[156:159], v[164:167], v[24:27]
	v_mfma_f32_16x16x32_bf16 v[20:23], v[144:147], v[216:219], v[20:23]
	v_mfma_f32_16x16x32_bf16 v[16:19], v[156:159], v[216:219], v[16:19]
	v_mfma_f32_16x16x32_bf16 v[12:15], v[144:147], v[224:227], v[12:15]
	v_mfma_f32_16x16x32_bf16 v[8:11], v[156:159], v[224:227], v[8:11]
	v_mfma_f32_16x16x32_bf16 v[4:7], v[144:147], v[232:235], v[4:7]
	v_mfma_f32_16x16x32_bf16 v[0:3], v[156:159], v[232:235], v[0:3]
	s_setprio 0
	s_barrier
	s_add_i32 s14, 0, 0x18000
	s_add_i32 s15, 0, 0x1c000
	v_add_u32_e32 v124, s14, v206
	v_add_u32_e32 v156, s15, v206
	ds_read_b128 v[104:107], v124
	ds_read_b128 v[108:111], v124 offset:1024
	ds_read_b128 v[120:123], v124 offset:2048
	ds_read_b128 v[124:127], v124 offset:3072
	ds_read_b128 v[136:139], v156
	ds_read_b128 v[144:147], v156 offset:1024
	ds_read_b128 v[152:155], v156 offset:2048
	ds_read_b128 v[156:159], v156 offset:3072
	s_add_u32 s62, s68, 0x28000
	s_addc_u32 s63, s69, 0
	s_mov_b32 m0, s31
	v_lshl_add_u64 v[242:243], s[62:63], 0, v[180:181]
	ds_read_b128 v[160:163], v211 offset:32768
	ds_read_b128 v[164:167], v211 offset:33792
	ds_read_b128 v[212:215], v211 offset:34816
	ds_read_b128 v[216:219], v211 offset:35840
	ds_read_b128 v[220:223], v211 offset:36864
	ds_read_b128 v[224:227], v211 offset:37888
	ds_read_b128 v[228:231], v211 offset:38912
	ds_read_b128 v[232:235], v211 offset:39936
	global_load_lds_dwordx4 v[242:243], off
	v_lshl_add_u64 v[242:243], s[62:63], 0, v[184:185]
	s_mov_b32 m0, s41
	s_nop 0
	global_load_lds_dwordx4 v[242:243], off
	s_waitcnt vmcnt(8)
	s_waitcnt lgkmcnt(0)
	s_barrier
	s_setprio 1
	v_mfma_f32_16x16x32_bf16 v[148:151], v[104:107], v[160:163], v[148:151]
	v_mfma_f32_16x16x32_bf16 v[140:143], v[120:123], v[160:163], v[140:143]
	v_mfma_f32_16x16x32_bf16 v[132:135], v[104:107], v[212:215], v[132:135]
	v_mfma_f32_16x16x32_bf16 v[128:131], v[120:123], v[212:215], v[128:131]
	v_mfma_f32_16x16x32_bf16 v[116:119], v[104:107], v[220:223], v[116:119]
	v_mfma_f32_16x16x32_bf16 v[112:115], v[120:123], v[220:223], v[112:115]
	v_mfma_f32_16x16x32_bf16 v[100:103], v[104:107], v[228:231], v[100:103]
	v_mfma_f32_16x16x32_bf16 v[96:99], v[120:123], v[228:231], v[96:99]
	v_mfma_f32_16x16x32_bf16 v[148:151], v[108:111], v[164:167], v[148:151]
	v_mfma_f32_16x16x32_bf16 v[140:143], v[124:127], v[164:167], v[140:143]
	v_mfma_f32_16x16x32_bf16 v[132:135], v[108:111], v[216:219], v[132:135]
	v_mfma_f32_16x16x32_bf16 v[128:131], v[124:127], v[216:219], v[128:131]
	v_mfma_f32_16x16x32_bf16 v[116:119], v[108:111], v[224:227], v[116:119]
	v_mfma_f32_16x16x32_bf16 v[112:115], v[124:127], v[224:227], v[112:115]
	v_mfma_f32_16x16x32_bf16 v[100:103], v[108:111], v[232:235], v[100:103]
	v_mfma_f32_16x16x32_bf16 v[96:99], v[124:127], v[232:235], v[96:99]
	v_mfma_f32_16x16x32_bf16 v[60:63], v[136:139], v[160:163], v[60:63]
	v_mfma_f32_16x16x32_bf16 v[56:59], v[152:155], v[160:163], v[56:59]
	v_mfma_f32_16x16x32_bf16 v[52:55], v[136:139], v[212:215], v[52:55]
	v_mfma_f32_16x16x32_bf16 v[48:51], v[152:155], v[212:215], v[48:51]
	v_mfma_f32_16x16x32_bf16 v[44:47], v[136:139], v[220:223], v[44:47]
	v_mfma_f32_16x16x32_bf16 v[40:43], v[152:155], v[220:223], v[40:43]
	v_mfma_f32_16x16x32_bf16 v[36:39], v[136:139], v[228:231], v[36:39]
	v_mfma_f32_16x16x32_bf16 v[32:35], v[152:155], v[228:231], v[32:35]
	v_mfma_f32_16x16x32_bf16 v[60:63], v[144:147], v[164:167], v[60:63]
	v_mfma_f32_16x16x32_bf16 v[56:59], v[156:159], v[164:167], v[56:59]
	v_mfma_f32_16x16x32_bf16 v[52:55], v[144:147], v[216:219], v[52:55]
	v_mfma_f32_16x16x32_bf16 v[48:51], v[156:159], v[216:219], v[48:51]
	v_mfma_f32_16x16x32_bf16 v[44:47], v[144:147], v[224:227], v[44:47]
	v_mfma_f32_16x16x32_bf16 v[40:43], v[156:159], v[224:227], v[40:43]
	v_mfma_f32_16x16x32_bf16 v[36:39], v[144:147], v[232:235], v[36:39]
	v_mfma_f32_16x16x32_bf16 v[32:35], v[156:159], v[232:235], v[32:35]
	s_setprio 0
	s_barrier
; #define PG8_STAGE(bufoff, gbase, voff) do { _Pragma("unroll") for (int _i = 0; _i < 2; ++_i) \
;         __builtin_amdgcn_global_load_lds((const unsigned*)((const char*)(gbase) + (voff)[_i]), (LAS unsigned*)(lds + (bufoff) + ldsw + _i * 8192), 16, 0, 0); } while (0)
; #define PG8_LDA(dst, b, h) do { _Pragma("unroll") for (int m = 0; m < 4; ++m) _Pragma("unroll") for (int k = 0; k < 2; ++k) dst[m][k] = *(const LAS bf16x8*)(lds + PG8_SA(b, h) + aoff + m * 2048 + k * 1024); } while (0)
; #define PG8_LDB(dst, b, h) do { _Pragma("unroll") for (int n = 0; n < 2; ++n) _Pragma("unroll") for (int k = 0; k < 2; ++k) dst[n][k] = *(const LAS bf16x8*)(lds + PG8_SB(b, h) + boff + n * 2048 + k * 1024); } while (0)
; #define PG8_BAR __builtin_amdgcn_s_barrier()
; template <class Epi, class Sched>
; __device__ __forceinline__ void gemm_phase(const int tid, LAS unsigned char* lds, const int lda, const int ldb, const int K, const Sched& S, const Epi& E) {
;     ...
;         for (int t = 0; t < nt; t += 2) {
;             const bool last = (t == nt - 2);
;             const char* a1 = cA + (size_t)(t + 1) * kstep;
;             const char* a2 = last ? nA : cA + (size_t)(t + 2) * kstep; const char* b2 = last ? nB : cB + (size_t)(t + 2) * kstep;
;             const char* a3 = a2 + kstep; const char* b3 = b2 + kstep;
;             PG8_LDB(B0, 0, 0); PG8_LDB(B1, 0, 1); PG8_SCHED; PG8_LDA(At, 0, 0); PG8_STAGE(PG8_SA(1, 1), a1 + hstepA, voffA);
;             PG8_WAIT_V(8); PG8_WAIT_L(0); PG8_BAR; PG8_MMA(0, 0, At, B0); PG8_MMA(0, 1, At, B1); PG8_BAR; PG8_SCHED;
;             PG8_LDA(At, 0, 1); PG8_STAGE(PG8_SB(0, 0), b2, voffB); PG8_STAGE(PG8_SB(0, 1), b2 + hstepB, voffB); PG8_STAGE(PG8_SA(0, 0), a2, voffA);
;             PG8_WAIT_V(8); PG8_WAIT_L(0); PG8_BAR; if (!cur.half) { PG8_MMA(1, 0, At, B0); PG8_MMA(1, 1, At, B1); } PG8_BAR; PG8_SCHED;
;             PG8_LDB(B0, 1, 0); PG8_LDB(B1, 1, 1); PG8_SCHED; PG8_LDA(At, 1, 0); PG8_STAGE(PG8_SA(0, 1), a2 + hstepA, voffA);
;             PG8_WAIT_V(8); PG8_WAIT_L(0); PG8_BAR; PG8_MMA(0, 0, At, B0); PG8_MMA(0, 1, At, B1); PG8_BAR; PG8_SCHED;
;             PG8_LDA(At, 1, 1); PG8_STAGE(PG8_SB(1, 0), b3, voffB); PG8_STAGE(PG8_SB(1, 1), b3 + hstepB, voffB); PG8_STAGE(PG8_SA(1, 0), a3, voffA);
;             PG8_WAIT_V(8); PG8_WAIT_L(0); PG8_BAR; if (!cur.half) { PG8_MMA(1, 0, At, B0); PG8_MMA(1, 1, At, B1); } PG8_BAR; PG8_SCHED;
;         }
	s_add_i32 s14, s14, s21
	v_lshl_add_u64 v[196:197], v[196:197], 0, s[6:7]
	s_mov_b32 m0, s14
	ds_read_b128 v[160:163], v211 offset:49152
	ds_read_b128 v[164:167], v211 offset:50176
	ds_read_b128 v[212:215], v211 offset:51200
	ds_read_b128 v[216:219], v211 offset:52224
	ds_read_b128 v[220:223], v211 offset:53248
	ds_read_b128 v[224:227], v211 offset:54272
	ds_read_b128 v[228:231], v211 offset:55296
	ds_read_b128 v[232:235], v211 offset:56320
	global_load_lds_dwordx4 v[196:197], off
	s_add_i32 m0, s14, 0x2000
	s_add_u32 s62, s66, 0x28080
	v_lshl_add_u64 v[196:197], v[236:237], 0, s[6:7]
	s_addc_u32 s63, s67, 0
	s_add_i32 s14, s15, s21
	global_load_lds_dwordx4 v[196:197], off
	v_lshl_add_u64 v[196:197], s[62:63], 0, v[182:183]
	s_mov_b32 m0, s14
	s_nop 0
	global_load_lds_dwordx4 v[196:197], off
	v_lshl_add_u64 v[196:197], s[62:63], 0, v[186:187]
	s_add_i32 m0, s14, 0x2000
	s_nop 0
	global_load_lds_dwordx4 v[196:197], off
	v_lshl_add_u64 v[196:197], v[238:239], 0, s[6:7]
	s_mov_b32 m0, s47
	s_nop 0
	global_load_lds_dwordx4 v[196:197], off
	v_lshl_add_u64 v[196:197], v[240:241], 0, s[6:7]
	s_mov_b32 m0, s70
	s_nop 0
	global_load_lds_dwordx4 v[196:197], off
	s_waitcnt vmcnt(8)
	s_waitcnt lgkmcnt(0)
	s_barrier
	s_setprio 1
	v_mfma_f32_16x16x32_bf16 v[92:95], v[104:107], v[160:163], v[92:95]
	v_mfma_f32_16x16x32_bf16 v[88:91], v[120:123], v[160:163], v[88:91]
	v_mfma_f32_16x16x32_bf16 v[84:87], v[104:107], v[212:215], v[84:87]
	v_mfma_f32_16x16x32_bf16 v[80:83], v[120:123], v[212:215], v[80:83]
	v_mfma_f32_16x16x32_bf16 v[76:79], v[104:107], v[220:223], v[76:79]
	v_mfma_f32_16x16x32_bf16 v[72:75], v[120:123], v[220:223], v[72:75]
	v_mfma_f32_16x16x32_bf16 v[68:71], v[104:107], v[228:231], v[68:71]
	v_mfma_f32_16x16x32_bf16 v[64:67], v[120:123], v[228:231], v[64:67]
	v_mfma_f32_16x16x32_bf16 v[92:95], v[108:111], v[164:167], v[92:95]
	v_mfma_f32_16x16x32_bf16 v[88:91], v[124:127], v[164:167], v[88:91]
	v_mfma_f32_16x16x32_bf16 v[84:87], v[108:111], v[216:219], v[84:87]
	v_mfma_f32_16x16x32_bf16 v[80:83], v[124:127], v[216:219], v[80:83]
	v_mfma_f32_16x16x32_bf16 v[76:79], v[108:111], v[224:227], v[76:79]
	v_mfma_f32_16x16x32_bf16 v[72:75], v[124:127], v[224:227], v[72:75]
	v_mfma_f32_16x16x32_bf16 v[68:71], v[108:111], v[232:235], v[68:71]
	v_mfma_f32_16x16x32_bf16 v[64:67], v[124:127], v[232:235], v[64:67]
	v_mfma_f32_16x16x32_bf16 v[28:31], v[136:139], v[160:163], v[28:31]
	v_mfma_f32_16x16x32_bf16 v[24:27], v[152:155], v[160:163], v[24:27]
	v_mfma_f32_16x16x32_bf16 v[20:23], v[136:139], v[212:215], v[20:23]
	v_mfma_f32_16x16x32_bf16 v[16:19], v[152:155], v[212:215], v[16:19]
	v_mfma_f32_16x16x32_bf16 v[12:15], v[136:139], v[220:223], v[12:15]
	v_mfma_f32_16x16x32_bf16 v[8:11], v[152:155], v[220:223], v[8:11]
	v_mfma_f32_16x16x32_bf16 v[4:7], v[136:139], v[228:231], v[4:7]
	v_mfma_f32_16x16x32_bf16 v[0:3], v[152:155], v[228:231], v[0:3]
	v_mfma_f32_16x16x32_bf16 v[28:31], v[144:147], v[164:167], v[28:31]
	v_mfma_f32_16x16x32_bf16 v[24:27], v[156:159], v[164:167], v[24:27]
	v_mfma_f32_16x16x32_bf16 v[20:23], v[144:147], v[216:219], v[20:23]
	v_mfma_f32_16x16x32_bf16 v[16:19], v[156:159], v[216:219], v[16:19]
	v_mfma_f32_16x16x32_bf16 v[12:15], v[144:147], v[224:227], v[12:15]
	v_mfma_f32_16x16x32_bf16 v[8:11], v[156:159], v[224:227], v[8:11]
	v_mfma_f32_16x16x32_bf16 v[4:7], v[144:147], v[232:235], v[4:7]
	v_mfma_f32_16x16x32_bf16 v[0:3], v[156:159], v[232:235], v[0:3]
	s_setprio 0
	s_barrier
	s_add_u32 s26, s26, 0x100
	s_addc_u32 s27, s27, 0
	s_cmp_ge_i32 s43, s4
	s_mov_b64 s[62:63], s[64:65]
	s_mov_b32 s42, s43
	s_cbranch_scc1 .Lkexit_793
.LBB0_793:
	s_add_i32 s43, s42, 2
	s_add_u32 s64, s62, 0x100
	s_addc_u32 s65, s63, 0
	s_add_i32 s14, 0, 0x10000
	s_cmp_eq_u32 s72, s42
	s_cselect_b32 s69, s3, s65
	s_cselect_b32 s68, s2, s64
	s_cselect_b32 s67, s61, s27
	s_cselect_b32 s66, s60, s26
	s_add_i32 s15, 0, 0x14000
	v_add_u32_e32 v124, s14, v206
	v_add_u32_e32 v156, s15, v206
	ds_read_b128 v[104:107], v124
	ds_read_b128 v[108:111], v124 offset:1024
	ds_read_b128 v[120:123], v124 offset:2048
	ds_read_b128 v[124:127], v124 offset:3072
	ds_read_b128 v[136:139], v156
	ds_read_b128 v[144:147], v156 offset:1024
	ds_read_b128 v[152:155], v156 offset:2048
	ds_read_b128 v[156:159], v156 offset:3072
	v_lshl_add_u64 v[196:197], s[62:63], 0, v[192:193]
	s_add_i32 m0, s23, 0xc000
	ds_read_b128 v[160:163], v211
	ds_read_b128 v[164:167], v211 offset:1024
	ds_read_b128 v[212:215], v211 offset:2048
	ds_read_b128 v[216:219], v211 offset:3072
	ds_read_b128 v[220:223], v211 offset:4096
	ds_read_b128 v[224:227], v211 offset:5120
	ds_read_b128 v[228:231], v211 offset:6144
	ds_read_b128 v[232:235], v211 offset:7168
	global_load_lds_dwordx4 v[196:197], off
	v_lshl_add_u64 v[196:197], s[62:63], 0, v[194:195]
	s_add_i32 m0, s23, 0xe000
	s_nop 0
	global_load_lds_dwordx4 v[196:197], off
	s_waitcnt vmcnt(8)
	s_waitcnt lgkmcnt(0)
	s_barrier
; #define PG8_STAGE(bufoff, gbase, voff) do { _Pragma("unroll") for (int _i = 0; _i < 2; ++_i) \
;         __builtin_amdgcn_global_load_lds((const unsigned*)((const char*)(gbase) + (voff)[_i]), (LAS unsigned*)(lds + (bufoff) + ldsw + _i * 8192), 16, 0, 0); } while (0)
; #define PG8_LDA(dst, b, h) do { _Pragma("unroll") for (int m = 0; m < 4; ++m) _Pragma("unroll") for (int k = 0; k < 2; ++k) dst[m][k] = *(const LAS bf16x8*)(lds + PG8_SA(b, h) + aoff + m * 2048 + k * 1024); } while (0)
; #define PG8_LDB(dst, b, h) do { _Pragma("unroll") for (int n = 0; n < 2; ++n) _Pragma("unroll") for (int k = 0; k < 2; ++k) dst[n][k] = *(const LAS bf16x8*)(lds + PG8_SB(b, h) + boff + n * 2048 + k * 1024); } while (0)
; #define PG8_MMA(ai, bj, At, Bt) do { __builtin_amdgcn_s_setprio(1); _Pragma("unroll") for (int m = 0; m < 4; ++m) _Pragma("unroll") for (int n = 0; n < 2; ++n) _Pragma("unroll") for (int k = 0; k < 2; ++k) \
;         acc[ai][bj][m][n] = __builtin_amdgcn_mfma_f32_16x16x32_bf16(Bt[n][k], At[m][k], acc[ai][bj][m][n], 0, 0, 0); __builtin_amdgcn_s_setprio(0); } while (0)
; #define PG8_WAIT_V(n) asm volatile("s_waitcnt vmcnt(" #n ")" ::: "memory")
; #define PG8_WAIT_L(n) asm volatile("s_waitcnt lgkmcnt(" #n ")" ::: "memory")
; #define PG8_BAR __builtin_amdgcn_s_barrier()
; #define PG8_SCHED __builtin_amdgcn_sched_barrier(0)
; template <class Epi, class Sched>
; __device__ __forceinline__ void gemm_phase(const int tid, LAS unsigned char* lds, const int lda, const int ldb, const int K, const Sched& S, const Epi& E) {
;     ...
;             PG8_WAIT_V(8); PG8_WAIT_L(0); PG8_BAR; PG8_MMA(0, 0, At, B0); PG8_MMA(0, 1, At, B1); PG8_BAR; PG8_SCHED;
;             PG8_LDA(At, 0, 1); PG8_STAGE(PG8_SB(0, 0), b2, voffB); PG8_STAGE(PG8_SB(0, 1), b2 + hstepB, voffB); PG8_STAGE(PG8_SA(0, 0), a2, voffA);
;             PG8_WAIT_V(8); PG8_WAIT_L(0); PG8_BAR; if (!cur.half) { PG8_MMA(1, 0, At, B0); PG8_MMA(1, 1, At, B1); } PG8_BAR; PG8_SCHED;
;             PG8_LDB(B0, 1, 0); PG8_LDB(B1, 1, 1); PG8_SCHED; PG8_LDA(At, 1, 0); PG8_STAGE(PG8_SA(0, 1), a2 + hstepA, voffA);
;             PG8_WAIT_V(8); PG8_WAIT_L(0); PG8_BAR; PG8_MMA(0, 0, At, B0); PG8_MMA(0, 1, At, B1); PG8_BAR; PG8_SCHED;
	s_setprio 1
	v_mfma_f32_16x16x32_bf16 v[148:151], v[104:107], v[160:163], v[148:151]
	v_mfma_f32_16x16x32_bf16 v[140:143], v[120:123], v[160:163], v[140:143]
	v_mfma_f32_16x16x32_bf16 v[132:135], v[104:107], v[212:215], v[132:135]
	v_mfma_f32_16x16x32_bf16 v[128:131], v[120:123], v[212:215], v[128:131]
	v_mfma_f32_16x16x32_bf16 v[116:119], v[104:107], v[220:223], v[116:119]
	v_mfma_f32_16x16x32_bf16 v[112:115], v[120:123], v[220:223], v[112:115]
	v_mfma_f32_16x16x32_bf16 v[100:103], v[104:107], v[228:231], v[100:103]
	v_mfma_f32_16x16x32_bf16 v[96:99], v[120:123], v[228:231], v[96:99]
	v_mfma_f32_16x16x32_bf16 v[148:151], v[108:111], v[164:167], v[148:151]
	v_mfma_f32_16x16x32_bf16 v[140:143], v[124:127], v[164:167], v[140:143]
	v_mfma_f32_16x16x32_bf16 v[132:135], v[108:111], v[216:219], v[132:135]
	v_mfma_f32_16x16x32_bf16 v[128:131], v[124:127], v[216:219], v[128:131]
	v_mfma_f32_16x16x32_bf16 v[116:119], v[108:111], v[224:227], v[116:119]
	v_mfma_f32_16x16x32_bf16 v[112:115], v[124:127], v[224:227], v[112:115]
	v_mfma_f32_16x16x32_bf16 v[100:103], v[108:111], v[232:235], v[100:103]
	v_mfma_f32_16x16x32_bf16 v[96:99], v[124:127], v[232:235], v[96:99]
	v_mfma_f32_16x16x32_bf16 v[60:63], v[136:139], v[160:163], v[60:63]
	v_mfma_f32_16x16x32_bf16 v[56:59], v[152:155], v[160:163], v[56:59]
	v_mfma_f32_16x16x32_bf16 v[52:55], v[136:139], v[212:215], v[52:55]
	v_mfma_f32_16x16x32_bf16 v[48:51], v[152:155], v[212:215], v[48:51]
	v_mfma_f32_16x16x32_bf16 v[44:47], v[136:139], v[220:223], v[44:47]
	v_mfma_f32_16x16x32_bf16 v[40:43], v[152:155], v[220:223], v[40:43]
	v_mfma_f32_16x16x32_bf16 v[36:39], v[136:139], v[228:231], v[36:39]
	v_mfma_f32_16x16x32_bf16 v[32:35], v[152:155], v[228:231], v[32:35]
	v_mfma_f32_16x16x32_bf16 v[60:63], v[144:147], v[164:167], v[60:63]
	v_mfma_f32_16x16x32_bf16 v[56:59], v[156:159], v[164:167], v[56:59]
	v_mfma_f32_16x16x32_bf16 v[52:55], v[144:147], v[216:219], v[52:55]
	v_mfma_f32_16x16x32_bf16 v[48:51], v[156:159], v[216:219], v[48:51]
	v_mfma_f32_16x16x32_bf16 v[44:47], v[144:147], v[224:227], v[44:47]
	v_mfma_f32_16x16x32_bf16 v[40:43], v[156:159], v[224:227], v[40:43]
	v_mfma_f32_16x16x32_bf16 v[36:39], v[144:147], v[232:235], v[36:39]
	v_mfma_f32_16x16x32_bf16 v[32:35], v[156:159], v[232:235], v[32:35]
	s_setprio 0
	s_barrier
	s_add_i32 s14, s14, s21
	v_lshl_add_u64 v[196:197], s[66:67], 0, v[182:183]
	s_mov_b32 m0, s14
	ds_read_b128 v[160:163], v211 offset:16384
	ds_read_b128 v[164:167], v211 offset:17408
	ds_read_b128 v[212:215], v211 offset:18432
	ds_read_b128 v[216:219], v211 offset:19456
	ds_read_b128 v[220:223], v211 offset:20480
	ds_read_b128 v[224:227], v211 offset:21504
	ds_read_b128 v[228:231], v211 offset:22528
	ds_read_b128 v[232:235], v211 offset:23552
	global_load_lds_dwordx4 v[196:197], off
	s_add_i32 m0, s14, 0x2000
	s_add_u32 s62, s66, 0x28000
	v_lshl_add_u64 v[236:237], s[66:67], 0, v[186:187]
	s_addc_u32 s63, s67, 0
	s_add_i32 s14, s15, s21
	global_load_lds_dwordx4 v[236:237], off
	v_lshl_add_u64 v[238:239], s[62:63], 0, v[182:183]
	s_mov_b32 m0, s14
	v_lshl_add_u64 v[240:241], s[68:69], 0, v[184:185]
	global_load_lds_dwordx4 v[238:239], off
	v_lshl_add_u64 v[238:239], s[62:63], 0, v[186:187]
	s_add_i32 m0, s14, 0x2000
	s_nop 0
	global_load_lds_dwordx4 v[238:239], off
	v_lshl_add_u64 v[238:239], s[68:69], 0, v[180:181]
	s_mov_b32 m0, s23
	s_nop 0
	global_load_lds_dwordx4 v[238:239], off
	s_mov_b32 m0, s29
	s_nop 0
	global_load_lds_dwordx4 v[240:241], off
	s_waitcnt vmcnt(8)
	s_waitcnt lgkmcnt(0)
	s_barrier
	s_setprio 1
	v_mfma_f32_16x16x32_bf16 v[92:95], v[104:107], v[160:163], v[92:95]
	v_mfma_f32_16x16x32_bf16 v[88:91], v[120:123], v[160:163], v[88:91]
	v_mfma_f32_16x16x32_bf16 v[84:87], v[104:107], v[212:215], v[84:87]
	v_mfma_f32_16x16x32_bf16 v[80:83], v[120:123], v[212:215], v[80:83]
	v_mfma_f32_16x16x32_bf16 v[76:79], v[104:107], v[220:223], v[76:79]
	v_mfma_f32_16x16x32_bf16 v[72:75], v[120:123], v[220:223], v[72:75]
	v_mfma_f32_16x16x32_bf16 v[68:71], v[104:107], v[228:231], v[68:71]
	v_mfma_f32_16x16x32_bf16 v[64:67], v[120:123], v[228:231], v[64:67]
	v_mfma_f32_16x16x32_bf16 v[92:95], v[108:111], v[164:167], v[92:95]
	v_mfma_f32_16x16x32_bf16 v[88:91], v[124:127], v[164:167], v[88:91]
	v_mfma_f32_16x16x32_bf16 v[84:87], v[108:111], v[216:219], v[84:87]
	v_mfma_f32_16x16x32_bf16 v[80:83], v[124:127], v[216:219], v[80:83]
	v_mfma_f32_16x16x32_bf16 v[76:79], v[108:111], v[224:227], v[76:79]
	v_mfma_f32_16x16x32_bf16 v[72:75], v[124:127], v[224:227], v[72:75]
	v_mfma_f32_16x16x32_bf16 v[68:71], v[108:111], v[232:235], v[68:71]
	v_mfma_f32_16x16x32_bf16 v[64:67], v[124:127], v[232:235], v[64:67]
	v_mfma_f32_16x16x32_bf16 v[28:31], v[136:139], v[160:163], v[28:31]
	v_mfma_f32_16x16x32_bf16 v[24:27], v[152:155], v[160:163], v[24:27]
	v_mfma_f32_16x16x32_bf16 v[20:23], v[136:139], v[212:215], v[20:23]
	v_mfma_f32_16x16x32_bf16 v[16:19], v[152:155], v[212:215], v[16:19]
	v_mfma_f32_16x16x32_bf16 v[12:15], v[136:139], v[220:223], v[12:15]
	v_mfma_f32_16x16x32_bf16 v[8:11], v[152:155], v[220:223], v[8:11]
	v_mfma_f32_16x16x32_bf16 v[4:7], v[136:139], v[228:231], v[4:7]
	v_mfma_f32_16x16x32_bf16 v[0:3], v[152:155], v[228:231], v[0:3]
	v_mfma_f32_16x16x32_bf16 v[28:31], v[144:147], v[164:167], v[28:31]
	v_mfma_f32_16x16x32_bf16 v[24:27], v[156:159], v[164:167], v[24:27]
	v_mfma_f32_16x16x32_bf16 v[20:23], v[144:147], v[216:219], v[20:23]
	v_mfma_f32_16x16x32_bf16 v[16:19], v[156:159], v[216:219], v[16:19]
	v_mfma_f32_16x16x32_bf16 v[12:15], v[144:147], v[224:227], v[12:15]
	v_mfma_f32_16x16x32_bf16 v[8:11], v[156:159], v[224:227], v[8:11]
	v_mfma_f32_16x16x32_bf16 v[4:7], v[144:147], v[232:235], v[4:7]
	v_mfma_f32_16x16x32_bf16 v[0:3], v[156:159], v[232:235], v[0:3]
	s_setprio 0
	s_barrier
; #define PG8_STAGE(bufoff, gbase, voff) do { _Pragma("unroll") for (int _i = 0; _i < 2; ++_i) \
;         __builtin_amdgcn_global_load_lds((const unsigned*)((const char*)(gbase) + (voff)[_i]), (LAS unsigned*)(lds + (bufoff) + ldsw + _i * 8192), 16, 0, 0); } while (0)
; #define PG8_LDA(dst, b, h) do { _Pragma("unroll") for (int m = 0; m < 4; ++m) _Pragma("unroll") for (int k = 0; k < 2; ++k) dst[m][k] = *(const LAS bf16x8*)(lds + PG8_SA(b, h) + aoff + m * 2048 + k * 1024); } while (0)
; #define PG8_LDB(dst, b, h) do { _Pragma("unroll") for (int n = 0; n < 2; ++n) _Pragma("unroll") for (int k = 0; k < 2; ++k) dst[n][k] = *(const LAS bf16x8*)(lds + PG8_SB(b, h) + boff + n * 2048 + k * 1024); } while (0)
; #define PG8_MMA(ai, bj, At, Bt) do { __builtin_amdgcn_s_setprio(1); _Pragma("unroll") for (int m = 0; m < 4; ++m) _Pragma("unroll") for (int n = 0; n < 2; ++n) _Pragma("unroll") for (int k = 0; k < 2; ++k) \
;         acc[ai][bj][m][n] = __builtin_amdgcn_mfma_f32_16x16x32_bf16(Bt[n][k], At[m][k], acc[ai][bj][m][n], 0, 0, 0); __builtin_amdgcn_s_setprio(0); } while (0)
; #define PG8_WAIT_V(n) asm volatile("s_waitcnt vmcnt(" #n ")" ::: "memory")
; #define PG8_WAIT_L(n) asm volatile("s_waitcnt lgkmcnt(" #n ")" ::: "memory")
; #define PG8_BAR __builtin_amdgcn_s_barrier()
; #define PG8_SCHED __builtin_amdgcn_sched_barrier(0)
; template <class Epi, class Sched>
; __device__ __forceinline__ void gemm_phase(const int tid, LAS unsigned char* lds, const int lda, const int ldb, const int K, const Sched& S, const Epi& E) {
;     ...
;             PG8_LDB(B0, 1, 0); PG8_LDB(B1, 1, 1); PG8_SCHED; PG8_LDA(At, 1, 0); PG8_STAGE(PG8_SA(0, 1), a2 + hstepA, voffA);
;             PG8_WAIT_V(8); PG8_WAIT_L(0); PG8_BAR; PG8_MMA(0, 0, At, B0); PG8_MMA(0, 1, At, B1); PG8_BAR; PG8_SCHED;
;             PG8_LDA(At, 1, 1); PG8_STAGE(PG8_SB(1, 0), b3, voffB); PG8_STAGE(PG8_SB(1, 1), b3 + hstepB, voffB); PG8_STAGE(PG8_SA(1, 0), a3, voffA);
;             PG8_WAIT_V(8); PG8_WAIT_L(0); PG8_BAR; if (!cur.half) { PG8_MMA(1, 0, At, B0); PG8_MMA(1, 1, At, B1); } PG8_BAR; PG8_SCHED;
;         }
	s_add_i32 s14, 0, 0x18000
	s_add_i32 s15, 0, 0x1c000
	v_add_u32_e32 v124, s14, v206
	v_add_u32_e32 v156, s15, v206
	ds_read_b128 v[104:107], v124
	ds_read_b128 v[108:111], v124 offset:1024
	ds_read_b128 v[120:123], v124 offset:2048
	ds_read_b128 v[124:127], v124 offset:3072
	ds_read_b128 v[136:139], v156
	ds_read_b128 v[144:147], v156 offset:1024
	ds_read_b128 v[152:155], v156 offset:2048
	ds_read_b128 v[156:159], v156 offset:3072
	s_add_u32 s62, s68, 0x28000
	s_addc_u32 s63, s69, 0
	s_mov_b32 m0, s31
	v_lshl_add_u64 v[242:243], s[62:63], 0, v[180:181]
	ds_read_b128 v[160:163], v211 offset:32768
	ds_read_b128 v[164:167], v211 offset:33792
	ds_read_b128 v[212:215], v211 offset:34816
	ds_read_b128 v[216:219], v211 offset:35840
	ds_read_b128 v[220:223], v211 offset:36864
	ds_read_b128 v[224:227], v211 offset:37888
	ds_read_b128 v[228:231], v211 offset:38912
	ds_read_b128 v[232:235], v211 offset:39936
	global_load_lds_dwordx4 v[242:243], off
	v_lshl_add_u64 v[242:243], s[62:63], 0, v[184:185]
	s_mov_b32 m0, s41
	s_nop 0
	global_load_lds_dwordx4 v[242:243], off
	s_waitcnt vmcnt(8)
	s_waitcnt lgkmcnt(0)
	s_barrier
	s_setprio 1
	v_mfma_f32_16x16x32_bf16 v[148:151], v[104:107], v[160:163], v[148:151]
	v_mfma_f32_16x16x32_bf16 v[140:143], v[120:123], v[160:163], v[140:143]
	v_mfma_f32_16x16x32_bf16 v[132:135], v[104:107], v[212:215], v[132:135]
	v_mfma_f32_16x16x32_bf16 v[128:131], v[120:123], v[212:215], v[128:131]
	v_mfma_f32_16x16x32_bf16 v[116:119], v[104:107], v[220:223], v[116:119]
	v_mfma_f32_16x16x32_bf16 v[112:115], v[120:123], v[220:223], v[112:115]
	v_mfma_f32_16x16x32_bf16 v[100:103], v[104:107], v[228:231], v[100:103]
	v_mfma_f32_16x16x32_bf16 v[96:99], v[120:123], v[228:231], v[96:99]
	v_mfma_f32_16x16x32_bf16 v[148:151], v[108:111], v[164:167], v[148:151]
	v_mfma_f32_16x16x32_bf16 v[140:143], v[124:127], v[164:167], v[140:143]
	v_mfma_f32_16x16x32_bf16 v[132:135], v[108:111], v[216:219], v[132:135]
	v_mfma_f32_16x16x32_bf16 v[128:131], v[124:127], v[216:219], v[128:131]
	v_mfma_f32_16x16x32_bf16 v[116:119], v[108:111], v[224:227], v[116:119]
	v_mfma_f32_16x16x32_bf16 v[112:115], v[124:127], v[224:227], v[112:115]
	v_mfma_f32_16x16x32_bf16 v[100:103], v[108:111], v[232:235], v[100:103]
	v_mfma_f32_16x16x32_bf16 v[96:99], v[124:127], v[232:235], v[96:99]
	v_mfma_f32_16x16x32_bf16 v[60:63], v[136:139], v[160:163], v[60:63]
	v_mfma_f32_16x16x32_bf16 v[56:59], v[152:155], v[160:163], v[56:59]
	v_mfma_f32_16x16x32_bf16 v[52:55], v[136:139], v[212:215], v[52:55]
	v_mfma_f32_16x16x32_bf16 v[48:51], v[152:155], v[212:215], v[48:51]
	v_mfma_f32_16x16x32_bf16 v[44:47], v[136:139], v[220:223], v[44:47]
	v_mfma_f32_16x16x32_bf16 v[40:43], v[152:155], v[220:223], v[40:43]
	v_mfma_f32_16x16x32_bf16 v[36:39], v[136:139], v[228:231], v[36:39]
	v_mfma_f32_16x16x32_bf16 v[32:35], v[152:155], v[228:231], v[32:35]
	v_mfma_f32_16x16x32_bf16 v[60:63], v[144:147], v[164:167], v[60:63]
	v_mfma_f32_16x16x32_bf16 v[56:59], v[156:159], v[164:167], v[56:59]
	v_mfma_f32_16x16x32_bf16 v[52:55], v[144:147], v[216:219], v[52:55]
	v_mfma_f32_16x16x32_bf16 v[48:51], v[156:159], v[216:219], v[48:51]
	v_mfma_f32_16x16x32_bf16 v[44:47], v[144:147], v[224:227], v[44:47]
	v_mfma_f32_16x16x32_bf16 v[40:43], v[156:159], v[224:227], v[40:43]
	v_mfma_f32_16x16x32_bf16 v[36:39], v[144:147], v[232:235], v[36:39]
	v_mfma_f32_16x16x32_bf16 v[32:35], v[156:159], v[232:235], v[32:35]
	s_setprio 0
	s_barrier
	s_add_i32 s14, s14, s21
	v_lshl_add_u64 v[196:197], v[196:197], 0, s[6:7]
	s_mov_b32 m0, s14
	ds_read_b128 v[160:163], v211 offset:49152
	ds_read_b128 v[164:167], v211 offset:50176
	ds_read_b128 v[212:215], v211 offset:51200
	ds_read_b128 v[216:219], v211 offset:52224
	ds_read_b128 v[220:223], v211 offset:53248
	ds_read_b128 v[224:227], v211 offset:54272
	ds_read_b128 v[228:231], v211 offset:55296
	ds_read_b128 v[232:235], v211 offset:56320
	global_load_lds_dwordx4 v[196:197], off
	s_add_i32 m0, s14, 0x2000
	s_add_u32 s62, s66, 0x28080
	v_lshl_add_u64 v[196:197], v[236:237], 0, s[6:7]
	s_addc_u32 s63, s67, 0
	s_add_i32 s14, s15, s21
	global_load_lds_dwordx4 v[196:197], off
	v_lshl_add_u64 v[196:197], s[62:63], 0, v[182:183]
	s_mov_b32 m0, s14
	s_nop 0
	global_load_lds_dwordx4 v[196:197], off
	v_lshl_add_u64 v[196:197], s[62:63], 0, v[186:187]
	s_add_i32 m0, s14, 0x2000
	s_nop 0
	global_load_lds_dwordx4 v[196:197], off
	v_lshl_add_u64 v[196:197], v[238:239], 0, s[6:7]
	s_mov_b32 m0, s47
	s_nop 0
	global_load_lds_dwordx4 v[196:197], off
	v_lshl_add_u64 v[196:197], v[240:241], 0, s[6:7]
	s_mov_b32 m0, s70
	s_nop 0
	global_load_lds_dwordx4 v[196:197], off
	s_waitcnt vmcnt(8)
	s_waitcnt lgkmcnt(0)
	s_barrier
	s_setprio 1
	v_mfma_f32_16x16x32_bf16 v[92:95], v[104:107], v[160:163], v[92:95]
	v_mfma_f32_16x16x32_bf16 v[88:91], v[120:123], v[160:163], v[88:91]
	v_mfma_f32_16x16x32_bf16 v[84:87], v[104:107], v[212:215], v[84:87]
	v_mfma_f32_16x16x32_bf16 v[80:83], v[120:123], v[212:215], v[80:83]
	v_mfma_f32_16x16x32_bf16 v[76:79], v[104:107], v[220:223], v[76:79]
	v_mfma_f32_16x16x32_bf16 v[72:75], v[120:123], v[220:223], v[72:75]
	v_mfma_f32_16x16x32_bf16 v[68:71], v[104:107], v[228:231], v[68:71]
	v_mfma_f32_16x16x32_bf16 v[64:67], v[120:123], v[228:231], v[64:67]
	v_mfma_f32_16x16x32_bf16 v[92:95], v[108:111], v[164:167], v[92:95]
	v_mfma_f32_16x16x32_bf16 v[88:91], v[124:127], v[164:167], v[88:91]
	v_mfma_f32_16x16x32_bf16 v[84:87], v[108:111], v[216:219], v[84:87]
	v_mfma_f32_16x16x32_bf16 v[80:83], v[124:127], v[216:219], v[80:83]
	v_mfma_f32_16x16x32_bf16 v[76:79], v[108:111], v[224:227], v[76:79]
	v_mfma_f32_16x16x32_bf16 v[72:75], v[124:127], v[224:227], v[72:75]
	v_mfma_f32_16x16x32_bf16 v[68:71], v[108:111], v[232:235], v[68:71]
	v_mfma_f32_16x16x32_bf16 v[64:67], v[124:127], v[232:235], v[64:67]
	v_mfma_f32_16x16x32_bf16 v[28:31], v[136:139], v[160:163], v[28:31]
	v_mfma_f32_16x16x32_bf16 v[24:27], v[152:155], v[160:163], v[24:27]
	v_mfma_f32_16x16x32_bf16 v[20:23], v[136:139], v[212:215], v[20:23]
	v_mfma_f32_16x16x32_bf16 v[16:19], v[152:155], v[212:215], v[16:19]
	v_mfma_f32_16x16x32_bf16 v[12:15], v[136:139], v[220:223], v[12:15]
	v_mfma_f32_16x16x32_bf16 v[8:11], v[152:155], v[220:223], v[8:11]
	v_mfma_f32_16x16x32_bf16 v[4:7], v[136:139], v[228:231], v[4:7]
	v_mfma_f32_16x16x32_bf16 v[0:3], v[152:155], v[228:231], v[0:3]
	v_mfma_f32_16x16x32_bf16 v[28:31], v[144:147], v[164:167], v[28:31]
	v_mfma_f32_16x16x32_bf16 v[24:27], v[156:159], v[164:167], v[24:27]
	v_mfma_f32_16x16x32_bf16 v[20:23], v[144:147], v[216:219], v[20:23]
	v_mfma_f32_16x16x32_bf16 v[16:19], v[156:159], v[216:219], v[16:19]
	v_mfma_f32_16x16x32_bf16 v[12:15], v[144:147], v[224:227], v[12:15]
	v_mfma_f32_16x16x32_bf16 v[8:11], v[156:159], v[224:227], v[8:11]
	v_mfma_f32_16x16x32_bf16 v[4:7], v[144:147], v[232:235], v[4:7]
	v_mfma_f32_16x16x32_bf16 v[0:3], v[156:159], v[232:235], v[0:3]
	s_setprio 0
	s_barrier
	s_add_u32 s26, s26, 0x100
	s_addc_u32 s27, s27, 0
	s_cmp_ge_i32 s43, s4
	s_mov_b64 s[62:63], s[64:65]
	s_mov_b32 s42, s43
	s_cbranch_scc0 .LBB0_793

; #define PG8_STAGE(bufoff, gbase, voff) do { _Pragma("unroll") for (int _i = 0; _i < 2; ++_i) \
;         __builtin_amdgcn_global_load_lds((const unsigned*)((const char*)(gbase) + (voff)[_i]), (LAS unsigned*)(lds + (bufoff) + ldsw + _i * 8192), 16, 0, 0); } while (0)
; #define PG8_LDA(dst, b, h) do { _Pragma("unroll") for (int m = 0; m < 4; ++m) _Pragma("unroll") for (int k = 0; k < 2; ++k) dst[m][k] = *(const LAS bf16x8*)(lds + PG8_SA(b, h) + aoff + m * 2048 + k * 1024); } while (0)
; #define PG8_LDB(dst, b, h) do { _Pragma("unroll") for (int n = 0; n < 2; ++n) _Pragma("unroll") for (int k = 0; k < 2; ++k) dst[n][k] = *(const LAS bf16x8*)(lds + PG8_SB(b, h) + boff + n * 2048 + k * 1024); } while (0)
; #define PG8_MMA(ai, bj, At, Bt) do { __builtin_amdgcn_s_setprio(1); _Pragma("unroll") for (int m = 0; m < 4; ++m) _Pragma("unroll") for (int n = 0; n < 2; ++n) _Pragma("unroll") for (int k = 0; k < 2; ++k) \
;         acc[ai][bj][m][n] = __builtin_amdgcn_mfma_f32_16x16x32_bf16(Bt[n][k], At[m][k], acc[ai][bj][m][n], 0, 0, 0); __builtin_amdgcn_s_setprio(0); } while (0)
; #define PG8_WAIT_V(n) asm volatile("s_waitcnt vmcnt(" #n ")" ::: "memory")
; #define PG8_WAIT_L(n) asm volatile("s_waitcnt lgkmcnt(" #n ")" ::: "memory")
; #define PG8_BAR __builtin_amdgcn_s_barrier()
; template <class Epi, class Sched>
; __device__ __forceinline__ void gemm_phase(const int tid, LAS unsigned char* lds, const int lda, const int ldb, const int K, const Sched& S, const Epi& E) {
;     ...
;         for (int t = 0; t < nt; t += 2) {
;             const bool last = (t == nt - 2);
;             const char* a1 = cA + (size_t)(t + 1) * kstep;
;             const char* a2 = last ? nA : cA + (size_t)(t + 2) * kstep; const char* b2 = last ? nB : cB + (size_t)(t + 2) * kstep;
;             const char* a3 = a2 + kstep; const char* b3 = b2 + kstep;
;             PG8_LDB(B0, 0, 0); PG8_LDB(B1, 0, 1); PG8_SCHED; PG8_LDA(At, 0, 0); PG8_STAGE(PG8_SA(1, 1), a1 + hstepA, voffA);
;             PG8_WAIT_V(8); PG8_WAIT_L(0); PG8_BAR; PG8_MMA(0, 0, At, B0); PG8_MMA(0, 1, At, B1); PG8_BAR; PG8_SCHED;
;             PG8_LDA(At, 0, 1); PG8_STAGE(PG8_SB(0, 0), b2, voffB); PG8_STAGE(PG8_SB(0, 1), b2 + hstepB, voffB); PG8_STAGE(PG8_SA(0, 0), a2, voffA);
;             PG8_WAIT_V(8); PG8_WAIT_L(0); PG8_BAR; if (!cur.half) { PG8_MMA(1, 0, At, B0); PG8_MMA(1, 1, At, B1); } PG8_BAR; PG8_SCHED;
.LBB0_816:
	s_add_i32 s24, s68, 2
	s_add_u32 s66, s64, 0x100
	s_addc_u32 s67, s65, 0
	s_add_i32 s14, 0, 0x10000
	v_add_u32_e32 v79, s14, v77
	ds_read_b128 v[80:83], v79
	ds_read_b128 v[84:87], v79 offset:1024
	ds_read_b128 v[88:91], v79 offset:2048
	ds_read_b128 v[92:95], v79 offset:3072
	s_cmp_eq_u32 s4, s68
	s_cselect_b32 s68, s62, s39
	s_cselect_b32 s71, s61, s67
	s_waitcnt lgkmcnt(0)
	s_cselect_b32 s70, s60, s66
	s_cselect_b32 s69, s63, s53
	v_lshl_add_u64 v[128:129], s[64:65], 0, v[72:73]
	s_add_i32 m0, s26, 0xc000
	ds_read_b128 v[96:99], v78
	ds_read_b128 v[100:103], v78 offset:1024
	ds_read_b128 v[104:107], v78 offset:2048
	ds_read_b128 v[108:111], v78 offset:3072
	ds_read_b128 v[112:115], v78 offset:4096
	ds_read_b128 v[116:119], v78 offset:5120
	ds_read_b128 v[120:123], v78 offset:6144
	ds_read_b128 v[124:127], v78 offset:7168
	global_load_lds_dwordx4 v[128:129], off
	v_lshl_add_u64 v[128:129], s[64:65], 0, v[74:75]
	s_add_i32 m0, s26, 0xe000
	s_nop 0
	global_load_lds_dwordx4 v[128:129], off
	s_waitcnt vmcnt(8)
	s_waitcnt lgkmcnt(0)
	s_barrier
	s_setprio 1
	v_mfma_f32_16x16x32_bf16 v[60:63], v[80:83], v[96:99], v[60:63]
	v_mfma_f32_16x16x32_bf16 v[56:59], v[88:91], v[96:99], v[56:59]
	v_mfma_f32_16x16x32_bf16 v[52:55], v[80:83], v[104:107], v[52:55]
	v_mfma_f32_16x16x32_bf16 v[48:51], v[88:91], v[104:107], v[48:51]
	v_mfma_f32_16x16x32_bf16 v[44:47], v[80:83], v[112:115], v[44:47]
	v_mfma_f32_16x16x32_bf16 v[40:43], v[88:91], v[112:115], v[40:43]
	v_mfma_f32_16x16x32_bf16 v[36:39], v[80:83], v[120:123], v[36:39]
	v_mfma_f32_16x16x32_bf16 v[32:35], v[88:91], v[120:123], v[32:35]
	v_mfma_f32_16x16x32_bf16 v[60:63], v[84:87], v[100:103], v[60:63]
	v_mfma_f32_16x16x32_bf16 v[56:59], v[92:95], v[100:103], v[56:59]
	v_mfma_f32_16x16x32_bf16 v[52:55], v[84:87], v[108:111], v[52:55]
	v_mfma_f32_16x16x32_bf16 v[48:51], v[92:95], v[108:111], v[48:51]
	v_mfma_f32_16x16x32_bf16 v[44:47], v[84:87], v[116:119], v[44:47]
	v_mfma_f32_16x16x32_bf16 v[40:43], v[92:95], v[116:119], v[40:43]
	v_mfma_f32_16x16x32_bf16 v[36:39], v[84:87], v[124:127], v[36:39]
	v_mfma_f32_16x16x32_bf16 v[32:35], v[92:95], v[124:127], v[32:35]
	s_setprio 0
	s_barrier
	s_add_i32 s14, s14, s13
	v_lshl_add_u64 v[128:129], s[68:69], 0, v[168:169]
	s_mov_b32 m0, s14
	ds_read_b128 v[96:99], v78 offset:16384
	ds_read_b128 v[100:103], v78 offset:17408
	ds_read_b128 v[104:107], v78 offset:18432
	ds_read_b128 v[108:111], v78 offset:19456
	ds_read_b128 v[112:115], v78 offset:20480
	ds_read_b128 v[116:119], v78 offset:21504
	ds_read_b128 v[120:123], v78 offset:22528
	ds_read_b128 v[124:127], v78 offset:23552
	global_load_lds_dwordx4 v[128:129], off
	s_add_i32 m0, s14, 0x2000
	s_add_u32 s64, s68, 0x20000
	v_lshl_add_u64 v[130:131], s[68:69], 0, v[64:65]
	s_addc_u32 s65, s69, 0
	global_load_lds_dwordx4 v[130:131], off
	v_lshl_add_u64 v[132:133], s[64:65], 0, v[168:169]
	s_mov_b32 m0, s27
	v_lshl_add_u64 v[134:135], s[70:71], 0, v[66:67]
	global_load_lds_dwordx4 v[132:133], off
	v_lshl_add_u64 v[132:133], s[64:65], 0, v[64:65]
	s_mov_b32 m0, s29
	s_nop 0
	global_load_lds_dwordx4 v[132:133], off
	v_lshl_add_u64 v[132:133], s[70:71], 0, v[68:69]
	s_mov_b32 m0, s26
	s_nop 0
	global_load_lds_dwordx4 v[132:133], off
	s_mov_b32 m0, s31
	s_nop 0
	global_load_lds_dwordx4 v[134:135], off
	s_waitcnt vmcnt(8)
	s_waitcnt lgkmcnt(0)
	s_barrier
	s_setprio 1
	v_mfma_f32_16x16x32_bf16 v[28:31], v[80:83], v[96:99], v[28:31]
	v_mfma_f32_16x16x32_bf16 v[24:27], v[88:91], v[96:99], v[24:27]
	v_mfma_f32_16x16x32_bf16 v[20:23], v[80:83], v[104:107], v[20:23]
	v_mfma_f32_16x16x32_bf16 v[16:19], v[88:91], v[104:107], v[16:19]
	v_mfma_f32_16x16x32_bf16 v[12:15], v[80:83], v[112:115], v[12:15]
	v_mfma_f32_16x16x32_bf16 v[8:11], v[88:91], v[112:115], v[8:11]
	v_mfma_f32_16x16x32_bf16 v[4:7], v[80:83], v[120:123], v[4:7]
	v_mfma_f32_16x16x32_bf16 v[0:3], v[88:91], v[120:123], v[0:3]
	v_mfma_f32_16x16x32_bf16 v[28:31], v[84:87], v[100:103], v[28:31]
	v_mfma_f32_16x16x32_bf16 v[24:27], v[92:95], v[100:103], v[24:27]
	v_mfma_f32_16x16x32_bf16 v[20:23], v[84:87], v[108:111], v[20:23]
	v_mfma_f32_16x16x32_bf16 v[16:19], v[92:95], v[108:111], v[16:19]
	v_mfma_f32_16x16x32_bf16 v[12:15], v[84:87], v[116:119], v[12:15]
	v_mfma_f32_16x16x32_bf16 v[8:11], v[92:95], v[116:119], v[8:11]
	v_mfma_f32_16x16x32_bf16 v[4:7], v[84:87], v[124:127], v[4:7]
	v_mfma_f32_16x16x32_bf16 v[0:3], v[92:95], v[124:127], v[0:3]
	s_setprio 0
	s_barrier
; #define PG8_STAGE(bufoff, gbase, voff) do { _Pragma("unroll") for (int _i = 0; _i < 2; ++_i) \
;         __builtin_amdgcn_global_load_lds((const unsigned*)((const char*)(gbase) + (voff)[_i]), (LAS unsigned*)(lds + (bufoff) + ldsw + _i * 8192), 16, 0, 0); } while (0)
; #define PG8_LDA(dst, b, h) do { _Pragma("unroll") for (int m = 0; m < 4; ++m) _Pragma("unroll") for (int k = 0; k < 2; ++k) dst[m][k] = *(const LAS bf16x8*)(lds + PG8_SA(b, h) + aoff + m * 2048 + k * 1024); } while (0)
; #define PG8_LDB(dst, b, h) do { _Pragma("unroll") for (int n = 0; n < 2; ++n) _Pragma("unroll") for (int k = 0; k < 2; ++k) dst[n][k] = *(const LAS bf16x8*)(lds + PG8_SB(b, h) + boff + n * 2048 + k * 1024); } while (0)
; #define PG8_MMA(ai, bj, At, Bt) do { __builtin_amdgcn_s_setprio(1); _Pragma("unroll") for (int m = 0; m < 4; ++m) _Pragma("unroll") for (int n = 0; n < 2; ++n) _Pragma("unroll") for (int k = 0; k < 2; ++k) \
;         acc[ai][bj][m][n] = __builtin_amdgcn_mfma_f32_16x16x32_bf16(Bt[n][k], At[m][k], acc[ai][bj][m][n], 0, 0, 0); __builtin_amdgcn_s_setprio(0); } while (0)
; #define PG8_WAIT_V(n) asm volatile("s_waitcnt vmcnt(" #n ")" ::: "memory")
; #define PG8_WAIT_L(n) asm volatile("s_waitcnt lgkmcnt(" #n ")" ::: "memory")
; #define PG8_BAR __builtin_amdgcn_s_barrier()
; #define PG8_SCHED __builtin_amdgcn_sched_barrier(0)
; template <class Epi, class Sched>
; __device__ __forceinline__ void gemm_phase(const int tid, LAS unsigned char* lds, const int lda, const int ldb, const int K, const Sched& S, const Epi& E) {
;     ...
;             PG8_LDB(B0, 1, 0); PG8_LDB(B1, 1, 1); PG8_SCHED; PG8_LDA(At, 1, 0); PG8_STAGE(PG8_SA(0, 1), a2 + hstepA, voffA);
;             PG8_WAIT_V(8); PG8_WAIT_L(0); PG8_BAR; PG8_MMA(0, 0, At, B0); PG8_MMA(0, 1, At, B1); PG8_BAR; PG8_SCHED;
;             PG8_LDA(At, 1, 1); PG8_STAGE(PG8_SB(1, 0), b3, voffB); PG8_STAGE(PG8_SB(1, 1), b3 + hstepB, voffB); PG8_STAGE(PG8_SA(1, 0), a3, voffA);
;             PG8_WAIT_V(8); PG8_WAIT_L(0); PG8_BAR; if (!cur.half) { PG8_MMA(1, 0, At, B0); PG8_MMA(1, 1, At, B1); } PG8_BAR; PG8_SCHED;
;         }
	s_add_i32 s14, 0, 0x18000
	v_add_u32_e32 v79, s14, v77
	ds_read_b128 v[80:83], v79
	ds_read_b128 v[84:87], v79 offset:1024
	ds_read_b128 v[88:91], v79 offset:2048
	ds_read_b128 v[92:95], v79 offset:3072
	s_add_u32 s64, s70, 0x28000
	s_addc_u32 s65, s71, 0
	s_mov_b32 m0, s42
	v_lshl_add_u64 v[138:139], s[64:65], 0, v[68:69]
	ds_read_b128 v[96:99], v78 offset:32768
	ds_read_b128 v[100:103], v78 offset:33792
	ds_read_b128 v[104:107], v78 offset:34816
	ds_read_b128 v[108:111], v78 offset:35840
	ds_read_b128 v[112:115], v78 offset:36864
	ds_read_b128 v[116:119], v78 offset:37888
	ds_read_b128 v[120:123], v78 offset:38912
	ds_read_b128 v[124:127], v78 offset:39936
	global_load_lds_dwordx4 v[138:139], off
	v_lshl_add_u64 v[138:139], s[64:65], 0, v[66:67]
	s_mov_b32 m0, s43
	s_nop 0
	global_load_lds_dwordx4 v[138:139], off
	s_waitcnt vmcnt(8)
	s_waitcnt lgkmcnt(0)
	s_barrier
	s_setprio 1
	v_mfma_f32_16x16x32_bf16 v[60:63], v[80:83], v[96:99], v[60:63]
	v_mfma_f32_16x16x32_bf16 v[56:59], v[88:91], v[96:99], v[56:59]
	v_mfma_f32_16x16x32_bf16 v[52:55], v[80:83], v[104:107], v[52:55]
	v_mfma_f32_16x16x32_bf16 v[48:51], v[88:91], v[104:107], v[48:51]
	v_mfma_f32_16x16x32_bf16 v[44:47], v[80:83], v[112:115], v[44:47]
	v_mfma_f32_16x16x32_bf16 v[40:43], v[88:91], v[112:115], v[40:43]
	v_mfma_f32_16x16x32_bf16 v[36:39], v[80:83], v[120:123], v[36:39]
	v_mfma_f32_16x16x32_bf16 v[32:35], v[88:91], v[120:123], v[32:35]
	v_mfma_f32_16x16x32_bf16 v[60:63], v[84:87], v[100:103], v[60:63]
	v_mfma_f32_16x16x32_bf16 v[56:59], v[92:95], v[100:103], v[56:59]
	v_mfma_f32_16x16x32_bf16 v[52:55], v[84:87], v[108:111], v[52:55]
	v_mfma_f32_16x16x32_bf16 v[48:51], v[92:95], v[108:111], v[48:51]
	v_mfma_f32_16x16x32_bf16 v[44:47], v[84:87], v[116:119], v[44:47]
	v_mfma_f32_16x16x32_bf16 v[40:43], v[92:95], v[116:119], v[40:43]
	v_mfma_f32_16x16x32_bf16 v[36:39], v[84:87], v[124:127], v[36:39]
	v_mfma_f32_16x16x32_bf16 v[32:35], v[92:95], v[124:127], v[32:35]
	s_setprio 0
	s_barrier
	s_add_i32 s14, s14, s13
	v_lshl_add_u64 v[128:129], v[128:129], 0, s[6:7]
	s_mov_b32 m0, s14
	ds_read_b128 v[96:99], v78 offset:49152
	ds_read_b128 v[100:103], v78 offset:50176
	ds_read_b128 v[104:107], v78 offset:51200
	ds_read_b128 v[108:111], v78 offset:52224
	ds_read_b128 v[112:115], v78 offset:53248
	ds_read_b128 v[116:119], v78 offset:54272
	ds_read_b128 v[120:123], v78 offset:55296
	ds_read_b128 v[124:127], v78 offset:56320
	global_load_lds_dwordx4 v[128:129], off
	s_add_i32 m0, s14, 0x2000
	s_add_u32 s64, s68, 0x20080
	v_lshl_add_u64 v[128:129], v[130:131], 0, s[6:7]
	s_addc_u32 s65, s69, 0
	global_load_lds_dwordx4 v[128:129], off
	v_lshl_add_u64 v[128:129], s[64:65], 0, v[168:169]
	s_mov_b32 m0, s74
	s_nop 0
	global_load_lds_dwordx4 v[128:129], off
	v_lshl_add_u64 v[128:129], s[64:65], 0, v[64:65]
	s_mov_b32 m0, s75
	s_nop 0
	global_load_lds_dwordx4 v[128:129], off
	v_lshl_add_u64 v[128:129], v[132:133], 0, s[6:7]
	s_mov_b32 m0, s72
	s_nop 0
	global_load_lds_dwordx4 v[128:129], off
	v_lshl_add_u64 v[128:129], v[134:135], 0, s[6:7]
	s_mov_b32 m0, s73
	s_nop 0
	global_load_lds_dwordx4 v[128:129], off
	s_waitcnt vmcnt(8)
	s_waitcnt lgkmcnt(0)
	s_barrier
	s_setprio 1
	v_mfma_f32_16x16x32_bf16 v[28:31], v[80:83], v[96:99], v[28:31]
	v_mfma_f32_16x16x32_bf16 v[24:27], v[88:91], v[96:99], v[24:27]
	v_mfma_f32_16x16x32_bf16 v[20:23], v[80:83], v[104:107], v[20:23]
	v_mfma_f32_16x16x32_bf16 v[16:19], v[88:91], v[104:107], v[16:19]
	v_mfma_f32_16x16x32_bf16 v[12:15], v[80:83], v[112:115], v[12:15]
	v_mfma_f32_16x16x32_bf16 v[8:11], v[88:91], v[112:115], v[8:11]
	v_mfma_f32_16x16x32_bf16 v[4:7], v[80:83], v[120:123], v[4:7]
	v_mfma_f32_16x16x32_bf16 v[0:3], v[88:91], v[120:123], v[0:3]
	v_mfma_f32_16x16x32_bf16 v[28:31], v[84:87], v[100:103], v[28:31]
	v_mfma_f32_16x16x32_bf16 v[24:27], v[92:95], v[100:103], v[24:27]
	v_mfma_f32_16x16x32_bf16 v[20:23], v[84:87], v[108:111], v[20:23]
	v_mfma_f32_16x16x32_bf16 v[16:19], v[92:95], v[108:111], v[16:19]
	v_mfma_f32_16x16x32_bf16 v[12:15], v[84:87], v[116:119], v[12:15]
	v_mfma_f32_16x16x32_bf16 v[8:11], v[92:95], v[116:119], v[8:11]
	v_mfma_f32_16x16x32_bf16 v[4:7], v[84:87], v[124:127], v[4:7]
	v_mfma_f32_16x16x32_bf16 v[0:3], v[92:95], v[124:127], v[0:3]
	s_setprio 0
	s_barrier
	s_add_u32 s39, s39, 0x100
	s_addc_u32 s53, s53, 0
	s_cmp_ge_i32 s24, s22
	s_mov_b64 s[64:65], s[66:67]
	s_mov_b32 s68, s24
	s_cbranch_scc0 .LBB0_816
	s_load_dword s70, s[0:1], 0x108
	v_readlane_b32 s68, v255, 13
	v_readlane_b32 s69, v255, 14
	s_movk_i32 s71, 0x1600
	s_branch .LBB0_819

; #define PG8_STAGE(bufoff, gbase, voff) do { _Pragma("unroll") for (int _i = 0; _i < 2; ++_i) \
;         __builtin_amdgcn_global_load_lds((const unsigned*)((const char*)(gbase) + (voff)[_i]), (LAS unsigned*)(lds + (bufoff) + ldsw + _i * 8192), 16, 0, 0); } while (0)
; #define PG8_LDA(dst, b, h) do { _Pragma("unroll") for (int m = 0; m < 4; ++m) _Pragma("unroll") for (int k = 0; k < 2; ++k) dst[m][k] = *(const LAS bf16x8*)(lds + PG8_SA(b, h) + aoff + m * 2048 + k * 1024); } while (0)
; #define PG8_LDB(dst, b, h) do { _Pragma("unroll") for (int n = 0; n < 2; ++n) _Pragma("unroll") for (int k = 0; k < 2; ++k) dst[n][k] = *(const LAS bf16x8*)(lds + PG8_SB(b, h) + boff + n * 2048 + k * 1024); } while (0)
; #define PG8_MMA(ai, bj, At, Bt) do { __builtin_amdgcn_s_setprio(1); _Pragma("unroll") for (int m = 0; m < 4; ++m) _Pragma("unroll") for (int n = 0; n < 2; ++n) _Pragma("unroll") for (int k = 0; k < 2; ++k) \
;         acc[ai][bj][m][n] = __builtin_amdgcn_mfma_f32_16x16x32_bf16(Bt[n][k], At[m][k], acc[ai][bj][m][n], 0, 0, 0); __builtin_amdgcn_s_setprio(0); } while (0)
; #define PG8_BAR __builtin_amdgcn_s_barrier()
; template <class Epi, class Sched>
; __device__ __forceinline__ void gemm_phase(const int tid, LAS unsigned char* lds, const int lda, const int ldb, const int K, const Sched& S, const Epi& E) {
;     ...
;     for (;;) {
;         const bool has_next = S.next(ui + 1, nxt);
;         const char* nA = has_next ? nxt.a : cA; const char* nB = has_next ? nxt.b : cB;
;         for (int t = 0; t < nt; t += 2) {
;             const bool last = (t == nt - 2);
;             const char* a1 = cA + (size_t)(t + 1) * kstep;
;             const char* a2 = last ? nA : cA + (size_t)(t + 2) * kstep; const char* b2 = last ? nB : cB + (size_t)(t + 2) * kstep;
;             const char* a3 = a2 + kstep; const char* b3 = b2 + kstep;
;             PG8_LDB(B0, 0, 0); PG8_LDB(B1, 0, 1); PG8_SCHED; PG8_LDA(At, 0, 0); PG8_STAGE(PG8_SA(1, 1), a1 + hstepA, voffA);
;             PG8_WAIT_V(8); PG8_WAIT_L(0); PG8_BAR; PG8_MMA(0, 0, At, B0); PG8_MMA(0, 1, At, B1); PG8_BAR; PG8_SCHED;
;             PG8_LDA(At, 0, 1); PG8_STAGE(PG8_SB(0, 0), b2, voffB); PG8_STAGE(PG8_SB(0, 1), b2 + hstepB, voffB); PG8_STAGE(PG8_SA(0, 0), a2, voffA);
;             PG8_WAIT_V(8); PG8_WAIT_L(0); PG8_BAR; if (!cur.half) { PG8_MMA(1, 0, At, B0); PG8_MMA(1, 1, At, B1); } PG8_BAR; PG8_SCHED;
.LBB0_872:
	s_andn2_b64 vcc, exec, s[40:41]
	s_cbranch_vccnz .LBB0_880
	s_add_u32 s50, s50, 0x40080
	s_addc_u32 s51, s51, 0
	s_add_u32 s45, s52, 0x100
	s_addc_u32 s63, s53, 0
	s_mov_b32 s52, 0
	s_add_i32 s64, s52, 2
	s_add_u32 s14, s50, 0xfffc0080
	s_addc_u32 s15, s51, -1
	s_add_i32 s24, 0, 0x10000
	s_cmp_eq_u32 s60, s52
	s_cselect_b32 s55, s3, s15
	s_cselect_b32 s54, s2, s14
	v_add_u32_e32 v141, s24, v148
	s_cselect_b32 s53, s39, s63
	s_cselect_b32 s52, s38, s45
	s_add_i32 s14, 0, 0x14000
	ds_read_b128 v[158:161], v141
	ds_read_b128 v[162:165], v141 offset:1024
	ds_read_b128 v[180:183], v141 offset:2048
	ds_read_b128 v[184:187], v141 offset:3072
	v_add_u32_e32 v141, s14, v148
	ds_read_b128 v[190:193], v141
	ds_read_b128 v[194:197], v141 offset:1024
	ds_read_b128 v[204:207], v141 offset:2048
	ds_read_b128 v[208:211], v141 offset:3072
	v_lshl_add_u64 v[166:167], s[50:51], 0, v[136:137]
	s_add_i32 m0, s21, 0xc000
	ds_read_b128 v[212:215], v155
	ds_read_b128 v[216:219], v155 offset:1024
	ds_read_b128 v[220:223], v155 offset:2048
	ds_read_b128 v[224:227], v155 offset:3072
	ds_read_b128 v[228:231], v155 offset:4096
	ds_read_b128 v[232:235], v155 offset:5120
	ds_read_b128 v[236:239], v155 offset:6144
	ds_read_b128 v[240:243], v155 offset:7168
	global_load_lds_dwordx4 v[166:167], off
	v_lshl_add_u64 v[166:167], s[50:51], 0, v[138:139]
	s_add_i32 m0, s21, 0xe000
	s_nop 0
	global_load_lds_dwordx4 v[166:167], off
	s_waitcnt vmcnt(8)
	s_waitcnt lgkmcnt(0)
	s_barrier
	s_setprio 1
	v_mfma_f32_16x16x32_bf16 v[124:127], v[158:161], v[212:215], 0
	v_mfma_f32_16x16x32_bf16 v[120:123], v[180:183], v[212:215], 0
	v_mfma_f32_16x16x32_bf16 v[108:111], v[158:161], v[220:223], 0
	v_mfma_f32_16x16x32_bf16 v[104:107], v[180:183], v[220:223], 0
	v_mfma_f32_16x16x32_bf16 v[92:95], v[158:161], v[228:231], 0
	v_mfma_f32_16x16x32_bf16 v[88:91], v[180:183], v[228:231], 0
	v_mfma_f32_16x16x32_bf16 v[76:79], v[158:161], v[236:239], 0
	v_mfma_f32_16x16x32_bf16 v[72:75], v[180:183], v[236:239], 0
	v_mfma_f32_16x16x32_bf16 v[124:127], v[162:165], v[216:219], v[124:127]
	v_mfma_f32_16x16x32_bf16 v[120:123], v[184:187], v[216:219], v[120:123]
	v_mfma_f32_16x16x32_bf16 v[108:111], v[162:165], v[224:227], v[108:111]
	v_mfma_f32_16x16x32_bf16 v[104:107], v[184:187], v[224:227], v[104:107]
	v_mfma_f32_16x16x32_bf16 v[92:95], v[162:165], v[232:235], v[92:95]
	v_mfma_f32_16x16x32_bf16 v[88:91], v[184:187], v[232:235], v[88:91]
	v_mfma_f32_16x16x32_bf16 v[76:79], v[162:165], v[240:243], v[76:79]
	v_mfma_f32_16x16x32_bf16 v[72:75], v[184:187], v[240:243], v[72:75]
	v_mfma_f32_16x16x32_bf16 v[116:119], v[190:193], v[212:215], 0
	v_mfma_f32_16x16x32_bf16 v[112:115], v[204:207], v[212:215], 0
	v_mfma_f32_16x16x32_bf16 v[100:103], v[190:193], v[220:223], 0
	v_mfma_f32_16x16x32_bf16 v[96:99], v[204:207], v[220:223], 0
	v_mfma_f32_16x16x32_bf16 v[84:87], v[190:193], v[228:231], 0
	v_mfma_f32_16x16x32_bf16 v[80:83], v[204:207], v[228:231], 0
	v_mfma_f32_16x16x32_bf16 v[68:71], v[190:193], v[236:239], 0
	v_mfma_f32_16x16x32_bf16 v[64:67], v[204:207], v[236:239], 0
	v_mfma_f32_16x16x32_bf16 v[116:119], v[194:197], v[216:219], v[116:119]
	v_mfma_f32_16x16x32_bf16 v[112:115], v[208:211], v[216:219], v[112:115]
	v_mfma_f32_16x16x32_bf16 v[100:103], v[194:197], v[224:227], v[100:103]
	v_mfma_f32_16x16x32_bf16 v[96:99], v[208:211], v[224:227], v[96:99]
	v_mfma_f32_16x16x32_bf16 v[84:87], v[194:197], v[232:235], v[84:87]
	v_mfma_f32_16x16x32_bf16 v[80:83], v[208:211], v[232:235], v[80:83]
	v_mfma_f32_16x16x32_bf16 v[68:71], v[194:197], v[240:243], v[68:71]
	v_mfma_f32_16x16x32_bf16 v[64:67], v[208:211], v[240:243], v[64:67]
	s_setprio 0
	s_barrier
	s_add_i32 s15, s24, s20
	v_lshl_add_u64 v[166:167], s[52:53], 0, v[130:131]
	s_mov_b32 m0, s15
	ds_read_b128 v[212:215], v155 offset:16384
	ds_read_b128 v[216:219], v155 offset:17408
	ds_read_b128 v[220:223], v155 offset:18432
	ds_read_b128 v[224:227], v155 offset:19456
	ds_read_b128 v[228:231], v155 offset:20480
	ds_read_b128 v[232:235], v155 offset:21504
	ds_read_b128 v[236:239], v155 offset:22528
	ds_read_b128 v[240:243], v155 offset:23552
	global_load_lds_dwordx4 v[166:167], off
	s_add_i32 m0, s15, 0x2000
	s_add_u32 s66, s52, 0x40000
	v_lshl_add_u64 v[244:245], s[52:53], 0, v[134:135]
	s_addc_u32 s67, s53, 0
	s_add_i32 s14, s14, s20
	global_load_lds_dwordx4 v[244:245], off
	v_lshl_add_u64 v[246:247], s[66:67], 0, v[130:131]
	s_mov_b32 m0, s14
	v_lshl_add_u64 v[248:249], s[54:55], 0, v[132:133]
	global_load_lds_dwordx4 v[246:247], off
	v_lshl_add_u64 v[246:247], s[66:67], 0, v[134:135]
	s_add_i32 m0, s14, 0x2000
	s_nop 0
	global_load_lds_dwordx4 v[246:247], off
	v_lshl_add_u64 v[246:247], s[54:55], 0, v[128:129]
	s_mov_b32 m0, s21
	s_nop 0
	global_load_lds_dwordx4 v[246:247], off
	s_mov_b32 m0, s29
	s_nop 0
	global_load_lds_dwordx4 v[248:249], off
	s_waitcnt vmcnt(8)
	s_waitcnt lgkmcnt(0)
	s_barrier
; #define PG8_STAGE(bufoff, gbase, voff) do { _Pragma("unroll") for (int _i = 0; _i < 2; ++_i) \
;         __builtin_amdgcn_global_load_lds((const unsigned*)((const char*)(gbase) + (voff)[_i]), (LAS unsigned*)(lds + (bufoff) + ldsw + _i * 8192), 16, 0, 0); } while (0)
; #define PG8_LDA(dst, b, h) do { _Pragma("unroll") for (int m = 0; m < 4; ++m) _Pragma("unroll") for (int k = 0; k < 2; ++k) dst[m][k] = *(const LAS bf16x8*)(lds + PG8_SA(b, h) + aoff + m * 2048 + k * 1024); } while (0)
; #define PG8_LDB(dst, b, h) do { _Pragma("unroll") for (int n = 0; n < 2; ++n) _Pragma("unroll") for (int k = 0; k < 2; ++k) dst[n][k] = *(const LAS bf16x8*)(lds + PG8_SB(b, h) + boff + n * 2048 + k * 1024); } while (0)
; #define PG8_MMA(ai, bj, At, Bt) do { __builtin_amdgcn_s_setprio(1); _Pragma("unroll") for (int m = 0; m < 4; ++m) _Pragma("unroll") for (int n = 0; n < 2; ++n) _Pragma("unroll") for (int k = 0; k < 2; ++k) \
;         acc[ai][bj][m][n] = __builtin_amdgcn_mfma_f32_16x16x32_bf16(Bt[n][k], At[m][k], acc[ai][bj][m][n], 0, 0, 0); __builtin_amdgcn_s_setprio(0); } while (0)
; #define PG8_WAIT_V(n) asm volatile("s_waitcnt vmcnt(" #n ")" ::: "memory")
; #define PG8_WAIT_L(n) asm volatile("s_waitcnt lgkmcnt(" #n ")" ::: "memory")
; #define PG8_BAR __builtin_amdgcn_s_barrier()
; #define PG8_SCHED __builtin_amdgcn_sched_barrier(0)
; template <class Epi, class Sched>
; __device__ __forceinline__ void gemm_phase(const int tid, LAS unsigned char* lds, const int lda, const int ldb, const int K, const Sched& S, const Epi& E) {
;     ...
;             PG8_WAIT_V(8); PG8_WAIT_L(0); PG8_BAR; PG8_MMA(0, 0, At, B0); PG8_MMA(0, 1, At, B1); PG8_BAR; PG8_SCHED;
;             PG8_LDA(At, 0, 1); PG8_STAGE(PG8_SB(0, 0), b2, voffB); PG8_STAGE(PG8_SB(0, 1), b2 + hstepB, voffB); PG8_STAGE(PG8_SA(0, 0), a2, voffA);
;             PG8_WAIT_V(8); PG8_WAIT_L(0); PG8_BAR; if (!cur.half) { PG8_MMA(1, 0, At, B0); PG8_MMA(1, 1, At, B1); } PG8_BAR; PG8_SCHED;
;             PG8_LDB(B0, 1, 0); PG8_LDB(B1, 1, 1); PG8_SCHED; PG8_LDA(At, 1, 0); PG8_STAGE(PG8_SA(0, 1), a2 + hstepA, voffA);
;             PG8_WAIT_V(8); PG8_WAIT_L(0); PG8_BAR; PG8_MMA(0, 0, At, B0); PG8_MMA(0, 1, At, B1); PG8_BAR; PG8_SCHED;
	s_setprio 1
	v_mfma_f32_16x16x32_bf16 v[60:63], v[158:161], v[212:215], 0
	v_mfma_f32_16x16x32_bf16 v[56:59], v[180:183], v[212:215], 0
	v_mfma_f32_16x16x32_bf16 v[44:47], v[158:161], v[220:223], 0
	v_mfma_f32_16x16x32_bf16 v[40:43], v[180:183], v[220:223], 0
	v_mfma_f32_16x16x32_bf16 v[28:31], v[158:161], v[228:231], 0
	v_mfma_f32_16x16x32_bf16 v[24:27], v[180:183], v[228:231], 0
	v_mfma_f32_16x16x32_bf16 v[12:15], v[158:161], v[236:239], 0
	v_mfma_f32_16x16x32_bf16 v[8:11], v[180:183], v[236:239], 0
	v_mfma_f32_16x16x32_bf16 v[60:63], v[162:165], v[216:219], v[60:63]
	v_mfma_f32_16x16x32_bf16 v[56:59], v[184:187], v[216:219], v[56:59]
	v_mfma_f32_16x16x32_bf16 v[44:47], v[162:165], v[224:227], v[44:47]
	v_mfma_f32_16x16x32_bf16 v[40:43], v[184:187], v[224:227], v[40:43]
	v_mfma_f32_16x16x32_bf16 v[28:31], v[162:165], v[232:235], v[28:31]
	v_mfma_f32_16x16x32_bf16 v[24:27], v[184:187], v[232:235], v[24:27]
	v_mfma_f32_16x16x32_bf16 v[12:15], v[162:165], v[240:243], v[12:15]
	v_mfma_f32_16x16x32_bf16 v[8:11], v[184:187], v[240:243], v[8:11]
	v_mfma_f32_16x16x32_bf16 v[52:55], v[190:193], v[212:215], 0
	v_mfma_f32_16x16x32_bf16 v[48:51], v[204:207], v[212:215], 0
	v_mfma_f32_16x16x32_bf16 v[36:39], v[190:193], v[220:223], 0
	v_mfma_f32_16x16x32_bf16 v[32:35], v[204:207], v[220:223], 0
	v_mfma_f32_16x16x32_bf16 v[20:23], v[190:193], v[228:231], 0
	v_mfma_f32_16x16x32_bf16 v[16:19], v[204:207], v[228:231], 0
	v_mfma_f32_16x16x32_bf16 v[4:7], v[190:193], v[236:239], 0
	v_mfma_f32_16x16x32_bf16 v[0:3], v[204:207], v[236:239], 0
	v_mfma_f32_16x16x32_bf16 v[52:55], v[194:197], v[216:219], v[52:55]
	v_mfma_f32_16x16x32_bf16 v[48:51], v[208:211], v[216:219], v[48:51]
	v_mfma_f32_16x16x32_bf16 v[36:39], v[194:197], v[224:227], v[36:39]
	v_mfma_f32_16x16x32_bf16 v[32:35], v[208:211], v[224:227], v[32:35]
	v_mfma_f32_16x16x32_bf16 v[20:23], v[194:197], v[232:235], v[20:23]
	v_mfma_f32_16x16x32_bf16 v[16:19], v[208:211], v[232:235], v[16:19]
	v_mfma_f32_16x16x32_bf16 v[4:7], v[194:197], v[240:243], v[4:7]
	v_mfma_f32_16x16x32_bf16 v[0:3], v[208:211], v[240:243], v[0:3]
	s_setprio 0
	s_barrier
	s_add_i32 s14, 0, 0x18000
	v_add_u32_e32 v141, s14, v148
	s_add_i32 s15, 0, 0x1c000
	ds_read_b128 v[158:161], v141
	ds_read_b128 v[162:165], v141 offset:1024
	ds_read_b128 v[180:183], v141 offset:2048
	ds_read_b128 v[184:187], v141 offset:3072
	v_add_u32_e32 v141, s15, v148
	ds_read_b128 v[190:193], v141
	ds_read_b128 v[194:197], v141 offset:1024
	ds_read_b128 v[204:207], v141 offset:2048
	ds_read_b128 v[208:211], v141 offset:3072
	s_add_u32 s54, s54, 0x40000
	s_addc_u32 s55, s55, 0
	s_mov_b32 m0, s31
	v_lshl_add_u64 v[250:251], s[54:55], 0, v[128:129]
	ds_read_b128 v[212:215], v155 offset:32768
	ds_read_b128 v[216:219], v155 offset:33792
	ds_read_b128 v[220:223], v155 offset:34816
	ds_read_b128 v[224:227], v155 offset:35840
	ds_read_b128 v[228:231], v155 offset:36864
	ds_read_b128 v[232:235], v155 offset:37888
	ds_read_b128 v[236:239], v155 offset:38912
	ds_read_b128 v[240:243], v155 offset:39936
	global_load_lds_dwordx4 v[250:251], off
	v_lshl_add_u64 v[250:251], s[54:55], 0, v[132:133]
	s_mov_b32 m0, s56
	s_nop 0
	global_load_lds_dwordx4 v[250:251], off
	s_waitcnt vmcnt(8)
	s_waitcnt lgkmcnt(0)
	s_barrier
	s_setprio 1
	v_mfma_f32_16x16x32_bf16 v[124:127], v[158:161], v[212:215], v[124:127]
	v_mfma_f32_16x16x32_bf16 v[120:123], v[180:183], v[212:215], v[120:123]
	v_mfma_f32_16x16x32_bf16 v[108:111], v[158:161], v[220:223], v[108:111]
	v_mfma_f32_16x16x32_bf16 v[104:107], v[180:183], v[220:223], v[104:107]
	v_mfma_f32_16x16x32_bf16 v[92:95], v[158:161], v[228:231], v[92:95]
	v_mfma_f32_16x16x32_bf16 v[88:91], v[180:183], v[228:231], v[88:91]
	v_mfma_f32_16x16x32_bf16 v[76:79], v[158:161], v[236:239], v[76:79]
	v_mfma_f32_16x16x32_bf16 v[72:75], v[180:183], v[236:239], v[72:75]
	v_mfma_f32_16x16x32_bf16 v[124:127], v[162:165], v[216:219], v[124:127]
	v_mfma_f32_16x16x32_bf16 v[120:123], v[184:187], v[216:219], v[120:123]
	v_mfma_f32_16x16x32_bf16 v[108:111], v[162:165], v[224:227], v[108:111]
	v_mfma_f32_16x16x32_bf16 v[104:107], v[184:187], v[224:227], v[104:107]
	v_mfma_f32_16x16x32_bf16 v[92:95], v[162:165], v[232:235], v[92:95]
	v_mfma_f32_16x16x32_bf16 v[88:91], v[184:187], v[232:235], v[88:91]
	v_mfma_f32_16x16x32_bf16 v[76:79], v[162:165], v[240:243], v[76:79]
	v_mfma_f32_16x16x32_bf16 v[72:75], v[184:187], v[240:243], v[72:75]
	v_mfma_f32_16x16x32_bf16 v[116:119], v[190:193], v[212:215], v[116:119]
	v_mfma_f32_16x16x32_bf16 v[112:115], v[204:207], v[212:215], v[112:115]
	v_mfma_f32_16x16x32_bf16 v[100:103], v[190:193], v[220:223], v[100:103]
	v_mfma_f32_16x16x32_bf16 v[96:99], v[204:207], v[220:223], v[96:99]
	v_mfma_f32_16x16x32_bf16 v[84:87], v[190:193], v[228:231], v[84:87]
	v_mfma_f32_16x16x32_bf16 v[80:83], v[204:207], v[228:231], v[80:83]
	v_mfma_f32_16x16x32_bf16 v[68:71], v[190:193], v[236:239], v[68:71]
	v_mfma_f32_16x16x32_bf16 v[64:67], v[204:207], v[236:239], v[64:67]
	v_mfma_f32_16x16x32_bf16 v[116:119], v[194:197], v[216:219], v[116:119]
	v_mfma_f32_16x16x32_bf16 v[112:115], v[208:211], v[216:219], v[112:115]
	v_mfma_f32_16x16x32_bf16 v[100:103], v[194:197], v[224:227], v[100:103]
	v_mfma_f32_16x16x32_bf16 v[96:99], v[208:211], v[224:227], v[96:99]
	v_mfma_f32_16x16x32_bf16 v[84:87], v[194:197], v[232:235], v[84:87]
	v_mfma_f32_16x16x32_bf16 v[80:83], v[208:211], v[232:235], v[80:83]
	v_mfma_f32_16x16x32_bf16 v[68:71], v[194:197], v[240:243], v[68:71]
	v_mfma_f32_16x16x32_bf16 v[64:67], v[208:211], v[240:243], v[64:67]
	s_setprio 0
	s_barrier
; #define PG8_STAGE(bufoff, gbase, voff) do { _Pragma("unroll") for (int _i = 0; _i < 2; ++_i) \
;         __builtin_amdgcn_global_load_lds((const unsigned*)((const char*)(gbase) + (voff)[_i]), (LAS unsigned*)(lds + (bufoff) + ldsw + _i * 8192), 16, 0, 0); } while (0)
; #define PG8_LDA(dst, b, h) do { _Pragma("unroll") for (int m = 0; m < 4; ++m) _Pragma("unroll") for (int k = 0; k < 2; ++k) dst[m][k] = *(const LAS bf16x8*)(lds + PG8_SA(b, h) + aoff + m * 2048 + k * 1024); } while (0)
; #define PG8_LDB(dst, b, h) do { _Pragma("unroll") for (int n = 0; n < 2; ++n) _Pragma("unroll") for (int k = 0; k < 2; ++k) dst[n][k] = *(const LAS bf16x8*)(lds + PG8_SB(b, h) + boff + n * 2048 + k * 1024); } while (0)
; #define PG8_MMA(ai, bj, At, Bt) do { __builtin_amdgcn_s_setprio(1); _Pragma("unroll") for (int m = 0; m < 4; ++m) _Pragma("unroll") for (int n = 0; n < 2; ++n) _Pragma("unroll") for (int k = 0; k < 2; ++k) \
;         acc[ai][bj][m][n] = __builtin_amdgcn_mfma_f32_16x16x32_bf16(Bt[n][k], At[m][k], acc[ai][bj][m][n], 0, 0, 0); __builtin_amdgcn_s_setprio(0); } while (0)
; #define PG8_WAIT_V(n) asm volatile("s_waitcnt vmcnt(" #n ")" ::: "memory")
; #define PG8_WAIT_L(n) asm volatile("s_waitcnt lgkmcnt(" #n ")" ::: "memory")
; #define PG8_BAR __builtin_amdgcn_s_barrier()
; template <class Epi, class Sched>
; __device__ __forceinline__ void gemm_phase(const int tid, LAS unsigned char* lds, const int lda, const int ldb, const int K, const Sched& S, const Epi& E) {
;     ...
;         for (int t = 0; t < nt; t += 2) {
;             const bool last = (t == nt - 2);
;             const char* a1 = cA + (size_t)(t + 1) * kstep;
;             const char* a2 = last ? nA : cA + (size_t)(t + 2) * kstep; const char* b2 = last ? nB : cB + (size_t)(t + 2) * kstep;
;             const char* a3 = a2 + kstep; const char* b3 = b2 + kstep;
;             PG8_LDB(B0, 0, 0); PG8_LDB(B1, 0, 1); PG8_SCHED; PG8_LDA(At, 0, 0); PG8_STAGE(PG8_SA(1, 1), a1 + hstepA, voffA);
;             PG8_WAIT_V(8); PG8_WAIT_L(0); PG8_BAR; PG8_MMA(0, 0, At, B0); PG8_MMA(0, 1, At, B1); PG8_BAR; PG8_SCHED;
;     ...
;             PG8_LDA(At, 1, 1); PG8_STAGE(PG8_SB(1, 0), b3, voffB); PG8_STAGE(PG8_SB(1, 1), b3 + hstepB, voffB); PG8_STAGE(PG8_SA(1, 0), a3, voffA);
;             PG8_WAIT_V(8); PG8_WAIT_L(0); PG8_BAR; if (!cur.half) { PG8_MMA(1, 0, At, B0); PG8_MMA(1, 1, At, B1); } PG8_BAR; PG8_SCHED;
	s_add_i32 s14, s14, s20
	v_lshl_add_u64 v[166:167], v[166:167], 0, s[6:7]
	s_mov_b32 m0, s14
	ds_read_b128 v[212:215], v155 offset:49152
	ds_read_b128 v[216:219], v155 offset:50176
	ds_read_b128 v[220:223], v155 offset:51200
	ds_read_b128 v[224:227], v155 offset:52224
	ds_read_b128 v[228:231], v155 offset:53248
	ds_read_b128 v[232:235], v155 offset:54272
	ds_read_b128 v[236:239], v155 offset:55296
	ds_read_b128 v[240:243], v155 offset:56320
	global_load_lds_dwordx4 v[166:167], off
	s_add_i32 m0, s14, 0x2000
	s_add_u32 s52, s52, 0x40080
	v_lshl_add_u64 v[166:167], v[244:245], 0, s[6:7]
	s_addc_u32 s53, s53, 0
	s_add_i32 s14, s15, s20
	global_load_lds_dwordx4 v[166:167], off
	v_lshl_add_u64 v[166:167], s[52:53], 0, v[130:131]
	s_mov_b32 m0, s14
	s_nop 0
	global_load_lds_dwordx4 v[166:167], off
	v_lshl_add_u64 v[166:167], s[52:53], 0, v[134:135]
	s_add_i32 m0, s14, 0x2000
	s_nop 0
	global_load_lds_dwordx4 v[166:167], off
	v_lshl_add_u64 v[166:167], v[246:247], 0, s[6:7]
	s_mov_b32 m0, s57
	s_nop 0
	global_load_lds_dwordx4 v[166:167], off
	v_lshl_add_u64 v[166:167], v[248:249], 0, s[6:7]
	s_mov_b32 m0, s58
	s_nop 0
	global_load_lds_dwordx4 v[166:167], off
	s_waitcnt vmcnt(8)
	s_waitcnt lgkmcnt(0)
	s_barrier
	s_setprio 1
	v_mfma_f32_16x16x32_bf16 v[60:63], v[158:161], v[212:215], v[60:63]
	v_mfma_f32_16x16x32_bf16 v[56:59], v[180:183], v[212:215], v[56:59]
	v_mfma_f32_16x16x32_bf16 v[44:47], v[158:161], v[220:223], v[44:47]
	v_mfma_f32_16x16x32_bf16 v[40:43], v[180:183], v[220:223], v[40:43]
	v_mfma_f32_16x16x32_bf16 v[28:31], v[158:161], v[228:231], v[28:31]
	v_mfma_f32_16x16x32_bf16 v[24:27], v[180:183], v[228:231], v[24:27]
	v_mfma_f32_16x16x32_bf16 v[12:15], v[158:161], v[236:239], v[12:15]
	v_mfma_f32_16x16x32_bf16 v[8:11], v[180:183], v[236:239], v[8:11]
	v_mfma_f32_16x16x32_bf16 v[60:63], v[162:165], v[216:219], v[60:63]
	v_mfma_f32_16x16x32_bf16 v[56:59], v[184:187], v[216:219], v[56:59]
	v_mfma_f32_16x16x32_bf16 v[44:47], v[162:165], v[224:227], v[44:47]
	v_mfma_f32_16x16x32_bf16 v[40:43], v[184:187], v[224:227], v[40:43]
	v_mfma_f32_16x16x32_bf16 v[28:31], v[162:165], v[232:235], v[28:31]
	v_mfma_f32_16x16x32_bf16 v[24:27], v[184:187], v[232:235], v[24:27]
	v_mfma_f32_16x16x32_bf16 v[12:15], v[162:165], v[240:243], v[12:15]
	v_mfma_f32_16x16x32_bf16 v[8:11], v[184:187], v[240:243], v[8:11]
	v_mfma_f32_16x16x32_bf16 v[52:55], v[190:193], v[212:215], v[52:55]
	v_mfma_f32_16x16x32_bf16 v[48:51], v[204:207], v[212:215], v[48:51]
	v_mfma_f32_16x16x32_bf16 v[36:39], v[190:193], v[220:223], v[36:39]
	v_mfma_f32_16x16x32_bf16 v[32:35], v[204:207], v[220:223], v[32:35]
	v_mfma_f32_16x16x32_bf16 v[20:23], v[190:193], v[228:231], v[20:23]
	v_mfma_f32_16x16x32_bf16 v[16:19], v[204:207], v[228:231], v[16:19]
	v_mfma_f32_16x16x32_bf16 v[4:7], v[190:193], v[236:239], v[4:7]
	v_mfma_f32_16x16x32_bf16 v[0:3], v[204:207], v[236:239], v[0:3]
	v_mfma_f32_16x16x32_bf16 v[52:55], v[194:197], v[216:219], v[52:55]
	v_mfma_f32_16x16x32_bf16 v[48:51], v[208:211], v[216:219], v[48:51]
	v_mfma_f32_16x16x32_bf16 v[36:39], v[194:197], v[224:227], v[36:39]
	v_mfma_f32_16x16x32_bf16 v[32:35], v[208:211], v[224:227], v[32:35]
	v_mfma_f32_16x16x32_bf16 v[20:23], v[194:197], v[232:235], v[20:23]
	v_mfma_f32_16x16x32_bf16 v[16:19], v[208:211], v[232:235], v[16:19]
	v_mfma_f32_16x16x32_bf16 v[4:7], v[194:197], v[240:243], v[4:7]
	v_mfma_f32_16x16x32_bf16 v[0:3], v[208:211], v[240:243], v[0:3]
	s_setprio 0
	s_barrier
	s_add_u32 s50, s50, 0x100
	s_addc_u32 s51, s51, 0
	s_add_u32 s45, s45, 0x100
	s_addc_u32 s63, s63, 0
	s_cmp_ge_i32 s64, s4
	s_mov_b32 s52, s64
	s_cbranch_scc1 .Lkexit_874
.LBB0_874:
	s_add_i32 s64, s52, 2
	s_add_u32 s14, s50, 0xfffc0080
	s_addc_u32 s15, s51, -1
	s_add_i32 s24, 0, 0x10000
	s_cmp_eq_u32 s60, s52
	s_cselect_b32 s55, s3, s15
	s_cselect_b32 s54, s2, s14
	v_add_u32_e32 v141, s24, v148
	s_cselect_b32 s53, s39, s63
	s_cselect_b32 s52, s38, s45
	s_add_i32 s14, 0, 0x14000
	ds_read_b128 v[158:161], v141
	ds_read_b128 v[162:165], v141 offset:1024
	ds_read_b128 v[180:183], v141 offset:2048
	ds_read_b128 v[184:187], v141 offset:3072
	v_add_u32_e32 v141, s14, v148
	ds_read_b128 v[190:193], v141
	ds_read_b128 v[194:197], v141 offset:1024
	ds_read_b128 v[204:207], v141 offset:2048
	ds_read_b128 v[208:211], v141 offset:3072
	v_lshl_add_u64 v[166:167], s[50:51], 0, v[136:137]
	s_add_i32 m0, s21, 0xc000
	ds_read_b128 v[212:215], v155
	ds_read_b128 v[216:219], v155 offset:1024
	ds_read_b128 v[220:223], v155 offset:2048
	ds_read_b128 v[224:227], v155 offset:3072
	ds_read_b128 v[228:231], v155 offset:4096
	ds_read_b128 v[232:235], v155 offset:5120
	ds_read_b128 v[236:239], v155 offset:6144
	ds_read_b128 v[240:243], v155 offset:7168
	global_load_lds_dwordx4 v[166:167], off
	v_lshl_add_u64 v[166:167], s[50:51], 0, v[138:139]
	s_add_i32 m0, s21, 0xe000
	s_nop 0
	global_load_lds_dwordx4 v[166:167], off
	s_waitcnt vmcnt(8)
	s_waitcnt lgkmcnt(0)
	s_barrier
; #define PG8_STAGE(bufoff, gbase, voff) do { _Pragma("unroll") for (int _i = 0; _i < 2; ++_i) \
;         __builtin_amdgcn_global_load_lds((const unsigned*)((const char*)(gbase) + (voff)[_i]), (LAS unsigned*)(lds + (bufoff) + ldsw + _i * 8192), 16, 0, 0); } while (0)
; #define PG8_LDA(dst, b, h) do { _Pragma("unroll") for (int m = 0; m < 4; ++m) _Pragma("unroll") for (int k = 0; k < 2; ++k) dst[m][k] = *(const LAS bf16x8*)(lds + PG8_SA(b, h) + aoff + m * 2048 + k * 1024); } while (0)
; #define PG8_LDB(dst, b, h) do { _Pragma("unroll") for (int n = 0; n < 2; ++n) _Pragma("unroll") for (int k = 0; k < 2; ++k) dst[n][k] = *(const LAS bf16x8*)(lds + PG8_SB(b, h) + boff + n * 2048 + k * 1024); } while (0)
; #define PG8_MMA(ai, bj, At, Bt) do { __builtin_amdgcn_s_setprio(1); _Pragma("unroll") for (int m = 0; m < 4; ++m) _Pragma("unroll") for (int n = 0; n < 2; ++n) _Pragma("unroll") for (int k = 0; k < 2; ++k) \
;         acc[ai][bj][m][n] = __builtin_amdgcn_mfma_f32_16x16x32_bf16(Bt[n][k], At[m][k], acc[ai][bj][m][n], 0, 0, 0); __builtin_amdgcn_s_setprio(0); } while (0)
; #define PG8_WAIT_V(n) asm volatile("s_waitcnt vmcnt(" #n ")" ::: "memory")
; #define PG8_WAIT_L(n) asm volatile("s_waitcnt lgkmcnt(" #n ")" ::: "memory")
; #define PG8_BAR __builtin_amdgcn_s_barrier()
; #define PG8_SCHED __builtin_amdgcn_sched_barrier(0)
; template <class Epi, class Sched>
; __device__ __forceinline__ void gemm_phase(const int tid, LAS unsigned char* lds, const int lda, const int ldb, const int K, const Sched& S, const Epi& E) {
;     ...
;             PG8_LDB(B0, 0, 0); PG8_LDB(B1, 0, 1); PG8_SCHED; PG8_LDA(At, 0, 0); PG8_STAGE(PG8_SA(1, 1), a1 + hstepA, voffA);
;             PG8_WAIT_V(8); PG8_WAIT_L(0); PG8_BAR; PG8_MMA(0, 0, At, B0); PG8_MMA(0, 1, At, B1); PG8_BAR; PG8_SCHED;
;             PG8_LDA(At, 0, 1); PG8_STAGE(PG8_SB(0, 0), b2, voffB); PG8_STAGE(PG8_SB(0, 1), b2 + hstepB, voffB); PG8_STAGE(PG8_SA(0, 0), a2, voffA);
;             PG8_WAIT_V(8); PG8_WAIT_L(0); PG8_BAR; if (!cur.half) { PG8_MMA(1, 0, At, B0); PG8_MMA(1, 1, At, B1); } PG8_BAR; PG8_SCHED;
	s_setprio 1
	v_mfma_f32_16x16x32_bf16 v[124:127], v[158:161], v[212:215], v[124:127]
	v_mfma_f32_16x16x32_bf16 v[120:123], v[180:183], v[212:215], v[120:123]
	v_mfma_f32_16x16x32_bf16 v[108:111], v[158:161], v[220:223], v[108:111]
	v_mfma_f32_16x16x32_bf16 v[104:107], v[180:183], v[220:223], v[104:107]
	v_mfma_f32_16x16x32_bf16 v[92:95], v[158:161], v[228:231], v[92:95]
	v_mfma_f32_16x16x32_bf16 v[88:91], v[180:183], v[228:231], v[88:91]
	v_mfma_f32_16x16x32_bf16 v[76:79], v[158:161], v[236:239], v[76:79]
	v_mfma_f32_16x16x32_bf16 v[72:75], v[180:183], v[236:239], v[72:75]
	v_mfma_f32_16x16x32_bf16 v[124:127], v[162:165], v[216:219], v[124:127]
	v_mfma_f32_16x16x32_bf16 v[120:123], v[184:187], v[216:219], v[120:123]
	v_mfma_f32_16x16x32_bf16 v[108:111], v[162:165], v[224:227], v[108:111]
	v_mfma_f32_16x16x32_bf16 v[104:107], v[184:187], v[224:227], v[104:107]
	v_mfma_f32_16x16x32_bf16 v[92:95], v[162:165], v[232:235], v[92:95]
	v_mfma_f32_16x16x32_bf16 v[88:91], v[184:187], v[232:235], v[88:91]
	v_mfma_f32_16x16x32_bf16 v[76:79], v[162:165], v[240:243], v[76:79]
	v_mfma_f32_16x16x32_bf16 v[72:75], v[184:187], v[240:243], v[72:75]
	v_mfma_f32_16x16x32_bf16 v[116:119], v[190:193], v[212:215], v[116:119]
	v_mfma_f32_16x16x32_bf16 v[112:115], v[204:207], v[212:215], v[112:115]
	v_mfma_f32_16x16x32_bf16 v[100:103], v[190:193], v[220:223], v[100:103]
	v_mfma_f32_16x16x32_bf16 v[96:99], v[204:207], v[220:223], v[96:99]
	v_mfma_f32_16x16x32_bf16 v[84:87], v[190:193], v[228:231], v[84:87]
	v_mfma_f32_16x16x32_bf16 v[80:83], v[204:207], v[228:231], v[80:83]
	v_mfma_f32_16x16x32_bf16 v[68:71], v[190:193], v[236:239], v[68:71]
	v_mfma_f32_16x16x32_bf16 v[64:67], v[204:207], v[236:239], v[64:67]
	v_mfma_f32_16x16x32_bf16 v[116:119], v[194:197], v[216:219], v[116:119]
	v_mfma_f32_16x16x32_bf16 v[112:115], v[208:211], v[216:219], v[112:115]
	v_mfma_f32_16x16x32_bf16 v[100:103], v[194:197], v[224:227], v[100:103]
	v_mfma_f32_16x16x32_bf16 v[96:99], v[208:211], v[224:227], v[96:99]
	v_mfma_f32_16x16x32_bf16 v[84:87], v[194:197], v[232:235], v[84:87]
	v_mfma_f32_16x16x32_bf16 v[80:83], v[208:211], v[232:235], v[80:83]
	v_mfma_f32_16x16x32_bf16 v[68:71], v[194:197], v[240:243], v[68:71]
	v_mfma_f32_16x16x32_bf16 v[64:67], v[208:211], v[240:243], v[64:67]
	s_setprio 0
	s_barrier
	s_add_i32 s15, s24, s20
	v_lshl_add_u64 v[166:167], s[52:53], 0, v[130:131]
	s_mov_b32 m0, s15
	ds_read_b128 v[212:215], v155 offset:16384
	ds_read_b128 v[216:219], v155 offset:17408
	ds_read_b128 v[220:223], v155 offset:18432
	ds_read_b128 v[224:227], v155 offset:19456
	ds_read_b128 v[228:231], v155 offset:20480
	ds_read_b128 v[232:235], v155 offset:21504
	ds_read_b128 v[236:239], v155 offset:22528
	ds_read_b128 v[240:243], v155 offset:23552
	global_load_lds_dwordx4 v[166:167], off
	s_add_i32 m0, s15, 0x2000
	s_add_u32 s66, s52, 0x40000
	v_lshl_add_u64 v[244:245], s[52:53], 0, v[134:135]
	s_addc_u32 s67, s53, 0
	s_add_i32 s14, s14, s20
	global_load_lds_dwordx4 v[244:245], off
	v_lshl_add_u64 v[246:247], s[66:67], 0, v[130:131]
	s_mov_b32 m0, s14
	v_lshl_add_u64 v[248:249], s[54:55], 0, v[132:133]
	global_load_lds_dwordx4 v[246:247], off
	v_lshl_add_u64 v[246:247], s[66:67], 0, v[134:135]
	s_add_i32 m0, s14, 0x2000
	s_nop 0
	global_load_lds_dwordx4 v[246:247], off
	v_lshl_add_u64 v[246:247], s[54:55], 0, v[128:129]
	s_mov_b32 m0, s21
	s_nop 0
	global_load_lds_dwordx4 v[246:247], off
	s_mov_b32 m0, s29
	s_nop 0
	global_load_lds_dwordx4 v[248:249], off
	s_waitcnt vmcnt(8)
	s_waitcnt lgkmcnt(0)
	s_barrier
	s_setprio 1
	v_mfma_f32_16x16x32_bf16 v[60:63], v[158:161], v[212:215], v[60:63]
	v_mfma_f32_16x16x32_bf16 v[56:59], v[180:183], v[212:215], v[56:59]
	v_mfma_f32_16x16x32_bf16 v[44:47], v[158:161], v[220:223], v[44:47]
	v_mfma_f32_16x16x32_bf16 v[40:43], v[180:183], v[220:223], v[40:43]
	v_mfma_f32_16x16x32_bf16 v[28:31], v[158:161], v[228:231], v[28:31]
	v_mfma_f32_16x16x32_bf16 v[24:27], v[180:183], v[228:231], v[24:27]
	v_mfma_f32_16x16x32_bf16 v[12:15], v[158:161], v[236:239], v[12:15]
	v_mfma_f32_16x16x32_bf16 v[8:11], v[180:183], v[236:239], v[8:11]
	v_mfma_f32_16x16x32_bf16 v[60:63], v[162:165], v[216:219], v[60:63]
	v_mfma_f32_16x16x32_bf16 v[56:59], v[184:187], v[216:219], v[56:59]
	v_mfma_f32_16x16x32_bf16 v[44:47], v[162:165], v[224:227], v[44:47]
	v_mfma_f32_16x16x32_bf16 v[40:43], v[184:187], v[224:227], v[40:43]
	v_mfma_f32_16x16x32_bf16 v[28:31], v[162:165], v[232:235], v[28:31]
	v_mfma_f32_16x16x32_bf16 v[24:27], v[184:187], v[232:235], v[24:27]
	v_mfma_f32_16x16x32_bf16 v[12:15], v[162:165], v[240:243], v[12:15]
	v_mfma_f32_16x16x32_bf16 v[8:11], v[184:187], v[240:243], v[8:11]
	v_mfma_f32_16x16x32_bf16 v[52:55], v[190:193], v[212:215], v[52:55]
	v_mfma_f32_16x16x32_bf16 v[48:51], v[204:207], v[212:215], v[48:51]
	v_mfma_f32_16x16x32_bf16 v[36:39], v[190:193], v[220:223], v[36:39]
	v_mfma_f32_16x16x32_bf16 v[32:35], v[204:207], v[220:223], v[32:35]
	v_mfma_f32_16x16x32_bf16 v[20:23], v[190:193], v[228:231], v[20:23]
	v_mfma_f32_16x16x32_bf16 v[16:19], v[204:207], v[228:231], v[16:19]
	v_mfma_f32_16x16x32_bf16 v[4:7], v[190:193], v[236:239], v[4:7]
	v_mfma_f32_16x16x32_bf16 v[0:3], v[204:207], v[236:239], v[0:3]
	v_mfma_f32_16x16x32_bf16 v[52:55], v[194:197], v[216:219], v[52:55]
	v_mfma_f32_16x16x32_bf16 v[48:51], v[208:211], v[216:219], v[48:51]
	v_mfma_f32_16x16x32_bf16 v[36:39], v[194:197], v[224:227], v[36:39]
	v_mfma_f32_16x16x32_bf16 v[32:35], v[208:211], v[224:227], v[32:35]
	v_mfma_f32_16x16x32_bf16 v[20:23], v[194:197], v[232:235], v[20:23]
	v_mfma_f32_16x16x32_bf16 v[16:19], v[208:211], v[232:235], v[16:19]
	v_mfma_f32_16x16x32_bf16 v[4:7], v[194:197], v[240:243], v[4:7]
	v_mfma_f32_16x16x32_bf16 v[0:3], v[208:211], v[240:243], v[0:3]
	s_setprio 0
	s_barrier
; #define PG8_STAGE(bufoff, gbase, voff) do { _Pragma("unroll") for (int _i = 0; _i < 2; ++_i) \
;         __builtin_amdgcn_global_load_lds((const unsigned*)((const char*)(gbase) + (voff)[_i]), (LAS unsigned*)(lds + (bufoff) + ldsw + _i * 8192), 16, 0, 0); } while (0)
; #define PG8_LDA(dst, b, h) do { _Pragma("unroll") for (int m = 0; m < 4; ++m) _Pragma("unroll") for (int k = 0; k < 2; ++k) dst[m][k] = *(const LAS bf16x8*)(lds + PG8_SA(b, h) + aoff + m * 2048 + k * 1024); } while (0)
; #define PG8_LDB(dst, b, h) do { _Pragma("unroll") for (int n = 0; n < 2; ++n) _Pragma("unroll") for (int k = 0; k < 2; ++k) dst[n][k] = *(const LAS bf16x8*)(lds + PG8_SB(b, h) + boff + n * 2048 + k * 1024); } while (0)
; #define PG8_MMA(ai, bj, At, Bt) do { __builtin_amdgcn_s_setprio(1); _Pragma("unroll") for (int m = 0; m < 4; ++m) _Pragma("unroll") for (int n = 0; n < 2; ++n) _Pragma("unroll") for (int k = 0; k < 2; ++k) \
;         acc[ai][bj][m][n] = __builtin_amdgcn_mfma_f32_16x16x32_bf16(Bt[n][k], At[m][k], acc[ai][bj][m][n], 0, 0, 0); __builtin_amdgcn_s_setprio(0); } while (0)
; #define PG8_WAIT_V(n) asm volatile("s_waitcnt vmcnt(" #n ")" ::: "memory")
; #define PG8_WAIT_L(n) asm volatile("s_waitcnt lgkmcnt(" #n ")" ::: "memory")
; #define PG8_BAR __builtin_amdgcn_s_barrier()
; #define PG8_SCHED __builtin_amdgcn_sched_barrier(0)
; template <class Epi, class Sched>
; __device__ __forceinline__ void gemm_phase(const int tid, LAS unsigned char* lds, const int lda, const int ldb, const int K, const Sched& S, const Epi& E) {
;     ...
;             PG8_LDB(B0, 1, 0); PG8_LDB(B1, 1, 1); PG8_SCHED; PG8_LDA(At, 1, 0); PG8_STAGE(PG8_SA(0, 1), a2 + hstepA, voffA);
;             PG8_WAIT_V(8); PG8_WAIT_L(0); PG8_BAR; PG8_MMA(0, 0, At, B0); PG8_MMA(0, 1, At, B1); PG8_BAR; PG8_SCHED;
;             PG8_LDA(At, 1, 1); PG8_STAGE(PG8_SB(1, 0), b3, voffB); PG8_STAGE(PG8_SB(1, 1), b3 + hstepB, voffB); PG8_STAGE(PG8_SA(1, 0), a3, voffA);
;             PG8_WAIT_V(8); PG8_WAIT_L(0); PG8_BAR; if (!cur.half) { PG8_MMA(1, 0, At, B0); PG8_MMA(1, 1, At, B1); } PG8_BAR; PG8_SCHED;
;         }
	s_add_i32 s14, 0, 0x18000
	v_add_u32_e32 v141, s14, v148
	s_add_i32 s15, 0, 0x1c000
	ds_read_b128 v[158:161], v141
	ds_read_b128 v[162:165], v141 offset:1024
	ds_read_b128 v[180:183], v141 offset:2048
	ds_read_b128 v[184:187], v141 offset:3072
	v_add_u32_e32 v141, s15, v148
	ds_read_b128 v[190:193], v141
	ds_read_b128 v[194:197], v141 offset:1024
	ds_read_b128 v[204:207], v141 offset:2048
	ds_read_b128 v[208:211], v141 offset:3072
	s_add_u32 s54, s54, 0x40000
	s_addc_u32 s55, s55, 0
	s_mov_b32 m0, s31
	v_lshl_add_u64 v[250:251], s[54:55], 0, v[128:129]
	ds_read_b128 v[212:215], v155 offset:32768
	ds_read_b128 v[216:219], v155 offset:33792
	ds_read_b128 v[220:223], v155 offset:34816
	ds_read_b128 v[224:227], v155 offset:35840
	ds_read_b128 v[228:231], v155 offset:36864
	ds_read_b128 v[232:235], v155 offset:37888
	ds_read_b128 v[236:239], v155 offset:38912
	ds_read_b128 v[240:243], v155 offset:39936
	global_load_lds_dwordx4 v[250:251], off
	v_lshl_add_u64 v[250:251], s[54:55], 0, v[132:133]
	s_mov_b32 m0, s56
	s_nop 0
	global_load_lds_dwordx4 v[250:251], off
	s_waitcnt vmcnt(8)
	s_waitcnt lgkmcnt(0)
	s_barrier
	s_setprio 1
	v_mfma_f32_16x16x32_bf16 v[124:127], v[158:161], v[212:215], v[124:127]
	v_mfma_f32_16x16x32_bf16 v[120:123], v[180:183], v[212:215], v[120:123]
	v_mfma_f32_16x16x32_bf16 v[108:111], v[158:161], v[220:223], v[108:111]
	v_mfma_f32_16x16x32_bf16 v[104:107], v[180:183], v[220:223], v[104:107]
	v_mfma_f32_16x16x32_bf16 v[92:95], v[158:161], v[228:231], v[92:95]
	v_mfma_f32_16x16x32_bf16 v[88:91], v[180:183], v[228:231], v[88:91]
	v_mfma_f32_16x16x32_bf16 v[76:79], v[158:161], v[236:239], v[76:79]
	v_mfma_f32_16x16x32_bf16 v[72:75], v[180:183], v[236:239], v[72:75]
	v_mfma_f32_16x16x32_bf16 v[124:127], v[162:165], v[216:219], v[124:127]
	v_mfma_f32_16x16x32_bf16 v[120:123], v[184:187], v[216:219], v[120:123]
	v_mfma_f32_16x16x32_bf16 v[108:111], v[162:165], v[224:227], v[108:111]
	v_mfma_f32_16x16x32_bf16 v[104:107], v[184:187], v[224:227], v[104:107]
	v_mfma_f32_16x16x32_bf16 v[92:95], v[162:165], v[232:235], v[92:95]
	v_mfma_f32_16x16x32_bf16 v[88:91], v[184:187], v[232:235], v[88:91]
	v_mfma_f32_16x16x32_bf16 v[76:79], v[162:165], v[240:243], v[76:79]
	v_mfma_f32_16x16x32_bf16 v[72:75], v[184:187], v[240:243], v[72:75]
	v_mfma_f32_16x16x32_bf16 v[116:119], v[190:193], v[212:215], v[116:119]
	v_mfma_f32_16x16x32_bf16 v[112:115], v[204:207], v[212:215], v[112:115]
	v_mfma_f32_16x16x32_bf16 v[100:103], v[190:193], v[220:223], v[100:103]
	v_mfma_f32_16x16x32_bf16 v[96:99], v[204:207], v[220:223], v[96:99]
	v_mfma_f32_16x16x32_bf16 v[84:87], v[190:193], v[228:231], v[84:87]
	v_mfma_f32_16x16x32_bf16 v[80:83], v[204:207], v[228:231], v[80:83]
	v_mfma_f32_16x16x32_bf16 v[68:71], v[190:193], v[236:239], v[68:71]
	v_mfma_f32_16x16x32_bf16 v[64:67], v[204:207], v[236:239], v[64:67]
	v_mfma_f32_16x16x32_bf16 v[116:119], v[194:197], v[216:219], v[116:119]
	v_mfma_f32_16x16x32_bf16 v[112:115], v[208:211], v[216:219], v[112:115]
	v_mfma_f32_16x16x32_bf16 v[100:103], v[194:197], v[224:227], v[100:103]
	v_mfma_f32_16x16x32_bf16 v[96:99], v[208:211], v[224:227], v[96:99]
	v_mfma_f32_16x16x32_bf16 v[84:87], v[194:197], v[232:235], v[84:87]
	v_mfma_f32_16x16x32_bf16 v[80:83], v[208:211], v[232:235], v[80:83]
	v_mfma_f32_16x16x32_bf16 v[68:71], v[194:197], v[240:243], v[68:71]
	v_mfma_f32_16x16x32_bf16 v[64:67], v[208:211], v[240:243], v[64:67]
	s_setprio 0
	s_barrier
	s_add_i32 s14, s14, s20
	v_lshl_add_u64 v[166:167], v[166:167], 0, s[6:7]
	s_mov_b32 m0, s14
	ds_read_b128 v[212:215], v155 offset:49152
	ds_read_b128 v[216:219], v155 offset:50176
	ds_read_b128 v[220:223], v155 offset:51200
	ds_read_b128 v[224:227], v155 offset:52224
	ds_read_b128 v[228:231], v155 offset:53248
	ds_read_b128 v[232:235], v155 offset:54272
	ds_read_b128 v[236:239], v155 offset:55296
	ds_read_b128 v[240:243], v155 offset:56320
	global_load_lds_dwordx4 v[166:167], off
	s_add_i32 m0, s14, 0x2000
	s_add_u32 s52, s52, 0x40080
	v_lshl_add_u64 v[166:167], v[244:245], 0, s[6:7]
	s_addc_u32 s53, s53, 0
	s_add_i32 s14, s15, s20
	global_load_lds_dwordx4 v[166:167], off
	v_lshl_add_u64 v[166:167], s[52:53], 0, v[130:131]
	s_mov_b32 m0, s14
	s_nop 0
	global_load_lds_dwordx4 v[166:167], off
	v_lshl_add_u64 v[166:167], s[52:53], 0, v[134:135]
	s_add_i32 m0, s14, 0x2000
	s_nop 0
	global_load_lds_dwordx4 v[166:167], off
	v_lshl_add_u64 v[166:167], v[246:247], 0, s[6:7]
	s_mov_b32 m0, s57
	s_nop 0
	global_load_lds_dwordx4 v[166:167], off
	v_lshl_add_u64 v[166:167], v[248:249], 0, s[6:7]
	s_mov_b32 m0, s58
	s_nop 0
	global_load_lds_dwordx4 v[166:167], off
	s_waitcnt vmcnt(8)
	s_waitcnt lgkmcnt(0)
	s_barrier
	s_setprio 1
	v_mfma_f32_16x16x32_bf16 v[60:63], v[158:161], v[212:215], v[60:63]
	v_mfma_f32_16x16x32_bf16 v[56:59], v[180:183], v[212:215], v[56:59]
	v_mfma_f32_16x16x32_bf16 v[44:47], v[158:161], v[220:223], v[44:47]
	v_mfma_f32_16x16x32_bf16 v[40:43], v[180:183], v[220:223], v[40:43]
	v_mfma_f32_16x16x32_bf16 v[28:31], v[158:161], v[228:231], v[28:31]
	v_mfma_f32_16x16x32_bf16 v[24:27], v[180:183], v[228:231], v[24:27]
	v_mfma_f32_16x16x32_bf16 v[12:15], v[158:161], v[236:239], v[12:15]
	v_mfma_f32_16x16x32_bf16 v[8:11], v[180:183], v[236:239], v[8:11]
	v_mfma_f32_16x16x32_bf16 v[60:63], v[162:165], v[216:219], v[60:63]
	v_mfma_f32_16x16x32_bf16 v[56:59], v[184:187], v[216:219], v[56:59]
	v_mfma_f32_16x16x32_bf16 v[44:47], v[162:165], v[224:227], v[44:47]
	v_mfma_f32_16x16x32_bf16 v[40:43], v[184:187], v[224:227], v[40:43]
	v_mfma_f32_16x16x32_bf16 v[28:31], v[162:165], v[232:235], v[28:31]
	v_mfma_f32_16x16x32_bf16 v[24:27], v[184:187], v[232:235], v[24:27]
	v_mfma_f32_16x16x32_bf16 v[12:15], v[162:165], v[240:243], v[12:15]
	v_mfma_f32_16x16x32_bf16 v[8:11], v[184:187], v[240:243], v[8:11]
	v_mfma_f32_16x16x32_bf16 v[52:55], v[190:193], v[212:215], v[52:55]
	v_mfma_f32_16x16x32_bf16 v[48:51], v[204:207], v[212:215], v[48:51]
	v_mfma_f32_16x16x32_bf16 v[36:39], v[190:193], v[220:223], v[36:39]
	v_mfma_f32_16x16x32_bf16 v[32:35], v[204:207], v[220:223], v[32:35]
	v_mfma_f32_16x16x32_bf16 v[20:23], v[190:193], v[228:231], v[20:23]
	v_mfma_f32_16x16x32_bf16 v[16:19], v[204:207], v[228:231], v[16:19]
	v_mfma_f32_16x16x32_bf16 v[4:7], v[190:193], v[236:239], v[4:7]
	v_mfma_f32_16x16x32_bf16 v[0:3], v[204:207], v[236:239], v[0:3]
	v_mfma_f32_16x16x32_bf16 v[52:55], v[194:197], v[216:219], v[52:55]
	v_mfma_f32_16x16x32_bf16 v[48:51], v[208:211], v[216:219], v[48:51]
	v_mfma_f32_16x16x32_bf16 v[36:39], v[194:197], v[224:227], v[36:39]
	v_mfma_f32_16x16x32_bf16 v[32:35], v[208:211], v[224:227], v[32:35]
	v_mfma_f32_16x16x32_bf16 v[20:23], v[194:197], v[232:235], v[20:23]
	v_mfma_f32_16x16x32_bf16 v[16:19], v[208:211], v[232:235], v[16:19]
	v_mfma_f32_16x16x32_bf16 v[4:7], v[194:197], v[240:243], v[4:7]
	v_mfma_f32_16x16x32_bf16 v[0:3], v[208:211], v[240:243], v[0:3]
	s_setprio 0
	s_barrier
	s_add_u32 s50, s50, 0x100
	s_addc_u32 s51, s51, 0
	s_add_u32 s45, s45, 0x100
	s_addc_u32 s63, s63, 0
	s_cmp_ge_i32 s64, s4
	s_mov_b32 s52, s64
	s_cbranch_scc0 .LBB0_874

; #define PG8_STAGE(bufoff, gbase, voff) do { _Pragma("unroll") for (int _i = 0; _i < 2; ++_i) \
;         __builtin_amdgcn_global_load_lds((const unsigned*)((const char*)(gbase) + (voff)[_i]), (LAS unsigned*)(lds + (bufoff) + ldsw + _i * 8192), 16, 0, 0); } while (0)
; #define PG8_LDA(dst, b, h) do { _Pragma("unroll") for (int m = 0; m < 4; ++m) _Pragma("unroll") for (int k = 0; k < 2; ++k) dst[m][k] = *(const LAS bf16x8*)(lds + PG8_SA(b, h) + aoff + m * 2048 + k * 1024); } while (0)
; #define PG8_LDB(dst, b, h) do { _Pragma("unroll") for (int n = 0; n < 2; ++n) _Pragma("unroll") for (int k = 0; k < 2; ++k) dst[n][k] = *(const LAS bf16x8*)(lds + PG8_SB(b, h) + boff + n * 2048 + k * 1024); } while (0)
; #define PG8_MMA(ai, bj, At, Bt) do { __builtin_amdgcn_s_setprio(1); _Pragma("unroll") for (int m = 0; m < 4; ++m) _Pragma("unroll") for (int n = 0; n < 2; ++n) _Pragma("unroll") for (int k = 0; k < 2; ++k) \
;         acc[ai][bj][m][n] = __builtin_amdgcn_mfma_f32_16x16x32_bf16(Bt[n][k], At[m][k], acc[ai][bj][m][n], 0, 0, 0); __builtin_amdgcn_s_setprio(0); } while (0)
; #define PG8_WAIT_V(n) asm volatile("s_waitcnt vmcnt(" #n ")" ::: "memory")
; #define PG8_WAIT_L(n) asm volatile("s_waitcnt lgkmcnt(" #n ")" ::: "memory")
; #define PG8_BAR __builtin_amdgcn_s_barrier()
; #define PG8_SCHED __builtin_amdgcn_sched_barrier(0)
; template <class Epi, class Sched>
; __device__ __forceinline__ void gemm_phase(const int tid, LAS unsigned char* lds, const int lda, const int ldb, const int K, const Sched& S, const Epi& E) {
;     ...
;             const bool last = (t == nt - 2);
;             const char* a1 = cA + (size_t)(t + 1) * kstep;
;             const char* a2 = last ? nA : cA + (size_t)(t + 2) * kstep; const char* b2 = last ? nB : cB + (size_t)(t + 2) * kstep;
;             const char* a3 = a2 + kstep; const char* b3 = b2 + kstep;
;             PG8_LDB(B0, 0, 0); PG8_LDB(B1, 0, 1); PG8_SCHED; PG8_LDA(At, 0, 0); PG8_STAGE(PG8_SA(1, 1), a1 + hstepA, voffA);
;             PG8_WAIT_V(8); PG8_WAIT_L(0); PG8_BAR; PG8_MMA(0, 0, At, B0); PG8_MMA(0, 1, At, B1); PG8_BAR; PG8_SCHED;
;             PG8_LDA(At, 0, 1); PG8_STAGE(PG8_SB(0, 0), b2, voffB); PG8_STAGE(PG8_SB(0, 1), b2 + hstepB, voffB); PG8_STAGE(PG8_SA(0, 0), a2, voffA);
;             PG8_WAIT_V(8); PG8_WAIT_L(0); PG8_BAR; if (!cur.half) { PG8_MMA(1, 0, At, B0); PG8_MMA(1, 1, At, B1); } PG8_BAR; PG8_SCHED;
.LBB0_894:
	s_andn2_b64 vcc, exec, s[40:41]
	s_cbranch_vccnz .LBB0_902
	s_add_u32 s50, s50, 0x40080
	s_addc_u32 s51, s51, 0
	s_add_u32 s45, s52, 0x100
	s_addc_u32 s64, s53, 0
	s_mov_b32 s52, 0
	s_add_i32 s65, s52, 2
	s_add_u32 s24, s50, 0xfffc0080
	s_addc_u32 s53, s51, -1
	s_add_i32 s66, 0, 0x10000
	s_cmp_eq_u32 s61, s52
	s_cselect_b32 s55, s3, s53
	s_cselect_b32 s54, s2, s24
	v_add_u32_e32 v166, s66, v146
	s_cselect_b32 s53, s39, s64
	s_cselect_b32 s52, s38, s45
	s_add_i32 s24, 0, 0x14000
	ds_read_b128 v[154:157], v166
	ds_read_b128 v[158:161], v166 offset:1024
	ds_read_b128 v[162:165], v166 offset:2048
	ds_read_b128 v[180:183], v166 offset:3072
	v_add_u32_e32 v166, s24, v146
	ds_read_b128 v[184:187], v166
	ds_read_b128 v[190:193], v166 offset:1024
	ds_read_b128 v[194:197], v166 offset:2048
	ds_read_b128 v[204:207], v166 offset:3072
	v_lshl_add_u64 v[166:167], s[50:51], 0, v[136:137]
	s_add_i32 m0, s29, 0xc000
	ds_read_b128 v[208:211], v153
	ds_read_b128 v[212:215], v153 offset:1024
	ds_read_b128 v[216:219], v153 offset:2048
	ds_read_b128 v[220:223], v153 offset:3072
	ds_read_b128 v[224:227], v153 offset:4096
	ds_read_b128 v[228:231], v153 offset:5120
	ds_read_b128 v[232:235], v153 offset:6144
	ds_read_b128 v[236:239], v153 offset:7168
	global_load_lds_dwordx4 v[166:167], off
	v_lshl_add_u64 v[166:167], s[50:51], 0, v[138:139]
	s_add_i32 m0, s29, 0xe000
	s_nop 0
	global_load_lds_dwordx4 v[166:167], off
	s_waitcnt vmcnt(10)
	s_waitcnt lgkmcnt(0)
	s_barrier
	s_setprio 1
	v_mfma_f32_16x16x32_bf16 v[124:127], v[154:157], v[208:211], 0
	v_mfma_f32_16x16x32_bf16 v[116:119], v[162:165], v[208:211], 0
	v_mfma_f32_16x16x32_bf16 v[108:111], v[154:157], v[216:219], 0
	v_mfma_f32_16x16x32_bf16 v[100:103], v[162:165], v[216:219], 0
	v_mfma_f32_16x16x32_bf16 v[92:95], v[154:157], v[224:227], 0
	v_mfma_f32_16x16x32_bf16 v[84:87], v[162:165], v[224:227], 0
	v_mfma_f32_16x16x32_bf16 v[76:79], v[154:157], v[232:235], 0
	v_mfma_f32_16x16x32_bf16 v[68:71], v[162:165], v[232:235], 0
	v_mfma_f32_16x16x32_bf16 v[124:127], v[158:161], v[212:215], v[124:127]
	v_mfma_f32_16x16x32_bf16 v[116:119], v[180:183], v[212:215], v[116:119]
	v_mfma_f32_16x16x32_bf16 v[108:111], v[158:161], v[220:223], v[108:111]
	v_mfma_f32_16x16x32_bf16 v[100:103], v[180:183], v[220:223], v[100:103]
	v_mfma_f32_16x16x32_bf16 v[92:95], v[158:161], v[228:231], v[92:95]
	v_mfma_f32_16x16x32_bf16 v[84:87], v[180:183], v[228:231], v[84:87]
	v_mfma_f32_16x16x32_bf16 v[76:79], v[158:161], v[236:239], v[76:79]
	v_mfma_f32_16x16x32_bf16 v[68:71], v[180:183], v[236:239], v[68:71]
	v_mfma_f32_16x16x32_bf16 v[120:123], v[184:187], v[208:211], 0
	v_mfma_f32_16x16x32_bf16 v[112:115], v[194:197], v[208:211], 0
	v_mfma_f32_16x16x32_bf16 v[104:107], v[184:187], v[216:219], 0
	v_mfma_f32_16x16x32_bf16 v[96:99], v[194:197], v[216:219], 0
	v_mfma_f32_16x16x32_bf16 v[88:91], v[184:187], v[224:227], 0
	v_mfma_f32_16x16x32_bf16 v[80:83], v[194:197], v[224:227], 0
	v_mfma_f32_16x16x32_bf16 v[72:75], v[184:187], v[232:235], 0
	v_mfma_f32_16x16x32_bf16 v[64:67], v[194:197], v[232:235], 0
	v_mfma_f32_16x16x32_bf16 v[120:123], v[190:193], v[212:215], v[120:123]
	v_mfma_f32_16x16x32_bf16 v[112:115], v[204:207], v[212:215], v[112:115]
	v_mfma_f32_16x16x32_bf16 v[104:107], v[190:193], v[220:223], v[104:107]
	v_mfma_f32_16x16x32_bf16 v[96:99], v[204:207], v[220:223], v[96:99]
	v_mfma_f32_16x16x32_bf16 v[88:91], v[190:193], v[228:231], v[88:91]
	v_mfma_f32_16x16x32_bf16 v[80:83], v[204:207], v[228:231], v[80:83]
	v_mfma_f32_16x16x32_bf16 v[72:75], v[190:193], v[236:239], v[72:75]
	v_mfma_f32_16x16x32_bf16 v[64:67], v[204:207], v[236:239], v[64:67]
	s_setprio 0
	s_barrier
	s_add_i32 s66, s66, s20
	v_lshl_add_u64 v[166:167], s[52:53], 0, v[132:133]
	s_mov_b32 m0, s66
	ds_read_b128 v[208:211], v153 offset:16384
	ds_read_b128 v[212:215], v153 offset:17408
	ds_read_b128 v[216:219], v153 offset:18432
	ds_read_b128 v[220:223], v153 offset:19456
	ds_read_b128 v[224:227], v153 offset:20480
	ds_read_b128 v[228:231], v153 offset:21504
	ds_read_b128 v[232:235], v153 offset:22528
	ds_read_b128 v[236:239], v153 offset:23552
	global_load_lds_dwordx4 v[166:167], off
	s_add_i32 m0, s66, 0x2000
	s_add_u32 s66, s52, 0x40000
	v_lshl_add_u64 v[240:241], s[52:53], 0, v[128:129]
	s_addc_u32 s67, s53, 0
	s_add_i32 s24, s24, s20
	global_load_lds_dwordx4 v[240:241], off
	v_lshl_add_u64 v[242:243], s[66:67], 0, v[132:133]
	s_mov_b32 m0, s24
	v_lshl_add_u64 v[244:245], s[54:55], 0, v[130:131]
	global_load_lds_dwordx4 v[242:243], off
	v_lshl_add_u64 v[242:243], s[66:67], 0, v[128:129]
	s_add_i32 m0, s24, 0x2000
	s_nop 0
	global_load_lds_dwordx4 v[242:243], off
	v_lshl_add_u64 v[242:243], s[54:55], 0, v[134:135]
	s_waitcnt vmcnt(14)
	s_waitcnt lgkmcnt(0)
	s_barrier
; #define PG8_STAGE(bufoff, gbase, voff) do { _Pragma("unroll") for (int _i = 0; _i < 2; ++_i) \
;         __builtin_amdgcn_global_load_lds((const unsigned*)((const char*)(gbase) + (voff)[_i]), (LAS unsigned*)(lds + (bufoff) + ldsw + _i * 8192), 16, 0, 0); } while (0)
; #define PG8_LDA(dst, b, h) do { _Pragma("unroll") for (int m = 0; m < 4; ++m) _Pragma("unroll") for (int k = 0; k < 2; ++k) dst[m][k] = *(const LAS bf16x8*)(lds + PG8_SA(b, h) + aoff + m * 2048 + k * 1024); } while (0)
; #define PG8_LDB(dst, b, h) do { _Pragma("unroll") for (int n = 0; n < 2; ++n) _Pragma("unroll") for (int k = 0; k < 2; ++k) dst[n][k] = *(const LAS bf16x8*)(lds + PG8_SB(b, h) + boff + n * 2048 + k * 1024); } while (0)
; #define PG8_MMA(ai, bj, At, Bt) do { __builtin_amdgcn_s_setprio(1); _Pragma("unroll") for (int m = 0; m < 4; ++m) _Pragma("unroll") for (int n = 0; n < 2; ++n) _Pragma("unroll") for (int k = 0; k < 2; ++k) \
;         acc[ai][bj][m][n] = __builtin_amdgcn_mfma_f32_16x16x32_bf16(Bt[n][k], At[m][k], acc[ai][bj][m][n], 0, 0, 0); __builtin_amdgcn_s_setprio(0); } while (0)
; #define PG8_WAIT_V(n) asm volatile("s_waitcnt vmcnt(" #n ")" ::: "memory")
; #define PG8_WAIT_L(n) asm volatile("s_waitcnt lgkmcnt(" #n ")" ::: "memory")
; #define PG8_BAR __builtin_amdgcn_s_barrier()
; #define PG8_SCHED __builtin_amdgcn_sched_barrier(0)
; template <class Epi, class Sched>
; __device__ __forceinline__ void gemm_phase(const int tid, LAS unsigned char* lds, const int lda, const int ldb, const int K, const Sched& S, const Epi& E) {
;     ...
;             PG8_WAIT_V(8); PG8_WAIT_L(0); PG8_BAR; if (!cur.half) { PG8_MMA(1, 0, At, B0); PG8_MMA(1, 1, At, B1); } PG8_BAR; PG8_SCHED;
;             PG8_LDB(B0, 1, 0); PG8_LDB(B1, 1, 1); PG8_SCHED; PG8_LDA(At, 1, 0); PG8_STAGE(PG8_SA(0, 1), a2 + hstepA, voffA);
;             PG8_WAIT_V(8); PG8_WAIT_L(0); PG8_BAR; PG8_MMA(0, 0, At, B0); PG8_MMA(0, 1, At, B1); PG8_BAR; PG8_SCHED;
	s_setprio 1
	v_mfma_f32_16x16x32_bf16 v[60:63], v[154:157], v[208:211], 0
	v_mfma_f32_16x16x32_bf16 v[52:55], v[162:165], v[208:211], 0
	v_mfma_f32_16x16x32_bf16 v[44:47], v[154:157], v[216:219], 0
	v_mfma_f32_16x16x32_bf16 v[36:39], v[162:165], v[216:219], 0
	v_mfma_f32_16x16x32_bf16 v[28:31], v[154:157], v[224:227], 0
	v_mfma_f32_16x16x32_bf16 v[20:23], v[162:165], v[224:227], 0
	v_mfma_f32_16x16x32_bf16 v[12:15], v[154:157], v[232:235], 0
	v_mfma_f32_16x16x32_bf16 v[4:7], v[162:165], v[232:235], 0
	v_mfma_f32_16x16x32_bf16 v[60:63], v[158:161], v[212:215], v[60:63]
	v_mfma_f32_16x16x32_bf16 v[52:55], v[180:183], v[212:215], v[52:55]
	v_mfma_f32_16x16x32_bf16 v[44:47], v[158:161], v[220:223], v[44:47]
	v_mfma_f32_16x16x32_bf16 v[36:39], v[180:183], v[220:223], v[36:39]
	v_mfma_f32_16x16x32_bf16 v[28:31], v[158:161], v[228:231], v[28:31]
	v_mfma_f32_16x16x32_bf16 v[20:23], v[180:183], v[228:231], v[20:23]
	v_mfma_f32_16x16x32_bf16 v[12:15], v[158:161], v[236:239], v[12:15]
	v_mfma_f32_16x16x32_bf16 v[4:7], v[180:183], v[236:239], v[4:7]
	v_mfma_f32_16x16x32_bf16 v[56:59], v[184:187], v[208:211], 0
	v_mfma_f32_16x16x32_bf16 v[48:51], v[194:197], v[208:211], 0
	v_mfma_f32_16x16x32_bf16 v[40:43], v[184:187], v[216:219], 0
	v_mfma_f32_16x16x32_bf16 v[32:35], v[194:197], v[216:219], 0
	v_mfma_f32_16x16x32_bf16 v[24:27], v[184:187], v[224:227], 0
	v_mfma_f32_16x16x32_bf16 v[16:19], v[194:197], v[224:227], 0
	v_mfma_f32_16x16x32_bf16 v[8:11], v[184:187], v[232:235], 0
	v_mfma_f32_16x16x32_bf16 v[0:3], v[194:197], v[232:235], 0
	v_mfma_f32_16x16x32_bf16 v[56:59], v[190:193], v[212:215], v[56:59]
	v_mfma_f32_16x16x32_bf16 v[48:51], v[204:207], v[212:215], v[48:51]
	v_mfma_f32_16x16x32_bf16 v[40:43], v[190:193], v[220:223], v[40:43]
	v_mfma_f32_16x16x32_bf16 v[32:35], v[204:207], v[220:223], v[32:35]
	v_mfma_f32_16x16x32_bf16 v[24:27], v[190:193], v[228:231], v[24:27]
	v_mfma_f32_16x16x32_bf16 v[16:19], v[204:207], v[228:231], v[16:19]
	v_mfma_f32_16x16x32_bf16 v[8:11], v[190:193], v[236:239], v[8:11]
	v_mfma_f32_16x16x32_bf16 v[0:3], v[204:207], v[236:239], v[0:3]
	s_setprio 0
	s_barrier
	s_add_i32 s24, 0, 0x18000
	v_add_u32_e32 v176, s24, v146
	s_add_i32 s66, 0, 0x1c000
	ds_read_b128 v[154:157], v176
	ds_read_b128 v[158:161], v176 offset:1024
	ds_read_b128 v[162:165], v176 offset:2048
	ds_read_b128 v[180:183], v176 offset:3072
	v_add_u32_e32 v176, s66, v146
	ds_read_b128 v[184:187], v176
	ds_read_b128 v[190:193], v176 offset:1024
	ds_read_b128 v[194:197], v176 offset:2048
	ds_read_b128 v[204:207], v176 offset:3072
	s_mov_b32 m0, s29
	s_nop 0
	global_load_lds_dwordx4 v[242:243], off
	s_mov_b32 m0, s31
	s_nop 0
	global_load_lds_dwordx4 v[244:245], off
	s_add_u32 s54, s54, 0x40000
	s_addc_u32 s55, s55, 0
	s_mov_b32 m0, s56
	v_lshl_add_u64 v[246:247], s[54:55], 0, v[134:135]
	ds_read_b128 v[208:211], v153 offset:32768
	ds_read_b128 v[212:215], v153 offset:33792
	ds_read_b128 v[216:219], v153 offset:34816
	ds_read_b128 v[220:223], v153 offset:35840
	ds_read_b128 v[224:227], v153 offset:36864
	ds_read_b128 v[228:231], v153 offset:37888
	ds_read_b128 v[232:235], v153 offset:38912
	ds_read_b128 v[236:239], v153 offset:39936
	global_load_lds_dwordx4 v[246:247], off
	v_lshl_add_u64 v[246:247], s[54:55], 0, v[130:131]
	s_mov_b32 m0, s57
	s_nop 0
	global_load_lds_dwordx4 v[246:247], off
	s_waitcnt vmcnt(8)
	s_waitcnt lgkmcnt(0)
	s_barrier
	s_setprio 1
	v_mfma_f32_16x16x32_bf16 v[124:127], v[154:157], v[208:211], v[124:127]
	v_mfma_f32_16x16x32_bf16 v[116:119], v[162:165], v[208:211], v[116:119]
	v_mfma_f32_16x16x32_bf16 v[108:111], v[154:157], v[216:219], v[108:111]
	v_mfma_f32_16x16x32_bf16 v[100:103], v[162:165], v[216:219], v[100:103]
	v_mfma_f32_16x16x32_bf16 v[92:95], v[154:157], v[224:227], v[92:95]
	v_mfma_f32_16x16x32_bf16 v[84:87], v[162:165], v[224:227], v[84:87]
	v_mfma_f32_16x16x32_bf16 v[76:79], v[154:157], v[232:235], v[76:79]
	v_mfma_f32_16x16x32_bf16 v[68:71], v[162:165], v[232:235], v[68:71]
	v_mfma_f32_16x16x32_bf16 v[124:127], v[158:161], v[212:215], v[124:127]
	v_mfma_f32_16x16x32_bf16 v[116:119], v[180:183], v[212:215], v[116:119]
	v_mfma_f32_16x16x32_bf16 v[108:111], v[158:161], v[220:223], v[108:111]
	v_mfma_f32_16x16x32_bf16 v[100:103], v[180:183], v[220:223], v[100:103]
	v_mfma_f32_16x16x32_bf16 v[92:95], v[158:161], v[228:231], v[92:95]
	v_mfma_f32_16x16x32_bf16 v[84:87], v[180:183], v[228:231], v[84:87]
	v_mfma_f32_16x16x32_bf16 v[76:79], v[158:161], v[236:239], v[76:79]
	v_mfma_f32_16x16x32_bf16 v[68:71], v[180:183], v[236:239], v[68:71]
	v_mfma_f32_16x16x32_bf16 v[120:123], v[184:187], v[208:211], v[120:123]
	v_mfma_f32_16x16x32_bf16 v[112:115], v[194:197], v[208:211], v[112:115]
	v_mfma_f32_16x16x32_bf16 v[104:107], v[184:187], v[216:219], v[104:107]
	v_mfma_f32_16x16x32_bf16 v[96:99], v[194:197], v[216:219], v[96:99]
	v_mfma_f32_16x16x32_bf16 v[88:91], v[184:187], v[224:227], v[88:91]
	v_mfma_f32_16x16x32_bf16 v[80:83], v[194:197], v[224:227], v[80:83]
	v_mfma_f32_16x16x32_bf16 v[72:75], v[184:187], v[232:235], v[72:75]
	v_mfma_f32_16x16x32_bf16 v[64:67], v[194:197], v[232:235], v[64:67]
	v_mfma_f32_16x16x32_bf16 v[120:123], v[190:193], v[212:215], v[120:123]
	v_mfma_f32_16x16x32_bf16 v[112:115], v[204:207], v[212:215], v[112:115]
	v_mfma_f32_16x16x32_bf16 v[104:107], v[190:193], v[220:223], v[104:107]
	v_mfma_f32_16x16x32_bf16 v[96:99], v[204:207], v[220:223], v[96:99]
	v_mfma_f32_16x16x32_bf16 v[88:91], v[190:193], v[228:231], v[88:91]
	v_mfma_f32_16x16x32_bf16 v[80:83], v[204:207], v[228:231], v[80:83]
	v_mfma_f32_16x16x32_bf16 v[72:75], v[190:193], v[236:239], v[72:75]
	v_mfma_f32_16x16x32_bf16 v[64:67], v[204:207], v[236:239], v[64:67]
	s_setprio 0
	s_barrier
; #define PG8_STAGE(bufoff, gbase, voff) do { _Pragma("unroll") for (int _i = 0; _i < 2; ++_i) \
;         __builtin_amdgcn_global_load_lds((const unsigned*)((const char*)(gbase) + (voff)[_i]), (LAS unsigned*)(lds + (bufoff) + ldsw + _i * 8192), 16, 0, 0); } while (0)
; #define PG8_LDA(dst, b, h) do { _Pragma("unroll") for (int m = 0; m < 4; ++m) _Pragma("unroll") for (int k = 0; k < 2; ++k) dst[m][k] = *(const LAS bf16x8*)(lds + PG8_SA(b, h) + aoff + m * 2048 + k * 1024); } while (0)
; #define PG8_LDB(dst, b, h) do { _Pragma("unroll") for (int n = 0; n < 2; ++n) _Pragma("unroll") for (int k = 0; k < 2; ++k) dst[n][k] = *(const LAS bf16x8*)(lds + PG8_SB(b, h) + boff + n * 2048 + k * 1024); } while (0)
; #define PG8_MMA(ai, bj, At, Bt) do { __builtin_amdgcn_s_setprio(1); _Pragma("unroll") for (int m = 0; m < 4; ++m) _Pragma("unroll") for (int n = 0; n < 2; ++n) _Pragma("unroll") for (int k = 0; k < 2; ++k) \
;         acc[ai][bj][m][n] = __builtin_amdgcn_mfma_f32_16x16x32_bf16(Bt[n][k], At[m][k], acc[ai][bj][m][n], 0, 0, 0); __builtin_amdgcn_s_setprio(0); } while (0)
; #define PG8_WAIT_V(n) asm volatile("s_waitcnt vmcnt(" #n ")" ::: "memory")
; #define PG8_WAIT_L(n) asm volatile("s_waitcnt lgkmcnt(" #n ")" ::: "memory")
; #define PG8_BAR __builtin_amdgcn_s_barrier()
; template <class Epi, class Sched>
; __device__ __forceinline__ void gemm_phase(const int tid, LAS unsigned char* lds, const int lda, const int ldb, const int K, const Sched& S, const Epi& E) {
;     ...
;         for (int t = 0; t < nt; t += 2) {
;             const bool last = (t == nt - 2);
;             const char* a1 = cA + (size_t)(t + 1) * kstep;
;             const char* a2 = last ? nA : cA + (size_t)(t + 2) * kstep; const char* b2 = last ? nB : cB + (size_t)(t + 2) * kstep;
;             const char* a3 = a2 + kstep; const char* b3 = b2 + kstep;
;             PG8_LDB(B0, 0, 0); PG8_LDB(B1, 0, 1); PG8_SCHED; PG8_LDA(At, 0, 0); PG8_STAGE(PG8_SA(1, 1), a1 + hstepA, voffA);
;             PG8_WAIT_V(8); PG8_WAIT_L(0); PG8_BAR; PG8_MMA(0, 0, At, B0); PG8_MMA(0, 1, At, B1); PG8_BAR; PG8_SCHED;
;     ...
;             PG8_LDA(At, 1, 1); PG8_STAGE(PG8_SB(1, 0), b3, voffB); PG8_STAGE(PG8_SB(1, 1), b3 + hstepB, voffB); PG8_STAGE(PG8_SA(1, 0), a3, voffA);
;             PG8_WAIT_V(8); PG8_WAIT_L(0); PG8_BAR; if (!cur.half) { PG8_MMA(1, 0, At, B0); PG8_MMA(1, 1, At, B1); } PG8_BAR; PG8_SCHED;
	s_add_i32 s24, s24, s20
	v_lshl_add_u64 v[166:167], v[166:167], 0, s[6:7]
	s_mov_b32 m0, s24
	ds_read_b128 v[208:211], v153 offset:49152
	ds_read_b128 v[212:215], v153 offset:50176
	ds_read_b128 v[216:219], v153 offset:51200
	ds_read_b128 v[220:223], v153 offset:52224
	ds_read_b128 v[224:227], v153 offset:53248
	ds_read_b128 v[228:231], v153 offset:54272
	ds_read_b128 v[232:235], v153 offset:55296
	ds_read_b128 v[236:239], v153 offset:56320
	global_load_lds_dwordx4 v[166:167], off
	s_add_i32 m0, s24, 0x2000
	s_add_u32 s52, s52, 0x40080
	v_lshl_add_u64 v[166:167], v[240:241], 0, s[6:7]
	s_addc_u32 s53, s53, 0
	s_add_i32 s24, s66, s20
	global_load_lds_dwordx4 v[166:167], off
	v_lshl_add_u64 v[166:167], s[52:53], 0, v[132:133]
	s_mov_b32 m0, s24
	s_nop 0
	global_load_lds_dwordx4 v[166:167], off
	v_lshl_add_u64 v[166:167], s[52:53], 0, v[128:129]
	s_add_i32 m0, s24, 0x2000
	s_nop 0
	global_load_lds_dwordx4 v[166:167], off
	v_lshl_add_u64 v[166:167], v[242:243], 0, s[6:7]
	s_mov_b32 m0, s58
	s_nop 0
	global_load_lds_dwordx4 v[166:167], off
	v_lshl_add_u64 v[166:167], v[244:245], 0, s[6:7]
	s_mov_b32 m0, s59
	s_nop 0
	global_load_lds_dwordx4 v[166:167], off
	s_waitcnt vmcnt(8)
	s_waitcnt lgkmcnt(0)
	s_barrier
	s_setprio 1
	v_mfma_f32_16x16x32_bf16 v[60:63], v[154:157], v[208:211], v[60:63]
	v_mfma_f32_16x16x32_bf16 v[52:55], v[162:165], v[208:211], v[52:55]
	v_mfma_f32_16x16x32_bf16 v[44:47], v[154:157], v[216:219], v[44:47]
	v_mfma_f32_16x16x32_bf16 v[36:39], v[162:165], v[216:219], v[36:39]
	v_mfma_f32_16x16x32_bf16 v[28:31], v[154:157], v[224:227], v[28:31]
	v_mfma_f32_16x16x32_bf16 v[20:23], v[162:165], v[224:227], v[20:23]
	v_mfma_f32_16x16x32_bf16 v[12:15], v[154:157], v[232:235], v[12:15]
	v_mfma_f32_16x16x32_bf16 v[4:7], v[162:165], v[232:235], v[4:7]
	v_mfma_f32_16x16x32_bf16 v[60:63], v[158:161], v[212:215], v[60:63]
	v_mfma_f32_16x16x32_bf16 v[52:55], v[180:183], v[212:215], v[52:55]
	v_mfma_f32_16x16x32_bf16 v[44:47], v[158:161], v[220:223], v[44:47]
	v_mfma_f32_16x16x32_bf16 v[36:39], v[180:183], v[220:223], v[36:39]
	v_mfma_f32_16x16x32_bf16 v[28:31], v[158:161], v[228:231], v[28:31]
	v_mfma_f32_16x16x32_bf16 v[20:23], v[180:183], v[228:231], v[20:23]
	v_mfma_f32_16x16x32_bf16 v[12:15], v[158:161], v[236:239], v[12:15]
	v_mfma_f32_16x16x32_bf16 v[4:7], v[180:183], v[236:239], v[4:7]
	v_mfma_f32_16x16x32_bf16 v[56:59], v[184:187], v[208:211], v[56:59]
	v_mfma_f32_16x16x32_bf16 v[48:51], v[194:197], v[208:211], v[48:51]
	v_mfma_f32_16x16x32_bf16 v[40:43], v[184:187], v[216:219], v[40:43]
	v_mfma_f32_16x16x32_bf16 v[32:35], v[194:197], v[216:219], v[32:35]
	v_mfma_f32_16x16x32_bf16 v[24:27], v[184:187], v[224:227], v[24:27]
	v_mfma_f32_16x16x32_bf16 v[16:19], v[194:197], v[224:227], v[16:19]
	v_mfma_f32_16x16x32_bf16 v[8:11], v[184:187], v[232:235], v[8:11]
	v_mfma_f32_16x16x32_bf16 v[0:3], v[194:197], v[232:235], v[0:3]
	v_mfma_f32_16x16x32_bf16 v[56:59], v[190:193], v[212:215], v[56:59]
	v_mfma_f32_16x16x32_bf16 v[48:51], v[204:207], v[212:215], v[48:51]
	v_mfma_f32_16x16x32_bf16 v[40:43], v[190:193], v[220:223], v[40:43]
	v_mfma_f32_16x16x32_bf16 v[32:35], v[204:207], v[220:223], v[32:35]
	v_mfma_f32_16x16x32_bf16 v[24:27], v[190:193], v[228:231], v[24:27]
	v_mfma_f32_16x16x32_bf16 v[16:19], v[204:207], v[228:231], v[16:19]
	v_mfma_f32_16x16x32_bf16 v[8:11], v[190:193], v[236:239], v[8:11]
	v_mfma_f32_16x16x32_bf16 v[0:3], v[204:207], v[236:239], v[0:3]
	s_setprio 0
	s_barrier
	s_add_u32 s50, s50, 0x100
	s_addc_u32 s51, s51, 0
	s_add_u32 s45, s45, 0x100
	s_addc_u32 s64, s64, 0
	s_cmp_ge_i32 s65, s13
	s_mov_b32 s52, s65
	s_cbranch_scc1 .Lkexit_896
.LBB0_896:
	s_add_i32 s65, s52, 2
	s_add_u32 s24, s50, 0xfffc0080
	s_addc_u32 s53, s51, -1
	s_add_i32 s66, 0, 0x10000
	s_cmp_eq_u32 s61, s52
	s_cselect_b32 s55, s3, s53
	s_cselect_b32 s54, s2, s24
	v_add_u32_e32 v166, s66, v146
	s_cselect_b32 s53, s39, s64
	s_cselect_b32 s52, s38, s45
	s_add_i32 s24, 0, 0x14000
	ds_read_b128 v[154:157], v166
	ds_read_b128 v[158:161], v166 offset:1024
	ds_read_b128 v[162:165], v166 offset:2048
	ds_read_b128 v[180:183], v166 offset:3072
	v_add_u32_e32 v166, s24, v146
	ds_read_b128 v[184:187], v166
	ds_read_b128 v[190:193], v166 offset:1024
	ds_read_b128 v[194:197], v166 offset:2048
	ds_read_b128 v[204:207], v166 offset:3072
	v_lshl_add_u64 v[166:167], s[50:51], 0, v[136:137]
	s_add_i32 m0, s29, 0xc000
	ds_read_b128 v[208:211], v153
	ds_read_b128 v[212:215], v153 offset:1024
	ds_read_b128 v[216:219], v153 offset:2048
	ds_read_b128 v[220:223], v153 offset:3072
	ds_read_b128 v[224:227], v153 offset:4096
	ds_read_b128 v[228:231], v153 offset:5120
	ds_read_b128 v[232:235], v153 offset:6144
	ds_read_b128 v[236:239], v153 offset:7168
	global_load_lds_dwordx4 v[166:167], off
	v_lshl_add_u64 v[166:167], s[50:51], 0, v[138:139]
	s_add_i32 m0, s29, 0xe000
	s_nop 0
	global_load_lds_dwordx4 v[166:167], off
	s_waitcnt vmcnt(8)
	s_waitcnt lgkmcnt(0)
	s_barrier
; #define PG8_STAGE(bufoff, gbase, voff) do { _Pragma("unroll") for (int _i = 0; _i < 2; ++_i) \
;         __builtin_amdgcn_global_load_lds((const unsigned*)((const char*)(gbase) + (voff)[_i]), (LAS unsigned*)(lds + (bufoff) + ldsw + _i * 8192), 16, 0, 0); } while (0)
; #define PG8_LDA(dst, b, h) do { _Pragma("unroll") for (int m = 0; m < 4; ++m) _Pragma("unroll") for (int k = 0; k < 2; ++k) dst[m][k] = *(const LAS bf16x8*)(lds + PG8_SA(b, h) + aoff + m * 2048 + k * 1024); } while (0)
; #define PG8_MMA(ai, bj, At, Bt) do { __builtin_amdgcn_s_setprio(1); _Pragma("unroll") for (int m = 0; m < 4; ++m) _Pragma("unroll") for (int n = 0; n < 2; ++n) _Pragma("unroll") for (int k = 0; k < 2; ++k) \
;         acc[ai][bj][m][n] = __builtin_amdgcn_mfma_f32_16x16x32_bf16(Bt[n][k], At[m][k], acc[ai][bj][m][n], 0, 0, 0); __builtin_amdgcn_s_setprio(0); } while (0)
; #define PG8_WAIT_V(n) asm volatile("s_waitcnt vmcnt(" #n ")" ::: "memory")
; #define PG8_WAIT_L(n) asm volatile("s_waitcnt lgkmcnt(" #n ")" ::: "memory")
; #define PG8_BAR __builtin_amdgcn_s_barrier()
; #define PG8_SCHED __builtin_amdgcn_sched_barrier(0)
; template <class Epi, class Sched>
; __device__ __forceinline__ void gemm_phase(const int tid, LAS unsigned char* lds, const int lda, const int ldb, const int K, const Sched& S, const Epi& E) {
;     ...
;             PG8_WAIT_V(8); PG8_WAIT_L(0); PG8_BAR; PG8_MMA(0, 0, At, B0); PG8_MMA(0, 1, At, B1); PG8_BAR; PG8_SCHED;
;             PG8_LDA(At, 0, 1); PG8_STAGE(PG8_SB(0, 0), b2, voffB); PG8_STAGE(PG8_SB(0, 1), b2 + hstepB, voffB); PG8_STAGE(PG8_SA(0, 0), a2, voffA);
;             PG8_WAIT_V(8); PG8_WAIT_L(0); PG8_BAR; if (!cur.half) { PG8_MMA(1, 0, At, B0); PG8_MMA(1, 1, At, B1); } PG8_BAR; PG8_SCHED;
	s_setprio 1
	v_mfma_f32_16x16x32_bf16 v[124:127], v[154:157], v[208:211], v[124:127]
	v_mfma_f32_16x16x32_bf16 v[116:119], v[162:165], v[208:211], v[116:119]
	v_mfma_f32_16x16x32_bf16 v[108:111], v[154:157], v[216:219], v[108:111]
	v_mfma_f32_16x16x32_bf16 v[100:103], v[162:165], v[216:219], v[100:103]
	v_mfma_f32_16x16x32_bf16 v[92:95], v[154:157], v[224:227], v[92:95]
	v_mfma_f32_16x16x32_bf16 v[84:87], v[162:165], v[224:227], v[84:87]
	v_mfma_f32_16x16x32_bf16 v[76:79], v[154:157], v[232:235], v[76:79]
	v_mfma_f32_16x16x32_bf16 v[68:71], v[162:165], v[232:235], v[68:71]
	v_mfma_f32_16x16x32_bf16 v[124:127], v[158:161], v[212:215], v[124:127]
	v_mfma_f32_16x16x32_bf16 v[116:119], v[180:183], v[212:215], v[116:119]
	v_mfma_f32_16x16x32_bf16 v[108:111], v[158:161], v[220:223], v[108:111]
	v_mfma_f32_16x16x32_bf16 v[100:103], v[180:183], v[220:223], v[100:103]
	v_mfma_f32_16x16x32_bf16 v[92:95], v[158:161], v[228:231], v[92:95]
	v_mfma_f32_16x16x32_bf16 v[84:87], v[180:183], v[228:231], v[84:87]
	v_mfma_f32_16x16x32_bf16 v[76:79], v[158:161], v[236:239], v[76:79]
	v_mfma_f32_16x16x32_bf16 v[68:71], v[180:183], v[236:239], v[68:71]
	v_mfma_f32_16x16x32_bf16 v[120:123], v[184:187], v[208:211], v[120:123]
	v_mfma_f32_16x16x32_bf16 v[112:115], v[194:197], v[208:211], v[112:115]
	v_mfma_f32_16x16x32_bf16 v[104:107], v[184:187], v[216:219], v[104:107]
	v_mfma_f32_16x16x32_bf16 v[96:99], v[194:197], v[216:219], v[96:99]
	v_mfma_f32_16x16x32_bf16 v[88:91], v[184:187], v[224:227], v[88:91]
	v_mfma_f32_16x16x32_bf16 v[80:83], v[194:197], v[224:227], v[80:83]
	v_mfma_f32_16x16x32_bf16 v[72:75], v[184:187], v[232:235], v[72:75]
	v_mfma_f32_16x16x32_bf16 v[64:67], v[194:197], v[232:235], v[64:67]
	v_mfma_f32_16x16x32_bf16 v[120:123], v[190:193], v[212:215], v[120:123]
	v_mfma_f32_16x16x32_bf16 v[112:115], v[204:207], v[212:215], v[112:115]
	v_mfma_f32_16x16x32_bf16 v[104:107], v[190:193], v[220:223], v[104:107]
	v_mfma_f32_16x16x32_bf16 v[96:99], v[204:207], v[220:223], v[96:99]
	v_mfma_f32_16x16x32_bf16 v[88:91], v[190:193], v[228:231], v[88:91]
	v_mfma_f32_16x16x32_bf16 v[80:83], v[204:207], v[228:231], v[80:83]
	v_mfma_f32_16x16x32_bf16 v[72:75], v[190:193], v[236:239], v[72:75]
	v_mfma_f32_16x16x32_bf16 v[64:67], v[204:207], v[236:239], v[64:67]
	s_setprio 0
	s_barrier
	s_add_i32 s66, s66, s20
	v_lshl_add_u64 v[166:167], s[52:53], 0, v[132:133]
	s_mov_b32 m0, s66
	ds_read_b128 v[208:211], v153 offset:16384
	ds_read_b128 v[212:215], v153 offset:17408
	ds_read_b128 v[216:219], v153 offset:18432
	ds_read_b128 v[220:223], v153 offset:19456
	ds_read_b128 v[224:227], v153 offset:20480
	ds_read_b128 v[228:231], v153 offset:21504
	ds_read_b128 v[232:235], v153 offset:22528
	ds_read_b128 v[236:239], v153 offset:23552
	global_load_lds_dwordx4 v[166:167], off
	s_add_i32 m0, s66, 0x2000
	s_add_u32 s66, s52, 0x40000
	v_lshl_add_u64 v[240:241], s[52:53], 0, v[128:129]
	s_addc_u32 s67, s53, 0
	s_add_i32 s24, s24, s20
	global_load_lds_dwordx4 v[240:241], off
	v_lshl_add_u64 v[242:243], s[66:67], 0, v[132:133]
	s_mov_b32 m0, s24
	v_lshl_add_u64 v[244:245], s[54:55], 0, v[130:131]
	global_load_lds_dwordx4 v[242:243], off
	v_lshl_add_u64 v[242:243], s[66:67], 0, v[128:129]
	s_add_i32 m0, s24, 0x2000
	s_nop 0
	global_load_lds_dwordx4 v[242:243], off
	v_lshl_add_u64 v[242:243], s[54:55], 0, v[134:135]
	s_waitcnt vmcnt(6)
	s_waitcnt lgkmcnt(0)
	s_barrier
	s_setprio 1
	v_mfma_f32_16x16x32_bf16 v[60:63], v[154:157], v[208:211], v[60:63]
	v_mfma_f32_16x16x32_bf16 v[52:55], v[162:165], v[208:211], v[52:55]
	v_mfma_f32_16x16x32_bf16 v[44:47], v[154:157], v[216:219], v[44:47]
	v_mfma_f32_16x16x32_bf16 v[36:39], v[162:165], v[216:219], v[36:39]
	v_mfma_f32_16x16x32_bf16 v[28:31], v[154:157], v[224:227], v[28:31]
	v_mfma_f32_16x16x32_bf16 v[20:23], v[162:165], v[224:227], v[20:23]
	v_mfma_f32_16x16x32_bf16 v[12:15], v[154:157], v[232:235], v[12:15]
	v_mfma_f32_16x16x32_bf16 v[4:7], v[162:165], v[232:235], v[4:7]
	v_mfma_f32_16x16x32_bf16 v[60:63], v[158:161], v[212:215], v[60:63]
	v_mfma_f32_16x16x32_bf16 v[52:55], v[180:183], v[212:215], v[52:55]
	v_mfma_f32_16x16x32_bf16 v[44:47], v[158:161], v[220:223], v[44:47]
	v_mfma_f32_16x16x32_bf16 v[36:39], v[180:183], v[220:223], v[36:39]
	v_mfma_f32_16x16x32_bf16 v[28:31], v[158:161], v[228:231], v[28:31]
	v_mfma_f32_16x16x32_bf16 v[20:23], v[180:183], v[228:231], v[20:23]
	v_mfma_f32_16x16x32_bf16 v[12:15], v[158:161], v[236:239], v[12:15]
	v_mfma_f32_16x16x32_bf16 v[4:7], v[180:183], v[236:239], v[4:7]
	v_mfma_f32_16x16x32_bf16 v[56:59], v[184:187], v[208:211], v[56:59]
	v_mfma_f32_16x16x32_bf16 v[48:51], v[194:197], v[208:211], v[48:51]
	v_mfma_f32_16x16x32_bf16 v[40:43], v[184:187], v[216:219], v[40:43]
	v_mfma_f32_16x16x32_bf16 v[32:35], v[194:197], v[216:219], v[32:35]
	v_mfma_f32_16x16x32_bf16 v[24:27], v[184:187], v[224:227], v[24:27]
	v_mfma_f32_16x16x32_bf16 v[16:19], v[194:197], v[224:227], v[16:19]
	v_mfma_f32_16x16x32_bf16 v[8:11], v[184:187], v[232:235], v[8:11]
	v_mfma_f32_16x16x32_bf16 v[0:3], v[194:197], v[232:235], v[0:3]
	v_mfma_f32_16x16x32_bf16 v[56:59], v[190:193], v[212:215], v[56:59]
	v_mfma_f32_16x16x32_bf16 v[48:51], v[204:207], v[212:215], v[48:51]
	v_mfma_f32_16x16x32_bf16 v[40:43], v[190:193], v[220:223], v[40:43]
	v_mfma_f32_16x16x32_bf16 v[32:35], v[204:207], v[220:223], v[32:35]
	v_mfma_f32_16x16x32_bf16 v[24:27], v[190:193], v[228:231], v[24:27]
	v_mfma_f32_16x16x32_bf16 v[16:19], v[204:207], v[228:231], v[16:19]
	v_mfma_f32_16x16x32_bf16 v[8:11], v[190:193], v[236:239], v[8:11]
	v_mfma_f32_16x16x32_bf16 v[0:3], v[204:207], v[236:239], v[0:3]
	s_setprio 0
	s_barrier
; #define PG8_STAGE(bufoff, gbase, voff) do { _Pragma("unroll") for (int _i = 0; _i < 2; ++_i) \
;         __builtin_amdgcn_global_load_lds((const unsigned*)((const char*)(gbase) + (voff)[_i]), (LAS unsigned*)(lds + (bufoff) + ldsw + _i * 8192), 16, 0, 0); } while (0)
; #define PG8_LDA(dst, b, h) do { _Pragma("unroll") for (int m = 0; m < 4; ++m) _Pragma("unroll") for (int k = 0; k < 2; ++k) dst[m][k] = *(const LAS bf16x8*)(lds + PG8_SA(b, h) + aoff + m * 2048 + k * 1024); } while (0)
; #define PG8_LDB(dst, b, h) do { _Pragma("unroll") for (int n = 0; n < 2; ++n) _Pragma("unroll") for (int k = 0; k < 2; ++k) dst[n][k] = *(const LAS bf16x8*)(lds + PG8_SB(b, h) + boff + n * 2048 + k * 1024); } while (0)
; #define PG8_MMA(ai, bj, At, Bt) do { __builtin_amdgcn_s_setprio(1); _Pragma("unroll") for (int m = 0; m < 4; ++m) _Pragma("unroll") for (int n = 0; n < 2; ++n) _Pragma("unroll") for (int k = 0; k < 2; ++k) \
;         acc[ai][bj][m][n] = __builtin_amdgcn_mfma_f32_16x16x32_bf16(Bt[n][k], At[m][k], acc[ai][bj][m][n], 0, 0, 0); __builtin_amdgcn_s_setprio(0); } while (0)
; #define PG8_WAIT_V(n) asm volatile("s_waitcnt vmcnt(" #n ")" ::: "memory")
; #define PG8_WAIT_L(n) asm volatile("s_waitcnt lgkmcnt(" #n ")" ::: "memory")
; #define PG8_BAR __builtin_amdgcn_s_barrier()
; #define PG8_SCHED __builtin_amdgcn_sched_barrier(0)
; template <class Epi, class Sched>
; __device__ __forceinline__ void gemm_phase(const int tid, LAS unsigned char* lds, const int lda, const int ldb, const int K, const Sched& S, const Epi& E) {
;     ...
;             PG8_LDB(B0, 1, 0); PG8_LDB(B1, 1, 1); PG8_SCHED; PG8_LDA(At, 1, 0); PG8_STAGE(PG8_SA(0, 1), a2 + hstepA, voffA);
;             PG8_WAIT_V(8); PG8_WAIT_L(0); PG8_BAR; PG8_MMA(0, 0, At, B0); PG8_MMA(0, 1, At, B1); PG8_BAR; PG8_SCHED;
	s_add_i32 s24, 0, 0x18000
	v_add_u32_e32 v176, s24, v146
	s_add_i32 s66, 0, 0x1c000
	ds_read_b128 v[154:157], v176
	ds_read_b128 v[158:161], v176 offset:1024
	ds_read_b128 v[162:165], v176 offset:2048
	ds_read_b128 v[180:183], v176 offset:3072
	v_add_u32_e32 v176, s66, v146
	ds_read_b128 v[184:187], v176
	ds_read_b128 v[190:193], v176 offset:1024
	ds_read_b128 v[194:197], v176 offset:2048
	ds_read_b128 v[204:207], v176 offset:3072
	s_mov_b32 m0, s29
	s_nop 0
	global_load_lds_dwordx4 v[242:243], off
	s_mov_b32 m0, s31
	s_nop 0
	global_load_lds_dwordx4 v[244:245], off
	s_add_u32 s54, s54, 0x40000
	s_addc_u32 s55, s55, 0
	s_mov_b32 m0, s56
	v_lshl_add_u64 v[246:247], s[54:55], 0, v[134:135]
	ds_read_b128 v[208:211], v153 offset:32768
	ds_read_b128 v[212:215], v153 offset:33792
	ds_read_b128 v[216:219], v153 offset:34816
	ds_read_b128 v[220:223], v153 offset:35840
	ds_read_b128 v[224:227], v153 offset:36864
	ds_read_b128 v[228:231], v153 offset:37888
	ds_read_b128 v[232:235], v153 offset:38912
	ds_read_b128 v[236:239], v153 offset:39936
	global_load_lds_dwordx4 v[246:247], off
	v_lshl_add_u64 v[246:247], s[54:55], 0, v[130:131]
	s_mov_b32 m0, s57
	s_nop 0
	global_load_lds_dwordx4 v[246:247], off
	s_waitcnt vmcnt(8)
	s_waitcnt lgkmcnt(0)
	s_barrier
	s_setprio 1
	v_mfma_f32_16x16x32_bf16 v[124:127], v[154:157], v[208:211], v[124:127]
	v_mfma_f32_16x16x32_bf16 v[116:119], v[162:165], v[208:211], v[116:119]
	v_mfma_f32_16x16x32_bf16 v[108:111], v[154:157], v[216:219], v[108:111]
	v_mfma_f32_16x16x32_bf16 v[100:103], v[162:165], v[216:219], v[100:103]
	v_mfma_f32_16x16x32_bf16 v[92:95], v[154:157], v[224:227], v[92:95]
	v_mfma_f32_16x16x32_bf16 v[84:87], v[162:165], v[224:227], v[84:87]
	v_mfma_f32_16x16x32_bf16 v[76:79], v[154:157], v[232:235], v[76:79]
	v_mfma_f32_16x16x32_bf16 v[68:71], v[162:165], v[232:235], v[68:71]
	v_mfma_f32_16x16x32_bf16 v[124:127], v[158:161], v[212:215], v[124:127]
	v_mfma_f32_16x16x32_bf16 v[116:119], v[180:183], v[212:215], v[116:119]
	v_mfma_f32_16x16x32_bf16 v[108:111], v[158:161], v[220:223], v[108:111]
	v_mfma_f32_16x16x32_bf16 v[100:103], v[180:183], v[220:223], v[100:103]
	v_mfma_f32_16x16x32_bf16 v[92:95], v[158:161], v[228:231], v[92:95]
	v_mfma_f32_16x16x32_bf16 v[84:87], v[180:183], v[228:231], v[84:87]
	v_mfma_f32_16x16x32_bf16 v[76:79], v[158:161], v[236:239], v[76:79]
	v_mfma_f32_16x16x32_bf16 v[68:71], v[180:183], v[236:239], v[68:71]
	v_mfma_f32_16x16x32_bf16 v[120:123], v[184:187], v[208:211], v[120:123]
	v_mfma_f32_16x16x32_bf16 v[112:115], v[194:197], v[208:211], v[112:115]
	v_mfma_f32_16x16x32_bf16 v[104:107], v[184:187], v[216:219], v[104:107]
	v_mfma_f32_16x16x32_bf16 v[96:99], v[194:197], v[216:219], v[96:99]
	v_mfma_f32_16x16x32_bf16 v[88:91], v[184:187], v[224:227], v[88:91]
	v_mfma_f32_16x16x32_bf16 v[80:83], v[194:197], v[224:227], v[80:83]
	v_mfma_f32_16x16x32_bf16 v[72:75], v[184:187], v[232:235], v[72:75]
	v_mfma_f32_16x16x32_bf16 v[64:67], v[194:197], v[232:235], v[64:67]
	v_mfma_f32_16x16x32_bf16 v[120:123], v[190:193], v[212:215], v[120:123]
	v_mfma_f32_16x16x32_bf16 v[112:115], v[204:207], v[212:215], v[112:115]
	v_mfma_f32_16x16x32_bf16 v[104:107], v[190:193], v[220:223], v[104:107]
	v_mfma_f32_16x16x32_bf16 v[96:99], v[204:207], v[220:223], v[96:99]
	v_mfma_f32_16x16x32_bf16 v[88:91], v[190:193], v[228:231], v[88:91]
	v_mfma_f32_16x16x32_bf16 v[80:83], v[204:207], v[228:231], v[80:83]
	v_mfma_f32_16x16x32_bf16 v[72:75], v[190:193], v[236:239], v[72:75]
	v_mfma_f32_16x16x32_bf16 v[64:67], v[204:207], v[236:239], v[64:67]
	s_setprio 0
	s_barrier
; #define PG8_STAGE(bufoff, gbase, voff) do { _Pragma("unroll") for (int _i = 0; _i < 2; ++_i) \
;         __builtin_amdgcn_global_load_lds((const unsigned*)((const char*)(gbase) + (voff)[_i]), (LAS unsigned*)(lds + (bufoff) + ldsw + _i * 8192), 16, 0, 0); } while (0)
; #define PG8_LDA(dst, b, h) do { _Pragma("unroll") for (int m = 0; m < 4; ++m) _Pragma("unroll") for (int k = 0; k < 2; ++k) dst[m][k] = *(const LAS bf16x8*)(lds + PG8_SA(b, h) + aoff + m * 2048 + k * 1024); } while (0)
; #define PG8_MMA(ai, bj, At, Bt) do { __builtin_amdgcn_s_setprio(1); _Pragma("unroll") for (int m = 0; m < 4; ++m) _Pragma("unroll") for (int n = 0; n < 2; ++n) _Pragma("unroll") for (int k = 0; k < 2; ++k) \
;         acc[ai][bj][m][n] = __builtin_amdgcn_mfma_f32_16x16x32_bf16(Bt[n][k], At[m][k], acc[ai][bj][m][n], 0, 0, 0); __builtin_amdgcn_s_setprio(0); } while (0)
; #define PG8_WAIT_V(n) asm volatile("s_waitcnt vmcnt(" #n ")" ::: "memory")
; #define PG8_WAIT_L(n) asm volatile("s_waitcnt lgkmcnt(" #n ")" ::: "memory")
; #define PG8_BAR __builtin_amdgcn_s_barrier()
; #define PG8_SCHED __builtin_amdgcn_sched_barrier(0)
; template <class Epi, class Sched>
; __device__ __forceinline__ void gemm_phase(const int tid, LAS unsigned char* lds, const int lda, const int ldb, const int K, const Sched& S, const Epi& E) {
;     ...
;             PG8_LDA(At, 1, 1); PG8_STAGE(PG8_SB(1, 0), b3, voffB); PG8_STAGE(PG8_SB(1, 1), b3 + hstepB, voffB); PG8_STAGE(PG8_SA(1, 0), a3, voffA);
;             PG8_WAIT_V(8); PG8_WAIT_L(0); PG8_BAR; if (!cur.half) { PG8_MMA(1, 0, At, B0); PG8_MMA(1, 1, At, B1); } PG8_BAR; PG8_SCHED;
;         }
	s_add_i32 s24, s24, s20
	v_lshl_add_u64 v[166:167], v[166:167], 0, s[6:7]
	s_mov_b32 m0, s24
	ds_read_b128 v[208:211], v153 offset:49152
	ds_read_b128 v[212:215], v153 offset:50176
	ds_read_b128 v[216:219], v153 offset:51200
	ds_read_b128 v[220:223], v153 offset:52224
	ds_read_b128 v[224:227], v153 offset:53248
	ds_read_b128 v[228:231], v153 offset:54272
	ds_read_b128 v[232:235], v153 offset:55296
	ds_read_b128 v[236:239], v153 offset:56320
	global_load_lds_dwordx4 v[166:167], off
	s_add_i32 m0, s24, 0x2000
	s_add_u32 s52, s52, 0x40080
	v_lshl_add_u64 v[166:167], v[240:241], 0, s[6:7]
	s_addc_u32 s53, s53, 0
	s_add_i32 s24, s66, s20
	global_load_lds_dwordx4 v[166:167], off
	v_lshl_add_u64 v[166:167], s[52:53], 0, v[132:133]
	s_mov_b32 m0, s24
	s_nop 0
	global_load_lds_dwordx4 v[166:167], off
	v_lshl_add_u64 v[166:167], s[52:53], 0, v[128:129]
	s_add_i32 m0, s24, 0x2000
	s_nop 0
	global_load_lds_dwordx4 v[166:167], off
	v_lshl_add_u64 v[166:167], v[242:243], 0, s[6:7]
	s_mov_b32 m0, s58
	s_nop 0
	global_load_lds_dwordx4 v[166:167], off
	v_lshl_add_u64 v[166:167], v[244:245], 0, s[6:7]
	s_mov_b32 m0, s59
	s_nop 0
	global_load_lds_dwordx4 v[166:167], off
	s_waitcnt vmcnt(8)
	s_waitcnt lgkmcnt(0)
	s_barrier
	s_setprio 1
	v_mfma_f32_16x16x32_bf16 v[60:63], v[154:157], v[208:211], v[60:63]
	v_mfma_f32_16x16x32_bf16 v[52:55], v[162:165], v[208:211], v[52:55]
	v_mfma_f32_16x16x32_bf16 v[44:47], v[154:157], v[216:219], v[44:47]
	v_mfma_f32_16x16x32_bf16 v[36:39], v[162:165], v[216:219], v[36:39]
	v_mfma_f32_16x16x32_bf16 v[28:31], v[154:157], v[224:227], v[28:31]
	v_mfma_f32_16x16x32_bf16 v[20:23], v[162:165], v[224:227], v[20:23]
	v_mfma_f32_16x16x32_bf16 v[12:15], v[154:157], v[232:235], v[12:15]
	v_mfma_f32_16x16x32_bf16 v[4:7], v[162:165], v[232:235], v[4:7]
	v_mfma_f32_16x16x32_bf16 v[60:63], v[158:161], v[212:215], v[60:63]
	v_mfma_f32_16x16x32_bf16 v[52:55], v[180:183], v[212:215], v[52:55]
	v_mfma_f32_16x16x32_bf16 v[44:47], v[158:161], v[220:223], v[44:47]
	v_mfma_f32_16x16x32_bf16 v[36:39], v[180:183], v[220:223], v[36:39]
	v_mfma_f32_16x16x32_bf16 v[28:31], v[158:161], v[228:231], v[28:31]
	v_mfma_f32_16x16x32_bf16 v[20:23], v[180:183], v[228:231], v[20:23]
	v_mfma_f32_16x16x32_bf16 v[12:15], v[158:161], v[236:239], v[12:15]
	v_mfma_f32_16x16x32_bf16 v[4:7], v[180:183], v[236:239], v[4:7]
	v_mfma_f32_16x16x32_bf16 v[56:59], v[184:187], v[208:211], v[56:59]
	v_mfma_f32_16x16x32_bf16 v[48:51], v[194:197], v[208:211], v[48:51]
	v_mfma_f32_16x16x32_bf16 v[40:43], v[184:187], v[216:219], v[40:43]
	v_mfma_f32_16x16x32_bf16 v[32:35], v[194:197], v[216:219], v[32:35]
	v_mfma_f32_16x16x32_bf16 v[24:27], v[184:187], v[224:227], v[24:27]
	v_mfma_f32_16x16x32_bf16 v[16:19], v[194:197], v[224:227], v[16:19]
	v_mfma_f32_16x16x32_bf16 v[8:11], v[184:187], v[232:235], v[8:11]
	v_mfma_f32_16x16x32_bf16 v[0:3], v[194:197], v[232:235], v[0:3]
	v_mfma_f32_16x16x32_bf16 v[56:59], v[190:193], v[212:215], v[56:59]
	v_mfma_f32_16x16x32_bf16 v[48:51], v[204:207], v[212:215], v[48:51]
	v_mfma_f32_16x16x32_bf16 v[40:43], v[190:193], v[220:223], v[40:43]
	v_mfma_f32_16x16x32_bf16 v[32:35], v[204:207], v[220:223], v[32:35]
	v_mfma_f32_16x16x32_bf16 v[24:27], v[190:193], v[228:231], v[24:27]
	v_mfma_f32_16x16x32_bf16 v[16:19], v[204:207], v[228:231], v[16:19]
	v_mfma_f32_16x16x32_bf16 v[8:11], v[190:193], v[236:239], v[8:11]
	v_mfma_f32_16x16x32_bf16 v[0:3], v[204:207], v[236:239], v[0:3]
	s_setprio 0
	s_barrier
	s_add_u32 s50, s50, 0x100
	s_addc_u32 s51, s51, 0
	s_add_u32 s45, s45, 0x100
	s_addc_u32 s64, s64, 0
	s_cmp_ge_i32 s65, s13
	s_mov_b32 s52, s65
	s_cbranch_scc0 .LBB0_896
